# GEMM loops: m0 write swapped with the DMA address add so the add supplies the M0 wait state; 66 s_nop pads dropped
# baseline (speedup 1.0000x reference)
; #define PG8_STAGE(bufoff, gbase, voff) do { _Pragma("unroll") for (int _i = 0; _i < 2; ++_i) \
;         __builtin_amdgcn_global_load_lds((const unsigned*)((const char*)(gbase) + (voff)[_i]), (LAS unsigned*)(lds + (bufoff) + ldsw + _i * 8192), 16, 0, 0); } while (0)
; #define PG8_LDA(dst, b, h) do { _Pragma("unroll") for (int m = 0; m < 4; ++m) _Pragma("unroll") for (int k = 0; k < 2; ++k) dst[m][k] = *(const LAS bf16x8*)(lds + PG8_SA(b, h) + aoff + m * 2048 + k * 1024); } while (0)
; #define PG8_LDB(dst, b, h) do { _Pragma("unroll") for (int n = 0; n < 2; ++n) _Pragma("unroll") for (int k = 0; k < 2; ++k) dst[n][k] = *(const LAS bf16x8*)(lds + PG8_SB(b, h) + boff + n * 2048 + k * 1024); } while (0)
; #define PG8_MMA(ai, bj, At, Bt) do { __builtin_amdgcn_s_setprio(1); _Pragma("unroll") for (int m = 0; m < 4; ++m) _Pragma("unroll") for (int n = 0; n < 2; ++n) _Pragma("unroll") for (int k = 0; k < 2; ++k) \
;         acc[ai][bj][m][n] = __builtin_amdgcn_mfma_f32_16x16x32_bf16(Bt[n][k], At[m][k], acc[ai][bj][m][n], 0, 0, 0); __builtin_amdgcn_s_setprio(0); } while (0)
; #define PG8_WAIT_L(n) asm volatile("s_waitcnt lgkmcnt(" #n ")" ::: "memory")
; #define PG8_BAR __builtin_amdgcn_s_barrier()
; #define PG8_SCHED __builtin_amdgcn_sched_barrier(0)
; template <class Epi, class Sched>
; __device__ __forceinline__ void gemm_phase(LAS unsigned char* lds, const Gemm g, const Sched& S, const Epi& E) {
;     ...
;             const char* a1 = cA + (size_t)(t + 1) * kstep;
;             const char* a2 = last ? nA : cA + (size_t)(t + 2) * kstep; const char* b2 = last ? nB : cB + (size_t)(t + 2) * kstep;
;             const char* a3 = a2 + kstep; const char* b3 = b2 + kstep;
;             PG8_LDB(B0, 0, 0); PG8_SCHED; PG8_LDA(At, 0, 0); PG8_STAGE(PG8_SA(1, 1), a1 + hstepA, voffA);
;             PG8_WAIT_L(8); PG8_BAR; PG8_WAIT_L(0); PG8_MMA(0, 0, At, B0); PG8_BAR; PG8_SCHED;
;             PG8_LDB(B1, 0, 1); PG8_STAGE(PG8_SB(0, 0), b2, voffB);
;             PG8_BAR; PG8_WAIT_L(0); PG8_MMA(0, 1, At, B1); PG8_BAR;
;             PG8_LDA(At, 0, 1); PG8_STAGE(PG8_SA(0, 0), a2, voffA);
;             PG8_BAR; PG8_WAIT_L(0); PG8_MMA(1, 0, At, B0); PG8_BAR; PG8_SCHED;
.LBB0_197:
	s_add_u32 s54, s52, 0xfff80080
	s_addc_u32 s55, s53, -1
	s_add_i32 s67, 0, 0x10000
	v_add_u32_e32 v146, s67, v139
	ds_read_b128 v[170:173], v146
	ds_read_b128 v[174:177], v146 offset:1024
	ds_read_b128 v[178:181], v146 offset:2048
	ds_read_b128 v[182:185], v146 offset:3072
	s_cmp_eq_u32 s66, 28
	s_cselect_b32 s57, s37, s55
	s_cselect_b32 s56, s51, s54
	s_cselect_b32 s55, s1, vcc_hi
	s_cselect_b32 s54, s93, vcc_lo
	v_lshl_add_u64 v[146:147], s[52:53], 0, v[142:143]
	s_add_i32 m0, s26, 0xc000
	ds_read_b128 v[186:189], v150
	ds_read_b128 v[190:193], v150 offset:1024
	ds_read_b128 v[194:197], v150 offset:2048
	ds_read_b128 v[210:213], v150 offset:3072
	ds_read_b128 v[214:217], v150 offset:4096
	ds_read_b128 v[218:221], v150 offset:5120
	ds_read_b128 v[222:225], v150 offset:6144
	ds_read_b128 v[226:229], v150 offset:7168
	global_load_lds_dwordx4 v[146:147], off
	s_add_i32 m0, s26, 0xe000
	v_lshl_add_u64 v[146:147], s[52:53], 0, v[144:145]
	global_load_lds_dwordx4 v[146:147], off
	s_waitcnt lgkmcnt(8)
	s_barrier
	s_waitcnt lgkmcnt(0)
	v_mfma_f32_16x16x32_bf16 v[126:129], v[170:173], v[186:189], v[126:129]
	v_mfma_f32_16x16x32_bf16 v[122:125], v[178:181], v[186:189], v[122:125]
	v_mfma_f32_16x16x32_bf16 v[110:113], v[170:173], v[194:197], v[110:113]
	v_mfma_f32_16x16x32_bf16 v[106:109], v[178:181], v[194:197], v[106:109]
	v_mfma_f32_16x16x32_bf16 v[94:97], v[170:173], v[214:217], v[94:97]
	v_mfma_f32_16x16x32_bf16 v[90:93], v[178:181], v[214:217], v[90:93]
	v_mfma_f32_16x16x32_bf16 v[78:81], v[170:173], v[222:225], v[78:81]
	v_mfma_f32_16x16x32_bf16 v[74:77], v[178:181], v[222:225], v[74:77]
	v_mfma_f32_16x16x32_bf16 v[126:129], v[174:177], v[190:193], v[126:129]
	v_mfma_f32_16x16x32_bf16 v[122:125], v[182:185], v[190:193], v[122:125]
	v_mfma_f32_16x16x32_bf16 v[110:113], v[174:177], v[210:213], v[110:113]
	v_mfma_f32_16x16x32_bf16 v[106:109], v[182:185], v[210:213], v[106:109]
	v_mfma_f32_16x16x32_bf16 v[94:97], v[174:177], v[218:221], v[94:97]
	v_mfma_f32_16x16x32_bf16 v[90:93], v[182:185], v[218:221], v[90:93]
	v_mfma_f32_16x16x32_bf16 v[78:81], v[174:177], v[226:229], v[78:81]
	v_mfma_f32_16x16x32_bf16 v[74:77], v[182:185], v[226:229], v[74:77]
	s_barrier
	s_add_i32 s23, 0, 0x14000
	v_add_u32_e32 v146, s23, v139
	s_add_i32 s67, s67, s25
	ds_read_b128 v[230:233], v146
	ds_read_b128 v[234:237], v146 offset:1024
	ds_read_b128 v[238:241], v146 offset:2048
	ds_read_b128 v[242:245], v146 offset:3072
	v_lshl_add_u64 v[146:147], s[54:55], 0, v[132:133]
	s_mov_b32 m0, s67
	v_lshl_add_u64 v[152:153], s[54:55], 0, v[136:137]
	global_load_lds_dwordx4 v[146:147], off
	s_add_i32 m0, s67, 0x2000
	s_nop 0
	global_load_lds_dwordx4 v[152:153], off
	s_barrier
	s_waitcnt lgkmcnt(0)
	v_mfma_f32_16x16x32_bf16 v[118:121], v[230:233], v[186:189], v[118:121]
	v_mfma_f32_16x16x32_bf16 v[114:117], v[238:241], v[186:189], v[114:117]
	v_mfma_f32_16x16x32_bf16 v[102:105], v[230:233], v[194:197], v[102:105]
	v_mfma_f32_16x16x32_bf16 v[98:101], v[238:241], v[194:197], v[98:101]
	v_mfma_f32_16x16x32_bf16 v[86:89], v[230:233], v[214:217], v[86:89]
	v_mfma_f32_16x16x32_bf16 v[82:85], v[238:241], v[214:217], v[82:85]
	v_mfma_f32_16x16x32_bf16 v[70:73], v[230:233], v[222:225], v[70:73]
	v_mfma_f32_16x16x32_bf16 v[66:69], v[238:241], v[222:225], v[66:69]
	v_mfma_f32_16x16x32_bf16 v[118:121], v[234:237], v[190:193], v[118:121]
	v_mfma_f32_16x16x32_bf16 v[114:117], v[242:245], v[190:193], v[114:117]
	v_mfma_f32_16x16x32_bf16 v[102:105], v[234:237], v[210:213], v[102:105]
	v_mfma_f32_16x16x32_bf16 v[98:101], v[242:245], v[210:213], v[98:101]
	v_mfma_f32_16x16x32_bf16 v[86:89], v[234:237], v[218:221], v[86:89]
	v_mfma_f32_16x16x32_bf16 v[82:85], v[242:245], v[218:221], v[82:85]
	v_mfma_f32_16x16x32_bf16 v[70:73], v[234:237], v[226:229], v[70:73]
	v_mfma_f32_16x16x32_bf16 v[66:69], v[242:245], v[226:229], v[66:69]
	s_mov_b32 m0, s26
	v_lshl_add_u64 v[198:199], s[56:57], 0, v[130:131]
	s_barrier
	ds_read_b128 v[186:189], v150 offset:16384
	ds_read_b128 v[190:193], v150 offset:17408
	ds_read_b128 v[194:197], v150 offset:18432
	ds_read_b128 v[210:213], v150 offset:19456
	ds_read_b128 v[214:217], v150 offset:20480
	ds_read_b128 v[218:221], v150 offset:21504
	ds_read_b128 v[222:225], v150 offset:22528
	ds_read_b128 v[226:229], v150 offset:23552
	global_load_lds_dwordx4 v[198:199], off
	s_mov_b32 m0, s27
	v_lshl_add_u64 v[246:247], s[56:57], 0, v[134:135]
	global_load_lds_dwordx4 v[246:247], off
	s_barrier
	s_waitcnt lgkmcnt(0)
	v_mfma_f32_16x16x32_bf16 v[62:65], v[170:173], v[186:189], v[62:65]
	v_mfma_f32_16x16x32_bf16 v[58:61], v[178:181], v[186:189], v[58:61]
	v_mfma_f32_16x16x32_bf16 v[46:49], v[170:173], v[194:197], v[46:49]
	v_mfma_f32_16x16x32_bf16 v[42:45], v[178:181], v[194:197], v[42:45]
	v_mfma_f32_16x16x32_bf16 v[30:33], v[170:173], v[214:217], v[30:33]
	v_mfma_f32_16x16x32_bf16 v[26:29], v[178:181], v[214:217], v[26:29]
	v_mfma_f32_16x16x32_bf16 v[14:17], v[170:173], v[222:225], v[14:17]
	v_mfma_f32_16x16x32_bf16 v[10:13], v[178:181], v[222:225], v[10:13]
	v_mfma_f32_16x16x32_bf16 v[62:65], v[174:177], v[190:193], v[62:65]
	v_mfma_f32_16x16x32_bf16 v[58:61], v[182:185], v[190:193], v[58:61]
	v_mfma_f32_16x16x32_bf16 v[46:49], v[174:177], v[210:213], v[46:49]
	v_mfma_f32_16x16x32_bf16 v[42:45], v[182:185], v[210:213], v[42:45]
	v_mfma_f32_16x16x32_bf16 v[30:33], v[174:177], v[218:221], v[30:33]
	v_mfma_f32_16x16x32_bf16 v[26:29], v[182:185], v[218:221], v[26:29]
	v_mfma_f32_16x16x32_bf16 v[14:17], v[174:177], v[226:229], v[14:17]
	v_mfma_f32_16x16x32_bf16 v[10:13], v[182:185], v[226:229], v[10:13]
	s_barrier
; #define PG8_STAGE(bufoff, gbase, voff) do { _Pragma("unroll") for (int _i = 0; _i < 2; ++_i) \
;         __builtin_amdgcn_global_load_lds((const unsigned*)((const char*)(gbase) + (voff)[_i]), (LAS unsigned*)(lds + (bufoff) + ldsw + _i * 8192), 16, 0, 0); } while (0)
; #define PG8_LDA(dst, b, h) do { _Pragma("unroll") for (int m = 0; m < 4; ++m) _Pragma("unroll") for (int k = 0; k < 2; ++k) dst[m][k] = *(const LAS bf16x8*)(lds + PG8_SA(b, h) + aoff + m * 2048 + k * 1024); } while (0)
; #define PG8_LDB(dst, b, h) do { _Pragma("unroll") for (int n = 0; n < 2; ++n) _Pragma("unroll") for (int k = 0; k < 2; ++k) dst[n][k] = *(const LAS bf16x8*)(lds + PG8_SB(b, h) + boff + n * 2048 + k * 1024); } while (0)
; #define PG8_MMA(ai, bj, At, Bt) do { __builtin_amdgcn_s_setprio(1); _Pragma("unroll") for (int m = 0; m < 4; ++m) _Pragma("unroll") for (int n = 0; n < 2; ++n) _Pragma("unroll") for (int k = 0; k < 2; ++k) \
;         acc[ai][bj][m][n] = __builtin_amdgcn_mfma_f32_16x16x32_bf16(Bt[n][k], At[m][k], acc[ai][bj][m][n], 0, 0, 0); __builtin_amdgcn_s_setprio(0); } while (0)
; #define PG8_WAIT_V(n) asm volatile("s_waitcnt vmcnt(" #n ")" ::: "memory")
; #define PG8_WAIT_L(n) asm volatile("s_waitcnt lgkmcnt(" #n ")" ::: "memory")
; #define PG8_BAR __builtin_amdgcn_s_barrier()
; #define PG8_SCHED __builtin_amdgcn_sched_barrier(0)
; template <class Epi, class Sched>
; __device__ __forceinline__ void gemm_phase(LAS unsigned char* lds, const Gemm g, const Sched& S, const Epi& E) {
;     ...
;             PG8_STAGE(PG8_SB(0, 1), b2 + hstepB, voffB);
;             PG8_WAIT_V(6); PG8_BAR; PG8_MMA(1, 1, At, B1); PG8_BAR;
;             PG8_LDB(B0, 1, 0); PG8_SCHED; PG8_LDA(At, 1, 0); PG8_STAGE(PG8_SA(0, 1), a2 + hstepA, voffA);
;             PG8_WAIT_L(8); PG8_BAR; PG8_WAIT_L(0); PG8_MMA(0, 0, At, B0); PG8_BAR; PG8_SCHED;
;             PG8_LDB(B1, 1, 1); PG8_STAGE(PG8_SB(1, 0), b3, voffB);
;             PG8_BAR; PG8_WAIT_L(0); PG8_MMA(0, 1, At, B1); PG8_BAR;
;             PG8_LDA(At, 1, 1); PG8_STAGE(PG8_SA(1, 0), a3, voffA);
	s_add_u32 s84, s54, 0x80000
	s_addc_u32 s85, s55, 0
	s_add_i32 s23, s23, s25
	s_mov_b32 m0, s23
	v_lshl_add_u64 v[170:171], s[84:85], 0, v[132:133]
	global_load_lds_dwordx4 v[170:171], off
	s_add_i32 m0, s23, 0x2000
	v_lshl_add_u64 v[170:171], s[84:85], 0, v[136:137]
	global_load_lds_dwordx4 v[170:171], off
	s_waitcnt vmcnt(6)
	s_barrier
	v_mfma_f32_16x16x32_bf16 v[54:57], v[230:233], v[186:189], v[54:57]
	v_mfma_f32_16x16x32_bf16 v[50:53], v[238:241], v[186:189], v[50:53]
	v_mfma_f32_16x16x32_bf16 v[38:41], v[230:233], v[194:197], v[38:41]
	v_mfma_f32_16x16x32_bf16 v[34:37], v[238:241], v[194:197], v[34:37]
	v_mfma_f32_16x16x32_bf16 v[22:25], v[230:233], v[214:217], v[22:25]
	v_mfma_f32_16x16x32_bf16 v[18:21], v[238:241], v[214:217], v[18:21]
	v_mfma_f32_16x16x32_bf16 v[6:9], v[230:233], v[222:225], v[6:9]
	v_mfma_f32_16x16x32_bf16 v[2:5], v[238:241], v[222:225], v[2:5]
	v_mfma_f32_16x16x32_bf16 v[54:57], v[234:237], v[190:193], v[54:57]
	v_mfma_f32_16x16x32_bf16 v[50:53], v[242:245], v[190:193], v[50:53]
	v_mfma_f32_16x16x32_bf16 v[38:41], v[234:237], v[210:213], v[38:41]
	v_mfma_f32_16x16x32_bf16 v[34:37], v[242:245], v[210:213], v[34:37]
	v_mfma_f32_16x16x32_bf16 v[22:25], v[234:237], v[218:221], v[22:25]
	v_mfma_f32_16x16x32_bf16 v[18:21], v[242:245], v[218:221], v[18:21]
	v_mfma_f32_16x16x32_bf16 v[6:9], v[234:237], v[226:229], v[6:9]
	v_mfma_f32_16x16x32_bf16 v[2:5], v[242:245], v[226:229], v[2:5]
	s_add_i32 s23, 0, 0x18000
	v_add_u32_e32 v151, s23, v139
	s_barrier
	ds_read_b128 v[170:173], v151
	ds_read_b128 v[174:177], v151 offset:1024
	ds_read_b128 v[178:181], v151 offset:2048
	ds_read_b128 v[182:185], v151 offset:3072
	s_add_u32 s56, s56, 0x80000
	s_addc_u32 s57, s57, 0
	s_mov_b32 m0, s28
	v_lshl_add_u64 v[230:231], s[56:57], 0, v[130:131]
	ds_read_b128 v[186:189], v150 offset:32768
	ds_read_b128 v[190:193], v150 offset:33792
	ds_read_b128 v[194:197], v150 offset:34816
	ds_read_b128 v[210:213], v150 offset:35840
	ds_read_b128 v[214:217], v150 offset:36864
	ds_read_b128 v[218:221], v150 offset:37888
	ds_read_b128 v[222:225], v150 offset:38912
	ds_read_b128 v[226:229], v150 offset:39936
	global_load_lds_dwordx4 v[230:231], off
	s_mov_b32 m0, s29
	v_lshl_add_u64 v[230:231], s[56:57], 0, v[134:135]
	global_load_lds_dwordx4 v[230:231], off
	s_waitcnt lgkmcnt(8)
	s_barrier
	s_waitcnt lgkmcnt(0)
	v_mfma_f32_16x16x32_bf16 v[126:129], v[170:173], v[186:189], v[126:129]
	v_mfma_f32_16x16x32_bf16 v[122:125], v[178:181], v[186:189], v[122:125]
	v_mfma_f32_16x16x32_bf16 v[110:113], v[170:173], v[194:197], v[110:113]
	v_mfma_f32_16x16x32_bf16 v[106:109], v[178:181], v[194:197], v[106:109]
	v_mfma_f32_16x16x32_bf16 v[94:97], v[170:173], v[214:217], v[94:97]
	v_mfma_f32_16x16x32_bf16 v[90:93], v[178:181], v[214:217], v[90:93]
	v_mfma_f32_16x16x32_bf16 v[78:81], v[170:173], v[222:225], v[78:81]
	v_mfma_f32_16x16x32_bf16 v[74:77], v[178:181], v[222:225], v[74:77]
	v_mfma_f32_16x16x32_bf16 v[126:129], v[174:177], v[190:193], v[126:129]
	v_mfma_f32_16x16x32_bf16 v[122:125], v[182:185], v[190:193], v[122:125]
	v_mfma_f32_16x16x32_bf16 v[110:113], v[174:177], v[210:213], v[110:113]
	v_mfma_f32_16x16x32_bf16 v[106:109], v[182:185], v[210:213], v[106:109]
	v_mfma_f32_16x16x32_bf16 v[94:97], v[174:177], v[218:221], v[94:97]
	v_mfma_f32_16x16x32_bf16 v[90:93], v[182:185], v[218:221], v[90:93]
	v_mfma_f32_16x16x32_bf16 v[78:81], v[174:177], v[226:229], v[78:81]
	v_mfma_f32_16x16x32_bf16 v[74:77], v[182:185], v[226:229], v[74:77]
	s_barrier
	s_add_i32 s56, 0, 0x1c000
	s_add_i32 s23, s23, s25
	v_add_u32_e32 v151, s56, v139
	v_lshl_add_u64 v[146:147], v[146:147], 0, s[10:11]
	s_mov_b32 m0, s23
	ds_read_b128 v[230:233], v151
	ds_read_b128 v[234:237], v151 offset:1024
	ds_read_b128 v[238:241], v151 offset:2048
	ds_read_b128 v[242:245], v151 offset:3072
	global_load_lds_dwordx4 v[146:147], off
	s_add_i32 m0, s23, 0x2000
	v_lshl_add_u64 v[146:147], v[152:153], 0, s[10:11]
	global_load_lds_dwordx4 v[146:147], off
	s_barrier
; #define PG8_STAGE(bufoff, gbase, voff) do { _Pragma("unroll") for (int _i = 0; _i < 2; ++_i) \
;         __builtin_amdgcn_global_load_lds((const unsigned*)((const char*)(gbase) + (voff)[_i]), (LAS unsigned*)(lds + (bufoff) + ldsw + _i * 8192), 16, 0, 0); } while (0)
; #define PG8_MMA(ai, bj, At, Bt) do { __builtin_amdgcn_s_setprio(1); _Pragma("unroll") for (int m = 0; m < 4; ++m) _Pragma("unroll") for (int n = 0; n < 2; ++n) _Pragma("unroll") for (int k = 0; k < 2; ++k) \
;         acc[ai][bj][m][n] = __builtin_amdgcn_mfma_f32_16x16x32_bf16(Bt[n][k], At[m][k], acc[ai][bj][m][n], 0, 0, 0); __builtin_amdgcn_s_setprio(0); } while (0)
; #define PG8_WAIT_V(n) asm volatile("s_waitcnt vmcnt(" #n ")" ::: "memory")
; #define PG8_WAIT_L(n) asm volatile("s_waitcnt lgkmcnt(" #n ")" ::: "memory")
; #define PG8_BAR __builtin_amdgcn_s_barrier()
; #define PG8_SCHED __builtin_amdgcn_sched_barrier(0)
;     __device__ __forceinline__ void operator()(const f32x4 (&acc)[2][2][4][2], const Unit& u, int ui, const LAS float* rtab, int wr, int wc, int fr, int fq) const {
;         const int row0 = u.pm * BM + wr * 64 + fr; const int colt = u.pn * BM; const int t = colt >> shift; const int lc0 = (colt & ((1 << shift) - 1)) + wc * 32 + 8 * fq;
;         bf16_t* base = (t == 0) ? Q : ((t == 1) ? K : V);
; template <class Epi, class Sched>
; __device__ __forceinline__ void gemm_phase(LAS unsigned char* lds, const Gemm g, const Sched& S, const Epi& E) {
;     ...
;             PG8_BAR; PG8_WAIT_L(0); PG8_MMA(1, 0, At, B0); PG8_BAR; PG8_SCHED;
;             PG8_STAGE(PG8_SB(1, 1), b3 + hstepB, voffB);
;             PG8_WAIT_V(6); PG8_BAR; PG8_MMA(1, 1, At, B1); PG8_BAR;
;         }
	s_waitcnt lgkmcnt(0)
	v_mfma_f32_16x16x32_bf16 v[118:121], v[230:233], v[186:189], v[118:121]
	v_mfma_f32_16x16x32_bf16 v[114:117], v[238:241], v[186:189], v[114:117]
	v_mfma_f32_16x16x32_bf16 v[102:105], v[230:233], v[194:197], v[102:105]
	v_mfma_f32_16x16x32_bf16 v[98:101], v[238:241], v[194:197], v[98:101]
	v_mfma_f32_16x16x32_bf16 v[86:89], v[230:233], v[214:217], v[86:89]
	v_mfma_f32_16x16x32_bf16 v[82:85], v[238:241], v[214:217], v[82:85]
	v_mfma_f32_16x16x32_bf16 v[70:73], v[230:233], v[222:225], v[70:73]
	v_mfma_f32_16x16x32_bf16 v[66:69], v[238:241], v[222:225], v[66:69]
	v_mfma_f32_16x16x32_bf16 v[118:121], v[234:237], v[190:193], v[118:121]
	v_mfma_f32_16x16x32_bf16 v[114:117], v[242:245], v[190:193], v[114:117]
	v_mfma_f32_16x16x32_bf16 v[102:105], v[234:237], v[210:213], v[102:105]
	v_mfma_f32_16x16x32_bf16 v[98:101], v[242:245], v[210:213], v[98:101]
	v_mfma_f32_16x16x32_bf16 v[86:89], v[234:237], v[218:221], v[86:89]
	v_mfma_f32_16x16x32_bf16 v[82:85], v[242:245], v[218:221], v[82:85]
	v_mfma_f32_16x16x32_bf16 v[70:73], v[234:237], v[226:229], v[70:73]
	v_mfma_f32_16x16x32_bf16 v[66:69], v[242:245], v[226:229], v[66:69]
	s_mov_b32 m0, s35
	v_lshl_add_u64 v[146:147], v[198:199], 0, s[10:11]
	s_barrier
	ds_read_b128 v[186:189], v150 offset:49152
	ds_read_b128 v[190:193], v150 offset:50176
	ds_read_b128 v[194:197], v150 offset:51200
	ds_read_b128 v[210:213], v150 offset:52224
	ds_read_b128 v[214:217], v150 offset:53248
	ds_read_b128 v[218:221], v150 offset:54272
	ds_read_b128 v[222:225], v150 offset:55296
	ds_read_b128 v[226:229], v150 offset:56320
	global_load_lds_dwordx4 v[146:147], off
	s_mov_b32 m0, s45
	v_lshl_add_u64 v[146:147], v[246:247], 0, s[10:11]
	global_load_lds_dwordx4 v[146:147], off
	s_barrier
	s_waitcnt lgkmcnt(0)
	v_mfma_f32_16x16x32_bf16 v[62:65], v[170:173], v[186:189], v[62:65]
	v_mfma_f32_16x16x32_bf16 v[58:61], v[178:181], v[186:189], v[58:61]
	v_mfma_f32_16x16x32_bf16 v[46:49], v[170:173], v[194:197], v[46:49]
	v_mfma_f32_16x16x32_bf16 v[42:45], v[178:181], v[194:197], v[42:45]
	v_mfma_f32_16x16x32_bf16 v[30:33], v[170:173], v[214:217], v[30:33]
	v_mfma_f32_16x16x32_bf16 v[26:29], v[178:181], v[214:217], v[26:29]
	v_mfma_f32_16x16x32_bf16 v[14:17], v[170:173], v[222:225], v[14:17]
	v_mfma_f32_16x16x32_bf16 v[10:13], v[178:181], v[222:225], v[10:13]
	v_mfma_f32_16x16x32_bf16 v[62:65], v[174:177], v[190:193], v[62:65]
	v_mfma_f32_16x16x32_bf16 v[58:61], v[182:185], v[190:193], v[58:61]
	v_mfma_f32_16x16x32_bf16 v[46:49], v[174:177], v[210:213], v[46:49]
	v_mfma_f32_16x16x32_bf16 v[42:45], v[182:185], v[210:213], v[42:45]
	v_mfma_f32_16x16x32_bf16 v[30:33], v[174:177], v[218:221], v[30:33]
	v_mfma_f32_16x16x32_bf16 v[26:29], v[182:185], v[218:221], v[26:29]
	v_mfma_f32_16x16x32_bf16 v[14:17], v[174:177], v[226:229], v[14:17]
	v_mfma_f32_16x16x32_bf16 v[10:13], v[182:185], v[226:229], v[10:13]
	s_barrier
	s_add_u32 s54, s54, 0x80080
	s_addc_u32 s55, s55, 0
	s_add_i32 s23, s56, s25
	s_mov_b32 m0, s23
	v_lshl_add_u64 v[146:147], s[54:55], 0, v[132:133]
	global_load_lds_dwordx4 v[146:147], off
	s_add_i32 m0, s23, 0x2000
	v_lshl_add_u64 v[146:147], s[54:55], 0, v[136:137]
	global_load_lds_dwordx4 v[146:147], off
	s_waitcnt vmcnt(6)
	s_barrier
	v_mfma_f32_16x16x32_bf16 v[54:57], v[230:233], v[186:189], v[54:57]
	v_mfma_f32_16x16x32_bf16 v[50:53], v[238:241], v[186:189], v[50:53]
	v_mfma_f32_16x16x32_bf16 v[38:41], v[230:233], v[194:197], v[38:41]
	v_mfma_f32_16x16x32_bf16 v[34:37], v[238:241], v[194:197], v[34:37]
	v_mfma_f32_16x16x32_bf16 v[22:25], v[230:233], v[214:217], v[22:25]
	v_mfma_f32_16x16x32_bf16 v[18:21], v[238:241], v[214:217], v[18:21]
	v_mfma_f32_16x16x32_bf16 v[6:9], v[230:233], v[222:225], v[6:9]
	v_mfma_f32_16x16x32_bf16 v[2:5], v[238:241], v[222:225], v[2:5]
	v_mfma_f32_16x16x32_bf16 v[54:57], v[234:237], v[190:193], v[54:57]
	v_mfma_f32_16x16x32_bf16 v[50:53], v[242:245], v[190:193], v[50:53]
	v_mfma_f32_16x16x32_bf16 v[38:41], v[234:237], v[210:213], v[38:41]
	v_mfma_f32_16x16x32_bf16 v[34:37], v[242:245], v[210:213], v[34:37]
	v_mfma_f32_16x16x32_bf16 v[22:25], v[234:237], v[218:221], v[22:25]
	v_mfma_f32_16x16x32_bf16 v[18:21], v[242:245], v[218:221], v[18:21]
	v_mfma_f32_16x16x32_bf16 v[6:9], v[234:237], v[226:229], v[6:9]
	v_mfma_f32_16x16x32_bf16 v[2:5], v[242:245], v[226:229], v[2:5]
	s_add_i32 s66, s66, 2
	s_add_u32 s52, s52, 0x100
	s_addc_u32 s53, s53, 0
	s_add_u32 vcc_lo, vcc_lo, 0x100
	s_addc_u32 vcc_hi, vcc_hi, 0
	s_cmp_gt_u32 s66, 29
	s_barrier
	s_cbranch_scc0 .LBB0_197
	s_lshl_b32 s37, s50, 8
	s_ashr_i32 s1, s37, s31
	s_cmp_lt_i32 s1, 1
	s_cbranch_scc1 .LBB0_202
	s_cmp_eq_u32 s1, 1
	s_mov_b64 s[52:53], -1
	s_cbranch_scc0 .LBB0_201
	s_mov_b64 s[52:53], 0

; #define PG8_STAGE(bufoff, gbase, voff) do { _Pragma("unroll") for (int _i = 0; _i < 2; ++_i) \
;         __builtin_amdgcn_global_load_lds((const unsigned*)((const char*)(gbase) + (voff)[_i]), (LAS unsigned*)(lds + (bufoff) + ldsw + _i * 8192), 16, 0, 0); } while (0)
; #define PG8_LDA(dst, b, h) do { _Pragma("unroll") for (int m = 0; m < 4; ++m) _Pragma("unroll") for (int k = 0; k < 2; ++k) dst[m][k] = *(const LAS bf16x8*)(lds + PG8_SA(b, h) + aoff + m * 2048 + k * 1024); } while (0)
; #define PG8_LDB(dst, b, h) do { _Pragma("unroll") for (int n = 0; n < 2; ++n) _Pragma("unroll") for (int k = 0; k < 2; ++k) dst[n][k] = *(const LAS bf16x8*)(lds + PG8_SB(b, h) + boff + n * 2048 + k * 1024); } while (0)
; #define PG8_MMA(ai, bj, At, Bt) do { __builtin_amdgcn_s_setprio(1); _Pragma("unroll") for (int m = 0; m < 4; ++m) _Pragma("unroll") for (int n = 0; n < 2; ++n) _Pragma("unroll") for (int k = 0; k < 2; ++k) \
;         acc[ai][bj][m][n] = __builtin_amdgcn_mfma_f32_16x16x32_bf16(Bt[n][k], At[m][k], acc[ai][bj][m][n], 0, 0, 0); __builtin_amdgcn_s_setprio(0); } while (0)
; #define PG8_WAIT_L(n) asm volatile("s_waitcnt lgkmcnt(" #n ")" ::: "memory")
; #define PG8_BAR __builtin_amdgcn_s_barrier()
; #define PG8_SCHED __builtin_amdgcn_sched_barrier(0)
; template <class Epi, class Sched>
; __device__ __forceinline__ void gemm_phase(LAS unsigned char* lds, const Gemm g, const Sched& S, const Epi& E) {
;     ...
;             const char* a1 = cA + (size_t)(t + 1) * kstep;
;             const char* a2 = last ? nA : cA + (size_t)(t + 2) * kstep; const char* b2 = last ? nB : cB + (size_t)(t + 2) * kstep;
;             const char* a3 = a2 + kstep; const char* b3 = b2 + kstep;
;             PG8_LDB(B0, 0, 0); PG8_SCHED; PG8_LDA(At, 0, 0); PG8_STAGE(PG8_SA(1, 1), a1 + hstepA, voffA);
;             PG8_WAIT_L(8); PG8_BAR; PG8_WAIT_L(0); PG8_MMA(0, 0, At, B0); PG8_BAR; PG8_SCHED;
;             PG8_LDB(B1, 0, 1); PG8_STAGE(PG8_SB(0, 0), b2, voffB);
;             PG8_BAR; PG8_WAIT_L(0); PG8_MMA(0, 1, At, B1); PG8_BAR;
;             PG8_LDA(At, 0, 1); PG8_STAGE(PG8_SA(0, 0), a2, voffA);
;             PG8_BAR; PG8_WAIT_L(0); PG8_MMA(1, 0, At, B0); PG8_BAR; PG8_SCHED;
.LBB0_580:
	s_add_u32 s42, s40, 0x100
	s_addc_u32 s43, s41, 0
	s_add_i32 s24, 0, 0x10000
	v_add_u32_e32 v162, s24, v144
	ds_read_b128 v[146:149], v162
	ds_read_b128 v[150:153], v162 offset:1024
	ds_read_b128 v[170:173], v162 offset:2048
	ds_read_b128 v[174:177], v162 offset:3072
	s_cmp_eq_u32 s58, 4
	s_cselect_b32 s47, s1, s43
	s_cselect_b32 s46, s0, s42
	s_cselect_b32 s45, s54, s57
	s_cselect_b32 s44, s55, s56
	v_lshl_add_u64 v[198:199], s[40:41], 0, v[140:141]
	s_add_i32 m0, s28, 0xc000
	ds_read_b128 v[178:181], v145
	ds_read_b128 v[182:185], v145 offset:1024
	ds_read_b128 v[186:189], v145 offset:2048
	ds_read_b128 v[190:193], v145 offset:3072
	ds_read_b128 v[194:197], v145 offset:4096
	ds_read_b128 v[210:213], v145 offset:5120
	ds_read_b128 v[214:217], v145 offset:6144
	ds_read_b128 v[218:221], v145 offset:7168
	global_load_lds_dwordx4 v[198:199], off
	s_add_i32 m0, s28, 0xe000
	v_lshl_add_u64 v[198:199], s[40:41], 0, v[142:143]
	global_load_lds_dwordx4 v[198:199], off
	s_waitcnt lgkmcnt(8)
	s_barrier
	s_waitcnt lgkmcnt(0)
	v_mfma_f32_16x16x32_bf16 v[126:129], v[146:149], v[178:181], v[126:129]
	v_mfma_f32_16x16x32_bf16 v[122:125], v[170:173], v[178:181], v[122:125]
	v_mfma_f32_16x16x32_bf16 v[118:121], v[146:149], v[186:189], v[118:121]
	v_mfma_f32_16x16x32_bf16 v[114:117], v[170:173], v[186:189], v[114:117]
	v_mfma_f32_16x16x32_bf16 v[106:109], v[146:149], v[194:197], v[106:109]
	v_mfma_f32_16x16x32_bf16 v[98:101], v[170:173], v[194:197], v[98:101]
	v_mfma_f32_16x16x32_bf16 v[90:93], v[146:149], v[214:217], v[90:93]
	v_mfma_f32_16x16x32_bf16 v[82:85], v[170:173], v[214:217], v[82:85]
	v_mfma_f32_16x16x32_bf16 v[126:129], v[150:153], v[182:185], v[126:129]
	v_mfma_f32_16x16x32_bf16 v[122:125], v[174:177], v[182:185], v[122:125]
	v_mfma_f32_16x16x32_bf16 v[118:121], v[150:153], v[190:193], v[118:121]
	v_mfma_f32_16x16x32_bf16 v[114:117], v[174:177], v[190:193], v[114:117]
	v_mfma_f32_16x16x32_bf16 v[106:109], v[150:153], v[210:213], v[106:109]
	v_mfma_f32_16x16x32_bf16 v[98:101], v[174:177], v[210:213], v[98:101]
	v_mfma_f32_16x16x32_bf16 v[90:93], v[150:153], v[218:221], v[90:93]
	v_mfma_f32_16x16x32_bf16 v[82:85], v[174:177], v[218:221], v[82:85]
	s_barrier
	s_add_i32 s25, 0, 0x14000
	s_add_i32 s23, s24, s26
	v_add_u32_e32 v162, s25, v144
	v_lshl_add_u64 v[198:199], s[44:45], 0, v[134:135]
	s_mov_b32 m0, s23
	ds_read_b128 v[222:225], v162
	ds_read_b128 v[226:229], v162 offset:1024
	ds_read_b128 v[230:233], v162 offset:2048
	ds_read_b128 v[234:237], v162 offset:3072
	global_load_lds_dwordx4 v[198:199], off
	s_add_i32 m0, s23, 0x2000
	v_lshl_add_u64 v[238:239], s[44:45], 0, v[130:131]
	global_load_lds_dwordx4 v[238:239], off
	s_barrier
	s_waitcnt lgkmcnt(0)
	v_mfma_f32_16x16x32_bf16 v[110:113], v[222:225], v[178:181], v[110:113]
	v_mfma_f32_16x16x32_bf16 v[102:105], v[230:233], v[178:181], v[102:105]
	v_mfma_f32_16x16x32_bf16 v[94:97], v[222:225], v[186:189], v[94:97]
	v_mfma_f32_16x16x32_bf16 v[86:89], v[230:233], v[186:189], v[86:89]
	v_mfma_f32_16x16x32_bf16 v[78:81], v[222:225], v[194:197], v[78:81]
	v_mfma_f32_16x16x32_bf16 v[74:77], v[230:233], v[194:197], v[74:77]
	v_mfma_f32_16x16x32_bf16 v[70:73], v[222:225], v[214:217], v[70:73]
	v_mfma_f32_16x16x32_bf16 v[66:69], v[230:233], v[214:217], v[66:69]
	v_mfma_f32_16x16x32_bf16 v[110:113], v[226:229], v[182:185], v[110:113]
	v_mfma_f32_16x16x32_bf16 v[102:105], v[234:237], v[182:185], v[102:105]
	v_mfma_f32_16x16x32_bf16 v[94:97], v[226:229], v[190:193], v[94:97]
	v_mfma_f32_16x16x32_bf16 v[86:89], v[234:237], v[190:193], v[86:89]
	v_mfma_f32_16x16x32_bf16 v[78:81], v[226:229], v[210:213], v[78:81]
	v_mfma_f32_16x16x32_bf16 v[74:77], v[234:237], v[210:213], v[74:77]
	v_mfma_f32_16x16x32_bf16 v[70:73], v[226:229], v[218:221], v[70:73]
	v_mfma_f32_16x16x32_bf16 v[66:69], v[234:237], v[218:221], v[66:69]
	s_mov_b32 m0, s28
	v_lshl_add_u64 v[240:241], s[46:47], 0, v[136:137]
	s_barrier
	ds_read_b128 v[178:181], v145 offset:16384
	ds_read_b128 v[182:185], v145 offset:17408
	ds_read_b128 v[186:189], v145 offset:18432
	ds_read_b128 v[190:193], v145 offset:19456
	ds_read_b128 v[194:197], v145 offset:20480
	ds_read_b128 v[210:213], v145 offset:21504
	ds_read_b128 v[214:217], v145 offset:22528
	ds_read_b128 v[218:221], v145 offset:23552
	global_load_lds_dwordx4 v[240:241], off
	s_mov_b32 m0, s29
	v_lshl_add_u64 v[242:243], s[46:47], 0, v[132:133]
	global_load_lds_dwordx4 v[242:243], off
	s_barrier
	s_waitcnt lgkmcnt(0)
	v_mfma_f32_16x16x32_bf16 v[62:65], v[146:149], v[178:181], v[62:65]
	v_mfma_f32_16x16x32_bf16 v[58:61], v[170:173], v[178:181], v[58:61]
	v_mfma_f32_16x16x32_bf16 v[54:57], v[146:149], v[186:189], v[54:57]
	v_mfma_f32_16x16x32_bf16 v[50:53], v[170:173], v[186:189], v[50:53]
	v_mfma_f32_16x16x32_bf16 v[38:41], v[146:149], v[194:197], v[38:41]
	v_mfma_f32_16x16x32_bf16 v[34:37], v[170:173], v[194:197], v[34:37]
	v_mfma_f32_16x16x32_bf16 v[22:25], v[146:149], v[214:217], v[22:25]
	v_mfma_f32_16x16x32_bf16 v[18:21], v[170:173], v[214:217], v[18:21]
	v_mfma_f32_16x16x32_bf16 v[62:65], v[150:153], v[182:185], v[62:65]
	v_mfma_f32_16x16x32_bf16 v[58:61], v[174:177], v[182:185], v[58:61]
	v_mfma_f32_16x16x32_bf16 v[54:57], v[150:153], v[190:193], v[54:57]
	v_mfma_f32_16x16x32_bf16 v[50:53], v[174:177], v[190:193], v[50:53]
	v_mfma_f32_16x16x32_bf16 v[38:41], v[150:153], v[210:213], v[38:41]
	v_mfma_f32_16x16x32_bf16 v[34:37], v[174:177], v[210:213], v[34:37]
	v_mfma_f32_16x16x32_bf16 v[22:25], v[150:153], v[218:221], v[22:25]
	v_mfma_f32_16x16x32_bf16 v[18:21], v[174:177], v[218:221], v[18:21]
	s_barrier
; #define PG8_STAGE(bufoff, gbase, voff) do { _Pragma("unroll") for (int _i = 0; _i < 2; ++_i) \
;         __builtin_amdgcn_global_load_lds((const unsigned*)((const char*)(gbase) + (voff)[_i]), (LAS unsigned*)(lds + (bufoff) + ldsw + _i * 8192), 16, 0, 0); } while (0)
; #define PG8_LDA(dst, b, h) do { _Pragma("unroll") for (int m = 0; m < 4; ++m) _Pragma("unroll") for (int k = 0; k < 2; ++k) dst[m][k] = *(const LAS bf16x8*)(lds + PG8_SA(b, h) + aoff + m * 2048 + k * 1024); } while (0)
; #define PG8_LDB(dst, b, h) do { _Pragma("unroll") for (int n = 0; n < 2; ++n) _Pragma("unroll") for (int k = 0; k < 2; ++k) dst[n][k] = *(const LAS bf16x8*)(lds + PG8_SB(b, h) + boff + n * 2048 + k * 1024); } while (0)
; #define PG8_MMA(ai, bj, At, Bt) do { __builtin_amdgcn_s_setprio(1); _Pragma("unroll") for (int m = 0; m < 4; ++m) _Pragma("unroll") for (int n = 0; n < 2; ++n) _Pragma("unroll") for (int k = 0; k < 2; ++k) \
;         acc[ai][bj][m][n] = __builtin_amdgcn_mfma_f32_16x16x32_bf16(Bt[n][k], At[m][k], acc[ai][bj][m][n], 0, 0, 0); __builtin_amdgcn_s_setprio(0); } while (0)
; #define PG8_WAIT_V(n) asm volatile("s_waitcnt vmcnt(" #n ")" ::: "memory")
; #define PG8_WAIT_L(n) asm volatile("s_waitcnt lgkmcnt(" #n ")" ::: "memory")
; #define PG8_BAR __builtin_amdgcn_s_barrier()
; #define PG8_SCHED __builtin_amdgcn_sched_barrier(0)
; template <class Epi, class Sched>
; __device__ __forceinline__ void gemm_phase(LAS unsigned char* lds, const Gemm g, const Sched& S, const Epi& E) {
;     ...
;             PG8_STAGE(PG8_SB(0, 1), b2 + hstepB, voffB);
;             PG8_WAIT_V(6); PG8_BAR; PG8_MMA(1, 1, At, B1); PG8_BAR;
;             PG8_LDB(B0, 1, 0); PG8_SCHED; PG8_LDA(At, 1, 0); PG8_STAGE(PG8_SA(0, 1), a2 + hstepA, voffA);
;             PG8_WAIT_L(8); PG8_BAR; PG8_WAIT_L(0); PG8_MMA(0, 0, At, B0); PG8_BAR; PG8_SCHED;
;             PG8_LDB(B1, 1, 1); PG8_STAGE(PG8_SB(1, 0), b3, voffB);
;             PG8_BAR; PG8_WAIT_L(0); PG8_MMA(0, 1, At, B1); PG8_BAR;
;             PG8_LDA(At, 1, 1); PG8_STAGE(PG8_SA(1, 0), a3, voffA);
	s_add_u32 s40, s44, 0x20000
	s_addc_u32 s41, s45, 0
	s_add_i32 s23, s25, s26
	s_mov_b32 m0, s23
	v_lshl_add_u64 v[146:147], s[40:41], 0, v[134:135]
	global_load_lds_dwordx4 v[146:147], off
	s_add_i32 m0, s23, 0x2000
	v_lshl_add_u64 v[146:147], s[40:41], 0, v[130:131]
	global_load_lds_dwordx4 v[146:147], off
	s_waitcnt vmcnt(6)
	s_barrier
	v_mfma_f32_16x16x32_bf16 v[46:49], v[222:225], v[178:181], v[46:49]
	v_mfma_f32_16x16x32_bf16 v[42:45], v[230:233], v[178:181], v[42:45]
	v_mfma_f32_16x16x32_bf16 v[30:33], v[222:225], v[186:189], v[30:33]
	v_mfma_f32_16x16x32_bf16 v[26:29], v[230:233], v[186:189], v[26:29]
	v_mfma_f32_16x16x32_bf16 v[14:17], v[222:225], v[194:197], v[14:17]
	v_mfma_f32_16x16x32_bf16 v[10:13], v[230:233], v[194:197], v[10:13]
	v_mfma_f32_16x16x32_bf16 v[6:9], v[222:225], v[214:217], v[6:9]
	v_mfma_f32_16x16x32_bf16 v[2:5], v[230:233], v[214:217], v[2:5]
	v_mfma_f32_16x16x32_bf16 v[46:49], v[226:229], v[182:185], v[46:49]
	v_mfma_f32_16x16x32_bf16 v[42:45], v[234:237], v[182:185], v[42:45]
	v_mfma_f32_16x16x32_bf16 v[30:33], v[226:229], v[190:193], v[30:33]
	v_mfma_f32_16x16x32_bf16 v[26:29], v[234:237], v[190:193], v[26:29]
	v_mfma_f32_16x16x32_bf16 v[14:17], v[226:229], v[210:213], v[14:17]
	v_mfma_f32_16x16x32_bf16 v[10:13], v[234:237], v[210:213], v[10:13]
	v_mfma_f32_16x16x32_bf16 v[6:9], v[226:229], v[218:221], v[6:9]
	v_mfma_f32_16x16x32_bf16 v[2:5], v[234:237], v[218:221], v[2:5]
	s_add_i32 s27, 0, 0x18000
	v_add_u32_e32 v162, s27, v144
	s_barrier
	ds_read_b128 v[146:149], v162
	ds_read_b128 v[150:153], v162 offset:1024
	ds_read_b128 v[170:173], v162 offset:2048
	ds_read_b128 v[174:177], v162 offset:3072
	s_add_u32 s40, s46, 0x30000
	s_addc_u32 s41, s47, 0
	s_mov_b32 m0, s35
	v_lshl_add_u64 v[222:223], s[40:41], 0, v[136:137]
	ds_read_b128 v[178:181], v145 offset:32768
	ds_read_b128 v[182:185], v145 offset:33792
	ds_read_b128 v[186:189], v145 offset:34816
	ds_read_b128 v[190:193], v145 offset:35840
	ds_read_b128 v[194:197], v145 offset:36864
	ds_read_b128 v[210:213], v145 offset:37888
	ds_read_b128 v[214:217], v145 offset:38912
	ds_read_b128 v[218:221], v145 offset:39936
	global_load_lds_dwordx4 v[222:223], off
	s_mov_b32 m0, s48
	v_lshl_add_u64 v[222:223], s[40:41], 0, v[132:133]
	global_load_lds_dwordx4 v[222:223], off
	s_waitcnt lgkmcnt(8)
	s_barrier
	s_waitcnt lgkmcnt(0)
	v_mfma_f32_16x16x32_bf16 v[126:129], v[146:149], v[178:181], v[126:129]
	v_mfma_f32_16x16x32_bf16 v[122:125], v[170:173], v[178:181], v[122:125]
	v_mfma_f32_16x16x32_bf16 v[118:121], v[146:149], v[186:189], v[118:121]
	v_mfma_f32_16x16x32_bf16 v[114:117], v[170:173], v[186:189], v[114:117]
	v_mfma_f32_16x16x32_bf16 v[106:109], v[146:149], v[194:197], v[106:109]
	v_mfma_f32_16x16x32_bf16 v[98:101], v[170:173], v[194:197], v[98:101]
	v_mfma_f32_16x16x32_bf16 v[90:93], v[146:149], v[214:217], v[90:93]
	v_mfma_f32_16x16x32_bf16 v[82:85], v[170:173], v[214:217], v[82:85]
	v_mfma_f32_16x16x32_bf16 v[126:129], v[150:153], v[182:185], v[126:129]
	v_mfma_f32_16x16x32_bf16 v[122:125], v[174:177], v[182:185], v[122:125]
	v_mfma_f32_16x16x32_bf16 v[118:121], v[150:153], v[190:193], v[118:121]
	v_mfma_f32_16x16x32_bf16 v[114:117], v[174:177], v[190:193], v[114:117]
	v_mfma_f32_16x16x32_bf16 v[106:109], v[150:153], v[210:213], v[106:109]
	v_mfma_f32_16x16x32_bf16 v[98:101], v[174:177], v[210:213], v[98:101]
	v_mfma_f32_16x16x32_bf16 v[90:93], v[150:153], v[218:221], v[90:93]
	v_mfma_f32_16x16x32_bf16 v[82:85], v[174:177], v[218:221], v[82:85]
	s_barrier
	s_add_i32 s31, 0, 0x1c000
	s_add_i32 s23, s27, s26
	v_add_u32_e32 v162, s31, v144
	v_lshl_add_u64 v[198:199], v[198:199], 0, s[10:11]
	s_mov_b32 m0, s23
	ds_read_b128 v[222:225], v162
	ds_read_b128 v[226:229], v162 offset:1024
	ds_read_b128 v[230:233], v162 offset:2048
	ds_read_b128 v[234:237], v162 offset:3072
	global_load_lds_dwordx4 v[198:199], off
	s_add_i32 m0, s23, 0x2000
	v_lshl_add_u64 v[198:199], v[238:239], 0, s[10:11]
	global_load_lds_dwordx4 v[198:199], off
	s_barrier
; #define PG8_STAGE(bufoff, gbase, voff) do { _Pragma("unroll") for (int _i = 0; _i < 2; ++_i) \
;         __builtin_amdgcn_global_load_lds((const unsigned*)((const char*)(gbase) + (voff)[_i]), (LAS unsigned*)(lds + (bufoff) + ldsw + _i * 8192), 16, 0, 0); } while (0)
; #define PG8_MMA(ai, bj, At, Bt) do { __builtin_amdgcn_s_setprio(1); _Pragma("unroll") for (int m = 0; m < 4; ++m) _Pragma("unroll") for (int n = 0; n < 2; ++n) _Pragma("unroll") for (int k = 0; k < 2; ++k) \
;         acc[ai][bj][m][n] = __builtin_amdgcn_mfma_f32_16x16x32_bf16(Bt[n][k], At[m][k], acc[ai][bj][m][n], 0, 0, 0); __builtin_amdgcn_s_setprio(0); } while (0)
; #define PG8_WAIT_V(n) asm volatile("s_waitcnt vmcnt(" #n ")" ::: "memory")
; #define PG8_WAIT_L(n) asm volatile("s_waitcnt lgkmcnt(" #n ")" ::: "memory")
; #define PG8_BAR __builtin_amdgcn_s_barrier()
; #define PG8_SCHED __builtin_amdgcn_sched_barrier(0)
; template <class Epi, class Sched>
; __device__ __forceinline__ void gemm_phase(LAS unsigned char* lds, const Gemm g, const Sched& S, const Epi& E) {
;     ...
;             PG8_BAR; PG8_WAIT_L(0); PG8_MMA(1, 0, At, B0); PG8_BAR; PG8_SCHED;
;             PG8_STAGE(PG8_SB(1, 1), b3 + hstepB, voffB);
;             PG8_WAIT_V(6); PG8_BAR; PG8_MMA(1, 1, At, B1); PG8_BAR;
;         }
;     ...
;         if (!has_next) break;
; #pragma unroll
;         for (int a = 0; a < 2; ++a)
; #pragma unroll
;             for (int b = 0; b < 2; ++b)
; #pragma unroll
;                 for (int m = 0; m < 4; ++m)
; #pragma unroll
;                     for (int n = 0; n < 2; ++n) acc[a][b][m][n] = (f32x4){0.f, 0.f, 0.f, 0.f};
;         cur = nxt; cA = nA; cB = nB; ++ui;
;     }
;     PG8_WAIT_V(0);
;     if (wr == 0) PG8_BAR;
;     PG8_BAR;
	s_waitcnt lgkmcnt(0)
	v_mfma_f32_16x16x32_bf16 v[110:113], v[222:225], v[178:181], v[110:113]
	v_mfma_f32_16x16x32_bf16 v[102:105], v[230:233], v[178:181], v[102:105]
	v_mfma_f32_16x16x32_bf16 v[94:97], v[222:225], v[186:189], v[94:97]
	v_mfma_f32_16x16x32_bf16 v[86:89], v[230:233], v[186:189], v[86:89]
	v_mfma_f32_16x16x32_bf16 v[78:81], v[222:225], v[194:197], v[78:81]
	v_mfma_f32_16x16x32_bf16 v[74:77], v[230:233], v[194:197], v[74:77]
	v_mfma_f32_16x16x32_bf16 v[70:73], v[222:225], v[214:217], v[70:73]
	v_mfma_f32_16x16x32_bf16 v[66:69], v[230:233], v[214:217], v[66:69]
	v_mfma_f32_16x16x32_bf16 v[110:113], v[226:229], v[182:185], v[110:113]
	v_mfma_f32_16x16x32_bf16 v[102:105], v[234:237], v[182:185], v[102:105]
	v_mfma_f32_16x16x32_bf16 v[94:97], v[226:229], v[190:193], v[94:97]
	v_mfma_f32_16x16x32_bf16 v[86:89], v[234:237], v[190:193], v[86:89]
	v_mfma_f32_16x16x32_bf16 v[78:81], v[226:229], v[210:213], v[78:81]
	v_mfma_f32_16x16x32_bf16 v[74:77], v[234:237], v[210:213], v[74:77]
	v_mfma_f32_16x16x32_bf16 v[70:73], v[226:229], v[218:221], v[70:73]
	v_mfma_f32_16x16x32_bf16 v[66:69], v[234:237], v[218:221], v[66:69]
	s_mov_b32 m0, s49
	v_lshl_add_u64 v[198:199], v[240:241], 0, s[10:11]
	s_barrier
	ds_read_b128 v[178:181], v145 offset:49152
	ds_read_b128 v[182:185], v145 offset:50176
	ds_read_b128 v[186:189], v145 offset:51200
	ds_read_b128 v[190:193], v145 offset:52224
	ds_read_b128 v[194:197], v145 offset:53248
	ds_read_b128 v[210:213], v145 offset:54272
	ds_read_b128 v[214:217], v145 offset:55296
	ds_read_b128 v[218:221], v145 offset:56320
	global_load_lds_dwordx4 v[198:199], off
	s_mov_b32 m0, s50
	v_lshl_add_u64 v[198:199], v[242:243], 0, s[10:11]
	global_load_lds_dwordx4 v[198:199], off
	s_barrier
	s_waitcnt lgkmcnt(0)
	v_mfma_f32_16x16x32_bf16 v[62:65], v[146:149], v[178:181], v[62:65]
	v_mfma_f32_16x16x32_bf16 v[58:61], v[170:173], v[178:181], v[58:61]
	v_mfma_f32_16x16x32_bf16 v[54:57], v[146:149], v[186:189], v[54:57]
	v_mfma_f32_16x16x32_bf16 v[50:53], v[170:173], v[186:189], v[50:53]
	v_mfma_f32_16x16x32_bf16 v[38:41], v[146:149], v[194:197], v[38:41]
	v_mfma_f32_16x16x32_bf16 v[34:37], v[170:173], v[194:197], v[34:37]
	v_mfma_f32_16x16x32_bf16 v[22:25], v[146:149], v[214:217], v[22:25]
	v_mfma_f32_16x16x32_bf16 v[18:21], v[170:173], v[214:217], v[18:21]
	v_mfma_f32_16x16x32_bf16 v[62:65], v[150:153], v[182:185], v[62:65]
	v_mfma_f32_16x16x32_bf16 v[58:61], v[174:177], v[182:185], v[58:61]
	v_mfma_f32_16x16x32_bf16 v[54:57], v[150:153], v[190:193], v[54:57]
	v_mfma_f32_16x16x32_bf16 v[50:53], v[174:177], v[190:193], v[50:53]
	v_mfma_f32_16x16x32_bf16 v[38:41], v[150:153], v[210:213], v[38:41]
	v_mfma_f32_16x16x32_bf16 v[34:37], v[174:177], v[210:213], v[34:37]
	v_mfma_f32_16x16x32_bf16 v[22:25], v[150:153], v[218:221], v[22:25]
	v_mfma_f32_16x16x32_bf16 v[18:21], v[174:177], v[218:221], v[18:21]
	s_barrier
	s_add_u32 s40, s44, 0x20080
	s_addc_u32 s41, s45, 0
	s_add_i32 s23, s31, s26
	s_mov_b32 m0, s23
	v_lshl_add_u64 v[146:147], s[40:41], 0, v[134:135]
	global_load_lds_dwordx4 v[146:147], off
	s_add_i32 m0, s23, 0x2000
	v_lshl_add_u64 v[146:147], s[40:41], 0, v[130:131]
	global_load_lds_dwordx4 v[146:147], off
	s_waitcnt vmcnt(6)
	s_barrier
	v_mfma_f32_16x16x32_bf16 v[46:49], v[222:225], v[178:181], v[46:49]
	v_mfma_f32_16x16x32_bf16 v[42:45], v[230:233], v[178:181], v[42:45]
	v_mfma_f32_16x16x32_bf16 v[30:33], v[222:225], v[186:189], v[30:33]
	v_mfma_f32_16x16x32_bf16 v[26:29], v[230:233], v[186:189], v[26:29]
	v_mfma_f32_16x16x32_bf16 v[14:17], v[222:225], v[194:197], v[14:17]
	v_mfma_f32_16x16x32_bf16 v[10:13], v[230:233], v[194:197], v[10:13]
	v_mfma_f32_16x16x32_bf16 v[6:9], v[222:225], v[214:217], v[6:9]
	v_mfma_f32_16x16x32_bf16 v[2:5], v[230:233], v[214:217], v[2:5]
	v_mfma_f32_16x16x32_bf16 v[46:49], v[226:229], v[182:185], v[46:49]
	v_mfma_f32_16x16x32_bf16 v[42:45], v[234:237], v[182:185], v[42:45]
	v_mfma_f32_16x16x32_bf16 v[30:33], v[226:229], v[190:193], v[30:33]
	v_mfma_f32_16x16x32_bf16 v[26:29], v[234:237], v[190:193], v[26:29]
	v_mfma_f32_16x16x32_bf16 v[14:17], v[226:229], v[210:213], v[14:17]
	v_mfma_f32_16x16x32_bf16 v[10:13], v[234:237], v[210:213], v[10:13]
	v_mfma_f32_16x16x32_bf16 v[6:9], v[226:229], v[218:221], v[6:9]
	v_mfma_f32_16x16x32_bf16 v[2:5], v[234:237], v[218:221], v[2:5]
	s_add_i32 s58, s58, 2
	s_add_u32 s56, s56, 0x100
	s_addc_u32 s57, s57, 0
	s_cmp_gt_u32 s58, 5
	s_mov_b64 s[40:41], s[42:43]
	s_barrier
	s_cbranch_scc0 .LBB0_580
	s_mov_b32 s23, 0x20000
	s_mov_b64 s[40:41], 0x20000
	s_mov_b32 s53, s52
	s_mov_b32 s46, s52
	s_mov_b64 s[42:43], s[36:37]
	s_nop 0
	s_nop 1
	s_mov_b32 s23, 0x24000
	s_nop 0
	s_mov_b64 s[40:41], 0x24000
	s_nop 0
	s_mov_b32 s23, 0x28000
	s_nop 0
	s_mov_b64 s[40:41], 0x28000
	s_nop 0
	s_nop 0
	s_mov_b64 s[40:41], 0x2c000
	s_nop 0
	s_nop 0
	s_and_b64 vcc, exec, s[20:21]
	s_mov_b64 s[40:41], s[0:1]
	s_cbranch_vccz .LBB0_577
	s_waitcnt vmcnt(0)
	s_cmpk_gt_u32 s34, 0xff
	s_cbranch_scc1 .LBB0_584
	s_barrier

; #define PG8_STAGE(bufoff, gbase, voff) do { _Pragma("unroll") for (int _i = 0; _i < 2; ++_i) \
;         __builtin_amdgcn_global_load_lds((const unsigned*)((const char*)(gbase) + (voff)[_i]), (LAS unsigned*)(lds + (bufoff) + ldsw + _i * 8192), 16, 0, 0); } while (0)
; #define PG8_LDA(dst, b, h) do { _Pragma("unroll") for (int m = 0; m < 4; ++m) _Pragma("unroll") for (int k = 0; k < 2; ++k) dst[m][k] = *(const LAS bf16x8*)(lds + PG8_SA(b, h) + aoff + m * 2048 + k * 1024); } while (0)
; #define PG8_LDB(dst, b, h) do { _Pragma("unroll") for (int n = 0; n < 2; ++n) _Pragma("unroll") for (int k = 0; k < 2; ++k) dst[n][k] = *(const LAS bf16x8*)(lds + PG8_SB(b, h) + boff + n * 2048 + k * 1024); } while (0)
; #define PG8_MMA(ai, bj, At, Bt) do { __builtin_amdgcn_s_setprio(1); _Pragma("unroll") for (int m = 0; m < 4; ++m) _Pragma("unroll") for (int n = 0; n < 2; ++n) _Pragma("unroll") for (int k = 0; k < 2; ++k) \
;         acc[ai][bj][m][n] = __builtin_amdgcn_mfma_f32_16x16x32_bf16(Bt[n][k], At[m][k], acc[ai][bj][m][n], 0, 0, 0); __builtin_amdgcn_s_setprio(0); } while (0)
; #define PG8_WAIT_L(n) asm volatile("s_waitcnt lgkmcnt(" #n ")" ::: "memory")
; #define PG8_BAR __builtin_amdgcn_s_barrier()
; #define PG8_SCHED __builtin_amdgcn_sched_barrier(0)
; template <class Epi, class Sched>
; __device__ __forceinline__ void gemm_phase(LAS unsigned char* lds, const Gemm g, const Sched& S, const Epi& E) {
;     ...
;             const char* a1 = cA + (size_t)(t + 1) * kstep;
;             const char* a2 = last ? nA : cA + (size_t)(t + 2) * kstep; const char* b2 = last ? nB : cB + (size_t)(t + 2) * kstep;
;             const char* a3 = a2 + kstep; const char* b3 = b2 + kstep;
;             PG8_LDB(B0, 0, 0); PG8_SCHED; PG8_LDA(At, 0, 0); PG8_STAGE(PG8_SA(1, 1), a1 + hstepA, voffA);
;             PG8_WAIT_L(8); PG8_BAR; PG8_WAIT_L(0); PG8_MMA(0, 0, At, B0); PG8_BAR; PG8_SCHED;
;             PG8_LDB(B1, 0, 1); PG8_STAGE(PG8_SB(0, 0), b2, voffB);
;             PG8_BAR; PG8_WAIT_L(0); PG8_MMA(0, 1, At, B1); PG8_BAR;
;             PG8_LDA(At, 0, 1); PG8_STAGE(PG8_SA(0, 0), a2, voffA);
;             PG8_BAR; PG8_WAIT_L(0); PG8_MMA(1, 0, At, B0); PG8_BAR; PG8_SCHED;
.LBB0_595:
	v_add_u32_e32 v144, s24, v1
	ds_read_b128 v[172:175], v144
	ds_read_b128 v[176:179], v144 offset:1024
	ds_read_b128 v[180:183], v144 offset:2048
	ds_read_b128 v[184:187], v144 offset:3072
	s_add_u32 s42, s36, 0x100
	s_addc_u32 s43, s37, 0
	s_cmp_eq_u32 s54, 8
	s_cselect_b32 s47, s21, s43
	s_cselect_b32 s46, s20, s42
	s_cselect_b32 s45, s1, s29
	s_cselect_b32 s44, s0, s28
	v_lshl_add_u64 v[144:145], s[36:37], 0, v[140:141]
	s_add_i32 m0, s34, 0xc000
	ds_read_b128 v[188:191], v170
	ds_read_b128 v[192:195], v170 offset:1024
	ds_read_b128 v[196:199], v170 offset:2048
	ds_read_b128 v[210:213], v170 offset:3072
	ds_read_b128 v[214:217], v170 offset:4096
	ds_read_b128 v[218:221], v170 offset:5120
	ds_read_b128 v[222:225], v170 offset:6144
	ds_read_b128 v[226:229], v170 offset:7168
	global_load_lds_dwordx4 v[144:145], off
	s_add_i32 m0, s34, 0xe000
	v_lshl_add_u64 v[144:145], s[36:37], 0, v[142:143]
	global_load_lds_dwordx4 v[144:145], off
	s_waitcnt lgkmcnt(8)
	s_barrier
	s_waitcnt lgkmcnt(0)
	v_mfma_f32_16x16x32_bf16 v[126:129], v[172:175], v[188:191], v[126:129]
	v_mfma_f32_16x16x32_bf16 v[122:125], v[180:183], v[188:191], v[122:125]
	v_mfma_f32_16x16x32_bf16 v[110:113], v[172:175], v[196:199], v[110:113]
	v_mfma_f32_16x16x32_bf16 v[106:109], v[180:183], v[196:199], v[106:109]
	v_mfma_f32_16x16x32_bf16 v[94:97], v[172:175], v[214:217], v[94:97]
	v_mfma_f32_16x16x32_bf16 v[90:93], v[180:183], v[214:217], v[90:93]
	v_mfma_f32_16x16x32_bf16 v[78:81], v[172:175], v[222:225], v[78:81]
	v_mfma_f32_16x16x32_bf16 v[74:77], v[180:183], v[222:225], v[74:77]
	v_mfma_f32_16x16x32_bf16 v[126:129], v[176:179], v[192:195], v[126:129]
	v_mfma_f32_16x16x32_bf16 v[122:125], v[184:187], v[192:195], v[122:125]
	v_mfma_f32_16x16x32_bf16 v[110:113], v[176:179], v[210:213], v[110:113]
	v_mfma_f32_16x16x32_bf16 v[106:109], v[184:187], v[210:213], v[106:109]
	v_mfma_f32_16x16x32_bf16 v[94:97], v[176:179], v[218:221], v[94:97]
	v_mfma_f32_16x16x32_bf16 v[90:93], v[184:187], v[218:221], v[90:93]
	v_mfma_f32_16x16x32_bf16 v[78:81], v[176:179], v[226:229], v[78:81]
	v_mfma_f32_16x16x32_bf16 v[74:77], v[184:187], v[226:229], v[74:77]
	s_barrier
	v_add_u32_e32 v144, s25, v1
	s_add_i32 s23, s24, s13
	ds_read_b128 v[230:233], v144
	ds_read_b128 v[234:237], v144 offset:1024
	ds_read_b128 v[238:241], v144 offset:2048
	ds_read_b128 v[242:245], v144 offset:3072
	v_lshl_add_u64 v[144:145], s[44:45], 0, v[132:133]
	s_mov_b32 m0, s23
	v_lshl_add_u64 v[246:247], s[44:45], 0, v[136:137]
	global_load_lds_dwordx4 v[144:145], off
	s_add_i32 m0, s23, 0x2000
	s_nop 0
	global_load_lds_dwordx4 v[246:247], off
	s_barrier
	s_waitcnt lgkmcnt(0)
	v_mfma_f32_16x16x32_bf16 v[118:121], v[230:233], v[188:191], v[118:121]
	v_mfma_f32_16x16x32_bf16 v[114:117], v[238:241], v[188:191], v[114:117]
	v_mfma_f32_16x16x32_bf16 v[102:105], v[230:233], v[196:199], v[102:105]
	v_mfma_f32_16x16x32_bf16 v[98:101], v[238:241], v[196:199], v[98:101]
	v_mfma_f32_16x16x32_bf16 v[86:89], v[230:233], v[214:217], v[86:89]
	v_mfma_f32_16x16x32_bf16 v[82:85], v[238:241], v[214:217], v[82:85]
	v_mfma_f32_16x16x32_bf16 v[70:73], v[230:233], v[222:225], v[70:73]
	v_mfma_f32_16x16x32_bf16 v[66:69], v[238:241], v[222:225], v[66:69]
	v_mfma_f32_16x16x32_bf16 v[118:121], v[234:237], v[192:195], v[118:121]
	v_mfma_f32_16x16x32_bf16 v[114:117], v[242:245], v[192:195], v[114:117]
	v_mfma_f32_16x16x32_bf16 v[102:105], v[234:237], v[210:213], v[102:105]
	v_mfma_f32_16x16x32_bf16 v[98:101], v[242:245], v[210:213], v[98:101]
	v_mfma_f32_16x16x32_bf16 v[86:89], v[234:237], v[218:221], v[86:89]
	v_mfma_f32_16x16x32_bf16 v[82:85], v[242:245], v[218:221], v[82:85]
	v_mfma_f32_16x16x32_bf16 v[70:73], v[234:237], v[226:229], v[70:73]
	v_mfma_f32_16x16x32_bf16 v[66:69], v[242:245], v[226:229], v[66:69]
	s_mov_b32 m0, s34
	v_lshl_add_u64 v[248:249], s[46:47], 0, v[130:131]
	s_barrier
	ds_read_b128 v[188:191], v170 offset:16384
	ds_read_b128 v[192:195], v170 offset:17408
	ds_read_b128 v[196:199], v170 offset:18432
	ds_read_b128 v[210:213], v170 offset:19456
	ds_read_b128 v[214:217], v170 offset:20480
	ds_read_b128 v[218:221], v170 offset:21504
	ds_read_b128 v[222:225], v170 offset:22528
	ds_read_b128 v[226:229], v170 offset:23552
	global_load_lds_dwordx4 v[248:249], off
	s_mov_b32 m0, s35
	v_lshl_add_u64 v[250:251], s[46:47], 0, v[134:135]
	global_load_lds_dwordx4 v[250:251], off
	s_barrier
	s_waitcnt lgkmcnt(0)
	v_mfma_f32_16x16x32_bf16 v[62:65], v[172:175], v[188:191], v[62:65]
	v_mfma_f32_16x16x32_bf16 v[58:61], v[180:183], v[188:191], v[58:61]
	v_mfma_f32_16x16x32_bf16 v[46:49], v[172:175], v[196:199], v[46:49]
	v_mfma_f32_16x16x32_bf16 v[42:45], v[180:183], v[196:199], v[42:45]
	v_mfma_f32_16x16x32_bf16 v[30:33], v[172:175], v[214:217], v[30:33]
	v_mfma_f32_16x16x32_bf16 v[26:29], v[180:183], v[214:217], v[26:29]
	v_mfma_f32_16x16x32_bf16 v[14:17], v[172:175], v[222:225], v[14:17]
	v_mfma_f32_16x16x32_bf16 v[10:13], v[180:183], v[222:225], v[10:13]
	v_mfma_f32_16x16x32_bf16 v[62:65], v[176:179], v[192:195], v[62:65]
	v_mfma_f32_16x16x32_bf16 v[58:61], v[184:187], v[192:195], v[58:61]
	v_mfma_f32_16x16x32_bf16 v[46:49], v[176:179], v[210:213], v[46:49]
	v_mfma_f32_16x16x32_bf16 v[42:45], v[184:187], v[210:213], v[42:45]
	v_mfma_f32_16x16x32_bf16 v[30:33], v[176:179], v[218:221], v[30:33]
	v_mfma_f32_16x16x32_bf16 v[26:29], v[184:187], v[218:221], v[26:29]
	v_mfma_f32_16x16x32_bf16 v[14:17], v[176:179], v[226:229], v[14:17]
	v_mfma_f32_16x16x32_bf16 v[10:13], v[184:187], v[226:229], v[10:13]
	s_barrier
; #define PG8_STAGE(bufoff, gbase, voff) do { _Pragma("unroll") for (int _i = 0; _i < 2; ++_i) \
;         __builtin_amdgcn_global_load_lds((const unsigned*)((const char*)(gbase) + (voff)[_i]), (LAS unsigned*)(lds + (bufoff) + ldsw + _i * 8192), 16, 0, 0); } while (0)
; #define PG8_LDA(dst, b, h) do { _Pragma("unroll") for (int m = 0; m < 4; ++m) _Pragma("unroll") for (int k = 0; k < 2; ++k) dst[m][k] = *(const LAS bf16x8*)(lds + PG8_SA(b, h) + aoff + m * 2048 + k * 1024); } while (0)
; #define PG8_LDB(dst, b, h) do { _Pragma("unroll") for (int n = 0; n < 2; ++n) _Pragma("unroll") for (int k = 0; k < 2; ++k) dst[n][k] = *(const LAS bf16x8*)(lds + PG8_SB(b, h) + boff + n * 2048 + k * 1024); } while (0)
; #define PG8_MMA(ai, bj, At, Bt) do { __builtin_amdgcn_s_setprio(1); _Pragma("unroll") for (int m = 0; m < 4; ++m) _Pragma("unroll") for (int n = 0; n < 2; ++n) _Pragma("unroll") for (int k = 0; k < 2; ++k) \
;         acc[ai][bj][m][n] = __builtin_amdgcn_mfma_f32_16x16x32_bf16(Bt[n][k], At[m][k], acc[ai][bj][m][n], 0, 0, 0); __builtin_amdgcn_s_setprio(0); } while (0)
; #define PG8_WAIT_V(n) asm volatile("s_waitcnt vmcnt(" #n ")" ::: "memory")
; #define PG8_WAIT_L(n) asm volatile("s_waitcnt lgkmcnt(" #n ")" ::: "memory")
; #define PG8_BAR __builtin_amdgcn_s_barrier()
; #define PG8_SCHED __builtin_amdgcn_sched_barrier(0)
; template <class Epi, class Sched>
; __device__ __forceinline__ void gemm_phase(LAS unsigned char* lds, const Gemm g, const Sched& S, const Epi& E) {
;     ...
;             PG8_STAGE(PG8_SB(0, 1), b2 + hstepB, voffB);
;             PG8_WAIT_V(6); PG8_BAR; PG8_MMA(1, 1, At, B1); PG8_BAR;
;             PG8_LDB(B0, 1, 0); PG8_SCHED; PG8_LDA(At, 1, 0); PG8_STAGE(PG8_SA(0, 1), a2 + hstepA, voffA);
;             PG8_WAIT_L(8); PG8_BAR; PG8_WAIT_L(0); PG8_MMA(0, 0, At, B0); PG8_BAR; PG8_SCHED;
;             PG8_LDB(B1, 1, 1); PG8_STAGE(PG8_SB(1, 0), b3, voffB);
;             PG8_BAR; PG8_WAIT_L(0); PG8_MMA(0, 1, At, B1); PG8_BAR;
;             PG8_LDA(At, 1, 1); PG8_STAGE(PG8_SA(1, 0), a3, voffA);
	s_add_u32 s36, s44, 0x30000
	s_addc_u32 s37, s45, 0
	s_add_i32 s23, s25, s13
	s_mov_b32 m0, s23
	v_lshl_add_u64 v[172:173], s[36:37], 0, v[132:133]
	global_load_lds_dwordx4 v[172:173], off
	s_add_i32 m0, s23, 0x2000
	v_lshl_add_u64 v[172:173], s[36:37], 0, v[136:137]
	global_load_lds_dwordx4 v[172:173], off
	s_waitcnt vmcnt(6)
	s_barrier
	v_mfma_f32_16x16x32_bf16 v[54:57], v[230:233], v[188:191], v[54:57]
	v_mfma_f32_16x16x32_bf16 v[50:53], v[238:241], v[188:191], v[50:53]
	v_mfma_f32_16x16x32_bf16 v[38:41], v[230:233], v[196:199], v[38:41]
	v_mfma_f32_16x16x32_bf16 v[34:37], v[238:241], v[196:199], v[34:37]
	v_mfma_f32_16x16x32_bf16 v[22:25], v[230:233], v[214:217], v[22:25]
	v_mfma_f32_16x16x32_bf16 v[18:21], v[238:241], v[214:217], v[18:21]
	v_mfma_f32_16x16x32_bf16 v[6:9], v[230:233], v[222:225], v[6:9]
	v_mfma_f32_16x16x32_bf16 v[2:5], v[238:241], v[222:225], v[2:5]
	v_mfma_f32_16x16x32_bf16 v[54:57], v[234:237], v[192:195], v[54:57]
	v_mfma_f32_16x16x32_bf16 v[50:53], v[242:245], v[192:195], v[50:53]
	v_mfma_f32_16x16x32_bf16 v[38:41], v[234:237], v[210:213], v[38:41]
	v_mfma_f32_16x16x32_bf16 v[34:37], v[242:245], v[210:213], v[34:37]
	v_mfma_f32_16x16x32_bf16 v[22:25], v[234:237], v[218:221], v[22:25]
	v_mfma_f32_16x16x32_bf16 v[18:21], v[242:245], v[218:221], v[18:21]
	v_mfma_f32_16x16x32_bf16 v[6:9], v[234:237], v[226:229], v[6:9]
	v_mfma_f32_16x16x32_bf16 v[2:5], v[242:245], v[226:229], v[2:5]
	v_add_u32_e32 v171, s27, v1
	s_barrier
	ds_read_b128 v[172:175], v171
	ds_read_b128 v[176:179], v171 offset:1024
	ds_read_b128 v[180:183], v171 offset:2048
	ds_read_b128 v[184:187], v171 offset:3072
	s_add_u32 s36, s46, 0x30000
	s_addc_u32 s37, s47, 0
	s_mov_b32 m0, s48
	v_lshl_add_u64 v[230:231], s[36:37], 0, v[130:131]
	ds_read_b128 v[188:191], v170 offset:32768
	ds_read_b128 v[192:195], v170 offset:33792
	ds_read_b128 v[196:199], v170 offset:34816
	ds_read_b128 v[210:213], v170 offset:35840
	ds_read_b128 v[214:217], v170 offset:36864
	ds_read_b128 v[218:221], v170 offset:37888
	ds_read_b128 v[222:225], v170 offset:38912
	ds_read_b128 v[226:229], v170 offset:39936
	global_load_lds_dwordx4 v[230:231], off
	s_mov_b32 m0, s49
	v_lshl_add_u64 v[230:231], s[36:37], 0, v[134:135]
	global_load_lds_dwordx4 v[230:231], off
	s_waitcnt lgkmcnt(8)
	s_barrier
	s_waitcnt lgkmcnt(0)
	v_mfma_f32_16x16x32_bf16 v[126:129], v[172:175], v[188:191], v[126:129]
	v_mfma_f32_16x16x32_bf16 v[122:125], v[180:183], v[188:191], v[122:125]
	v_mfma_f32_16x16x32_bf16 v[110:113], v[172:175], v[196:199], v[110:113]
	v_mfma_f32_16x16x32_bf16 v[106:109], v[180:183], v[196:199], v[106:109]
	v_mfma_f32_16x16x32_bf16 v[94:97], v[172:175], v[214:217], v[94:97]
	v_mfma_f32_16x16x32_bf16 v[90:93], v[180:183], v[214:217], v[90:93]
	v_mfma_f32_16x16x32_bf16 v[78:81], v[172:175], v[222:225], v[78:81]
	v_mfma_f32_16x16x32_bf16 v[74:77], v[180:183], v[222:225], v[74:77]
	v_mfma_f32_16x16x32_bf16 v[126:129], v[176:179], v[192:195], v[126:129]
	v_mfma_f32_16x16x32_bf16 v[122:125], v[184:187], v[192:195], v[122:125]
	v_mfma_f32_16x16x32_bf16 v[110:113], v[176:179], v[210:213], v[110:113]
	v_mfma_f32_16x16x32_bf16 v[106:109], v[184:187], v[210:213], v[106:109]
	v_mfma_f32_16x16x32_bf16 v[94:97], v[176:179], v[218:221], v[94:97]
	v_mfma_f32_16x16x32_bf16 v[90:93], v[184:187], v[218:221], v[90:93]
	v_mfma_f32_16x16x32_bf16 v[78:81], v[176:179], v[226:229], v[78:81]
	v_mfma_f32_16x16x32_bf16 v[74:77], v[184:187], v[226:229], v[74:77]
	s_barrier
	s_add_i32 s23, s27, s13
	v_add_u32_e32 v171, s31, v1
	v_lshl_add_u64 v[144:145], v[144:145], 0, s[10:11]
	s_mov_b32 m0, s23
	ds_read_b128 v[230:233], v171
	ds_read_b128 v[234:237], v171 offset:1024
	ds_read_b128 v[238:241], v171 offset:2048
	ds_read_b128 v[242:245], v171 offset:3072
	global_load_lds_dwordx4 v[144:145], off
	s_add_i32 m0, s23, 0x2000
	v_lshl_add_u64 v[144:145], v[246:247], 0, s[10:11]
	global_load_lds_dwordx4 v[144:145], off
	s_barrier
	s_waitcnt lgkmcnt(0)
	v_mfma_f32_16x16x32_bf16 v[118:121], v[230:233], v[188:191], v[118:121]
	v_mfma_f32_16x16x32_bf16 v[114:117], v[238:241], v[188:191], v[114:117]
	v_mfma_f32_16x16x32_bf16 v[102:105], v[230:233], v[196:199], v[102:105]
	v_mfma_f32_16x16x32_bf16 v[98:101], v[238:241], v[196:199], v[98:101]
	v_mfma_f32_16x16x32_bf16 v[86:89], v[230:233], v[214:217], v[86:89]
	v_mfma_f32_16x16x32_bf16 v[82:85], v[238:241], v[214:217], v[82:85]
	v_mfma_f32_16x16x32_bf16 v[70:73], v[230:233], v[222:225], v[70:73]
	v_mfma_f32_16x16x32_bf16 v[66:69], v[238:241], v[222:225], v[66:69]
	v_mfma_f32_16x16x32_bf16 v[118:121], v[234:237], v[192:195], v[118:121]
	v_mfma_f32_16x16x32_bf16 v[114:117], v[242:245], v[192:195], v[114:117]
	v_mfma_f32_16x16x32_bf16 v[102:105], v[234:237], v[210:213], v[102:105]
	v_mfma_f32_16x16x32_bf16 v[98:101], v[242:245], v[210:213], v[98:101]
	v_mfma_f32_16x16x32_bf16 v[86:89], v[234:237], v[218:221], v[86:89]
	v_mfma_f32_16x16x32_bf16 v[82:85], v[242:245], v[218:221], v[82:85]
	v_mfma_f32_16x16x32_bf16 v[70:73], v[234:237], v[226:229], v[70:73]
	v_mfma_f32_16x16x32_bf16 v[66:69], v[242:245], v[226:229], v[66:69]
	s_mov_b32 m0, s50
	v_lshl_add_u64 v[144:145], v[248:249], 0, s[10:11]
	s_barrier
	ds_read_b128 v[188:191], v170 offset:49152
	ds_read_b128 v[192:195], v170 offset:50176
	ds_read_b128 v[196:199], v170 offset:51200
	ds_read_b128 v[210:213], v170 offset:52224
	ds_read_b128 v[214:217], v170 offset:53248
	ds_read_b128 v[218:221], v170 offset:54272
	ds_read_b128 v[222:225], v170 offset:55296
	ds_read_b128 v[226:229], v170 offset:56320
	global_load_lds_dwordx4 v[144:145], off
	s_mov_b32 m0, s51
	v_lshl_add_u64 v[144:145], v[250:251], 0, s[10:11]
	global_load_lds_dwordx4 v[144:145], off
	s_barrier
; __device__ __forceinline__ unsigned cvt_pk_bf16(float lo, float hi) { unsigned r; asm volatile("v_cvt_pk_bf16_f32 %0, %1, %2" : "=v"(r) : "v"(lo), "v"(hi)); return r; }
; __device__ __forceinline__ float gelu_tanh(float x) { const float z = 0.7978845608f * (x + 0.044715f * x * x * x); const float th = 1.0f - 2.0f / (__expf(2.0f * z) + 1.0f); return 0.5f * x * (1.0f + th); }
; #define PG8_STAGE(bufoff, gbase, voff) do { _Pragma("unroll") for (int _i = 0; _i < 2; ++_i) \
;         __builtin_amdgcn_global_load_lds((const unsigned*)((const char*)(gbase) + (voff)[_i]), (LAS unsigned*)(lds + (bufoff) + ldsw + _i * 8192), 16, 0, 0); } while (0)
; #define PG8_MMA(ai, bj, At, Bt) do { __builtin_amdgcn_s_setprio(1); _Pragma("unroll") for (int m = 0; m < 4; ++m) _Pragma("unroll") for (int n = 0; n < 2; ++n) _Pragma("unroll") for (int k = 0; k < 2; ++k) \
;         acc[ai][bj][m][n] = __builtin_amdgcn_mfma_f32_16x16x32_bf16(Bt[n][k], At[m][k], acc[ai][bj][m][n], 0, 0, 0); __builtin_amdgcn_s_setprio(0); } while (0)
; #define PG8_WAIT_V(n) asm volatile("s_waitcnt vmcnt(" #n ")" ::: "memory")
; #define PG8_WAIT_L(n) asm volatile("s_waitcnt lgkmcnt(" #n ")" ::: "memory")
; #define PG8_BAR __builtin_amdgcn_s_barrier()
; #define PG8_SCHED __builtin_amdgcn_sched_barrier(0)
;     __device__ __forceinline__ void operator()(const f32x4 (&acc)[2][2][4][2], const Unit& u, int ui, const LAS float* rtab, int wr, int wc, int fr, int fq) const {
;     ...
;                     const int lc = lc0 + bj * HALF, t = lc >> 4, co = lc & 15; const int token = n * 32 + t;
;                     const f32x4 a0 = acc[ai][bj][m][0], a1 = acc[ai][bj][m][1];
;                     u32x4 w; w.x = cvt_pk_bf16(gelu_tanh(a0[0]), gelu_tanh(a0[1])); w.y = cvt_pk_bf16(gelu_tanh(a0[2]), gelu_tanh(a0[3]));
;                     w.z = cvt_pk_bf16(gelu_tanh(a1[0]), gelu_tanh(a1[1])); w.w = cvt_pk_bf16(gelu_tanh(a1[2]), gelu_tanh(a1[3]));
; template <class Epi, class Sched>
; __device__ __forceinline__ void gemm_phase(LAS unsigned char* lds, const Gemm g, const Sched& S, const Epi& E) {
;     ...
;             PG8_BAR; PG8_WAIT_L(0); PG8_MMA(1, 0, At, B0); PG8_BAR; PG8_SCHED;
;             PG8_STAGE(PG8_SB(1, 1), b3 + hstepB, voffB);
;             PG8_WAIT_V(6); PG8_BAR; PG8_MMA(1, 1, At, B1); PG8_BAR;
;         }
	s_waitcnt lgkmcnt(0)
	v_mfma_f32_16x16x32_bf16 v[62:65], v[172:175], v[188:191], v[62:65]
	v_mfma_f32_16x16x32_bf16 v[58:61], v[180:183], v[188:191], v[58:61]
	v_mfma_f32_16x16x32_bf16 v[46:49], v[172:175], v[196:199], v[46:49]
	v_mfma_f32_16x16x32_bf16 v[42:45], v[180:183], v[196:199], v[42:45]
	v_mfma_f32_16x16x32_bf16 v[30:33], v[172:175], v[214:217], v[30:33]
	v_mfma_f32_16x16x32_bf16 v[26:29], v[180:183], v[214:217], v[26:29]
	v_mfma_f32_16x16x32_bf16 v[14:17], v[172:175], v[222:225], v[14:17]
	v_mfma_f32_16x16x32_bf16 v[10:13], v[180:183], v[222:225], v[10:13]
	v_mfma_f32_16x16x32_bf16 v[62:65], v[176:179], v[192:195], v[62:65]
	v_mfma_f32_16x16x32_bf16 v[58:61], v[184:187], v[192:195], v[58:61]
	v_mfma_f32_16x16x32_bf16 v[46:49], v[176:179], v[210:213], v[46:49]
	v_mfma_f32_16x16x32_bf16 v[42:45], v[184:187], v[210:213], v[42:45]
	v_mfma_f32_16x16x32_bf16 v[30:33], v[176:179], v[218:221], v[30:33]
	v_mfma_f32_16x16x32_bf16 v[26:29], v[184:187], v[218:221], v[26:29]
	v_mfma_f32_16x16x32_bf16 v[14:17], v[176:179], v[226:229], v[14:17]
	v_mfma_f32_16x16x32_bf16 v[10:13], v[184:187], v[226:229], v[10:13]
	s_barrier
	s_add_u32 s36, s44, 0x30080
	s_addc_u32 s37, s45, 0
	s_add_i32 s23, s31, s13
	s_mov_b32 m0, s23
	v_lshl_add_u64 v[144:145], s[36:37], 0, v[132:133]
	global_load_lds_dwordx4 v[144:145], off
	s_add_i32 m0, s23, 0x2000
	v_lshl_add_u64 v[144:145], s[36:37], 0, v[136:137]
	global_load_lds_dwordx4 v[144:145], off
	s_waitcnt vmcnt(6)
	s_barrier
	v_mfma_f32_16x16x32_bf16 v[54:57], v[230:233], v[188:191], v[54:57]
	v_mfma_f32_16x16x32_bf16 v[50:53], v[238:241], v[188:191], v[50:53]
	v_mfma_f32_16x16x32_bf16 v[38:41], v[230:233], v[196:199], v[38:41]
	v_mfma_f32_16x16x32_bf16 v[34:37], v[238:241], v[196:199], v[34:37]
	v_mfma_f32_16x16x32_bf16 v[22:25], v[230:233], v[214:217], v[22:25]
	v_mfma_f32_16x16x32_bf16 v[18:21], v[238:241], v[214:217], v[18:21]
	v_mfma_f32_16x16x32_bf16 v[6:9], v[230:233], v[222:225], v[6:9]
	v_mfma_f32_16x16x32_bf16 v[2:5], v[238:241], v[222:225], v[2:5]
	v_mfma_f32_16x16x32_bf16 v[54:57], v[234:237], v[192:195], v[54:57]
	v_mfma_f32_16x16x32_bf16 v[50:53], v[242:245], v[192:195], v[50:53]
	v_mfma_f32_16x16x32_bf16 v[38:41], v[234:237], v[210:213], v[38:41]
	v_mfma_f32_16x16x32_bf16 v[34:37], v[242:245], v[210:213], v[34:37]
	v_mfma_f32_16x16x32_bf16 v[22:25], v[234:237], v[218:221], v[22:25]
	v_mfma_f32_16x16x32_bf16 v[18:21], v[242:245], v[218:221], v[18:21]
	v_mfma_f32_16x16x32_bf16 v[6:9], v[234:237], v[226:229], v[6:9]
	v_mfma_f32_16x16x32_bf16 v[2:5], v[242:245], v[226:229], v[2:5]
	s_add_i32 s54, s54, 2
	s_add_u32 s28, s28, 0x100
	s_addc_u32 s29, s29, 0
	s_cmp_gt_u32 s54, 9
	s_mov_b64 s[36:37], s[42:43]
	s_barrier
	s_cbranch_scc0 .LBB0_595
	v_mul_f32_e32 v144, 0x3d372713, v126
	v_mul_f32_e32 v144, v126, v144
	v_fma_f32 v144, v126, v144, v126
	v_mul_f32_e32 v144, 0x3f4c422a, v144
	v_add_f32_e32 v144, v144, v144
	v_mul_f32_e32 v144, 0x3fb8aa3b, v144
	v_exp_f32_e32 v144, v144
	v_mul_f32_e32 v126, 0.5, v126
	s_lshl_b32 s23, s26, 8
	s_and_b32 s23, s23, 0x100
	v_add_f32_e32 v145, 1.0, v144
	v_div_scale_f32 v172, s[28:29], v145, v145, 2.0
	v_rcp_f32_e32 v173, v172
	v_or_b32_e32 v144, s23, v162
	v_lshrrev_b32_e32 v171, 4, v144
	v_or_b32_e32 v144, v171, v146
	v_fma_f32 v174, -v172, v173, 1.0
	v_fmac_f32_e32 v173, v174, v173
	v_div_scale_f32 v174, vcc, 2.0, v145, 2.0
	v_mul_f32_e32 v175, v174, v173
	v_fma_f32 v176, -v172, v175, v174
	v_fmac_f32_e32 v175, v176, v173
	v_fma_f32 v172, -v172, v175, v174
	v_mul_f32_e32 v174, 0x3d372713, v127
	v_mul_f32_e32 v174, v127, v174
	v_fma_f32 v174, v127, v174, v127
	v_mul_f32_e32 v174, 0x3f4c422a, v174
	v_add_f32_e32 v174, v174, v174
	v_mul_f32_e32 v174, 0x3fb8aa3b, v174
	v_exp_f32_e32 v174, v174
	v_div_fmas_f32 v172, v172, v173, v175
	v_div_fixup_f32 v145, v172, v145, 2.0
	v_sub_f32_e32 v145, 1.0, v145
	v_add_f32_e32 v172, 1.0, v174
	v_div_scale_f32 v173, s[28:29], v172, v172, 2.0
	v_rcp_f32_e32 v174, v173
	v_add_f32_e32 v145, 1.0, v145
	v_mul_f32_e32 v126, v126, v145
	v_mul_f32_e32 v127, 0.5, v127
	v_fma_f32 v145, -v173, v174, 1.0
	v_fmac_f32_e32 v174, v145, v174
	v_div_scale_f32 v145, vcc, 2.0, v172, 2.0
	v_mul_f32_e32 v175, v145, v174
	v_fma_f32 v176, -v173, v175, v145
	v_fmac_f32_e32 v175, v176, v174
	v_fma_f32 v145, -v173, v175, v145
	v_mul_f32_e32 v173, 0x3d372713, v128
	v_mul_f32_e32 v173, v128, v173
	v_fma_f32 v173, v128, v173, v128
	v_mul_f32_e32 v173, 0x3f4c422a, v173
	v_add_f32_e32 v173, v173, v173
	v_mul_f32_e32 v173, 0x3fb8aa3b, v173
	v_exp_f32_e32 v173, v173
	v_div_fmas_f32 v145, v145, v174, v175
	v_div_fixup_f32 v145, v145, v172, 2.0
	v_sub_f32_e32 v145, 1.0, v145
	v_add_f32_e32 v172, 1.0, v173
	v_div_scale_f32 v173, s[28:29], v172, v172, 2.0
	v_rcp_f32_e32 v174, v173
	v_add_f32_e32 v145, 1.0, v145
	v_mul_f32_e32 v127, v127, v145
	v_cvt_pk_bf16_f32 v126, v126, v127
	v_fma_f32 v127, -v173, v174, 1.0
	v_fmac_f32_e32 v174, v127, v174
	v_div_scale_f32 v127, vcc, 2.0, v172, 2.0
	v_mul_f32_e32 v145, v127, v174
	v_fma_f32 v175, -v173, v145, v127
	v_fmac_f32_e32 v145, v175, v174
	v_fma_f32 v127, -v173, v145, v127
	v_mul_f32_e32 v173, 0x3d372713, v129
	v_mul_f32_e32 v173, v129, v173
	v_fma_f32 v173, v129, v173, v129
	v_mul_f32_e32 v173, 0x3f4c422a, v173
	v_add_f32_e32 v173, v173, v173
	v_mul_f32_e32 v173, 0x3fb8aa3b, v173
	v_exp_f32_e32 v173, v173
	v_div_fmas_f32 v127, v127, v174, v145
	v_div_fixup_f32 v127, v127, v172, 2.0
	v_sub_f32_e32 v127, 1.0, v127
	v_add_f32_e32 v145, 1.0, v173
	v_div_scale_f32 v172, s[28:29], v145, v145, 2.0
	v_rcp_f32_e32 v173, v172
	v_mul_f32_e32 v128, 0.5, v128
	v_add_f32_e32 v127, 1.0, v127
	v_mul_f32_e32 v127, v128, v127
; #define LAS __attribute__((address_space(3)))
; __device__ __forceinline__ unsigned cvt_pk_bf16(float lo, float hi) { unsigned r; asm volatile("v_cvt_pk_bf16_f32 %0, %1, %2" : "=v"(r) : "v"(lo), "v"(hi)); return r; }
; __device__ __forceinline__ float gelu_tanh(float x) { const float z = 0.7978845608f * (x + 0.044715f * x * x * x); const float th = 1.0f - 2.0f / (__expf(2.0f * z) + 1.0f); return 0.5f * x * (1.0f + th); }
;     __device__ __forceinline__ void operator()(const f32x4 (&acc)[2][2][4][2], const Unit& u, int ui, const LAS float* rtab, int wr, int wc, int fr, int fq) const {
;         const int g = u.pm; const int n0 = wr * 64 + fr; const int lc0 = (u.pn & 1) * 256 + wc * 32 + 8 * fq;
; #pragma unroll
;         for (int ai = 0; ai < 2; ++ai)
; #pragma unroll
;             for (int m = 0; m < 4; ++m) {
;                 const int n = n0 + ai * HALF + m * 16;
; #pragma unroll
;                 for (int bj = 0; bj < 2; ++bj) {
;                     const int lc = lc0 + bj * HALF, t = lc >> 4, co = lc & 15; const int token = n * 32 + t;
;                     const f32x4 a0 = acc[ai][bj][m][0], a1 = acc[ai][bj][m][1];
;                     u32x4 w; w.x = cvt_pk_bf16(gelu_tanh(a0[0]), gelu_tanh(a0[1])); w.y = cvt_pk_bf16(gelu_tanh(a0[2]), gelu_tanh(a0[3]));
;                     w.z = cvt_pk_bf16(gelu_tanh(a1[0]), gelu_tanh(a1[1])); w.w = cvt_pk_bf16(gelu_tanh(a1[2]), gelu_tanh(a1[3]));
;                     *(u32x4*)(Y + (size_t)token * 1024 + 16 * g + co) = w;
;                 }
;             }
;     }
	v_fma_f32 v128, -v172, v173, 1.0
	v_fmac_f32_e32 v173, v128, v173
	v_div_scale_f32 v128, vcc, 2.0, v145, 2.0
	v_mul_f32_e32 v174, v128, v173
	v_fma_f32 v175, -v172, v174, v128
	v_fmac_f32_e32 v174, v175, v173
	v_fma_f32 v128, -v172, v174, v128
	v_mul_f32_e32 v172, 0x3d372713, v122
	v_mul_f32_e32 v172, v122, v172
	v_fma_f32 v172, v122, v172, v122
	v_mul_f32_e32 v172, 0x3f4c422a, v172
	v_add_f32_e32 v172, v172, v172
	v_mul_f32_e32 v172, 0x3fb8aa3b, v172
	v_exp_f32_e32 v172, v172
	v_div_fmas_f32 v128, v128, v173, v174
	v_div_fixup_f32 v128, v128, v145, 2.0
	v_sub_f32_e32 v128, 1.0, v128
	v_add_f32_e32 v145, 1.0, v172
	v_div_scale_f32 v172, s[28:29], v145, v145, 2.0
	v_rcp_f32_e32 v173, v172
	v_mul_f32_e32 v129, 0.5, v129
	v_add_f32_e32 v128, 1.0, v128
	v_mul_f32_e32 v128, v129, v128
	v_cvt_pk_bf16_f32 v127, v127, v128
	v_fma_f32 v128, -v172, v173, 1.0
	v_fmac_f32_e32 v173, v128, v173
	v_div_scale_f32 v128, vcc, 2.0, v145, 2.0
	v_mul_f32_e32 v129, v128, v173
	v_fma_f32 v174, -v172, v129, v128
	v_fmac_f32_e32 v129, v174, v173
	v_fma_f32 v128, -v172, v129, v128
	v_mul_f32_e32 v172, 0x3d372713, v123
	v_mul_f32_e32 v172, v123, v172
	v_fma_f32 v172, v123, v172, v123
	v_mul_f32_e32 v172, 0x3f4c422a, v172
	v_add_f32_e32 v172, v172, v172
	v_mul_f32_e32 v172, 0x3fb8aa3b, v172
	v_exp_f32_e32 v172, v172
	v_div_fmas_f32 v128, v128, v173, v129
	v_div_fixup_f32 v128, v128, v145, 2.0
	v_sub_f32_e32 v128, 1.0, v128
	v_add_f32_e32 v129, 1.0, v172
	v_div_scale_f32 v145, s[28:29], v129, v129, 2.0
	v_rcp_f32_e32 v172, v145
	v_mul_f32_e32 v122, 0.5, v122
	v_add_f32_e32 v128, 1.0, v128
	v_mul_f32_e32 v122, v122, v128
	v_fma_f32 v128, -v145, v172, 1.0
	v_fmac_f32_e32 v172, v128, v172
	v_div_scale_f32 v128, vcc, 2.0, v129, 2.0
	v_mul_f32_e32 v173, v128, v172
	v_fma_f32 v174, -v145, v173, v128
	v_fmac_f32_e32 v173, v174, v172
	v_fma_f32 v128, -v145, v173, v128
	v_mul_f32_e32 v145, 0x3d372713, v124
	v_mul_f32_e32 v145, v124, v145
	v_fma_f32 v145, v124, v145, v124
	v_mul_f32_e32 v145, 0x3f4c422a, v145
	v_add_f32_e32 v145, v145, v145
	v_mul_f32_e32 v145, 0x3fb8aa3b, v145
	v_exp_f32_e32 v145, v145
	v_div_fmas_f32 v128, v128, v172, v173
	v_div_fixup_f32 v128, v128, v129, 2.0
	v_sub_f32_e32 v128, 1.0, v128
	v_add_f32_e32 v129, 1.0, v145
	v_div_scale_f32 v145, s[28:29], v129, v129, 2.0
	v_rcp_f32_e32 v172, v145
	v_mul_f32_e32 v123, 0.5, v123
	v_add_f32_e32 v128, 1.0, v128
	v_mul_f32_e32 v123, v123, v128
	v_cvt_pk_bf16_f32 v128, v122, v123
	v_fma_f32 v122, -v145, v172, 1.0
	v_fmac_f32_e32 v172, v122, v172
	v_div_scale_f32 v122, vcc, 2.0, v129, 2.0
	v_mul_f32_e32 v123, v122, v172
	v_fma_f32 v173, -v145, v123, v122
	v_fmac_f32_e32 v123, v173, v172
	v_fma_f32 v122, -v145, v123, v122
	v_mul_f32_e32 v145, 0x3d372713, v125
	v_mul_f32_e32 v145, v125, v145
	v_fma_f32 v145, v125, v145, v125
	v_mul_f32_e32 v145, 0x3f4c422a, v145
	v_add_f32_e32 v145, v145, v145
	v_mul_f32_e32 v145, 0x3fb8aa3b, v145
	v_exp_f32_e32 v145, v145
	v_div_fmas_f32 v122, v122, v172, v123
	v_div_fixup_f32 v122, v122, v129, 2.0
	v_sub_f32_e32 v122, 1.0, v122
	v_add_f32_e32 v123, 1.0, v145
	v_div_scale_f32 v129, s[28:29], v123, v123, 2.0
	v_rcp_f32_e32 v145, v129
	v_mul_f32_e32 v124, 0.5, v124
	v_add_f32_e32 v122, 1.0, v122
	v_mul_f32_e32 v122, v124, v122
	v_fma_f32 v124, -v129, v145, 1.0
	v_fmac_f32_e32 v145, v124, v145
	v_div_scale_f32 v124, vcc, 2.0, v123, 2.0
	v_mul_f32_e32 v172, v124, v145
	v_fma_f32 v173, -v129, v172, v124
	v_fmac_f32_e32 v172, v173, v145
	v_fma_f32 v124, -v129, v172, v124
	v_div_fmas_f32 v124, v124, v145, v172
	v_div_fixup_f32 v123, v124, v123, 2.0
	v_sub_f32_e32 v123, 1.0, v123
	v_mul_f32_e32 v124, 0.5, v125
	v_add_f32_e32 v123, 1.0, v123
	v_mul_f32_e32 v123, v124, v123
	v_cvt_pk_bf16_f32 v129, v122, v123
	v_mul_f32_e32 v122, 0x3d372713, v118
	v_mul_f32_e32 v122, v118, v122
	v_fma_f32 v122, v118, v122, v118
	v_mul_f32_e32 v122, 0x3f4c422a, v122
	v_add_f32_e32 v122, v122, v122
	v_mul_f32_e32 v122, 0x3fb8aa3b, v122
	v_exp_f32_e32 v124, v122
	v_ashrrev_i32_e32 v145, 31, v144
	v_lshlrev_b64 v[122:123], 11, v[144:145]
	v_lshl_add_u64 v[122:123], v[138:139], 0, v[122:123]
	v_add_f32_e32 v125, 1.0, v124
	v_div_scale_f32 v144, s[28:29], v125, v125, 2.0
	v_rcp_f32_e32 v145, v144
	global_store_dwordx4 v[122:123], v[126:129], off
	v_mul_f32_e32 v118, 0.5, v118
	v_or_b32_e32 v124, 8, v171
	v_fma_f32 v123, -v144, v145, 1.0
	v_fmac_f32_e32 v145, v123, v145
	v_div_scale_f32 v123, vcc, 2.0, v125, 2.0
	v_mul_f32_e32 v126, v123, v145
	v_fma_f32 v127, -v144, v126, v123
	v_fmac_f32_e32 v126, v127, v145
	v_mul_f32_e32 v127, 0x3d372713, v119
	v_mul_f32_e32 v127, v119, v127
	v_fma_f32 v127, v119, v127, v119
	v_mul_f32_e32 v127, 0x3f4c422a, v127
	v_add_f32_e32 v127, v127, v127
	v_mul_f32_e32 v127, 0x3fb8aa3b, v127
	v_exp_f32_e32 v127, v127
	v_fma_f32 v123, -v144, v126, v123
	v_div_fmas_f32 v123, v123, v145, v126
	v_div_fixup_f32 v123, v123, v125, 2.0
	v_add_f32_e32 v125, 1.0, v127
	v_div_scale_f32 v126, s[28:29], v125, v125, 2.0
	v_rcp_f32_e32 v127, v126
	v_sub_f32_e32 v123, 1.0, v123
	v_add_f32_e32 v123, 1.0, v123
	v_mul_f32_e32 v118, v118, v123
	v_fma_f32 v123, -v126, v127, 1.0
	v_fmac_f32_e32 v127, v123, v127
	v_div_scale_f32 v123, vcc, 2.0, v125, 2.0
	v_mul_f32_e32 v128, v123, v127
	v_fma_f32 v129, -v126, v128, v123
	v_fmac_f32_e32 v128, v129, v127
	v_fma_f32 v123, -v126, v128, v123
	v_mul_f32_e32 v126, 0x3d372713, v120
	v_mul_f32_e32 v126, v120, v126
	v_fma_f32 v126, v120, v126, v120
	v_mul_f32_e32 v126, 0x3f4c422a, v126
	v_add_f32_e32 v126, v126, v126
	v_mul_f32_e32 v126, 0x3fb8aa3b, v126
	v_exp_f32_e32 v126, v126
	v_div_fmas_f32 v123, v123, v127, v128
	v_div_fixup_f32 v123, v123, v125, 2.0
; #define LAS __attribute__((address_space(3)))
; __device__ __forceinline__ unsigned cvt_pk_bf16(float lo, float hi) { unsigned r; asm volatile("v_cvt_pk_bf16_f32 %0, %1, %2" : "=v"(r) : "v"(lo), "v"(hi)); return r; }
; __device__ __forceinline__ float gelu_tanh(float x) { const float z = 0.7978845608f * (x + 0.044715f * x * x * x); const float th = 1.0f - 2.0f / (__expf(2.0f * z) + 1.0f); return 0.5f * x * (1.0f + th); }
;     __device__ __forceinline__ void operator()(const f32x4 (&acc)[2][2][4][2], const Unit& u, int ui, const LAS float* rtab, int wr, int wc, int fr, int fq) const {
;         const int g = u.pm; const int n0 = wr * 64 + fr; const int lc0 = (u.pn & 1) * 256 + wc * 32 + 8 * fq;
; #pragma unroll
;         for (int ai = 0; ai < 2; ++ai)
; #pragma unroll
;             for (int m = 0; m < 4; ++m) {
;                 const int n = n0 + ai * HALF + m * 16;
; #pragma unroll
;                 for (int bj = 0; bj < 2; ++bj) {
;                     const int lc = lc0 + bj * HALF, t = lc >> 4, co = lc & 15; const int token = n * 32 + t;
;                     const f32x4 a0 = acc[ai][bj][m][0], a1 = acc[ai][bj][m][1];
;                     u32x4 w; w.x = cvt_pk_bf16(gelu_tanh(a0[0]), gelu_tanh(a0[1])); w.y = cvt_pk_bf16(gelu_tanh(a0[2]), gelu_tanh(a0[3]));
;                     w.z = cvt_pk_bf16(gelu_tanh(a1[0]), gelu_tanh(a1[1])); w.w = cvt_pk_bf16(gelu_tanh(a1[2]), gelu_tanh(a1[3]));
;                     *(u32x4*)(Y + (size_t)token * 1024 + 16 * g + co) = w;
;                 }
;             }
;     }
	v_sub_f32_e32 v123, 1.0, v123
	v_add_f32_e32 v125, 1.0, v126
	v_div_scale_f32 v126, s[28:29], v125, v125, 2.0
	v_rcp_f32_e32 v127, v126
	v_mul_f32_e32 v119, 0.5, v119
	v_add_f32_e32 v123, 1.0, v123
	v_mul_f32_e32 v119, v119, v123
	v_cvt_pk_bf16_f32 v118, v118, v119
	v_fma_f32 v119, -v126, v127, 1.0
	v_fmac_f32_e32 v127, v119, v127
	v_div_scale_f32 v119, vcc, 2.0, v125, 2.0
	v_mul_f32_e32 v123, v119, v127
	v_fma_f32 v128, -v126, v123, v119
	v_fmac_f32_e32 v123, v128, v127
	v_fma_f32 v119, -v126, v123, v119
	v_mul_f32_e32 v126, 0x3d372713, v121
	v_mul_f32_e32 v126, v121, v126
	v_fma_f32 v126, v121, v126, v121
	v_mul_f32_e32 v126, 0x3f4c422a, v126
	v_add_f32_e32 v126, v126, v126
	v_mul_f32_e32 v126, 0x3fb8aa3b, v126
	v_exp_f32_e32 v126, v126
	v_div_fmas_f32 v119, v119, v127, v123
	v_div_fixup_f32 v119, v119, v125, 2.0
	v_sub_f32_e32 v119, 1.0, v119
	v_add_f32_e32 v123, 1.0, v126
	v_div_scale_f32 v125, s[28:29], v123, v123, 2.0
	v_rcp_f32_e32 v126, v125
	v_mul_f32_e32 v120, 0.5, v120
	v_add_f32_e32 v119, 1.0, v119
	v_mul_f32_e32 v119, v120, v119
	v_fma_f32 v120, -v125, v126, 1.0
	v_fmac_f32_e32 v126, v120, v126
	v_div_scale_f32 v120, vcc, 2.0, v123, 2.0
	v_mul_f32_e32 v127, v120, v126
	v_fma_f32 v128, -v125, v127, v120
	v_fmac_f32_e32 v127, v128, v126
	v_fma_f32 v120, -v125, v127, v120
	v_mul_f32_e32 v125, 0x3d372713, v114
	v_mul_f32_e32 v125, v114, v125
	v_fma_f32 v125, v114, v125, v114
	v_mul_f32_e32 v125, 0x3f4c422a, v125
	v_add_f32_e32 v125, v125, v125
	v_mul_f32_e32 v125, 0x3fb8aa3b, v125
	v_exp_f32_e32 v125, v125
	v_div_fmas_f32 v120, v120, v126, v127
	v_div_fixup_f32 v120, v120, v123, 2.0
	v_sub_f32_e32 v120, 1.0, v120
	v_add_f32_e32 v123, 1.0, v125
	v_div_scale_f32 v125, s[28:29], v123, v123, 2.0
	v_rcp_f32_e32 v126, v125
	v_mul_f32_e32 v121, 0.5, v121
	v_add_f32_e32 v120, 1.0, v120
	v_mul_f32_e32 v120, v121, v120
	v_cvt_pk_bf16_f32 v119, v119, v120
	v_fma_f32 v120, -v125, v126, 1.0
	v_fmac_f32_e32 v126, v120, v126
	v_div_scale_f32 v120, vcc, 2.0, v123, 2.0
	v_mul_f32_e32 v121, v120, v126
	v_fma_f32 v127, -v125, v121, v120
	v_fmac_f32_e32 v121, v127, v126
	v_fma_f32 v120, -v125, v121, v120
	v_mul_f32_e32 v125, 0x3d372713, v115
	v_mul_f32_e32 v125, v115, v125
	v_fma_f32 v125, v115, v125, v115
	v_mul_f32_e32 v125, 0x3f4c422a, v125
	v_add_f32_e32 v125, v125, v125
	v_mul_f32_e32 v125, 0x3fb8aa3b, v125
	v_exp_f32_e32 v125, v125
	v_div_fmas_f32 v120, v120, v126, v121
	v_div_fixup_f32 v120, v120, v123, 2.0
	v_sub_f32_e32 v120, 1.0, v120
	v_add_f32_e32 v121, 1.0, v125
	v_div_scale_f32 v123, s[28:29], v121, v121, 2.0
	v_rcp_f32_e32 v125, v123
	v_mul_f32_e32 v114, 0.5, v114
	v_add_f32_e32 v120, 1.0, v120
	v_mul_f32_e32 v114, v114, v120
	v_fma_f32 v120, -v123, v125, 1.0
	v_fmac_f32_e32 v125, v120, v125
	v_div_scale_f32 v120, vcc, 2.0, v121, 2.0
	v_mul_f32_e32 v126, v120, v125
	v_fma_f32 v127, -v123, v126, v120
	v_fmac_f32_e32 v126, v127, v125
	v_fma_f32 v120, -v123, v126, v120
	v_mul_f32_e32 v123, 0x3d372713, v116
	v_mul_f32_e32 v123, v116, v123
	v_fma_f32 v123, v116, v123, v116
	v_mul_f32_e32 v123, 0x3f4c422a, v123
	v_add_f32_e32 v123, v123, v123
	v_mul_f32_e32 v123, 0x3fb8aa3b, v123
	v_exp_f32_e32 v123, v123
	v_div_fmas_f32 v120, v120, v125, v126
	v_div_fixup_f32 v120, v120, v121, 2.0
	v_sub_f32_e32 v120, 1.0, v120
	v_add_f32_e32 v121, 1.0, v123
	v_div_scale_f32 v123, s[28:29], v121, v121, 2.0
	v_rcp_f32_e32 v125, v123
	v_mul_f32_e32 v115, 0.5, v115
	v_add_f32_e32 v120, 1.0, v120
	v_mul_f32_e32 v115, v115, v120
	v_cvt_pk_bf16_f32 v120, v114, v115
	v_fma_f32 v114, -v123, v125, 1.0
	v_fmac_f32_e32 v125, v114, v125
	v_div_scale_f32 v114, vcc, 2.0, v121, 2.0
	v_mul_f32_e32 v115, v114, v125
	v_fma_f32 v126, -v123, v115, v114
	v_fmac_f32_e32 v115, v126, v125
	v_fma_f32 v114, -v123, v115, v114
	v_mul_f32_e32 v123, 0x3d372713, v117
	v_mul_f32_e32 v123, v117, v123
	v_fma_f32 v123, v117, v123, v117
	v_mul_f32_e32 v123, 0x3f4c422a, v123
	v_add_f32_e32 v123, v123, v123
	v_mul_f32_e32 v123, 0x3fb8aa3b, v123
	v_exp_f32_e32 v123, v123
	v_div_fmas_f32 v114, v114, v125, v115
	v_div_fixup_f32 v114, v114, v121, 2.0
	v_sub_f32_e32 v114, 1.0, v114
	v_add_f32_e32 v115, 1.0, v123
	v_div_scale_f32 v121, s[28:29], v115, v115, 2.0
	v_rcp_f32_e32 v123, v121
	v_mul_f32_e32 v116, 0.5, v116
	v_add_f32_e32 v114, 1.0, v114
	v_mul_f32_e32 v114, v116, v114
	v_fma_f32 v116, -v121, v123, 1.0
	v_fmac_f32_e32 v123, v116, v123
	v_div_scale_f32 v116, vcc, 2.0, v115, 2.0
	v_mul_f32_e32 v125, v116, v123
	v_fma_f32 v126, -v121, v125, v116
	v_fmac_f32_e32 v125, v126, v123
	v_fma_f32 v116, -v121, v125, v116
	v_div_fmas_f32 v116, v116, v123, v125
	v_div_fixup_f32 v115, v116, v115, 2.0
	v_sub_f32_e32 v115, 1.0, v115
	v_mul_f32_e32 v116, 0.5, v117
	v_add_f32_e32 v115, 1.0, v115
	v_mul_f32_e32 v115, v116, v115
	v_mul_f32_e32 v116, 0x3d372713, v110
	v_mul_f32_e32 v116, v110, v116
	v_fma_f32 v116, v110, v116, v110
	v_mul_f32_e32 v116, 0x3f4c422a, v116
	v_add_f32_e32 v116, v116, v116
	v_mul_f32_e32 v116, 0x3fb8aa3b, v116
	v_exp_f32_e32 v116, v116
	v_or_b32_e32 v122, v124, v146
	v_ashrrev_i32_e32 v123, 31, v122
	v_cvt_pk_bf16_f32 v121, v114, v115
	v_add_f32_e32 v116, 1.0, v116
	v_div_scale_f32 v117, s[28:29], v116, v116, 2.0
	v_lshlrev_b64 v[114:115], 11, v[122:123]
	v_rcp_f32_e32 v122, v117
	v_lshl_add_u64 v[114:115], v[138:139], 0, v[114:115]
	global_store_dwordx4 v[114:115], v[118:121], off
	v_mul_f32_e32 v110, 0.5, v110
	v_fma_f32 v115, -v117, v122, 1.0
	v_fmac_f32_e32 v122, v115, v122
	v_div_scale_f32 v115, vcc, 2.0, v116, 2.0
	v_mul_f32_e32 v118, v115, v122
	v_fma_f32 v119, -v117, v118, v115
	v_fmac_f32_e32 v118, v119, v122
	v_fma_f32 v115, -v117, v118, v115
	v_mul_f32_e32 v117, 0x3d372713, v111
; #define LAS __attribute__((address_space(3)))
; __device__ __forceinline__ unsigned cvt_pk_bf16(float lo, float hi) { unsigned r; asm volatile("v_cvt_pk_bf16_f32 %0, %1, %2" : "=v"(r) : "v"(lo), "v"(hi)); return r; }
; __device__ __forceinline__ float gelu_tanh(float x) { const float z = 0.7978845608f * (x + 0.044715f * x * x * x); const float th = 1.0f - 2.0f / (__expf(2.0f * z) + 1.0f); return 0.5f * x * (1.0f + th); }
;     __device__ __forceinline__ void operator()(const f32x4 (&acc)[2][2][4][2], const Unit& u, int ui, const LAS float* rtab, int wr, int wc, int fr, int fq) const {
;         const int g = u.pm; const int n0 = wr * 64 + fr; const int lc0 = (u.pn & 1) * 256 + wc * 32 + 8 * fq;
; #pragma unroll
;         for (int ai = 0; ai < 2; ++ai)
; #pragma unroll
;             for (int m = 0; m < 4; ++m) {
;                 const int n = n0 + ai * HALF + m * 16;
; #pragma unroll
;                 for (int bj = 0; bj < 2; ++bj) {
;                     const int lc = lc0 + bj * HALF, t = lc >> 4, co = lc & 15; const int token = n * 32 + t;
;                     const f32x4 a0 = acc[ai][bj][m][0], a1 = acc[ai][bj][m][1];
;                     u32x4 w; w.x = cvt_pk_bf16(gelu_tanh(a0[0]), gelu_tanh(a0[1])); w.y = cvt_pk_bf16(gelu_tanh(a0[2]), gelu_tanh(a0[3]));
;                     w.z = cvt_pk_bf16(gelu_tanh(a1[0]), gelu_tanh(a1[1])); w.w = cvt_pk_bf16(gelu_tanh(a1[2]), gelu_tanh(a1[3]));
;                     *(u32x4*)(Y + (size_t)token * 1024 + 16 * g + co) = w;
;                 }
;             }
;     }
	v_mul_f32_e32 v117, v111, v117
	v_fma_f32 v117, v111, v117, v111
	v_mul_f32_e32 v117, 0x3f4c422a, v117
	v_add_f32_e32 v117, v117, v117
	v_mul_f32_e32 v117, 0x3fb8aa3b, v117
	v_exp_f32_e32 v117, v117
	v_div_fmas_f32 v115, v115, v122, v118
	v_div_fixup_f32 v115, v115, v116, 2.0
	v_sub_f32_e32 v115, 1.0, v115
	v_add_f32_e32 v116, 1.0, v117
	v_div_scale_f32 v117, s[28:29], v116, v116, 2.0
	v_rcp_f32_e32 v118, v117
	v_add_f32_e32 v115, 1.0, v115
	v_mul_f32_e32 v110, v110, v115
	v_mul_f32_e32 v111, 0.5, v111
	v_fma_f32 v115, -v117, v118, 1.0
	v_fmac_f32_e32 v118, v115, v118
	v_div_scale_f32 v115, vcc, 2.0, v116, 2.0
	v_mul_f32_e32 v119, v115, v118
	v_fma_f32 v120, -v117, v119, v115
	v_fmac_f32_e32 v119, v120, v118
	v_fma_f32 v115, -v117, v119, v115
	v_mul_f32_e32 v117, 0x3d372713, v112
	v_mul_f32_e32 v117, v112, v117
	v_fma_f32 v117, v112, v117, v112
	v_mul_f32_e32 v117, 0x3f4c422a, v117
	v_add_f32_e32 v117, v117, v117
	v_mul_f32_e32 v117, 0x3fb8aa3b, v117
	v_exp_f32_e32 v117, v117
	v_div_fmas_f32 v115, v115, v118, v119
	v_div_fixup_f32 v115, v115, v116, 2.0
	v_sub_f32_e32 v115, 1.0, v115
	v_add_f32_e32 v116, 1.0, v117
	v_div_scale_f32 v117, s[28:29], v116, v116, 2.0
	v_rcp_f32_e32 v118, v117
	v_add_f32_e32 v115, 1.0, v115
	v_mul_f32_e32 v111, v111, v115
	v_cvt_pk_bf16_f32 v110, v110, v111
	v_fma_f32 v111, -v117, v118, 1.0
	v_fmac_f32_e32 v118, v111, v118
	v_div_scale_f32 v111, vcc, 2.0, v116, 2.0
	v_mul_f32_e32 v115, v111, v118
	v_fma_f32 v119, -v117, v115, v111
	v_fmac_f32_e32 v115, v119, v118
	v_fma_f32 v111, -v117, v115, v111
	v_mul_f32_e32 v117, 0x3d372713, v113
	v_mul_f32_e32 v117, v113, v117
	v_fma_f32 v117, v113, v117, v113
	v_mul_f32_e32 v117, 0x3f4c422a, v117
	v_add_f32_e32 v117, v117, v117
	v_mul_f32_e32 v117, 0x3fb8aa3b, v117
	v_exp_f32_e32 v117, v117
	v_div_fmas_f32 v111, v111, v118, v115
	v_div_fixup_f32 v111, v111, v116, 2.0
	v_sub_f32_e32 v111, 1.0, v111
	v_add_f32_e32 v115, 1.0, v117
	v_div_scale_f32 v116, s[28:29], v115, v115, 2.0
	v_rcp_f32_e32 v117, v116
	v_mul_f32_e32 v112, 0.5, v112
	v_add_f32_e32 v111, 1.0, v111
	v_mul_f32_e32 v111, v112, v111
	v_fma_f32 v112, -v116, v117, 1.0
	v_fmac_f32_e32 v117, v112, v117
	v_div_scale_f32 v112, vcc, 2.0, v115, 2.0
	v_mul_f32_e32 v118, v112, v117
	v_fma_f32 v119, -v116, v118, v112
	v_fmac_f32_e32 v118, v119, v117
	v_fma_f32 v112, -v116, v118, v112
	v_mul_f32_e32 v116, 0x3d372713, v106
	v_mul_f32_e32 v116, v106, v116
	v_fma_f32 v116, v106, v116, v106
	v_mul_f32_e32 v116, 0x3f4c422a, v116
	v_add_f32_e32 v116, v116, v116
	v_mul_f32_e32 v116, 0x3fb8aa3b, v116
	v_exp_f32_e32 v116, v116
	v_div_fmas_f32 v112, v112, v117, v118
	v_div_fixup_f32 v112, v112, v115, 2.0
	v_sub_f32_e32 v112, 1.0, v112
	v_add_f32_e32 v115, 1.0, v116
	v_div_scale_f32 v116, s[28:29], v115, v115, 2.0
	v_rcp_f32_e32 v117, v116
	v_mul_f32_e32 v113, 0.5, v113
	v_add_f32_e32 v112, 1.0, v112
	v_mul_f32_e32 v112, v113, v112
	v_cvt_pk_bf16_f32 v111, v111, v112
	v_fma_f32 v112, -v116, v117, 1.0
	v_fmac_f32_e32 v117, v112, v117
	v_div_scale_f32 v112, vcc, 2.0, v115, 2.0
	v_mul_f32_e32 v113, v112, v117
	v_fma_f32 v118, -v116, v113, v112
	v_fmac_f32_e32 v113, v118, v117
	v_fma_f32 v112, -v116, v113, v112
	v_mul_f32_e32 v116, 0x3d372713, v107
	v_mul_f32_e32 v116, v107, v116
	v_fma_f32 v116, v107, v116, v107
	v_mul_f32_e32 v116, 0x3f4c422a, v116
	v_add_f32_e32 v116, v116, v116
	v_mul_f32_e32 v116, 0x3fb8aa3b, v116
	v_exp_f32_e32 v116, v116
	v_div_fmas_f32 v112, v112, v117, v113
	v_div_fixup_f32 v112, v112, v115, 2.0
	v_sub_f32_e32 v112, 1.0, v112
	v_add_f32_e32 v113, 1.0, v116
	v_div_scale_f32 v115, s[28:29], v113, v113, 2.0
	v_rcp_f32_e32 v116, v115
	v_mul_f32_e32 v106, 0.5, v106
	v_add_f32_e32 v112, 1.0, v112
	v_mul_f32_e32 v106, v106, v112
	v_fma_f32 v112, -v115, v116, 1.0
	v_fmac_f32_e32 v116, v112, v116
	v_div_scale_f32 v112, vcc, 2.0, v113, 2.0
	v_mul_f32_e32 v117, v112, v116
	v_fma_f32 v118, -v115, v117, v112
	v_fmac_f32_e32 v117, v118, v116
	v_fma_f32 v112, -v115, v117, v112
	v_mul_f32_e32 v115, 0x3d372713, v108
	v_mul_f32_e32 v115, v108, v115
	v_fma_f32 v115, v108, v115, v108
	v_mul_f32_e32 v115, 0x3f4c422a, v115
	v_add_f32_e32 v115, v115, v115
	v_mul_f32_e32 v115, 0x3fb8aa3b, v115
	v_exp_f32_e32 v115, v115
	v_div_fmas_f32 v112, v112, v116, v117
	v_div_fixup_f32 v112, v112, v113, 2.0
	v_sub_f32_e32 v112, 1.0, v112
	v_add_f32_e32 v113, 1.0, v115
	v_div_scale_f32 v115, s[28:29], v113, v113, 2.0
	v_rcp_f32_e32 v116, v115
	v_mul_f32_e32 v107, 0.5, v107
	v_add_f32_e32 v112, 1.0, v112
	v_mul_f32_e32 v107, v107, v112
	v_cvt_pk_bf16_f32 v112, v106, v107
	v_fma_f32 v106, -v115, v116, 1.0
	v_fmac_f32_e32 v116, v106, v116
	v_div_scale_f32 v106, vcc, 2.0, v113, 2.0
	v_mul_f32_e32 v107, v106, v116
	v_fma_f32 v117, -v115, v107, v106
	v_fmac_f32_e32 v107, v117, v116
	v_fma_f32 v106, -v115, v107, v106
	v_mul_f32_e32 v115, 0x3d372713, v109
	v_mul_f32_e32 v115, v109, v115
	v_fma_f32 v115, v109, v115, v109
	v_mul_f32_e32 v115, 0x3f4c422a, v115
	v_add_f32_e32 v115, v115, v115
	v_mul_f32_e32 v115, 0x3fb8aa3b, v115
	v_exp_f32_e32 v115, v115
	v_div_fmas_f32 v106, v106, v116, v107
	v_div_fixup_f32 v106, v106, v113, 2.0
	v_sub_f32_e32 v106, 1.0, v106
	v_add_f32_e32 v107, 1.0, v115
	v_div_scale_f32 v113, s[28:29], v107, v107, 2.0
	v_rcp_f32_e32 v115, v113
	v_mul_f32_e32 v108, 0.5, v108
	v_add_f32_e32 v106, 1.0, v106
	v_mul_f32_e32 v106, v108, v106
	v_fma_f32 v108, -v113, v115, 1.0
	v_fmac_f32_e32 v115, v108, v115
	v_div_scale_f32 v108, vcc, 2.0, v107, 2.0
	v_mul_f32_e32 v116, v108, v115
	v_fma_f32 v117, -v113, v116, v108
	v_fmac_f32_e32 v116, v117, v115
	v_fma_f32 v108, -v113, v116, v108
	v_div_fmas_f32 v108, v108, v115, v116
; #define LAS __attribute__((address_space(3)))
; __device__ __forceinline__ unsigned cvt_pk_bf16(float lo, float hi) { unsigned r; asm volatile("v_cvt_pk_bf16_f32 %0, %1, %2" : "=v"(r) : "v"(lo), "v"(hi)); return r; }
; __device__ __forceinline__ float gelu_tanh(float x) { const float z = 0.7978845608f * (x + 0.044715f * x * x * x); const float th = 1.0f - 2.0f / (__expf(2.0f * z) + 1.0f); return 0.5f * x * (1.0f + th); }
;     __device__ __forceinline__ void operator()(const f32x4 (&acc)[2][2][4][2], const Unit& u, int ui, const LAS float* rtab, int wr, int wc, int fr, int fq) const {
;         const int g = u.pm; const int n0 = wr * 64 + fr; const int lc0 = (u.pn & 1) * 256 + wc * 32 + 8 * fq;
; #pragma unroll
;         for (int ai = 0; ai < 2; ++ai)
; #pragma unroll
;             for (int m = 0; m < 4; ++m) {
;                 const int n = n0 + ai * HALF + m * 16;
; #pragma unroll
;                 for (int bj = 0; bj < 2; ++bj) {
;                     const int lc = lc0 + bj * HALF, t = lc >> 4, co = lc & 15; const int token = n * 32 + t;
;                     const f32x4 a0 = acc[ai][bj][m][0], a1 = acc[ai][bj][m][1];
;                     u32x4 w; w.x = cvt_pk_bf16(gelu_tanh(a0[0]), gelu_tanh(a0[1])); w.y = cvt_pk_bf16(gelu_tanh(a0[2]), gelu_tanh(a0[3]));
;                     w.z = cvt_pk_bf16(gelu_tanh(a1[0]), gelu_tanh(a1[1])); w.w = cvt_pk_bf16(gelu_tanh(a1[2]), gelu_tanh(a1[3]));
;                     *(u32x4*)(Y + (size_t)token * 1024 + 16 * g + co) = w;
;                 }
;             }
;     }
	v_div_fixup_f32 v107, v108, v107, 2.0
	v_sub_f32_e32 v107, 1.0, v107
	v_mul_f32_e32 v108, 0.5, v109
	v_add_f32_e32 v107, 1.0, v107
	v_mul_f32_e32 v107, v108, v107
	v_mul_f32_e32 v108, 0x3d372713, v102
	v_mul_f32_e32 v108, v102, v108
	v_fma_f32 v108, v102, v108, v102
	v_mul_f32_e32 v108, 0x3f4c422a, v108
	v_add_f32_e32 v108, v108, v108
	v_mul_f32_e32 v108, 0x3fb8aa3b, v108
	v_exp_f32_e32 v108, v108
	v_or_b32_e32 v114, v171, v147
	v_ashrrev_i32_e32 v115, 31, v114
	v_cvt_pk_bf16_f32 v113, v106, v107
	v_add_f32_e32 v108, 1.0, v108
	v_div_scale_f32 v109, s[28:29], v108, v108, 2.0
	v_lshlrev_b64 v[106:107], 11, v[114:115]
	v_rcp_f32_e32 v114, v109
	v_lshl_add_u64 v[106:107], v[138:139], 0, v[106:107]
	global_store_dwordx4 v[106:107], v[110:113], off
	v_mul_f32_e32 v102, 0.5, v102
	v_fma_f32 v107, -v109, v114, 1.0
	v_fmac_f32_e32 v114, v107, v114
	v_div_scale_f32 v107, vcc, 2.0, v108, 2.0
	v_mul_f32_e32 v110, v107, v114
	v_fma_f32 v111, -v109, v110, v107
	v_fmac_f32_e32 v110, v111, v114
	v_fma_f32 v107, -v109, v110, v107
	v_mul_f32_e32 v109, 0x3d372713, v103
	v_mul_f32_e32 v109, v103, v109
	v_fma_f32 v109, v103, v109, v103
	v_mul_f32_e32 v109, 0x3f4c422a, v109
	v_add_f32_e32 v109, v109, v109
	v_mul_f32_e32 v109, 0x3fb8aa3b, v109
	v_exp_f32_e32 v109, v109
	v_div_fmas_f32 v107, v107, v114, v110
	v_div_fixup_f32 v107, v107, v108, 2.0
	v_sub_f32_e32 v107, 1.0, v107
	v_add_f32_e32 v108, 1.0, v109
	v_div_scale_f32 v109, s[28:29], v108, v108, 2.0
	v_rcp_f32_e32 v110, v109
	v_add_f32_e32 v107, 1.0, v107
	v_mul_f32_e32 v102, v102, v107
	v_mul_f32_e32 v103, 0.5, v103
	v_fma_f32 v107, -v109, v110, 1.0
	v_fmac_f32_e32 v110, v107, v110
	v_div_scale_f32 v107, vcc, 2.0, v108, 2.0
	v_mul_f32_e32 v111, v107, v110
	v_fma_f32 v112, -v109, v111, v107
	v_fmac_f32_e32 v111, v112, v110
	v_fma_f32 v107, -v109, v111, v107
	v_mul_f32_e32 v109, 0x3d372713, v104
	v_mul_f32_e32 v109, v104, v109
	v_fma_f32 v109, v104, v109, v104
	v_mul_f32_e32 v109, 0x3f4c422a, v109
	v_add_f32_e32 v109, v109, v109
	v_mul_f32_e32 v109, 0x3fb8aa3b, v109
	v_exp_f32_e32 v109, v109
	v_div_fmas_f32 v107, v107, v110, v111
	v_div_fixup_f32 v107, v107, v108, 2.0
	v_sub_f32_e32 v107, 1.0, v107
	v_add_f32_e32 v108, 1.0, v109
	v_div_scale_f32 v109, s[28:29], v108, v108, 2.0
	v_rcp_f32_e32 v110, v109
	v_add_f32_e32 v107, 1.0, v107
	v_mul_f32_e32 v103, v103, v107
	v_cvt_pk_bf16_f32 v102, v102, v103
	v_fma_f32 v103, -v109, v110, 1.0
	v_fmac_f32_e32 v110, v103, v110
	v_div_scale_f32 v103, vcc, 2.0, v108, 2.0
	v_mul_f32_e32 v107, v103, v110
	v_fma_f32 v111, -v109, v107, v103
	v_fmac_f32_e32 v107, v111, v110
	v_fma_f32 v103, -v109, v107, v103
	v_mul_f32_e32 v109, 0x3d372713, v105
	v_mul_f32_e32 v109, v105, v109
	v_fma_f32 v109, v105, v109, v105
	v_mul_f32_e32 v109, 0x3f4c422a, v109
	v_add_f32_e32 v109, v109, v109
	v_mul_f32_e32 v109, 0x3fb8aa3b, v109
	v_exp_f32_e32 v109, v109
	v_div_fmas_f32 v103, v103, v110, v107
	v_div_fixup_f32 v103, v103, v108, 2.0
	v_sub_f32_e32 v103, 1.0, v103
	v_add_f32_e32 v107, 1.0, v109
	v_div_scale_f32 v108, s[28:29], v107, v107, 2.0
	v_rcp_f32_e32 v109, v108
	v_mul_f32_e32 v104, 0.5, v104
	v_add_f32_e32 v103, 1.0, v103
	v_mul_f32_e32 v103, v104, v103
	v_fma_f32 v104, -v108, v109, 1.0
	v_fmac_f32_e32 v109, v104, v109
	v_div_scale_f32 v104, vcc, 2.0, v107, 2.0
	v_mul_f32_e32 v110, v104, v109
	v_fma_f32 v111, -v108, v110, v104
	v_fmac_f32_e32 v110, v111, v109
	v_fma_f32 v104, -v108, v110, v104
	v_mul_f32_e32 v108, 0x3d372713, v98
	v_mul_f32_e32 v108, v98, v108
	v_fma_f32 v108, v98, v108, v98
	v_mul_f32_e32 v108, 0x3f4c422a, v108
	v_add_f32_e32 v108, v108, v108
	v_mul_f32_e32 v108, 0x3fb8aa3b, v108
	v_exp_f32_e32 v108, v108
	v_div_fmas_f32 v104, v104, v109, v110
	v_div_fixup_f32 v104, v104, v107, 2.0
	v_sub_f32_e32 v104, 1.0, v104
	v_add_f32_e32 v107, 1.0, v108
	v_div_scale_f32 v108, s[28:29], v107, v107, 2.0
	v_rcp_f32_e32 v109, v108
	v_mul_f32_e32 v105, 0.5, v105
	v_add_f32_e32 v104, 1.0, v104
	v_mul_f32_e32 v104, v105, v104
	v_cvt_pk_bf16_f32 v103, v103, v104
	v_fma_f32 v104, -v108, v109, 1.0
	v_fmac_f32_e32 v109, v104, v109
	v_div_scale_f32 v104, vcc, 2.0, v107, 2.0
	v_mul_f32_e32 v105, v104, v109
	v_fma_f32 v110, -v108, v105, v104
	v_fmac_f32_e32 v105, v110, v109
	v_fma_f32 v104, -v108, v105, v104
	v_mul_f32_e32 v108, 0x3d372713, v99
	v_mul_f32_e32 v108, v99, v108
	v_fma_f32 v108, v99, v108, v99
	v_mul_f32_e32 v108, 0x3f4c422a, v108
	v_add_f32_e32 v108, v108, v108
	v_mul_f32_e32 v108, 0x3fb8aa3b, v108
	v_exp_f32_e32 v108, v108
	v_div_fmas_f32 v104, v104, v109, v105
	v_div_fixup_f32 v104, v104, v107, 2.0
	v_sub_f32_e32 v104, 1.0, v104
	v_add_f32_e32 v105, 1.0, v108
	v_div_scale_f32 v107, s[28:29], v105, v105, 2.0
	v_rcp_f32_e32 v108, v107
	v_mul_f32_e32 v98, 0.5, v98
	v_add_f32_e32 v104, 1.0, v104
	v_mul_f32_e32 v98, v98, v104
	v_fma_f32 v104, -v107, v108, 1.0
	v_fmac_f32_e32 v108, v104, v108
	v_div_scale_f32 v104, vcc, 2.0, v105, 2.0
	v_mul_f32_e32 v109, v104, v108
	v_fma_f32 v110, -v107, v109, v104
	v_fmac_f32_e32 v109, v110, v108
	v_fma_f32 v104, -v107, v109, v104
	v_mul_f32_e32 v107, 0x3d372713, v100
	v_mul_f32_e32 v107, v100, v107
	v_fma_f32 v107, v100, v107, v100
	v_mul_f32_e32 v107, 0x3f4c422a, v107
	v_add_f32_e32 v107, v107, v107
	v_mul_f32_e32 v107, 0x3fb8aa3b, v107
	v_exp_f32_e32 v107, v107
	v_div_fmas_f32 v104, v104, v108, v109
	v_div_fixup_f32 v104, v104, v105, 2.0
	v_sub_f32_e32 v104, 1.0, v104
	v_add_f32_e32 v105, 1.0, v107
	v_div_scale_f32 v107, s[28:29], v105, v105, 2.0
	v_rcp_f32_e32 v108, v107
	v_mul_f32_e32 v99, 0.5, v99
	v_add_f32_e32 v104, 1.0, v104
	v_mul_f32_e32 v99, v99, v104
	v_cvt_pk_bf16_f32 v104, v98, v99
	v_fma_f32 v98, -v107, v108, 1.0
; #define LAS __attribute__((address_space(3)))
; __device__ __forceinline__ unsigned cvt_pk_bf16(float lo, float hi) { unsigned r; asm volatile("v_cvt_pk_bf16_f32 %0, %1, %2" : "=v"(r) : "v"(lo), "v"(hi)); return r; }
; __device__ __forceinline__ float gelu_tanh(float x) { const float z = 0.7978845608f * (x + 0.044715f * x * x * x); const float th = 1.0f - 2.0f / (__expf(2.0f * z) + 1.0f); return 0.5f * x * (1.0f + th); }
;     __device__ __forceinline__ void operator()(const f32x4 (&acc)[2][2][4][2], const Unit& u, int ui, const LAS float* rtab, int wr, int wc, int fr, int fq) const {
;         const int g = u.pm; const int n0 = wr * 64 + fr; const int lc0 = (u.pn & 1) * 256 + wc * 32 + 8 * fq;
; #pragma unroll
;         for (int ai = 0; ai < 2; ++ai)
; #pragma unroll
;             for (int m = 0; m < 4; ++m) {
;                 const int n = n0 + ai * HALF + m * 16;
; #pragma unroll
;                 for (int bj = 0; bj < 2; ++bj) {
;                     const int lc = lc0 + bj * HALF, t = lc >> 4, co = lc & 15; const int token = n * 32 + t;
;                     const f32x4 a0 = acc[ai][bj][m][0], a1 = acc[ai][bj][m][1];
;                     u32x4 w; w.x = cvt_pk_bf16(gelu_tanh(a0[0]), gelu_tanh(a0[1])); w.y = cvt_pk_bf16(gelu_tanh(a0[2]), gelu_tanh(a0[3]));
;                     w.z = cvt_pk_bf16(gelu_tanh(a1[0]), gelu_tanh(a1[1])); w.w = cvt_pk_bf16(gelu_tanh(a1[2]), gelu_tanh(a1[3]));
;                     *(u32x4*)(Y + (size_t)token * 1024 + 16 * g + co) = w;
;                 }
;             }
;     }
	v_fmac_f32_e32 v108, v98, v108
	v_div_scale_f32 v98, vcc, 2.0, v105, 2.0
	v_mul_f32_e32 v99, v98, v108
	v_fma_f32 v109, -v107, v99, v98
	v_fmac_f32_e32 v99, v109, v108
	v_fma_f32 v98, -v107, v99, v98
	v_mul_f32_e32 v107, 0x3d372713, v101
	v_mul_f32_e32 v107, v101, v107
	v_fma_f32 v107, v101, v107, v101
	v_mul_f32_e32 v107, 0x3f4c422a, v107
	v_add_f32_e32 v107, v107, v107
	v_mul_f32_e32 v107, 0x3fb8aa3b, v107
	v_exp_f32_e32 v107, v107
	v_div_fmas_f32 v98, v98, v108, v99
	v_div_fixup_f32 v98, v98, v105, 2.0
	v_sub_f32_e32 v98, 1.0, v98
	v_add_f32_e32 v99, 1.0, v107
	v_div_scale_f32 v105, s[28:29], v99, v99, 2.0
	v_rcp_f32_e32 v107, v105
	v_mul_f32_e32 v100, 0.5, v100
	v_add_f32_e32 v98, 1.0, v98
	v_mul_f32_e32 v98, v100, v98
	v_fma_f32 v100, -v105, v107, 1.0
	v_fmac_f32_e32 v107, v100, v107
	v_div_scale_f32 v100, vcc, 2.0, v99, 2.0
	v_mul_f32_e32 v108, v100, v107
	v_fma_f32 v109, -v105, v108, v100
	v_fmac_f32_e32 v108, v109, v107
	v_fma_f32 v100, -v105, v108, v100
	v_div_fmas_f32 v100, v100, v107, v108
	v_div_fixup_f32 v99, v100, v99, 2.0
	v_sub_f32_e32 v99, 1.0, v99
	v_mul_f32_e32 v100, 0.5, v101
	v_add_f32_e32 v99, 1.0, v99
	v_mul_f32_e32 v99, v100, v99
	v_mul_f32_e32 v100, 0x3d372713, v94
	v_mul_f32_e32 v100, v94, v100
	v_fma_f32 v100, v94, v100, v94
	v_mul_f32_e32 v100, 0x3f4c422a, v100
	v_add_f32_e32 v100, v100, v100
	v_mul_f32_e32 v100, 0x3fb8aa3b, v100
	v_exp_f32_e32 v100, v100
	v_or_b32_e32 v106, v124, v147
	v_ashrrev_i32_e32 v107, 31, v106
	v_cvt_pk_bf16_f32 v105, v98, v99
	v_add_f32_e32 v100, 1.0, v100
	v_div_scale_f32 v101, s[28:29], v100, v100, 2.0
	v_lshlrev_b64 v[98:99], 11, v[106:107]
	v_rcp_f32_e32 v106, v101
	v_lshl_add_u64 v[98:99], v[138:139], 0, v[98:99]
	global_store_dwordx4 v[98:99], v[102:105], off
	v_mul_f32_e32 v94, 0.5, v94
	v_fma_f32 v99, -v101, v106, 1.0
	v_fmac_f32_e32 v106, v99, v106
	v_div_scale_f32 v99, vcc, 2.0, v100, 2.0
	v_mul_f32_e32 v102, v99, v106
	v_fma_f32 v103, -v101, v102, v99
	v_fmac_f32_e32 v102, v103, v106
	v_fma_f32 v99, -v101, v102, v99
	v_mul_f32_e32 v101, 0x3d372713, v95
	v_mul_f32_e32 v101, v95, v101
	v_fma_f32 v101, v95, v101, v95
	v_mul_f32_e32 v101, 0x3f4c422a, v101
	v_add_f32_e32 v101, v101, v101
	v_mul_f32_e32 v101, 0x3fb8aa3b, v101
	v_exp_f32_e32 v101, v101
	v_div_fmas_f32 v99, v99, v106, v102
	v_div_fixup_f32 v99, v99, v100, 2.0
	v_sub_f32_e32 v99, 1.0, v99
	v_add_f32_e32 v100, 1.0, v101
	v_div_scale_f32 v101, s[28:29], v100, v100, 2.0
	v_rcp_f32_e32 v102, v101
	v_add_f32_e32 v99, 1.0, v99
	v_mul_f32_e32 v94, v94, v99
	v_mul_f32_e32 v95, 0.5, v95
	v_fma_f32 v99, -v101, v102, 1.0
	v_fmac_f32_e32 v102, v99, v102
	v_div_scale_f32 v99, vcc, 2.0, v100, 2.0
	v_mul_f32_e32 v103, v99, v102
	v_fma_f32 v104, -v101, v103, v99
	v_fmac_f32_e32 v103, v104, v102
	v_fma_f32 v99, -v101, v103, v99
	v_mul_f32_e32 v101, 0x3d372713, v96
	v_mul_f32_e32 v101, v96, v101
	v_fma_f32 v101, v96, v101, v96
	v_mul_f32_e32 v101, 0x3f4c422a, v101
	v_add_f32_e32 v101, v101, v101
	v_mul_f32_e32 v101, 0x3fb8aa3b, v101
	v_exp_f32_e32 v101, v101
	v_div_fmas_f32 v99, v99, v102, v103
	v_div_fixup_f32 v99, v99, v100, 2.0
	v_sub_f32_e32 v99, 1.0, v99
	v_add_f32_e32 v100, 1.0, v101
	v_div_scale_f32 v101, s[28:29], v100, v100, 2.0
	v_rcp_f32_e32 v102, v101
	v_add_f32_e32 v99, 1.0, v99
	v_mul_f32_e32 v95, v95, v99
	v_cvt_pk_bf16_f32 v94, v94, v95
	v_fma_f32 v95, -v101, v102, 1.0
	v_fmac_f32_e32 v102, v95, v102
	v_div_scale_f32 v95, vcc, 2.0, v100, 2.0
	v_mul_f32_e32 v99, v95, v102
	v_fma_f32 v103, -v101, v99, v95
	v_fmac_f32_e32 v99, v103, v102
	v_fma_f32 v95, -v101, v99, v95
	v_mul_f32_e32 v101, 0x3d372713, v97
	v_mul_f32_e32 v101, v97, v101
	v_fma_f32 v101, v97, v101, v97
	v_mul_f32_e32 v101, 0x3f4c422a, v101
	v_add_f32_e32 v101, v101, v101
	v_mul_f32_e32 v101, 0x3fb8aa3b, v101
	v_exp_f32_e32 v101, v101
	v_div_fmas_f32 v95, v95, v102, v99
	v_div_fixup_f32 v95, v95, v100, 2.0
	v_sub_f32_e32 v95, 1.0, v95
	v_add_f32_e32 v99, 1.0, v101
	v_div_scale_f32 v100, s[28:29], v99, v99, 2.0
	v_rcp_f32_e32 v101, v100
	v_mul_f32_e32 v96, 0.5, v96
	v_add_f32_e32 v95, 1.0, v95
	v_mul_f32_e32 v95, v96, v95
	v_fma_f32 v96, -v100, v101, 1.0
	v_fmac_f32_e32 v101, v96, v101
	v_div_scale_f32 v96, vcc, 2.0, v99, 2.0
	v_mul_f32_e32 v102, v96, v101
	v_fma_f32 v103, -v100, v102, v96
	v_fmac_f32_e32 v102, v103, v101
	v_fma_f32 v96, -v100, v102, v96
	v_mul_f32_e32 v100, 0x3d372713, v90
	v_mul_f32_e32 v100, v90, v100
	v_fma_f32 v100, v90, v100, v90
	v_mul_f32_e32 v100, 0x3f4c422a, v100
	v_add_f32_e32 v100, v100, v100
	v_mul_f32_e32 v100, 0x3fb8aa3b, v100
	v_exp_f32_e32 v100, v100
	v_div_fmas_f32 v96, v96, v101, v102
	v_div_fixup_f32 v96, v96, v99, 2.0
	v_sub_f32_e32 v96, 1.0, v96
	v_add_f32_e32 v99, 1.0, v100
	v_div_scale_f32 v100, s[28:29], v99, v99, 2.0
	v_rcp_f32_e32 v101, v100
	v_mul_f32_e32 v97, 0.5, v97
	v_add_f32_e32 v96, 1.0, v96
	v_mul_f32_e32 v96, v97, v96
	v_cvt_pk_bf16_f32 v95, v95, v96
	v_fma_f32 v96, -v100, v101, 1.0
	v_fmac_f32_e32 v101, v96, v101
	v_div_scale_f32 v96, vcc, 2.0, v99, 2.0
	v_mul_f32_e32 v97, v96, v101
	v_fma_f32 v102, -v100, v97, v96
	v_fmac_f32_e32 v97, v102, v101
	v_fma_f32 v96, -v100, v97, v96
	v_mul_f32_e32 v100, 0x3d372713, v91
	v_mul_f32_e32 v100, v91, v100
	v_fma_f32 v100, v91, v100, v91
	v_mul_f32_e32 v100, 0x3f4c422a, v100
	v_add_f32_e32 v100, v100, v100
	v_mul_f32_e32 v100, 0x3fb8aa3b, v100
	v_exp_f32_e32 v100, v100
	v_div_fmas_f32 v96, v96, v101, v97
	v_div_fixup_f32 v96, v96, v99, 2.0
	v_sub_f32_e32 v96, 1.0, v96
	v_add_f32_e32 v97, 1.0, v100
	v_div_scale_f32 v99, s[28:29], v97, v97, 2.0
	v_rcp_f32_e32 v100, v99
	v_mul_f32_e32 v90, 0.5, v90
	v_add_f32_e32 v96, 1.0, v96
	v_mul_f32_e32 v90, v90, v96
; #define LAS __attribute__((address_space(3)))
; __device__ __forceinline__ unsigned cvt_pk_bf16(float lo, float hi) { unsigned r; asm volatile("v_cvt_pk_bf16_f32 %0, %1, %2" : "=v"(r) : "v"(lo), "v"(hi)); return r; }
; __device__ __forceinline__ float gelu_tanh(float x) { const float z = 0.7978845608f * (x + 0.044715f * x * x * x); const float th = 1.0f - 2.0f / (__expf(2.0f * z) + 1.0f); return 0.5f * x * (1.0f + th); }
;     __device__ __forceinline__ void operator()(const f32x4 (&acc)[2][2][4][2], const Unit& u, int ui, const LAS float* rtab, int wr, int wc, int fr, int fq) const {
;         const int g = u.pm; const int n0 = wr * 64 + fr; const int lc0 = (u.pn & 1) * 256 + wc * 32 + 8 * fq;
; #pragma unroll
;         for (int ai = 0; ai < 2; ++ai)
; #pragma unroll
;             for (int m = 0; m < 4; ++m) {
;                 const int n = n0 + ai * HALF + m * 16;
; #pragma unroll
;                 for (int bj = 0; bj < 2; ++bj) {
;                     const int lc = lc0 + bj * HALF, t = lc >> 4, co = lc & 15; const int token = n * 32 + t;
;                     const f32x4 a0 = acc[ai][bj][m][0], a1 = acc[ai][bj][m][1];
;                     u32x4 w; w.x = cvt_pk_bf16(gelu_tanh(a0[0]), gelu_tanh(a0[1])); w.y = cvt_pk_bf16(gelu_tanh(a0[2]), gelu_tanh(a0[3]));
;                     w.z = cvt_pk_bf16(gelu_tanh(a1[0]), gelu_tanh(a1[1])); w.w = cvt_pk_bf16(gelu_tanh(a1[2]), gelu_tanh(a1[3]));
;                     *(u32x4*)(Y + (size_t)token * 1024 + 16 * g + co) = w;
;                 }
;             }
;     }
	v_fma_f32 v96, -v99, v100, 1.0
	v_fmac_f32_e32 v100, v96, v100
	v_div_scale_f32 v96, vcc, 2.0, v97, 2.0
	v_mul_f32_e32 v101, v96, v100
	v_fma_f32 v102, -v99, v101, v96
	v_fmac_f32_e32 v101, v102, v100
	v_fma_f32 v96, -v99, v101, v96
	v_mul_f32_e32 v99, 0x3d372713, v92
	v_mul_f32_e32 v99, v92, v99
	v_fma_f32 v99, v92, v99, v92
	v_mul_f32_e32 v99, 0x3f4c422a, v99
	v_add_f32_e32 v99, v99, v99
	v_mul_f32_e32 v99, 0x3fb8aa3b, v99
	v_exp_f32_e32 v99, v99
	v_div_fmas_f32 v96, v96, v100, v101
	v_div_fixup_f32 v96, v96, v97, 2.0
	v_sub_f32_e32 v96, 1.0, v96
	v_add_f32_e32 v97, 1.0, v99
	v_div_scale_f32 v99, s[28:29], v97, v97, 2.0
	v_rcp_f32_e32 v100, v99
	v_mul_f32_e32 v91, 0.5, v91
	v_add_f32_e32 v96, 1.0, v96
	v_mul_f32_e32 v91, v91, v96
	v_cvt_pk_bf16_f32 v96, v90, v91
	v_fma_f32 v90, -v99, v100, 1.0
	v_fmac_f32_e32 v100, v90, v100
	v_div_scale_f32 v90, vcc, 2.0, v97, 2.0
	v_mul_f32_e32 v91, v90, v100
	v_fma_f32 v101, -v99, v91, v90
	v_fmac_f32_e32 v91, v101, v100
	v_fma_f32 v90, -v99, v91, v90
	v_mul_f32_e32 v99, 0x3d372713, v93
	v_mul_f32_e32 v99, v93, v99
	v_fma_f32 v99, v93, v99, v93
	v_mul_f32_e32 v99, 0x3f4c422a, v99
	v_add_f32_e32 v99, v99, v99
	v_mul_f32_e32 v99, 0x3fb8aa3b, v99
	v_exp_f32_e32 v99, v99
	v_div_fmas_f32 v90, v90, v100, v91
	v_div_fixup_f32 v90, v90, v97, 2.0
	v_sub_f32_e32 v90, 1.0, v90
	v_add_f32_e32 v91, 1.0, v99
	v_div_scale_f32 v97, s[28:29], v91, v91, 2.0
	v_rcp_f32_e32 v99, v97
	v_mul_f32_e32 v92, 0.5, v92
	v_add_f32_e32 v90, 1.0, v90
	v_mul_f32_e32 v90, v92, v90
	v_fma_f32 v92, -v97, v99, 1.0
	v_fmac_f32_e32 v99, v92, v99
	v_div_scale_f32 v92, vcc, 2.0, v91, 2.0
	v_mul_f32_e32 v100, v92, v99
	v_fma_f32 v101, -v97, v100, v92
	v_fmac_f32_e32 v100, v101, v99
	v_fma_f32 v92, -v97, v100, v92
	v_div_fmas_f32 v92, v92, v99, v100
	v_div_fixup_f32 v91, v92, v91, 2.0
	v_sub_f32_e32 v91, 1.0, v91
	v_mul_f32_e32 v92, 0.5, v93
	v_add_f32_e32 v91, 1.0, v91
	v_mul_f32_e32 v91, v92, v91
	v_mul_f32_e32 v92, 0x3d372713, v86
	v_mul_f32_e32 v92, v86, v92
	v_fma_f32 v92, v86, v92, v86
	v_mul_f32_e32 v92, 0x3f4c422a, v92
	v_add_f32_e32 v92, v92, v92
	v_mul_f32_e32 v92, 0x3fb8aa3b, v92
	v_exp_f32_e32 v92, v92
	v_or_b32_e32 v98, v171, v148
	v_ashrrev_i32_e32 v99, 31, v98
	v_cvt_pk_bf16_f32 v97, v90, v91
	v_add_f32_e32 v92, 1.0, v92
	v_div_scale_f32 v93, s[28:29], v92, v92, 2.0
	v_lshlrev_b64 v[90:91], 11, v[98:99]
	v_rcp_f32_e32 v98, v93
	v_lshl_add_u64 v[90:91], v[138:139], 0, v[90:91]
	global_store_dwordx4 v[90:91], v[94:97], off
	v_mul_f32_e32 v86, 0.5, v86
	v_fma_f32 v91, -v93, v98, 1.0
	v_fmac_f32_e32 v98, v91, v98
	v_div_scale_f32 v91, vcc, 2.0, v92, 2.0
	v_mul_f32_e32 v94, v91, v98
	v_fma_f32 v95, -v93, v94, v91
	v_fmac_f32_e32 v94, v95, v98
	v_fma_f32 v91, -v93, v94, v91
	v_mul_f32_e32 v93, 0x3d372713, v87
	v_mul_f32_e32 v93, v87, v93
	v_fma_f32 v93, v87, v93, v87
	v_mul_f32_e32 v93, 0x3f4c422a, v93
	v_add_f32_e32 v93, v93, v93
	v_mul_f32_e32 v93, 0x3fb8aa3b, v93
	v_exp_f32_e32 v93, v93
	v_div_fmas_f32 v91, v91, v98, v94
	v_div_fixup_f32 v91, v91, v92, 2.0
	v_sub_f32_e32 v91, 1.0, v91
	v_add_f32_e32 v92, 1.0, v93
	v_div_scale_f32 v93, s[28:29], v92, v92, 2.0
	v_rcp_f32_e32 v94, v93
	v_add_f32_e32 v91, 1.0, v91
	v_mul_f32_e32 v86, v86, v91
	v_mul_f32_e32 v87, 0.5, v87
	v_fma_f32 v91, -v93, v94, 1.0
	v_fmac_f32_e32 v94, v91, v94
	v_div_scale_f32 v91, vcc, 2.0, v92, 2.0
	v_mul_f32_e32 v95, v91, v94
	v_fma_f32 v96, -v93, v95, v91
	v_fmac_f32_e32 v95, v96, v94
	v_fma_f32 v91, -v93, v95, v91
	v_mul_f32_e32 v93, 0x3d372713, v88
	v_mul_f32_e32 v93, v88, v93
	v_fma_f32 v93, v88, v93, v88
	v_mul_f32_e32 v93, 0x3f4c422a, v93
	v_add_f32_e32 v93, v93, v93
	v_mul_f32_e32 v93, 0x3fb8aa3b, v93
	v_exp_f32_e32 v93, v93
	v_div_fmas_f32 v91, v91, v94, v95
	v_div_fixup_f32 v91, v91, v92, 2.0
	v_sub_f32_e32 v91, 1.0, v91
	v_add_f32_e32 v92, 1.0, v93
	v_div_scale_f32 v93, s[28:29], v92, v92, 2.0
	v_rcp_f32_e32 v94, v93
	v_add_f32_e32 v91, 1.0, v91
	v_mul_f32_e32 v87, v87, v91
	v_cvt_pk_bf16_f32 v86, v86, v87
	v_fma_f32 v87, -v93, v94, 1.0
	v_fmac_f32_e32 v94, v87, v94
	v_div_scale_f32 v87, vcc, 2.0, v92, 2.0
	v_mul_f32_e32 v91, v87, v94
	v_fma_f32 v95, -v93, v91, v87
	v_fmac_f32_e32 v91, v95, v94
	v_fma_f32 v87, -v93, v91, v87
	v_mul_f32_e32 v93, 0x3d372713, v89
	v_mul_f32_e32 v93, v89, v93
	v_fma_f32 v93, v89, v93, v89
	v_mul_f32_e32 v93, 0x3f4c422a, v93
	v_add_f32_e32 v93, v93, v93
	v_mul_f32_e32 v93, 0x3fb8aa3b, v93
	v_exp_f32_e32 v93, v93
	v_div_fmas_f32 v87, v87, v94, v91
	v_div_fixup_f32 v87, v87, v92, 2.0
	v_sub_f32_e32 v87, 1.0, v87
	v_add_f32_e32 v91, 1.0, v93
	v_div_scale_f32 v92, s[28:29], v91, v91, 2.0
	v_rcp_f32_e32 v93, v92
	v_mul_f32_e32 v88, 0.5, v88
	v_add_f32_e32 v87, 1.0, v87
	v_mul_f32_e32 v87, v88, v87
	v_fma_f32 v88, -v92, v93, 1.0
	v_fmac_f32_e32 v93, v88, v93
	v_div_scale_f32 v88, vcc, 2.0, v91, 2.0
	v_mul_f32_e32 v94, v88, v93
	v_fma_f32 v95, -v92, v94, v88
	v_fmac_f32_e32 v94, v95, v93
	v_fma_f32 v88, -v92, v94, v88
	v_mul_f32_e32 v92, 0x3d372713, v82
	v_mul_f32_e32 v92, v82, v92
	v_fma_f32 v92, v82, v92, v82
	v_mul_f32_e32 v92, 0x3f4c422a, v92
	v_add_f32_e32 v92, v92, v92
	v_mul_f32_e32 v92, 0x3fb8aa3b, v92
	v_exp_f32_e32 v92, v92
	v_div_fmas_f32 v88, v88, v93, v94
	v_div_fixup_f32 v88, v88, v91, 2.0
	v_sub_f32_e32 v88, 1.0, v88
	v_add_f32_e32 v91, 1.0, v92
	v_div_scale_f32 v92, s[28:29], v91, v91, 2.0
	v_rcp_f32_e32 v93, v92
	v_mul_f32_e32 v89, 0.5, v89
	v_add_f32_e32 v88, 1.0, v88
	v_mul_f32_e32 v88, v89, v88
	v_cvt_pk_bf16_f32 v87, v87, v88
	v_fma_f32 v88, -v92, v93, 1.0
	v_fmac_f32_e32 v93, v88, v93
	v_div_scale_f32 v88, vcc, 2.0, v91, 2.0
	v_mul_f32_e32 v89, v88, v93
	v_fma_f32 v94, -v92, v89, v88
	v_fmac_f32_e32 v89, v94, v93
; #define LAS __attribute__((address_space(3)))
; __device__ __forceinline__ unsigned cvt_pk_bf16(float lo, float hi) { unsigned r; asm volatile("v_cvt_pk_bf16_f32 %0, %1, %2" : "=v"(r) : "v"(lo), "v"(hi)); return r; }
; __device__ __forceinline__ float gelu_tanh(float x) { const float z = 0.7978845608f * (x + 0.044715f * x * x * x); const float th = 1.0f - 2.0f / (__expf(2.0f * z) + 1.0f); return 0.5f * x * (1.0f + th); }
;     __device__ __forceinline__ void operator()(const f32x4 (&acc)[2][2][4][2], const Unit& u, int ui, const LAS float* rtab, int wr, int wc, int fr, int fq) const {
;         const int g = u.pm; const int n0 = wr * 64 + fr; const int lc0 = (u.pn & 1) * 256 + wc * 32 + 8 * fq;
; #pragma unroll
;         for (int ai = 0; ai < 2; ++ai)
; #pragma unroll
;             for (int m = 0; m < 4; ++m) {
;                 const int n = n0 + ai * HALF + m * 16;
; #pragma unroll
;                 for (int bj = 0; bj < 2; ++bj) {
;                     const int lc = lc0 + bj * HALF, t = lc >> 4, co = lc & 15; const int token = n * 32 + t;
;                     const f32x4 a0 = acc[ai][bj][m][0], a1 = acc[ai][bj][m][1];
;                     u32x4 w; w.x = cvt_pk_bf16(gelu_tanh(a0[0]), gelu_tanh(a0[1])); w.y = cvt_pk_bf16(gelu_tanh(a0[2]), gelu_tanh(a0[3]));
;                     w.z = cvt_pk_bf16(gelu_tanh(a1[0]), gelu_tanh(a1[1])); w.w = cvt_pk_bf16(gelu_tanh(a1[2]), gelu_tanh(a1[3]));
;                     *(u32x4*)(Y + (size_t)token * 1024 + 16 * g + co) = w;
;                 }
;             }
;     }
	v_fma_f32 v88, -v92, v89, v88
	v_mul_f32_e32 v92, 0x3d372713, v83
	v_mul_f32_e32 v92, v83, v92
	v_fma_f32 v92, v83, v92, v83
	v_mul_f32_e32 v92, 0x3f4c422a, v92
	v_add_f32_e32 v92, v92, v92
	v_mul_f32_e32 v92, 0x3fb8aa3b, v92
	v_exp_f32_e32 v92, v92
	v_div_fmas_f32 v88, v88, v93, v89
	v_div_fixup_f32 v88, v88, v91, 2.0
	v_sub_f32_e32 v88, 1.0, v88
	v_add_f32_e32 v89, 1.0, v92
	v_div_scale_f32 v91, s[28:29], v89, v89, 2.0
	v_rcp_f32_e32 v92, v91
	v_mul_f32_e32 v82, 0.5, v82
	v_add_f32_e32 v88, 1.0, v88
	v_mul_f32_e32 v82, v82, v88
	v_fma_f32 v88, -v91, v92, 1.0
	v_fmac_f32_e32 v92, v88, v92
	v_div_scale_f32 v88, vcc, 2.0, v89, 2.0
	v_mul_f32_e32 v93, v88, v92
	v_fma_f32 v94, -v91, v93, v88
	v_fmac_f32_e32 v93, v94, v92
	v_fma_f32 v88, -v91, v93, v88
	v_mul_f32_e32 v91, 0x3d372713, v84
	v_mul_f32_e32 v91, v84, v91
	v_fma_f32 v91, v84, v91, v84
	v_mul_f32_e32 v91, 0x3f4c422a, v91
	v_add_f32_e32 v91, v91, v91
	v_mul_f32_e32 v91, 0x3fb8aa3b, v91
	v_exp_f32_e32 v91, v91
	v_div_fmas_f32 v88, v88, v92, v93
	v_div_fixup_f32 v88, v88, v89, 2.0
	v_sub_f32_e32 v88, 1.0, v88
	v_add_f32_e32 v89, 1.0, v91
	v_div_scale_f32 v91, s[28:29], v89, v89, 2.0
	v_rcp_f32_e32 v92, v91
	v_mul_f32_e32 v83, 0.5, v83
	v_add_f32_e32 v88, 1.0, v88
	v_mul_f32_e32 v83, v83, v88
	v_cvt_pk_bf16_f32 v88, v82, v83
	v_fma_f32 v82, -v91, v92, 1.0
	v_fmac_f32_e32 v92, v82, v92
	v_div_scale_f32 v82, vcc, 2.0, v89, 2.0
	v_mul_f32_e32 v83, v82, v92
	v_fma_f32 v93, -v91, v83, v82
	v_fmac_f32_e32 v83, v93, v92
	v_fma_f32 v82, -v91, v83, v82
	v_mul_f32_e32 v91, 0x3d372713, v85
	v_mul_f32_e32 v91, v85, v91
	v_fma_f32 v91, v85, v91, v85
	v_mul_f32_e32 v91, 0x3f4c422a, v91
	v_add_f32_e32 v91, v91, v91
	v_mul_f32_e32 v91, 0x3fb8aa3b, v91
	v_exp_f32_e32 v91, v91
	v_div_fmas_f32 v82, v82, v92, v83
	v_div_fixup_f32 v82, v82, v89, 2.0
	v_sub_f32_e32 v82, 1.0, v82
	v_add_f32_e32 v83, 1.0, v91
	v_div_scale_f32 v89, s[28:29], v83, v83, 2.0
	v_rcp_f32_e32 v91, v89
	v_mul_f32_e32 v84, 0.5, v84
	v_add_f32_e32 v82, 1.0, v82
	v_mul_f32_e32 v82, v84, v82
	v_fma_f32 v84, -v89, v91, 1.0
	v_fmac_f32_e32 v91, v84, v91
	v_div_scale_f32 v84, vcc, 2.0, v83, 2.0
	v_mul_f32_e32 v92, v84, v91
	v_fma_f32 v93, -v89, v92, v84
	v_fmac_f32_e32 v92, v93, v91
	v_fma_f32 v84, -v89, v92, v84
	v_div_fmas_f32 v84, v84, v91, v92
	v_div_fixup_f32 v83, v84, v83, 2.0
	v_sub_f32_e32 v83, 1.0, v83
	v_mul_f32_e32 v84, 0.5, v85
	v_add_f32_e32 v83, 1.0, v83
	v_mul_f32_e32 v83, v84, v83
	v_mul_f32_e32 v84, 0x3d372713, v78
	v_mul_f32_e32 v84, v78, v84
	v_fma_f32 v84, v78, v84, v78
	v_mul_f32_e32 v84, 0x3f4c422a, v84
	v_add_f32_e32 v84, v84, v84
	v_mul_f32_e32 v84, 0x3fb8aa3b, v84
	v_exp_f32_e32 v84, v84
	v_or_b32_e32 v90, v124, v148
	v_ashrrev_i32_e32 v91, 31, v90
	v_cvt_pk_bf16_f32 v89, v82, v83
	v_add_f32_e32 v84, 1.0, v84
	v_div_scale_f32 v85, s[28:29], v84, v84, 2.0
	v_lshlrev_b64 v[82:83], 11, v[90:91]
	v_rcp_f32_e32 v90, v85
	v_lshl_add_u64 v[82:83], v[138:139], 0, v[82:83]
	global_store_dwordx4 v[82:83], v[86:89], off
	v_mul_f32_e32 v78, 0.5, v78
	v_fma_f32 v83, -v85, v90, 1.0
	v_fmac_f32_e32 v90, v83, v90
	v_div_scale_f32 v83, vcc, 2.0, v84, 2.0
	v_mul_f32_e32 v86, v83, v90
	v_fma_f32 v87, -v85, v86, v83
	v_fmac_f32_e32 v86, v87, v90
	v_fma_f32 v83, -v85, v86, v83
	v_mul_f32_e32 v85, 0x3d372713, v79
	v_mul_f32_e32 v85, v79, v85
	v_fma_f32 v85, v79, v85, v79
	v_mul_f32_e32 v85, 0x3f4c422a, v85
	v_add_f32_e32 v85, v85, v85
	v_mul_f32_e32 v85, 0x3fb8aa3b, v85
	v_exp_f32_e32 v85, v85
	v_div_fmas_f32 v83, v83, v90, v86
	v_div_fixup_f32 v83, v83, v84, 2.0
	v_sub_f32_e32 v83, 1.0, v83
	v_add_f32_e32 v84, 1.0, v85
	v_div_scale_f32 v85, s[28:29], v84, v84, 2.0
	v_rcp_f32_e32 v86, v85
	v_add_f32_e32 v83, 1.0, v83
	v_mul_f32_e32 v78, v78, v83
	v_mul_f32_e32 v79, 0.5, v79
	v_fma_f32 v83, -v85, v86, 1.0
	v_fmac_f32_e32 v86, v83, v86
	v_div_scale_f32 v83, vcc, 2.0, v84, 2.0
	v_mul_f32_e32 v87, v83, v86
	v_fma_f32 v88, -v85, v87, v83
	v_fmac_f32_e32 v87, v88, v86
	v_fma_f32 v83, -v85, v87, v83
	v_mul_f32_e32 v85, 0x3d372713, v80
	v_mul_f32_e32 v85, v80, v85
	v_fma_f32 v85, v80, v85, v80
	v_mul_f32_e32 v85, 0x3f4c422a, v85
	v_add_f32_e32 v85, v85, v85
	v_mul_f32_e32 v85, 0x3fb8aa3b, v85
	v_exp_f32_e32 v85, v85
	v_div_fmas_f32 v83, v83, v86, v87
	v_div_fixup_f32 v83, v83, v84, 2.0
	v_sub_f32_e32 v83, 1.0, v83
	v_add_f32_e32 v84, 1.0, v85
	v_div_scale_f32 v85, s[28:29], v84, v84, 2.0
	v_rcp_f32_e32 v86, v85
	v_add_f32_e32 v83, 1.0, v83
	v_mul_f32_e32 v79, v79, v83
	v_cvt_pk_bf16_f32 v78, v78, v79
	v_fma_f32 v79, -v85, v86, 1.0
	v_fmac_f32_e32 v86, v79, v86
	v_div_scale_f32 v79, vcc, 2.0, v84, 2.0
	v_mul_f32_e32 v83, v79, v86
	v_fma_f32 v87, -v85, v83, v79
	v_fmac_f32_e32 v83, v87, v86
	v_fma_f32 v79, -v85, v83, v79
	v_mul_f32_e32 v85, 0x3d372713, v81
	v_mul_f32_e32 v85, v81, v85
	v_fma_f32 v85, v81, v85, v81
	v_mul_f32_e32 v85, 0x3f4c422a, v85
	v_add_f32_e32 v85, v85, v85
	v_mul_f32_e32 v85, 0x3fb8aa3b, v85
	v_exp_f32_e32 v85, v85
	v_div_fmas_f32 v79, v79, v86, v83
	v_div_fixup_f32 v79, v79, v84, 2.0
	v_sub_f32_e32 v79, 1.0, v79
	v_add_f32_e32 v83, 1.0, v85
	v_div_scale_f32 v84, s[28:29], v83, v83, 2.0
	v_rcp_f32_e32 v85, v84
	v_mul_f32_e32 v80, 0.5, v80
	v_add_f32_e32 v79, 1.0, v79
	v_mul_f32_e32 v79, v80, v79
	v_fma_f32 v80, -v84, v85, 1.0
	v_fmac_f32_e32 v85, v80, v85
	v_div_scale_f32 v80, vcc, 2.0, v83, 2.0
	v_mul_f32_e32 v86, v80, v85
	v_fma_f32 v87, -v84, v86, v80
	v_fmac_f32_e32 v86, v87, v85
	v_fma_f32 v80, -v84, v86, v80
	v_mul_f32_e32 v84, 0x3d372713, v74
	v_mul_f32_e32 v84, v74, v84
	v_fma_f32 v84, v74, v84, v74
	v_mul_f32_e32 v84, 0x3f4c422a, v84
	v_add_f32_e32 v84, v84, v84
	v_mul_f32_e32 v84, 0x3fb8aa3b, v84
	v_exp_f32_e32 v84, v84
; #define LAS __attribute__((address_space(3)))
; __device__ __forceinline__ unsigned cvt_pk_bf16(float lo, float hi) { unsigned r; asm volatile("v_cvt_pk_bf16_f32 %0, %1, %2" : "=v"(r) : "v"(lo), "v"(hi)); return r; }
; __device__ __forceinline__ float gelu_tanh(float x) { const float z = 0.7978845608f * (x + 0.044715f * x * x * x); const float th = 1.0f - 2.0f / (__expf(2.0f * z) + 1.0f); return 0.5f * x * (1.0f + th); }
;     __device__ __forceinline__ void operator()(const f32x4 (&acc)[2][2][4][2], const Unit& u, int ui, const LAS float* rtab, int wr, int wc, int fr, int fq) const {
;         const int g = u.pm; const int n0 = wr * 64 + fr; const int lc0 = (u.pn & 1) * 256 + wc * 32 + 8 * fq;
; #pragma unroll
;         for (int ai = 0; ai < 2; ++ai)
; #pragma unroll
;             for (int m = 0; m < 4; ++m) {
;                 const int n = n0 + ai * HALF + m * 16;
; #pragma unroll
;                 for (int bj = 0; bj < 2; ++bj) {
;                     const int lc = lc0 + bj * HALF, t = lc >> 4, co = lc & 15; const int token = n * 32 + t;
;                     const f32x4 a0 = acc[ai][bj][m][0], a1 = acc[ai][bj][m][1];
;                     u32x4 w; w.x = cvt_pk_bf16(gelu_tanh(a0[0]), gelu_tanh(a0[1])); w.y = cvt_pk_bf16(gelu_tanh(a0[2]), gelu_tanh(a0[3]));
;                     w.z = cvt_pk_bf16(gelu_tanh(a1[0]), gelu_tanh(a1[1])); w.w = cvt_pk_bf16(gelu_tanh(a1[2]), gelu_tanh(a1[3]));
;                     *(u32x4*)(Y + (size_t)token * 1024 + 16 * g + co) = w;
;                 }
;             }
;     }
	v_div_fmas_f32 v80, v80, v85, v86
	v_div_fixup_f32 v80, v80, v83, 2.0
	v_sub_f32_e32 v80, 1.0, v80
	v_add_f32_e32 v83, 1.0, v84
	v_div_scale_f32 v84, s[28:29], v83, v83, 2.0
	v_rcp_f32_e32 v85, v84
	v_mul_f32_e32 v81, 0.5, v81
	v_add_f32_e32 v80, 1.0, v80
	v_mul_f32_e32 v80, v81, v80
	v_cvt_pk_bf16_f32 v79, v79, v80
	v_fma_f32 v80, -v84, v85, 1.0
	v_fmac_f32_e32 v85, v80, v85
	v_div_scale_f32 v80, vcc, 2.0, v83, 2.0
	v_mul_f32_e32 v81, v80, v85
	v_fma_f32 v86, -v84, v81, v80
	v_fmac_f32_e32 v81, v86, v85
	v_fma_f32 v80, -v84, v81, v80
	v_mul_f32_e32 v84, 0x3d372713, v75
	v_mul_f32_e32 v84, v75, v84
	v_fma_f32 v84, v75, v84, v75
	v_mul_f32_e32 v84, 0x3f4c422a, v84
	v_add_f32_e32 v84, v84, v84
	v_mul_f32_e32 v84, 0x3fb8aa3b, v84
	v_exp_f32_e32 v84, v84
	v_div_fmas_f32 v80, v80, v85, v81
	v_div_fixup_f32 v80, v80, v83, 2.0
	v_sub_f32_e32 v80, 1.0, v80
	v_add_f32_e32 v81, 1.0, v84
	v_div_scale_f32 v83, s[28:29], v81, v81, 2.0
	v_rcp_f32_e32 v84, v83
	v_mul_f32_e32 v74, 0.5, v74
	v_add_f32_e32 v80, 1.0, v80
	v_mul_f32_e32 v74, v74, v80
	v_fma_f32 v80, -v83, v84, 1.0
	v_fmac_f32_e32 v84, v80, v84
	v_div_scale_f32 v80, vcc, 2.0, v81, 2.0
	v_mul_f32_e32 v85, v80, v84
	v_fma_f32 v86, -v83, v85, v80
	v_fmac_f32_e32 v85, v86, v84
	v_fma_f32 v80, -v83, v85, v80
	v_mul_f32_e32 v83, 0x3d372713, v76
	v_mul_f32_e32 v83, v76, v83
	v_fma_f32 v83, v76, v83, v76
	v_mul_f32_e32 v83, 0x3f4c422a, v83
	v_add_f32_e32 v83, v83, v83
	v_mul_f32_e32 v83, 0x3fb8aa3b, v83
	v_exp_f32_e32 v83, v83
	v_div_fmas_f32 v80, v80, v84, v85
	v_div_fixup_f32 v80, v80, v81, 2.0
	v_sub_f32_e32 v80, 1.0, v80
	v_add_f32_e32 v81, 1.0, v83
	v_div_scale_f32 v83, s[28:29], v81, v81, 2.0
	v_rcp_f32_e32 v84, v83
	v_mul_f32_e32 v75, 0.5, v75
	v_add_f32_e32 v80, 1.0, v80
	v_mul_f32_e32 v75, v75, v80
	v_cvt_pk_bf16_f32 v80, v74, v75
	v_fma_f32 v74, -v83, v84, 1.0
	v_fmac_f32_e32 v84, v74, v84
	v_div_scale_f32 v74, vcc, 2.0, v81, 2.0
	v_mul_f32_e32 v75, v74, v84
	v_fma_f32 v85, -v83, v75, v74
	v_fmac_f32_e32 v75, v85, v84
	v_fma_f32 v74, -v83, v75, v74
	v_mul_f32_e32 v83, 0x3d372713, v77
	v_mul_f32_e32 v83, v77, v83
	v_fma_f32 v83, v77, v83, v77
	v_mul_f32_e32 v83, 0x3f4c422a, v83
	v_add_f32_e32 v83, v83, v83
	v_mul_f32_e32 v83, 0x3fb8aa3b, v83
	v_exp_f32_e32 v83, v83
	v_div_fmas_f32 v74, v74, v84, v75
	v_div_fixup_f32 v74, v74, v81, 2.0
	v_sub_f32_e32 v74, 1.0, v74
	v_add_f32_e32 v75, 1.0, v83
	v_div_scale_f32 v81, s[28:29], v75, v75, 2.0
	v_rcp_f32_e32 v83, v81
	v_mul_f32_e32 v76, 0.5, v76
	v_add_f32_e32 v74, 1.0, v74
	v_mul_f32_e32 v74, v76, v74
	v_fma_f32 v76, -v81, v83, 1.0
	v_fmac_f32_e32 v83, v76, v83
	v_div_scale_f32 v76, vcc, 2.0, v75, 2.0
	v_mul_f32_e32 v84, v76, v83
	v_fma_f32 v85, -v81, v84, v76
	v_fmac_f32_e32 v84, v85, v83
	v_fma_f32 v76, -v81, v84, v76
	v_div_fmas_f32 v76, v76, v83, v84
	v_div_fixup_f32 v75, v76, v75, 2.0
	v_sub_f32_e32 v75, 1.0, v75
	v_mul_f32_e32 v76, 0.5, v77
	v_add_f32_e32 v75, 1.0, v75
	v_mul_f32_e32 v75, v76, v75
	v_mul_f32_e32 v76, 0x3d372713, v70
	v_mul_f32_e32 v76, v70, v76
	v_fma_f32 v76, v70, v76, v70
	v_mul_f32_e32 v76, 0x3f4c422a, v76
	v_add_f32_e32 v76, v76, v76
	v_mul_f32_e32 v76, 0x3fb8aa3b, v76
	v_exp_f32_e32 v76, v76
	v_or_b32_e32 v82, v171, v149
	v_ashrrev_i32_e32 v83, 31, v82
	v_cvt_pk_bf16_f32 v81, v74, v75
	v_add_f32_e32 v76, 1.0, v76
	v_div_scale_f32 v77, s[28:29], v76, v76, 2.0
	v_lshlrev_b64 v[74:75], 11, v[82:83]
	v_rcp_f32_e32 v82, v77
	v_lshl_add_u64 v[74:75], v[138:139], 0, v[74:75]
	global_store_dwordx4 v[74:75], v[78:81], off
	v_mul_f32_e32 v70, 0.5, v70
	v_fma_f32 v75, -v77, v82, 1.0
	v_fmac_f32_e32 v82, v75, v82
	v_div_scale_f32 v75, vcc, 2.0, v76, 2.0
	v_mul_f32_e32 v78, v75, v82
	v_fma_f32 v79, -v77, v78, v75
	v_fmac_f32_e32 v78, v79, v82
	v_fma_f32 v75, -v77, v78, v75
	v_mul_f32_e32 v77, 0x3d372713, v71
	v_mul_f32_e32 v77, v71, v77
	v_fma_f32 v77, v71, v77, v71
	v_mul_f32_e32 v77, 0x3f4c422a, v77
	v_add_f32_e32 v77, v77, v77
	v_mul_f32_e32 v77, 0x3fb8aa3b, v77
	v_exp_f32_e32 v77, v77
	v_div_fmas_f32 v75, v75, v82, v78
	v_div_fixup_f32 v75, v75, v76, 2.0
	v_sub_f32_e32 v75, 1.0, v75
	v_add_f32_e32 v76, 1.0, v77
	v_div_scale_f32 v77, s[28:29], v76, v76, 2.0
	v_rcp_f32_e32 v78, v77
	v_add_f32_e32 v75, 1.0, v75
	v_mul_f32_e32 v70, v70, v75
	v_mul_f32_e32 v71, 0.5, v71
	v_fma_f32 v75, -v77, v78, 1.0
	v_fmac_f32_e32 v78, v75, v78
	v_div_scale_f32 v75, vcc, 2.0, v76, 2.0
	v_mul_f32_e32 v79, v75, v78
	v_fma_f32 v80, -v77, v79, v75
	v_fmac_f32_e32 v79, v80, v78
	v_fma_f32 v75, -v77, v79, v75
	v_mul_f32_e32 v77, 0x3d372713, v72
	v_mul_f32_e32 v77, v72, v77
	v_fma_f32 v77, v72, v77, v72
	v_mul_f32_e32 v77, 0x3f4c422a, v77
	v_add_f32_e32 v77, v77, v77
	v_mul_f32_e32 v77, 0x3fb8aa3b, v77
	v_exp_f32_e32 v77, v77
	v_div_fmas_f32 v75, v75, v78, v79
	v_div_fixup_f32 v75, v75, v76, 2.0
	v_sub_f32_e32 v75, 1.0, v75
	v_add_f32_e32 v76, 1.0, v77
	v_div_scale_f32 v77, s[28:29], v76, v76, 2.0
	v_rcp_f32_e32 v78, v77
	v_add_f32_e32 v75, 1.0, v75
	v_mul_f32_e32 v71, v71, v75
	v_cvt_pk_bf16_f32 v70, v70, v71
	v_fma_f32 v71, -v77, v78, 1.0
	v_fmac_f32_e32 v78, v71, v78
	v_div_scale_f32 v71, vcc, 2.0, v76, 2.0
	v_mul_f32_e32 v75, v71, v78
	v_fma_f32 v79, -v77, v75, v71
	v_fmac_f32_e32 v75, v79, v78
	v_fma_f32 v71, -v77, v75, v71
	v_mul_f32_e32 v77, 0x3d372713, v73
	v_mul_f32_e32 v77, v73, v77
	v_fma_f32 v77, v73, v77, v73
	v_mul_f32_e32 v77, 0x3f4c422a, v77
	v_add_f32_e32 v77, v77, v77
	v_mul_f32_e32 v77, 0x3fb8aa3b, v77
	v_exp_f32_e32 v77, v77
	v_div_fmas_f32 v71, v71, v78, v75
	v_div_fixup_f32 v71, v71, v76, 2.0
	v_sub_f32_e32 v71, 1.0, v71
	v_add_f32_e32 v75, 1.0, v77
	v_div_scale_f32 v76, s[28:29], v75, v75, 2.0
	v_rcp_f32_e32 v77, v76
; #define LAS __attribute__((address_space(3)))
; __device__ __forceinline__ unsigned cvt_pk_bf16(float lo, float hi) { unsigned r; asm volatile("v_cvt_pk_bf16_f32 %0, %1, %2" : "=v"(r) : "v"(lo), "v"(hi)); return r; }
; __device__ __forceinline__ float gelu_tanh(float x) { const float z = 0.7978845608f * (x + 0.044715f * x * x * x); const float th = 1.0f - 2.0f / (__expf(2.0f * z) + 1.0f); return 0.5f * x * (1.0f + th); }
;     __device__ __forceinline__ void operator()(const f32x4 (&acc)[2][2][4][2], const Unit& u, int ui, const LAS float* rtab, int wr, int wc, int fr, int fq) const {
;         const int g = u.pm; const int n0 = wr * 64 + fr; const int lc0 = (u.pn & 1) * 256 + wc * 32 + 8 * fq;
; #pragma unroll
;         for (int ai = 0; ai < 2; ++ai)
; #pragma unroll
;             for (int m = 0; m < 4; ++m) {
;                 const int n = n0 + ai * HALF + m * 16;
; #pragma unroll
;                 for (int bj = 0; bj < 2; ++bj) {
;                     const int lc = lc0 + bj * HALF, t = lc >> 4, co = lc & 15; const int token = n * 32 + t;
;                     const f32x4 a0 = acc[ai][bj][m][0], a1 = acc[ai][bj][m][1];
;                     u32x4 w; w.x = cvt_pk_bf16(gelu_tanh(a0[0]), gelu_tanh(a0[1])); w.y = cvt_pk_bf16(gelu_tanh(a0[2]), gelu_tanh(a0[3]));
;                     w.z = cvt_pk_bf16(gelu_tanh(a1[0]), gelu_tanh(a1[1])); w.w = cvt_pk_bf16(gelu_tanh(a1[2]), gelu_tanh(a1[3]));
;                     *(u32x4*)(Y + (size_t)token * 1024 + 16 * g + co) = w;
;                 }
;             }
;     }
	v_mul_f32_e32 v72, 0.5, v72
	v_add_f32_e32 v71, 1.0, v71
	v_mul_f32_e32 v71, v72, v71
	v_fma_f32 v72, -v76, v77, 1.0
	v_fmac_f32_e32 v77, v72, v77
	v_div_scale_f32 v72, vcc, 2.0, v75, 2.0
	v_mul_f32_e32 v78, v72, v77
	v_fma_f32 v79, -v76, v78, v72
	v_fmac_f32_e32 v78, v79, v77
	v_fma_f32 v72, -v76, v78, v72
	v_mul_f32_e32 v76, 0x3d372713, v66
	v_mul_f32_e32 v76, v66, v76
	v_fma_f32 v76, v66, v76, v66
	v_mul_f32_e32 v76, 0x3f4c422a, v76
	v_add_f32_e32 v76, v76, v76
	v_mul_f32_e32 v76, 0x3fb8aa3b, v76
	v_exp_f32_e32 v76, v76
	v_div_fmas_f32 v72, v72, v77, v78
	v_div_fixup_f32 v72, v72, v75, 2.0
	v_sub_f32_e32 v72, 1.0, v72
	v_add_f32_e32 v75, 1.0, v76
	v_div_scale_f32 v76, s[28:29], v75, v75, 2.0
	v_rcp_f32_e32 v77, v76
	v_mul_f32_e32 v73, 0.5, v73
	v_add_f32_e32 v72, 1.0, v72
	v_mul_f32_e32 v72, v73, v72
	v_cvt_pk_bf16_f32 v71, v71, v72
	v_fma_f32 v72, -v76, v77, 1.0
	v_fmac_f32_e32 v77, v72, v77
	v_div_scale_f32 v72, vcc, 2.0, v75, 2.0
	v_mul_f32_e32 v73, v72, v77
	v_fma_f32 v78, -v76, v73, v72
	v_fmac_f32_e32 v73, v78, v77
	v_fma_f32 v72, -v76, v73, v72
	v_mul_f32_e32 v76, 0x3d372713, v67
	v_mul_f32_e32 v76, v67, v76
	v_fma_f32 v76, v67, v76, v67
	v_mul_f32_e32 v76, 0x3f4c422a, v76
	v_add_f32_e32 v76, v76, v76
	v_mul_f32_e32 v76, 0x3fb8aa3b, v76
	v_exp_f32_e32 v76, v76
	v_div_fmas_f32 v72, v72, v77, v73
	v_div_fixup_f32 v72, v72, v75, 2.0
	v_sub_f32_e32 v72, 1.0, v72
	v_add_f32_e32 v73, 1.0, v76
	v_div_scale_f32 v75, s[28:29], v73, v73, 2.0
	v_rcp_f32_e32 v76, v75
	v_mul_f32_e32 v66, 0.5, v66
	v_add_f32_e32 v72, 1.0, v72
	v_mul_f32_e32 v66, v66, v72
	v_fma_f32 v72, -v75, v76, 1.0
	v_fmac_f32_e32 v76, v72, v76
	v_div_scale_f32 v72, vcc, 2.0, v73, 2.0
	v_mul_f32_e32 v77, v72, v76
	v_fma_f32 v78, -v75, v77, v72
	v_fmac_f32_e32 v77, v78, v76
	v_fma_f32 v72, -v75, v77, v72
	v_mul_f32_e32 v75, 0x3d372713, v68
	v_mul_f32_e32 v75, v68, v75
	v_fma_f32 v75, v68, v75, v68
	v_mul_f32_e32 v75, 0x3f4c422a, v75
	v_add_f32_e32 v75, v75, v75
	v_mul_f32_e32 v75, 0x3fb8aa3b, v75
	v_exp_f32_e32 v75, v75
	v_div_fmas_f32 v72, v72, v76, v77
	v_div_fixup_f32 v72, v72, v73, 2.0
	v_sub_f32_e32 v72, 1.0, v72
	v_add_f32_e32 v73, 1.0, v75
	v_div_scale_f32 v75, s[28:29], v73, v73, 2.0
	v_rcp_f32_e32 v76, v75
	v_mul_f32_e32 v67, 0.5, v67
	v_add_f32_e32 v72, 1.0, v72
	v_mul_f32_e32 v67, v67, v72
	v_cvt_pk_bf16_f32 v72, v66, v67
	v_fma_f32 v66, -v75, v76, 1.0
	v_fmac_f32_e32 v76, v66, v76
	v_div_scale_f32 v66, vcc, 2.0, v73, 2.0
	v_mul_f32_e32 v67, v66, v76
	v_fma_f32 v77, -v75, v67, v66
	v_fmac_f32_e32 v67, v77, v76
	v_fma_f32 v66, -v75, v67, v66
	v_mul_f32_e32 v75, 0x3d372713, v69
	v_mul_f32_e32 v75, v69, v75
	v_fma_f32 v75, v69, v75, v69
	v_mul_f32_e32 v75, 0x3f4c422a, v75
	v_add_f32_e32 v75, v75, v75
	v_mul_f32_e32 v75, 0x3fb8aa3b, v75
	v_exp_f32_e32 v75, v75
	v_div_fmas_f32 v66, v66, v76, v67
	v_div_fixup_f32 v66, v66, v73, 2.0
	v_sub_f32_e32 v66, 1.0, v66
	v_add_f32_e32 v67, 1.0, v75
	v_div_scale_f32 v73, s[28:29], v67, v67, 2.0
	v_rcp_f32_e32 v75, v73
	v_mul_f32_e32 v68, 0.5, v68
	v_add_f32_e32 v66, 1.0, v66
	v_mul_f32_e32 v66, v68, v66
	v_fma_f32 v68, -v73, v75, 1.0
	v_fmac_f32_e32 v75, v68, v75
	v_div_scale_f32 v68, vcc, 2.0, v67, 2.0
	v_mul_f32_e32 v76, v68, v75
	v_fma_f32 v77, -v73, v76, v68
	v_fmac_f32_e32 v76, v77, v75
	v_fma_f32 v68, -v73, v76, v68
	v_div_fmas_f32 v68, v68, v75, v76
	v_div_fixup_f32 v67, v68, v67, 2.0
	v_sub_f32_e32 v67, 1.0, v67
	v_mul_f32_e32 v68, 0.5, v69
	v_add_f32_e32 v67, 1.0, v67
	v_mul_f32_e32 v67, v68, v67
	v_mul_f32_e32 v68, 0x3d372713, v62
	v_mul_f32_e32 v68, v62, v68
	v_fma_f32 v68, v62, v68, v62
	v_mul_f32_e32 v68, 0x3f4c422a, v68
	v_add_f32_e32 v68, v68, v68
	v_mul_f32_e32 v68, 0x3fb8aa3b, v68
	v_exp_f32_e32 v68, v68
	v_or_b32_e32 v74, v124, v149
	v_ashrrev_i32_e32 v75, 31, v74
	v_cvt_pk_bf16_f32 v73, v66, v67
	v_add_f32_e32 v68, 1.0, v68
	v_div_scale_f32 v69, s[28:29], v68, v68, 2.0
	v_lshlrev_b64 v[66:67], 11, v[74:75]
	v_rcp_f32_e32 v74, v69
	v_lshl_add_u64 v[66:67], v[138:139], 0, v[66:67]
	global_store_dwordx4 v[66:67], v[70:73], off
	v_mul_f32_e32 v62, 0.5, v62
	v_fma_f32 v67, -v69, v74, 1.0
	v_fmac_f32_e32 v74, v67, v74
	v_div_scale_f32 v67, vcc, 2.0, v68, 2.0
	v_mul_f32_e32 v70, v67, v74
	v_fma_f32 v71, -v69, v70, v67
	v_fmac_f32_e32 v70, v71, v74
	v_fma_f32 v67, -v69, v70, v67
	v_mul_f32_e32 v69, 0x3d372713, v63
	v_mul_f32_e32 v69, v63, v69
	v_fma_f32 v69, v63, v69, v63
	v_mul_f32_e32 v69, 0x3f4c422a, v69
	v_add_f32_e32 v69, v69, v69
	v_mul_f32_e32 v69, 0x3fb8aa3b, v69
	v_exp_f32_e32 v69, v69
	v_div_fmas_f32 v67, v67, v74, v70
	v_div_fixup_f32 v67, v67, v68, 2.0
	v_sub_f32_e32 v67, 1.0, v67
	v_add_f32_e32 v68, 1.0, v69
	v_div_scale_f32 v69, s[28:29], v68, v68, 2.0
	v_rcp_f32_e32 v70, v69
	v_add_f32_e32 v67, 1.0, v67
	v_mul_f32_e32 v62, v62, v67
	v_mul_f32_e32 v63, 0.5, v63
	v_fma_f32 v67, -v69, v70, 1.0
	v_fmac_f32_e32 v70, v67, v70
	v_div_scale_f32 v67, vcc, 2.0, v68, 2.0
	v_mul_f32_e32 v71, v67, v70
	v_fma_f32 v72, -v69, v71, v67
	v_fmac_f32_e32 v71, v72, v70
	v_fma_f32 v67, -v69, v71, v67
	v_mul_f32_e32 v69, 0x3d372713, v64
	v_mul_f32_e32 v69, v64, v69
	v_fma_f32 v69, v64, v69, v64
	v_mul_f32_e32 v69, 0x3f4c422a, v69
	v_add_f32_e32 v69, v69, v69
	v_mul_f32_e32 v69, 0x3fb8aa3b, v69
	v_exp_f32_e32 v69, v69
	v_div_fmas_f32 v67, v67, v70, v71
	v_div_fixup_f32 v67, v67, v68, 2.0
	v_sub_f32_e32 v67, 1.0, v67
	v_add_f32_e32 v68, 1.0, v69
	v_div_scale_f32 v69, s[28:29], v68, v68, 2.0
	v_rcp_f32_e32 v70, v69
	v_add_f32_e32 v67, 1.0, v67
	v_mul_f32_e32 v63, v63, v67
	v_cvt_pk_bf16_f32 v62, v62, v63
	v_fma_f32 v63, -v69, v70, 1.0
	v_fmac_f32_e32 v70, v63, v70
	v_div_scale_f32 v63, vcc, 2.0, v68, 2.0
	v_mul_f32_e32 v67, v63, v70
; #define LAS __attribute__((address_space(3)))
; __device__ __forceinline__ unsigned cvt_pk_bf16(float lo, float hi) { unsigned r; asm volatile("v_cvt_pk_bf16_f32 %0, %1, %2" : "=v"(r) : "v"(lo), "v"(hi)); return r; }
; __device__ __forceinline__ float gelu_tanh(float x) { const float z = 0.7978845608f * (x + 0.044715f * x * x * x); const float th = 1.0f - 2.0f / (__expf(2.0f * z) + 1.0f); return 0.5f * x * (1.0f + th); }
;     __device__ __forceinline__ void operator()(const f32x4 (&acc)[2][2][4][2], const Unit& u, int ui, const LAS float* rtab, int wr, int wc, int fr, int fq) const {
;         const int g = u.pm; const int n0 = wr * 64 + fr; const int lc0 = (u.pn & 1) * 256 + wc * 32 + 8 * fq;
; #pragma unroll
;         for (int ai = 0; ai < 2; ++ai)
; #pragma unroll
;             for (int m = 0; m < 4; ++m) {
;                 const int n = n0 + ai * HALF + m * 16;
; #pragma unroll
;                 for (int bj = 0; bj < 2; ++bj) {
;                     const int lc = lc0 + bj * HALF, t = lc >> 4, co = lc & 15; const int token = n * 32 + t;
;                     const f32x4 a0 = acc[ai][bj][m][0], a1 = acc[ai][bj][m][1];
;                     u32x4 w; w.x = cvt_pk_bf16(gelu_tanh(a0[0]), gelu_tanh(a0[1])); w.y = cvt_pk_bf16(gelu_tanh(a0[2]), gelu_tanh(a0[3]));
;                     w.z = cvt_pk_bf16(gelu_tanh(a1[0]), gelu_tanh(a1[1])); w.w = cvt_pk_bf16(gelu_tanh(a1[2]), gelu_tanh(a1[3]));
;                     *(u32x4*)(Y + (size_t)token * 1024 + 16 * g + co) = w;
;                 }
;             }
;     }
	v_fma_f32 v71, -v69, v67, v63
	v_fmac_f32_e32 v67, v71, v70
	v_fma_f32 v63, -v69, v67, v63
	v_mul_f32_e32 v69, 0x3d372713, v65
	v_mul_f32_e32 v69, v65, v69
	v_fma_f32 v69, v65, v69, v65
	v_mul_f32_e32 v69, 0x3f4c422a, v69
	v_add_f32_e32 v69, v69, v69
	v_mul_f32_e32 v69, 0x3fb8aa3b, v69
	v_exp_f32_e32 v69, v69
	v_div_fmas_f32 v63, v63, v70, v67
	v_div_fixup_f32 v63, v63, v68, 2.0
	v_sub_f32_e32 v63, 1.0, v63
	v_add_f32_e32 v67, 1.0, v69
	v_div_scale_f32 v68, s[28:29], v67, v67, 2.0
	v_rcp_f32_e32 v69, v68
	v_mul_f32_e32 v64, 0.5, v64
	v_add_f32_e32 v63, 1.0, v63
	v_mul_f32_e32 v63, v64, v63
	v_fma_f32 v64, -v68, v69, 1.0
	v_fmac_f32_e32 v69, v64, v69
	v_div_scale_f32 v64, vcc, 2.0, v67, 2.0
	v_mul_f32_e32 v70, v64, v69
	v_fma_f32 v71, -v68, v70, v64
	v_fmac_f32_e32 v70, v71, v69
	v_fma_f32 v64, -v68, v70, v64
	v_mul_f32_e32 v68, 0x3d372713, v58
	v_mul_f32_e32 v68, v58, v68
	v_fma_f32 v68, v58, v68, v58
	v_mul_f32_e32 v68, 0x3f4c422a, v68
	v_add_f32_e32 v68, v68, v68
	v_mul_f32_e32 v68, 0x3fb8aa3b, v68
	v_exp_f32_e32 v68, v68
	v_div_fmas_f32 v64, v64, v69, v70
	v_div_fixup_f32 v64, v64, v67, 2.0
	v_sub_f32_e32 v64, 1.0, v64
	v_add_f32_e32 v67, 1.0, v68
	v_div_scale_f32 v68, s[28:29], v67, v67, 2.0
	v_rcp_f32_e32 v69, v68
	v_mul_f32_e32 v65, 0.5, v65
	v_add_f32_e32 v64, 1.0, v64
	v_mul_f32_e32 v64, v65, v64
	v_cvt_pk_bf16_f32 v63, v63, v64
	v_fma_f32 v64, -v68, v69, 1.0
	v_fmac_f32_e32 v69, v64, v69
	v_div_scale_f32 v64, vcc, 2.0, v67, 2.0
	v_mul_f32_e32 v65, v64, v69
	v_fma_f32 v70, -v68, v65, v64
	v_fmac_f32_e32 v65, v70, v69
	v_fma_f32 v64, -v68, v65, v64
	v_mul_f32_e32 v68, 0x3d372713, v59
	v_mul_f32_e32 v68, v59, v68
	v_fma_f32 v68, v59, v68, v59
	v_mul_f32_e32 v68, 0x3f4c422a, v68
	v_add_f32_e32 v68, v68, v68
	v_mul_f32_e32 v68, 0x3fb8aa3b, v68
	v_exp_f32_e32 v68, v68
	v_div_fmas_f32 v64, v64, v69, v65
	v_div_fixup_f32 v64, v64, v67, 2.0
	v_sub_f32_e32 v64, 1.0, v64
	v_add_f32_e32 v65, 1.0, v68
	v_div_scale_f32 v67, s[28:29], v65, v65, 2.0
	v_rcp_f32_e32 v68, v67
	v_mul_f32_e32 v58, 0.5, v58
	v_add_f32_e32 v64, 1.0, v64
	v_mul_f32_e32 v58, v58, v64
	v_fma_f32 v64, -v67, v68, 1.0
	v_fmac_f32_e32 v68, v64, v68
	v_div_scale_f32 v64, vcc, 2.0, v65, 2.0
	v_mul_f32_e32 v69, v64, v68
	v_fma_f32 v70, -v67, v69, v64
	v_fmac_f32_e32 v69, v70, v68
	v_fma_f32 v64, -v67, v69, v64
	v_mul_f32_e32 v67, 0x3d372713, v60
	v_mul_f32_e32 v67, v60, v67
	v_fma_f32 v67, v60, v67, v60
	v_mul_f32_e32 v67, 0x3f4c422a, v67
	v_add_f32_e32 v67, v67, v67
	v_mul_f32_e32 v67, 0x3fb8aa3b, v67
	v_exp_f32_e32 v67, v67
	v_div_fmas_f32 v64, v64, v68, v69
	v_div_fixup_f32 v64, v64, v65, 2.0
	v_sub_f32_e32 v64, 1.0, v64
	v_add_f32_e32 v65, 1.0, v67
	v_div_scale_f32 v67, s[28:29], v65, v65, 2.0
	v_rcp_f32_e32 v68, v67
	v_mul_f32_e32 v59, 0.5, v59
	v_add_f32_e32 v64, 1.0, v64
	v_mul_f32_e32 v59, v59, v64
	v_cvt_pk_bf16_f32 v64, v58, v59
	v_fma_f32 v58, -v67, v68, 1.0
	v_fmac_f32_e32 v68, v58, v68
	v_div_scale_f32 v58, vcc, 2.0, v65, 2.0
	v_mul_f32_e32 v59, v58, v68
	v_fma_f32 v69, -v67, v59, v58
	v_fmac_f32_e32 v59, v69, v68
	v_fma_f32 v58, -v67, v59, v58
	v_mul_f32_e32 v67, 0x3d372713, v61
	v_mul_f32_e32 v67, v61, v67
	v_fma_f32 v67, v61, v67, v61
	v_mul_f32_e32 v67, 0x3f4c422a, v67
	v_add_f32_e32 v67, v67, v67
	v_mul_f32_e32 v67, 0x3fb8aa3b, v67
	v_exp_f32_e32 v67, v67
	v_div_fmas_f32 v58, v58, v68, v59
	v_div_fixup_f32 v58, v58, v65, 2.0
	v_sub_f32_e32 v58, 1.0, v58
	v_add_f32_e32 v59, 1.0, v67
	v_div_scale_f32 v65, s[28:29], v59, v59, 2.0
	v_rcp_f32_e32 v67, v65
	v_mul_f32_e32 v60, 0.5, v60
	v_add_f32_e32 v58, 1.0, v58
	v_mul_f32_e32 v58, v60, v58
	v_fma_f32 v60, -v65, v67, 1.0
	v_fmac_f32_e32 v67, v60, v67
	v_div_scale_f32 v60, vcc, 2.0, v59, 2.0
	v_mul_f32_e32 v68, v60, v67
	v_fma_f32 v69, -v65, v68, v60
	v_fmac_f32_e32 v68, v69, v67
	v_fma_f32 v60, -v65, v68, v60
	v_div_fmas_f32 v60, v60, v67, v68
	v_div_fixup_f32 v59, v60, v59, 2.0
	v_sub_f32_e32 v59, 1.0, v59
	v_mul_f32_e32 v60, 0.5, v61
	v_add_f32_e32 v59, 1.0, v59
	v_mul_f32_e32 v59, v60, v59
	v_mul_f32_e32 v60, 0x3d372713, v54
	v_mul_f32_e32 v60, v54, v60
	v_fma_f32 v60, v54, v60, v54
	v_mul_f32_e32 v60, 0x3f4c422a, v60
	v_add_f32_e32 v60, v60, v60
	v_mul_f32_e32 v60, 0x3fb8aa3b, v60
	v_exp_f32_e32 v60, v60
	v_or_b32_e32 v66, v171, v150
	v_ashrrev_i32_e32 v67, 31, v66
	v_cvt_pk_bf16_f32 v65, v58, v59
	v_add_f32_e32 v60, 1.0, v60
	v_div_scale_f32 v61, s[28:29], v60, v60, 2.0
	v_lshlrev_b64 v[58:59], 11, v[66:67]
	v_rcp_f32_e32 v66, v61
	v_lshl_add_u64 v[58:59], v[138:139], 0, v[58:59]
	global_store_dwordx4 v[58:59], v[62:65], off
	v_mul_f32_e32 v54, 0.5, v54
	v_fma_f32 v59, -v61, v66, 1.0
	v_fmac_f32_e32 v66, v59, v66
	v_div_scale_f32 v59, vcc, 2.0, v60, 2.0
	v_mul_f32_e32 v62, v59, v66
	v_fma_f32 v63, -v61, v62, v59
	v_fmac_f32_e32 v62, v63, v66
	v_fma_f32 v59, -v61, v62, v59
	v_mul_f32_e32 v61, 0x3d372713, v55
	v_mul_f32_e32 v61, v55, v61
	v_fma_f32 v61, v55, v61, v55
	v_mul_f32_e32 v61, 0x3f4c422a, v61
	v_add_f32_e32 v61, v61, v61
	v_mul_f32_e32 v61, 0x3fb8aa3b, v61
	v_exp_f32_e32 v61, v61
	v_div_fmas_f32 v59, v59, v66, v62
	v_div_fixup_f32 v59, v59, v60, 2.0
	v_sub_f32_e32 v59, 1.0, v59
	v_add_f32_e32 v60, 1.0, v61
	v_div_scale_f32 v61, s[28:29], v60, v60, 2.0
	v_rcp_f32_e32 v62, v61
	v_add_f32_e32 v59, 1.0, v59
	v_mul_f32_e32 v54, v54, v59
	v_mul_f32_e32 v55, 0.5, v55
	v_fma_f32 v59, -v61, v62, 1.0
	v_fmac_f32_e32 v62, v59, v62
	v_div_scale_f32 v59, vcc, 2.0, v60, 2.0
	v_mul_f32_e32 v63, v59, v62
	v_fma_f32 v64, -v61, v63, v59
	v_fmac_f32_e32 v63, v64, v62
	v_fma_f32 v59, -v61, v63, v59
	v_mul_f32_e32 v61, 0x3d372713, v56
	v_mul_f32_e32 v61, v56, v61
	v_fma_f32 v61, v56, v61, v56
	v_mul_f32_e32 v61, 0x3f4c422a, v61
; #define LAS __attribute__((address_space(3)))
; __device__ __forceinline__ unsigned cvt_pk_bf16(float lo, float hi) { unsigned r; asm volatile("v_cvt_pk_bf16_f32 %0, %1, %2" : "=v"(r) : "v"(lo), "v"(hi)); return r; }
; __device__ __forceinline__ float gelu_tanh(float x) { const float z = 0.7978845608f * (x + 0.044715f * x * x * x); const float th = 1.0f - 2.0f / (__expf(2.0f * z) + 1.0f); return 0.5f * x * (1.0f + th); }
;     __device__ __forceinline__ void operator()(const f32x4 (&acc)[2][2][4][2], const Unit& u, int ui, const LAS float* rtab, int wr, int wc, int fr, int fq) const {
;         const int g = u.pm; const int n0 = wr * 64 + fr; const int lc0 = (u.pn & 1) * 256 + wc * 32 + 8 * fq;
; #pragma unroll
;         for (int ai = 0; ai < 2; ++ai)
; #pragma unroll
;             for (int m = 0; m < 4; ++m) {
;                 const int n = n0 + ai * HALF + m * 16;
; #pragma unroll
;                 for (int bj = 0; bj < 2; ++bj) {
;                     const int lc = lc0 + bj * HALF, t = lc >> 4, co = lc & 15; const int token = n * 32 + t;
;                     const f32x4 a0 = acc[ai][bj][m][0], a1 = acc[ai][bj][m][1];
;                     u32x4 w; w.x = cvt_pk_bf16(gelu_tanh(a0[0]), gelu_tanh(a0[1])); w.y = cvt_pk_bf16(gelu_tanh(a0[2]), gelu_tanh(a0[3]));
;                     w.z = cvt_pk_bf16(gelu_tanh(a1[0]), gelu_tanh(a1[1])); w.w = cvt_pk_bf16(gelu_tanh(a1[2]), gelu_tanh(a1[3]));
;                     *(u32x4*)(Y + (size_t)token * 1024 + 16 * g + co) = w;
;                 }
;             }
;     }
	v_add_f32_e32 v61, v61, v61
	v_mul_f32_e32 v61, 0x3fb8aa3b, v61
	v_exp_f32_e32 v61, v61
	v_div_fmas_f32 v59, v59, v62, v63
	v_div_fixup_f32 v59, v59, v60, 2.0
	v_sub_f32_e32 v59, 1.0, v59
	v_add_f32_e32 v60, 1.0, v61
	v_div_scale_f32 v61, s[28:29], v60, v60, 2.0
	v_rcp_f32_e32 v62, v61
	v_add_f32_e32 v59, 1.0, v59
	v_mul_f32_e32 v55, v55, v59
	v_cvt_pk_bf16_f32 v54, v54, v55
	v_fma_f32 v55, -v61, v62, 1.0
	v_fmac_f32_e32 v62, v55, v62
	v_div_scale_f32 v55, vcc, 2.0, v60, 2.0
	v_mul_f32_e32 v59, v55, v62
	v_fma_f32 v63, -v61, v59, v55
	v_fmac_f32_e32 v59, v63, v62
	v_fma_f32 v55, -v61, v59, v55
	v_mul_f32_e32 v61, 0x3d372713, v57
	v_mul_f32_e32 v61, v57, v61
	v_fma_f32 v61, v57, v61, v57
	v_mul_f32_e32 v61, 0x3f4c422a, v61
	v_add_f32_e32 v61, v61, v61
	v_mul_f32_e32 v61, 0x3fb8aa3b, v61
	v_exp_f32_e32 v61, v61
	v_div_fmas_f32 v55, v55, v62, v59
	v_div_fixup_f32 v55, v55, v60, 2.0
	v_sub_f32_e32 v55, 1.0, v55
	v_add_f32_e32 v59, 1.0, v61
	v_div_scale_f32 v60, s[28:29], v59, v59, 2.0
	v_rcp_f32_e32 v61, v60
	v_mul_f32_e32 v56, 0.5, v56
	v_add_f32_e32 v55, 1.0, v55
	v_mul_f32_e32 v55, v56, v55
	v_fma_f32 v56, -v60, v61, 1.0
	v_fmac_f32_e32 v61, v56, v61
	v_div_scale_f32 v56, vcc, 2.0, v59, 2.0
	v_mul_f32_e32 v62, v56, v61
	v_fma_f32 v63, -v60, v62, v56
	v_fmac_f32_e32 v62, v63, v61
	v_fma_f32 v56, -v60, v62, v56
	v_mul_f32_e32 v60, 0x3d372713, v50
	v_mul_f32_e32 v60, v50, v60
	v_fma_f32 v60, v50, v60, v50
	v_mul_f32_e32 v60, 0x3f4c422a, v60
	v_add_f32_e32 v60, v60, v60
	v_mul_f32_e32 v60, 0x3fb8aa3b, v60
	v_exp_f32_e32 v60, v60
	v_div_fmas_f32 v56, v56, v61, v62
	v_div_fixup_f32 v56, v56, v59, 2.0
	v_sub_f32_e32 v56, 1.0, v56
	v_add_f32_e32 v59, 1.0, v60
	v_div_scale_f32 v60, s[28:29], v59, v59, 2.0
	v_rcp_f32_e32 v61, v60
	v_mul_f32_e32 v57, 0.5, v57
	v_add_f32_e32 v56, 1.0, v56
	v_mul_f32_e32 v56, v57, v56
	v_cvt_pk_bf16_f32 v55, v55, v56
	v_fma_f32 v56, -v60, v61, 1.0
	v_fmac_f32_e32 v61, v56, v61
	v_div_scale_f32 v56, vcc, 2.0, v59, 2.0
	v_mul_f32_e32 v57, v56, v61
	v_fma_f32 v62, -v60, v57, v56
	v_fmac_f32_e32 v57, v62, v61
	v_fma_f32 v56, -v60, v57, v56
	v_mul_f32_e32 v60, 0x3d372713, v51
	v_mul_f32_e32 v60, v51, v60
	v_fma_f32 v60, v51, v60, v51
	v_mul_f32_e32 v60, 0x3f4c422a, v60
	v_add_f32_e32 v60, v60, v60
	v_mul_f32_e32 v60, 0x3fb8aa3b, v60
	v_exp_f32_e32 v60, v60
	v_div_fmas_f32 v56, v56, v61, v57
	v_div_fixup_f32 v56, v56, v59, 2.0
	v_sub_f32_e32 v56, 1.0, v56
	v_add_f32_e32 v57, 1.0, v60
	v_div_scale_f32 v59, s[28:29], v57, v57, 2.0
	v_rcp_f32_e32 v60, v59
	v_mul_f32_e32 v50, 0.5, v50
	v_add_f32_e32 v56, 1.0, v56
	v_mul_f32_e32 v50, v50, v56
	v_fma_f32 v56, -v59, v60, 1.0
	v_fmac_f32_e32 v60, v56, v60
	v_div_scale_f32 v56, vcc, 2.0, v57, 2.0
	v_mul_f32_e32 v61, v56, v60
	v_fma_f32 v62, -v59, v61, v56
	v_fmac_f32_e32 v61, v62, v60
	v_fma_f32 v56, -v59, v61, v56
	v_mul_f32_e32 v59, 0x3d372713, v52
	v_mul_f32_e32 v59, v52, v59
	v_fma_f32 v59, v52, v59, v52
	v_mul_f32_e32 v59, 0x3f4c422a, v59
	v_add_f32_e32 v59, v59, v59
	v_mul_f32_e32 v59, 0x3fb8aa3b, v59
	v_exp_f32_e32 v59, v59
	v_div_fmas_f32 v56, v56, v60, v61
	v_div_fixup_f32 v56, v56, v57, 2.0
	v_sub_f32_e32 v56, 1.0, v56
	v_add_f32_e32 v57, 1.0, v59
	v_div_scale_f32 v59, s[28:29], v57, v57, 2.0
	v_rcp_f32_e32 v60, v59
	v_mul_f32_e32 v51, 0.5, v51
	v_add_f32_e32 v56, 1.0, v56
	v_mul_f32_e32 v51, v51, v56
	v_cvt_pk_bf16_f32 v56, v50, v51
	v_fma_f32 v50, -v59, v60, 1.0
	v_fmac_f32_e32 v60, v50, v60
	v_div_scale_f32 v50, vcc, 2.0, v57, 2.0
	v_mul_f32_e32 v51, v50, v60
	v_fma_f32 v61, -v59, v51, v50
	v_fmac_f32_e32 v51, v61, v60
	v_fma_f32 v50, -v59, v51, v50
	v_mul_f32_e32 v59, 0x3d372713, v53
	v_mul_f32_e32 v59, v53, v59
	v_fma_f32 v59, v53, v59, v53
	v_mul_f32_e32 v59, 0x3f4c422a, v59
	v_add_f32_e32 v59, v59, v59
	v_mul_f32_e32 v59, 0x3fb8aa3b, v59
	v_exp_f32_e32 v59, v59
	v_div_fmas_f32 v50, v50, v60, v51
	v_div_fixup_f32 v50, v50, v57, 2.0
	v_sub_f32_e32 v50, 1.0, v50
	v_add_f32_e32 v51, 1.0, v59
	v_div_scale_f32 v57, s[28:29], v51, v51, 2.0
	v_rcp_f32_e32 v59, v57
	v_mul_f32_e32 v52, 0.5, v52
	v_add_f32_e32 v50, 1.0, v50
	v_mul_f32_e32 v50, v52, v50
	v_fma_f32 v52, -v57, v59, 1.0
	v_fmac_f32_e32 v59, v52, v59
	v_div_scale_f32 v52, vcc, 2.0, v51, 2.0
	v_mul_f32_e32 v60, v52, v59
	v_fma_f32 v61, -v57, v60, v52
	v_fmac_f32_e32 v60, v61, v59
	v_fma_f32 v52, -v57, v60, v52
	v_div_fmas_f32 v52, v52, v59, v60
	v_div_fixup_f32 v51, v52, v51, 2.0
	v_sub_f32_e32 v51, 1.0, v51
	v_mul_f32_e32 v52, 0.5, v53
	v_add_f32_e32 v51, 1.0, v51
	v_mul_f32_e32 v51, v52, v51
	v_mul_f32_e32 v52, 0x3d372713, v46
	v_mul_f32_e32 v52, v46, v52
	v_fma_f32 v52, v46, v52, v46
	v_mul_f32_e32 v52, 0x3f4c422a, v52
	v_add_f32_e32 v52, v52, v52
	v_mul_f32_e32 v52, 0x3fb8aa3b, v52
	v_exp_f32_e32 v52, v52
	v_or_b32_e32 v58, v124, v150
	v_ashrrev_i32_e32 v59, 31, v58
	v_cvt_pk_bf16_f32 v57, v50, v51
	v_add_f32_e32 v52, 1.0, v52
	v_div_scale_f32 v53, s[28:29], v52, v52, 2.0
	v_lshlrev_b64 v[50:51], 11, v[58:59]
	v_rcp_f32_e32 v58, v53
	v_lshl_add_u64 v[50:51], v[138:139], 0, v[50:51]
	global_store_dwordx4 v[50:51], v[54:57], off
	v_mul_f32_e32 v46, 0.5, v46
	v_fma_f32 v51, -v53, v58, 1.0
	v_fmac_f32_e32 v58, v51, v58
	v_div_scale_f32 v51, vcc, 2.0, v52, 2.0
	v_mul_f32_e32 v54, v51, v58
	v_fma_f32 v55, -v53, v54, v51
	v_fmac_f32_e32 v54, v55, v58
	v_fma_f32 v51, -v53, v54, v51
	v_mul_f32_e32 v53, 0x3d372713, v47
	v_mul_f32_e32 v53, v47, v53
	v_fma_f32 v53, v47, v53, v47
	v_mul_f32_e32 v53, 0x3f4c422a, v53
	v_add_f32_e32 v53, v53, v53
	v_mul_f32_e32 v53, 0x3fb8aa3b, v53
	v_exp_f32_e32 v53, v53
	v_div_fmas_f32 v51, v51, v58, v54
	v_div_fixup_f32 v51, v51, v52, 2.0
	v_sub_f32_e32 v51, 1.0, v51
	v_add_f32_e32 v52, 1.0, v53
; #define LAS __attribute__((address_space(3)))
; __device__ __forceinline__ unsigned cvt_pk_bf16(float lo, float hi) { unsigned r; asm volatile("v_cvt_pk_bf16_f32 %0, %1, %2" : "=v"(r) : "v"(lo), "v"(hi)); return r; }
; __device__ __forceinline__ float gelu_tanh(float x) { const float z = 0.7978845608f * (x + 0.044715f * x * x * x); const float th = 1.0f - 2.0f / (__expf(2.0f * z) + 1.0f); return 0.5f * x * (1.0f + th); }
;     __device__ __forceinline__ void operator()(const f32x4 (&acc)[2][2][4][2], const Unit& u, int ui, const LAS float* rtab, int wr, int wc, int fr, int fq) const {
;         const int g = u.pm; const int n0 = wr * 64 + fr; const int lc0 = (u.pn & 1) * 256 + wc * 32 + 8 * fq;
; #pragma unroll
;         for (int ai = 0; ai < 2; ++ai)
; #pragma unroll
;             for (int m = 0; m < 4; ++m) {
;                 const int n = n0 + ai * HALF + m * 16;
; #pragma unroll
;                 for (int bj = 0; bj < 2; ++bj) {
;                     const int lc = lc0 + bj * HALF, t = lc >> 4, co = lc & 15; const int token = n * 32 + t;
;                     const f32x4 a0 = acc[ai][bj][m][0], a1 = acc[ai][bj][m][1];
;                     u32x4 w; w.x = cvt_pk_bf16(gelu_tanh(a0[0]), gelu_tanh(a0[1])); w.y = cvt_pk_bf16(gelu_tanh(a0[2]), gelu_tanh(a0[3]));
;                     w.z = cvt_pk_bf16(gelu_tanh(a1[0]), gelu_tanh(a1[1])); w.w = cvt_pk_bf16(gelu_tanh(a1[2]), gelu_tanh(a1[3]));
;                     *(u32x4*)(Y + (size_t)token * 1024 + 16 * g + co) = w;
;                 }
;             }
;     }
	v_div_scale_f32 v53, s[28:29], v52, v52, 2.0
	v_rcp_f32_e32 v54, v53
	v_add_f32_e32 v51, 1.0, v51
	v_mul_f32_e32 v46, v46, v51
	v_mul_f32_e32 v47, 0.5, v47
	v_fma_f32 v51, -v53, v54, 1.0
	v_fmac_f32_e32 v54, v51, v54
	v_div_scale_f32 v51, vcc, 2.0, v52, 2.0
	v_mul_f32_e32 v55, v51, v54
	v_fma_f32 v56, -v53, v55, v51
	v_fmac_f32_e32 v55, v56, v54
	v_fma_f32 v51, -v53, v55, v51
	v_mul_f32_e32 v53, 0x3d372713, v48
	v_mul_f32_e32 v53, v48, v53
	v_fma_f32 v53, v48, v53, v48
	v_mul_f32_e32 v53, 0x3f4c422a, v53
	v_add_f32_e32 v53, v53, v53
	v_mul_f32_e32 v53, 0x3fb8aa3b, v53
	v_exp_f32_e32 v53, v53
	v_div_fmas_f32 v51, v51, v54, v55
	v_div_fixup_f32 v51, v51, v52, 2.0
	v_sub_f32_e32 v51, 1.0, v51
	v_add_f32_e32 v52, 1.0, v53
	v_div_scale_f32 v53, s[28:29], v52, v52, 2.0
	v_rcp_f32_e32 v54, v53
	v_add_f32_e32 v51, 1.0, v51
	v_mul_f32_e32 v47, v47, v51
	v_cvt_pk_bf16_f32 v46, v46, v47
	v_fma_f32 v47, -v53, v54, 1.0
	v_fmac_f32_e32 v54, v47, v54
	v_div_scale_f32 v47, vcc, 2.0, v52, 2.0
	v_mul_f32_e32 v51, v47, v54
	v_fma_f32 v55, -v53, v51, v47
	v_fmac_f32_e32 v51, v55, v54
	v_fma_f32 v47, -v53, v51, v47
	v_mul_f32_e32 v53, 0x3d372713, v49
	v_mul_f32_e32 v53, v49, v53
	v_fma_f32 v53, v49, v53, v49
	v_mul_f32_e32 v53, 0x3f4c422a, v53
	v_add_f32_e32 v53, v53, v53
	v_mul_f32_e32 v53, 0x3fb8aa3b, v53
	v_exp_f32_e32 v53, v53
	v_div_fmas_f32 v47, v47, v54, v51
	v_div_fixup_f32 v47, v47, v52, 2.0
	v_sub_f32_e32 v47, 1.0, v47
	v_add_f32_e32 v51, 1.0, v53
	v_div_scale_f32 v52, s[28:29], v51, v51, 2.0
	v_rcp_f32_e32 v53, v52
	v_mul_f32_e32 v48, 0.5, v48
	v_add_f32_e32 v47, 1.0, v47
	v_mul_f32_e32 v47, v48, v47
	v_fma_f32 v48, -v52, v53, 1.0
	v_fmac_f32_e32 v53, v48, v53
	v_div_scale_f32 v48, vcc, 2.0, v51, 2.0
	v_mul_f32_e32 v54, v48, v53
	v_fma_f32 v55, -v52, v54, v48
	v_fmac_f32_e32 v54, v55, v53
	v_fma_f32 v48, -v52, v54, v48
	v_mul_f32_e32 v52, 0x3d372713, v42
	v_mul_f32_e32 v52, v42, v52
	v_fma_f32 v52, v42, v52, v42
	v_mul_f32_e32 v52, 0x3f4c422a, v52
	v_add_f32_e32 v52, v52, v52
	v_mul_f32_e32 v52, 0x3fb8aa3b, v52
	v_exp_f32_e32 v52, v52
	v_div_fmas_f32 v48, v48, v53, v54
	v_div_fixup_f32 v48, v48, v51, 2.0
	v_sub_f32_e32 v48, 1.0, v48
	v_add_f32_e32 v51, 1.0, v52
	v_div_scale_f32 v52, s[28:29], v51, v51, 2.0
	v_rcp_f32_e32 v53, v52
	v_mul_f32_e32 v49, 0.5, v49
	v_add_f32_e32 v48, 1.0, v48
	v_mul_f32_e32 v48, v49, v48
	v_cvt_pk_bf16_f32 v47, v47, v48
	v_fma_f32 v48, -v52, v53, 1.0
	v_fmac_f32_e32 v53, v48, v53
	v_div_scale_f32 v48, vcc, 2.0, v51, 2.0
	v_mul_f32_e32 v49, v48, v53
	v_fma_f32 v54, -v52, v49, v48
	v_fmac_f32_e32 v49, v54, v53
	v_fma_f32 v48, -v52, v49, v48
	v_mul_f32_e32 v52, 0x3d372713, v43
	v_mul_f32_e32 v52, v43, v52
	v_fma_f32 v52, v43, v52, v43
	v_mul_f32_e32 v52, 0x3f4c422a, v52
	v_add_f32_e32 v52, v52, v52
	v_mul_f32_e32 v52, 0x3fb8aa3b, v52
	v_exp_f32_e32 v52, v52
	v_div_fmas_f32 v48, v48, v53, v49
	v_div_fixup_f32 v48, v48, v51, 2.0
	v_sub_f32_e32 v48, 1.0, v48
	v_add_f32_e32 v49, 1.0, v52
	v_div_scale_f32 v51, s[28:29], v49, v49, 2.0
	v_rcp_f32_e32 v52, v51
	v_mul_f32_e32 v42, 0.5, v42
	v_add_f32_e32 v48, 1.0, v48
	v_mul_f32_e32 v42, v42, v48
	v_fma_f32 v48, -v51, v52, 1.0
	v_fmac_f32_e32 v52, v48, v52
	v_div_scale_f32 v48, vcc, 2.0, v49, 2.0
	v_mul_f32_e32 v53, v48, v52
	v_fma_f32 v54, -v51, v53, v48
	v_fmac_f32_e32 v53, v54, v52
	v_fma_f32 v48, -v51, v53, v48
	v_mul_f32_e32 v51, 0x3d372713, v44
	v_mul_f32_e32 v51, v44, v51
	v_fma_f32 v51, v44, v51, v44
	v_mul_f32_e32 v51, 0x3f4c422a, v51
	v_add_f32_e32 v51, v51, v51
	v_mul_f32_e32 v51, 0x3fb8aa3b, v51
	v_exp_f32_e32 v51, v51
	v_div_fmas_f32 v48, v48, v52, v53
	v_div_fixup_f32 v48, v48, v49, 2.0
	v_sub_f32_e32 v48, 1.0, v48
	v_add_f32_e32 v49, 1.0, v51
	v_div_scale_f32 v51, s[28:29], v49, v49, 2.0
	v_rcp_f32_e32 v52, v51
	v_mul_f32_e32 v43, 0.5, v43
	v_add_f32_e32 v48, 1.0, v48
	v_mul_f32_e32 v43, v43, v48
	v_cvt_pk_bf16_f32 v48, v42, v43
	v_fma_f32 v42, -v51, v52, 1.0
	v_fmac_f32_e32 v52, v42, v52
	v_div_scale_f32 v42, vcc, 2.0, v49, 2.0
	v_mul_f32_e32 v43, v42, v52
	v_fma_f32 v53, -v51, v43, v42
	v_fmac_f32_e32 v43, v53, v52
	v_fma_f32 v42, -v51, v43, v42
	v_mul_f32_e32 v51, 0x3d372713, v45
	v_mul_f32_e32 v51, v45, v51
	v_fma_f32 v51, v45, v51, v45
	v_mul_f32_e32 v51, 0x3f4c422a, v51
	v_add_f32_e32 v51, v51, v51
	v_mul_f32_e32 v51, 0x3fb8aa3b, v51
	v_exp_f32_e32 v51, v51
	v_div_fmas_f32 v42, v42, v52, v43
	v_div_fixup_f32 v42, v42, v49, 2.0
	v_sub_f32_e32 v42, 1.0, v42
	v_add_f32_e32 v43, 1.0, v51
	v_div_scale_f32 v49, s[28:29], v43, v43, 2.0
	v_rcp_f32_e32 v51, v49
	v_mul_f32_e32 v44, 0.5, v44
	v_add_f32_e32 v42, 1.0, v42
	v_mul_f32_e32 v42, v44, v42
	v_fma_f32 v44, -v49, v51, 1.0
	v_fmac_f32_e32 v51, v44, v51
	v_div_scale_f32 v44, vcc, 2.0, v43, 2.0
	v_mul_f32_e32 v52, v44, v51
	v_fma_f32 v53, -v49, v52, v44
	v_fmac_f32_e32 v52, v53, v51
	v_fma_f32 v44, -v49, v52, v44
	v_div_fmas_f32 v44, v44, v51, v52
	v_div_fixup_f32 v43, v44, v43, 2.0
	v_sub_f32_e32 v43, 1.0, v43
	v_mul_f32_e32 v44, 0.5, v45
	v_add_f32_e32 v43, 1.0, v43
	v_mul_f32_e32 v43, v44, v43
	v_mul_f32_e32 v44, 0x3d372713, v38
	v_mul_f32_e32 v44, v38, v44
	v_fma_f32 v44, v38, v44, v38
	v_mul_f32_e32 v44, 0x3f4c422a, v44
	v_add_f32_e32 v44, v44, v44
	v_mul_f32_e32 v44, 0x3fb8aa3b, v44
	v_exp_f32_e32 v44, v44
	v_or_b32_e32 v50, v171, v151
	v_ashrrev_i32_e32 v51, 31, v50
	v_cvt_pk_bf16_f32 v49, v42, v43
	v_add_f32_e32 v44, 1.0, v44
	v_div_scale_f32 v45, s[28:29], v44, v44, 2.0
	v_lshlrev_b64 v[42:43], 11, v[50:51]
	v_rcp_f32_e32 v50, v45
	v_lshl_add_u64 v[42:43], v[138:139], 0, v[42:43]
	global_store_dwordx4 v[42:43], v[46:49], off
	v_mul_f32_e32 v38, 0.5, v38
	v_fma_f32 v43, -v45, v50, 1.0
	v_fmac_f32_e32 v50, v43, v50
; #define LAS __attribute__((address_space(3)))
; __device__ __forceinline__ unsigned cvt_pk_bf16(float lo, float hi) { unsigned r; asm volatile("v_cvt_pk_bf16_f32 %0, %1, %2" : "=v"(r) : "v"(lo), "v"(hi)); return r; }
; __device__ __forceinline__ float gelu_tanh(float x) { const float z = 0.7978845608f * (x + 0.044715f * x * x * x); const float th = 1.0f - 2.0f / (__expf(2.0f * z) + 1.0f); return 0.5f * x * (1.0f + th); }
;     __device__ __forceinline__ void operator()(const f32x4 (&acc)[2][2][4][2], const Unit& u, int ui, const LAS float* rtab, int wr, int wc, int fr, int fq) const {
;         const int g = u.pm; const int n0 = wr * 64 + fr; const int lc0 = (u.pn & 1) * 256 + wc * 32 + 8 * fq;
; #pragma unroll
;         for (int ai = 0; ai < 2; ++ai)
; #pragma unroll
;             for (int m = 0; m < 4; ++m) {
;                 const int n = n0 + ai * HALF + m * 16;
; #pragma unroll
;                 for (int bj = 0; bj < 2; ++bj) {
;                     const int lc = lc0 + bj * HALF, t = lc >> 4, co = lc & 15; const int token = n * 32 + t;
;                     const f32x4 a0 = acc[ai][bj][m][0], a1 = acc[ai][bj][m][1];
;                     u32x4 w; w.x = cvt_pk_bf16(gelu_tanh(a0[0]), gelu_tanh(a0[1])); w.y = cvt_pk_bf16(gelu_tanh(a0[2]), gelu_tanh(a0[3]));
;                     w.z = cvt_pk_bf16(gelu_tanh(a1[0]), gelu_tanh(a1[1])); w.w = cvt_pk_bf16(gelu_tanh(a1[2]), gelu_tanh(a1[3]));
;                     *(u32x4*)(Y + (size_t)token * 1024 + 16 * g + co) = w;
;                 }
;             }
;     }
	v_div_scale_f32 v43, vcc, 2.0, v44, 2.0
	v_mul_f32_e32 v46, v43, v50
	v_fma_f32 v47, -v45, v46, v43
	v_fmac_f32_e32 v46, v47, v50
	v_fma_f32 v43, -v45, v46, v43
	v_mul_f32_e32 v45, 0x3d372713, v39
	v_mul_f32_e32 v45, v39, v45
	v_fma_f32 v45, v39, v45, v39
	v_mul_f32_e32 v45, 0x3f4c422a, v45
	v_add_f32_e32 v45, v45, v45
	v_mul_f32_e32 v45, 0x3fb8aa3b, v45
	v_exp_f32_e32 v45, v45
	v_div_fmas_f32 v43, v43, v50, v46
	v_div_fixup_f32 v43, v43, v44, 2.0
	v_sub_f32_e32 v43, 1.0, v43
	v_add_f32_e32 v44, 1.0, v45
	v_div_scale_f32 v45, s[28:29], v44, v44, 2.0
	v_rcp_f32_e32 v46, v45
	v_add_f32_e32 v43, 1.0, v43
	v_mul_f32_e32 v38, v38, v43
	v_mul_f32_e32 v39, 0.5, v39
	v_fma_f32 v43, -v45, v46, 1.0
	v_fmac_f32_e32 v46, v43, v46
	v_div_scale_f32 v43, vcc, 2.0, v44, 2.0
	v_mul_f32_e32 v47, v43, v46
	v_fma_f32 v48, -v45, v47, v43
	v_fmac_f32_e32 v47, v48, v46
	v_fma_f32 v43, -v45, v47, v43
	v_mul_f32_e32 v45, 0x3d372713, v40
	v_mul_f32_e32 v45, v40, v45
	v_fma_f32 v45, v40, v45, v40
	v_mul_f32_e32 v45, 0x3f4c422a, v45
	v_add_f32_e32 v45, v45, v45
	v_mul_f32_e32 v45, 0x3fb8aa3b, v45
	v_exp_f32_e32 v45, v45
	v_div_fmas_f32 v43, v43, v46, v47
	v_div_fixup_f32 v43, v43, v44, 2.0
	v_sub_f32_e32 v43, 1.0, v43
	v_add_f32_e32 v44, 1.0, v45
	v_div_scale_f32 v45, s[28:29], v44, v44, 2.0
	v_rcp_f32_e32 v46, v45
	v_add_f32_e32 v43, 1.0, v43
	v_mul_f32_e32 v39, v39, v43
	v_cvt_pk_bf16_f32 v38, v38, v39
	v_fma_f32 v39, -v45, v46, 1.0
	v_fmac_f32_e32 v46, v39, v46
	v_div_scale_f32 v39, vcc, 2.0, v44, 2.0
	v_mul_f32_e32 v43, v39, v46
	v_fma_f32 v47, -v45, v43, v39
	v_fmac_f32_e32 v43, v47, v46
	v_fma_f32 v39, -v45, v43, v39
	v_mul_f32_e32 v45, 0x3d372713, v41
	v_mul_f32_e32 v45, v41, v45
	v_fma_f32 v45, v41, v45, v41
	v_mul_f32_e32 v45, 0x3f4c422a, v45
	v_add_f32_e32 v45, v45, v45
	v_mul_f32_e32 v45, 0x3fb8aa3b, v45
	v_exp_f32_e32 v45, v45
	v_div_fmas_f32 v39, v39, v46, v43
	v_div_fixup_f32 v39, v39, v44, 2.0
	v_sub_f32_e32 v39, 1.0, v39
	v_add_f32_e32 v43, 1.0, v45
	v_div_scale_f32 v44, s[28:29], v43, v43, 2.0
	v_rcp_f32_e32 v45, v44
	v_mul_f32_e32 v40, 0.5, v40
	v_add_f32_e32 v39, 1.0, v39
	v_mul_f32_e32 v39, v40, v39
	v_fma_f32 v40, -v44, v45, 1.0
	v_fmac_f32_e32 v45, v40, v45
	v_div_scale_f32 v40, vcc, 2.0, v43, 2.0
	v_mul_f32_e32 v46, v40, v45
	v_fma_f32 v47, -v44, v46, v40
	v_fmac_f32_e32 v46, v47, v45
	v_fma_f32 v40, -v44, v46, v40
	v_mul_f32_e32 v44, 0x3d372713, v34
	v_mul_f32_e32 v44, v34, v44
	v_fma_f32 v44, v34, v44, v34
	v_mul_f32_e32 v44, 0x3f4c422a, v44
	v_add_f32_e32 v44, v44, v44
	v_mul_f32_e32 v44, 0x3fb8aa3b, v44
	v_exp_f32_e32 v44, v44
	v_div_fmas_f32 v40, v40, v45, v46
	v_div_fixup_f32 v40, v40, v43, 2.0
	v_sub_f32_e32 v40, 1.0, v40
	v_add_f32_e32 v43, 1.0, v44
	v_div_scale_f32 v44, s[28:29], v43, v43, 2.0
	v_rcp_f32_e32 v45, v44
	v_mul_f32_e32 v41, 0.5, v41
	v_add_f32_e32 v40, 1.0, v40
	v_mul_f32_e32 v40, v41, v40
	v_cvt_pk_bf16_f32 v39, v39, v40
	v_fma_f32 v40, -v44, v45, 1.0
	v_fmac_f32_e32 v45, v40, v45
	v_div_scale_f32 v40, vcc, 2.0, v43, 2.0
	v_mul_f32_e32 v41, v40, v45
	v_fma_f32 v46, -v44, v41, v40
	v_fmac_f32_e32 v41, v46, v45
	v_fma_f32 v40, -v44, v41, v40
	v_mul_f32_e32 v44, 0x3d372713, v35
	v_mul_f32_e32 v44, v35, v44
	v_fma_f32 v44, v35, v44, v35
	v_mul_f32_e32 v44, 0x3f4c422a, v44
	v_add_f32_e32 v44, v44, v44
	v_mul_f32_e32 v44, 0x3fb8aa3b, v44
	v_exp_f32_e32 v44, v44
	v_div_fmas_f32 v40, v40, v45, v41
	v_div_fixup_f32 v40, v40, v43, 2.0
	v_sub_f32_e32 v40, 1.0, v40
	v_add_f32_e32 v41, 1.0, v44
	v_div_scale_f32 v43, s[28:29], v41, v41, 2.0
	v_rcp_f32_e32 v44, v43
	v_mul_f32_e32 v34, 0.5, v34
	v_add_f32_e32 v40, 1.0, v40
	v_mul_f32_e32 v34, v34, v40
	v_fma_f32 v40, -v43, v44, 1.0
	v_fmac_f32_e32 v44, v40, v44
	v_div_scale_f32 v40, vcc, 2.0, v41, 2.0
	v_mul_f32_e32 v45, v40, v44
	v_fma_f32 v46, -v43, v45, v40
	v_fmac_f32_e32 v45, v46, v44
	v_fma_f32 v40, -v43, v45, v40
	v_mul_f32_e32 v43, 0x3d372713, v36
	v_mul_f32_e32 v43, v36, v43
	v_fma_f32 v43, v36, v43, v36
	v_mul_f32_e32 v43, 0x3f4c422a, v43
	v_add_f32_e32 v43, v43, v43
	v_mul_f32_e32 v43, 0x3fb8aa3b, v43
	v_exp_f32_e32 v43, v43
	v_div_fmas_f32 v40, v40, v44, v45
	v_div_fixup_f32 v40, v40, v41, 2.0
	v_sub_f32_e32 v40, 1.0, v40
	v_add_f32_e32 v41, 1.0, v43
	v_div_scale_f32 v43, s[28:29], v41, v41, 2.0
	v_rcp_f32_e32 v44, v43
	v_mul_f32_e32 v35, 0.5, v35
	v_add_f32_e32 v40, 1.0, v40
	v_mul_f32_e32 v35, v35, v40
	v_cvt_pk_bf16_f32 v40, v34, v35
	v_fma_f32 v34, -v43, v44, 1.0
	v_fmac_f32_e32 v44, v34, v44
	v_div_scale_f32 v34, vcc, 2.0, v41, 2.0
	v_mul_f32_e32 v35, v34, v44
	v_fma_f32 v45, -v43, v35, v34
	v_fmac_f32_e32 v35, v45, v44
	v_fma_f32 v34, -v43, v35, v34
	v_mul_f32_e32 v43, 0x3d372713, v37
	v_mul_f32_e32 v43, v37, v43
	v_fma_f32 v43, v37, v43, v37
	v_mul_f32_e32 v43, 0x3f4c422a, v43
	v_add_f32_e32 v43, v43, v43
	v_mul_f32_e32 v43, 0x3fb8aa3b, v43
	v_exp_f32_e32 v43, v43
	v_div_fmas_f32 v34, v34, v44, v35
	v_div_fixup_f32 v34, v34, v41, 2.0
	v_sub_f32_e32 v34, 1.0, v34
	v_add_f32_e32 v35, 1.0, v43
	v_div_scale_f32 v41, s[28:29], v35, v35, 2.0
	v_rcp_f32_e32 v43, v41
	v_mul_f32_e32 v36, 0.5, v36
	v_add_f32_e32 v34, 1.0, v34
	v_mul_f32_e32 v34, v36, v34
	v_fma_f32 v36, -v41, v43, 1.0
	v_fmac_f32_e32 v43, v36, v43
	v_div_scale_f32 v36, vcc, 2.0, v35, 2.0
	v_mul_f32_e32 v44, v36, v43
	v_fma_f32 v45, -v41, v44, v36
	v_fmac_f32_e32 v44, v45, v43
	v_fma_f32 v36, -v41, v44, v36
	v_div_fmas_f32 v36, v36, v43, v44
	v_div_fixup_f32 v35, v36, v35, 2.0
	v_sub_f32_e32 v35, 1.0, v35
	v_mul_f32_e32 v36, 0.5, v37
	v_add_f32_e32 v35, 1.0, v35
	v_mul_f32_e32 v35, v36, v35
	v_mul_f32_e32 v36, 0x3d372713, v30
	v_mul_f32_e32 v36, v30, v36
	v_fma_f32 v36, v30, v36, v30
	v_mul_f32_e32 v36, 0x3f4c422a, v36
; #define LAS __attribute__((address_space(3)))
; __device__ __forceinline__ unsigned cvt_pk_bf16(float lo, float hi) { unsigned r; asm volatile("v_cvt_pk_bf16_f32 %0, %1, %2" : "=v"(r) : "v"(lo), "v"(hi)); return r; }
; __device__ __forceinline__ float gelu_tanh(float x) { const float z = 0.7978845608f * (x + 0.044715f * x * x * x); const float th = 1.0f - 2.0f / (__expf(2.0f * z) + 1.0f); return 0.5f * x * (1.0f + th); }
;     __device__ __forceinline__ void operator()(const f32x4 (&acc)[2][2][4][2], const Unit& u, int ui, const LAS float* rtab, int wr, int wc, int fr, int fq) const {
;         const int g = u.pm; const int n0 = wr * 64 + fr; const int lc0 = (u.pn & 1) * 256 + wc * 32 + 8 * fq;
; #pragma unroll
;         for (int ai = 0; ai < 2; ++ai)
; #pragma unroll
;             for (int m = 0; m < 4; ++m) {
;                 const int n = n0 + ai * HALF + m * 16;
; #pragma unroll
;                 for (int bj = 0; bj < 2; ++bj) {
;                     const int lc = lc0 + bj * HALF, t = lc >> 4, co = lc & 15; const int token = n * 32 + t;
;                     const f32x4 a0 = acc[ai][bj][m][0], a1 = acc[ai][bj][m][1];
;                     u32x4 w; w.x = cvt_pk_bf16(gelu_tanh(a0[0]), gelu_tanh(a0[1])); w.y = cvt_pk_bf16(gelu_tanh(a0[2]), gelu_tanh(a0[3]));
;                     w.z = cvt_pk_bf16(gelu_tanh(a1[0]), gelu_tanh(a1[1])); w.w = cvt_pk_bf16(gelu_tanh(a1[2]), gelu_tanh(a1[3]));
;                     *(u32x4*)(Y + (size_t)token * 1024 + 16 * g + co) = w;
;                 }
;             }
;     }
	v_add_f32_e32 v36, v36, v36
	v_mul_f32_e32 v36, 0x3fb8aa3b, v36
	v_exp_f32_e32 v36, v36
	v_or_b32_e32 v42, v124, v151
	v_ashrrev_i32_e32 v43, 31, v42
	v_cvt_pk_bf16_f32 v41, v34, v35
	v_add_f32_e32 v36, 1.0, v36
	v_div_scale_f32 v37, s[28:29], v36, v36, 2.0
	v_lshlrev_b64 v[34:35], 11, v[42:43]
	v_rcp_f32_e32 v42, v37
	v_lshl_add_u64 v[34:35], v[138:139], 0, v[34:35]
	global_store_dwordx4 v[34:35], v[38:41], off
	v_mul_f32_e32 v30, 0.5, v30
	v_fma_f32 v35, -v37, v42, 1.0
	v_fmac_f32_e32 v42, v35, v42
	v_div_scale_f32 v35, vcc, 2.0, v36, 2.0
	v_mul_f32_e32 v38, v35, v42
	v_fma_f32 v39, -v37, v38, v35
	v_fmac_f32_e32 v38, v39, v42
	v_fma_f32 v35, -v37, v38, v35
	v_mul_f32_e32 v37, 0x3d372713, v31
	v_mul_f32_e32 v37, v31, v37
	v_fma_f32 v37, v31, v37, v31
	v_mul_f32_e32 v37, 0x3f4c422a, v37
	v_add_f32_e32 v37, v37, v37
	v_mul_f32_e32 v37, 0x3fb8aa3b, v37
	v_exp_f32_e32 v37, v37
	v_div_fmas_f32 v35, v35, v42, v38
	v_div_fixup_f32 v35, v35, v36, 2.0
	v_sub_f32_e32 v35, 1.0, v35
	v_add_f32_e32 v36, 1.0, v37
	v_div_scale_f32 v37, s[28:29], v36, v36, 2.0
	v_rcp_f32_e32 v38, v37
	v_add_f32_e32 v35, 1.0, v35
	v_mul_f32_e32 v30, v30, v35
	v_mul_f32_e32 v31, 0.5, v31
	v_fma_f32 v35, -v37, v38, 1.0
	v_fmac_f32_e32 v38, v35, v38
	v_div_scale_f32 v35, vcc, 2.0, v36, 2.0
	v_mul_f32_e32 v39, v35, v38
	v_fma_f32 v40, -v37, v39, v35
	v_fmac_f32_e32 v39, v40, v38
	v_fma_f32 v35, -v37, v39, v35
	v_mul_f32_e32 v37, 0x3d372713, v32
	v_mul_f32_e32 v37, v32, v37
	v_fma_f32 v37, v32, v37, v32
	v_mul_f32_e32 v37, 0x3f4c422a, v37
	v_add_f32_e32 v37, v37, v37
	v_mul_f32_e32 v37, 0x3fb8aa3b, v37
	v_exp_f32_e32 v37, v37
	v_div_fmas_f32 v35, v35, v38, v39
	v_div_fixup_f32 v35, v35, v36, 2.0
	v_sub_f32_e32 v35, 1.0, v35
	v_add_f32_e32 v36, 1.0, v37
	v_div_scale_f32 v37, s[28:29], v36, v36, 2.0
	v_rcp_f32_e32 v38, v37
	v_add_f32_e32 v35, 1.0, v35
	v_mul_f32_e32 v31, v31, v35
	v_cvt_pk_bf16_f32 v30, v30, v31
	v_fma_f32 v31, -v37, v38, 1.0
	v_fmac_f32_e32 v38, v31, v38
	v_div_scale_f32 v31, vcc, 2.0, v36, 2.0
	v_mul_f32_e32 v35, v31, v38
	v_fma_f32 v39, -v37, v35, v31
	v_fmac_f32_e32 v35, v39, v38
	v_fma_f32 v31, -v37, v35, v31
	v_mul_f32_e32 v37, 0x3d372713, v33
	v_mul_f32_e32 v37, v33, v37
	v_fma_f32 v37, v33, v37, v33
	v_mul_f32_e32 v37, 0x3f4c422a, v37
	v_add_f32_e32 v37, v37, v37
	v_mul_f32_e32 v37, 0x3fb8aa3b, v37
	v_exp_f32_e32 v37, v37
	v_div_fmas_f32 v31, v31, v38, v35
	v_div_fixup_f32 v31, v31, v36, 2.0
	v_sub_f32_e32 v31, 1.0, v31
	v_add_f32_e32 v35, 1.0, v37
	v_div_scale_f32 v36, s[28:29], v35, v35, 2.0
	v_rcp_f32_e32 v37, v36
	v_mul_f32_e32 v32, 0.5, v32
	v_add_f32_e32 v31, 1.0, v31
	v_mul_f32_e32 v31, v32, v31
	v_fma_f32 v32, -v36, v37, 1.0
	v_fmac_f32_e32 v37, v32, v37
	v_div_scale_f32 v32, vcc, 2.0, v35, 2.0
	v_mul_f32_e32 v38, v32, v37
	v_fma_f32 v39, -v36, v38, v32
	v_fmac_f32_e32 v38, v39, v37
	v_fma_f32 v32, -v36, v38, v32
	v_mul_f32_e32 v36, 0x3d372713, v26
	v_mul_f32_e32 v36, v26, v36
	v_fma_f32 v36, v26, v36, v26
	v_mul_f32_e32 v36, 0x3f4c422a, v36
	v_add_f32_e32 v36, v36, v36
	v_mul_f32_e32 v36, 0x3fb8aa3b, v36
	v_exp_f32_e32 v36, v36
	v_div_fmas_f32 v32, v32, v37, v38
	v_div_fixup_f32 v32, v32, v35, 2.0
	v_sub_f32_e32 v32, 1.0, v32
	v_add_f32_e32 v35, 1.0, v36
	v_div_scale_f32 v36, s[28:29], v35, v35, 2.0
	v_rcp_f32_e32 v37, v36
	v_mul_f32_e32 v33, 0.5, v33
	v_add_f32_e32 v32, 1.0, v32
	v_mul_f32_e32 v32, v33, v32
	v_cvt_pk_bf16_f32 v31, v31, v32
	v_fma_f32 v32, -v36, v37, 1.0
	v_fmac_f32_e32 v37, v32, v37
	v_div_scale_f32 v32, vcc, 2.0, v35, 2.0
	v_mul_f32_e32 v33, v32, v37
	v_fma_f32 v38, -v36, v33, v32
	v_fmac_f32_e32 v33, v38, v37
	v_fma_f32 v32, -v36, v33, v32
	v_mul_f32_e32 v36, 0x3d372713, v27
	v_mul_f32_e32 v36, v27, v36
	v_fma_f32 v36, v27, v36, v27
	v_mul_f32_e32 v36, 0x3f4c422a, v36
	v_add_f32_e32 v36, v36, v36
	v_mul_f32_e32 v36, 0x3fb8aa3b, v36
	v_exp_f32_e32 v36, v36
	v_div_fmas_f32 v32, v32, v37, v33
	v_div_fixup_f32 v32, v32, v35, 2.0
	v_sub_f32_e32 v32, 1.0, v32
	v_add_f32_e32 v33, 1.0, v36
	v_div_scale_f32 v35, s[28:29], v33, v33, 2.0
	v_rcp_f32_e32 v36, v35
	v_mul_f32_e32 v26, 0.5, v26
	v_add_f32_e32 v32, 1.0, v32
	v_mul_f32_e32 v26, v26, v32
	v_fma_f32 v32, -v35, v36, 1.0
	v_fmac_f32_e32 v36, v32, v36
	v_div_scale_f32 v32, vcc, 2.0, v33, 2.0
	v_mul_f32_e32 v37, v32, v36
	v_fma_f32 v38, -v35, v37, v32
	v_fmac_f32_e32 v37, v38, v36
	v_fma_f32 v32, -v35, v37, v32
	v_mul_f32_e32 v35, 0x3d372713, v28
	v_mul_f32_e32 v35, v28, v35
	v_fma_f32 v35, v28, v35, v28
	v_mul_f32_e32 v35, 0x3f4c422a, v35
	v_add_f32_e32 v35, v35, v35
	v_mul_f32_e32 v35, 0x3fb8aa3b, v35
	v_exp_f32_e32 v35, v35
	v_div_fmas_f32 v32, v32, v36, v37
	v_div_fixup_f32 v32, v32, v33, 2.0
	v_sub_f32_e32 v32, 1.0, v32
	v_add_f32_e32 v33, 1.0, v35
	v_div_scale_f32 v35, s[28:29], v33, v33, 2.0
	v_rcp_f32_e32 v36, v35
	v_mul_f32_e32 v27, 0.5, v27
	v_add_f32_e32 v32, 1.0, v32
	v_mul_f32_e32 v27, v27, v32
	v_cvt_pk_bf16_f32 v32, v26, v27
	v_fma_f32 v26, -v35, v36, 1.0
	v_fmac_f32_e32 v36, v26, v36
	v_div_scale_f32 v26, vcc, 2.0, v33, 2.0
	v_mul_f32_e32 v27, v26, v36
	v_fma_f32 v37, -v35, v27, v26
	v_fmac_f32_e32 v27, v37, v36
	v_fma_f32 v26, -v35, v27, v26
	v_mul_f32_e32 v35, 0x3d372713, v29
	v_mul_f32_e32 v35, v29, v35
	v_fma_f32 v35, v29, v35, v29
	v_mul_f32_e32 v35, 0x3f4c422a, v35
	v_add_f32_e32 v35, v35, v35
	v_mul_f32_e32 v35, 0x3fb8aa3b, v35
	v_exp_f32_e32 v35, v35
	v_div_fmas_f32 v26, v26, v36, v27
	v_div_fixup_f32 v26, v26, v33, 2.0
	v_sub_f32_e32 v26, 1.0, v26
	v_add_f32_e32 v27, 1.0, v35
	v_div_scale_f32 v33, s[28:29], v27, v27, 2.0
	v_rcp_f32_e32 v35, v33
	v_mul_f32_e32 v28, 0.5, v28
	v_add_f32_e32 v26, 1.0, v26
	v_mul_f32_e32 v26, v28, v26
	v_fma_f32 v28, -v33, v35, 1.0
; #define LAS __attribute__((address_space(3)))
; __device__ __forceinline__ unsigned cvt_pk_bf16(float lo, float hi) { unsigned r; asm volatile("v_cvt_pk_bf16_f32 %0, %1, %2" : "=v"(r) : "v"(lo), "v"(hi)); return r; }
; __device__ __forceinline__ float gelu_tanh(float x) { const float z = 0.7978845608f * (x + 0.044715f * x * x * x); const float th = 1.0f - 2.0f / (__expf(2.0f * z) + 1.0f); return 0.5f * x * (1.0f + th); }
;     __device__ __forceinline__ void operator()(const f32x4 (&acc)[2][2][4][2], const Unit& u, int ui, const LAS float* rtab, int wr, int wc, int fr, int fq) const {
;         const int g = u.pm; const int n0 = wr * 64 + fr; const int lc0 = (u.pn & 1) * 256 + wc * 32 + 8 * fq;
; #pragma unroll
;         for (int ai = 0; ai < 2; ++ai)
; #pragma unroll
;             for (int m = 0; m < 4; ++m) {
;                 const int n = n0 + ai * HALF + m * 16;
; #pragma unroll
;                 for (int bj = 0; bj < 2; ++bj) {
;                     const int lc = lc0 + bj * HALF, t = lc >> 4, co = lc & 15; const int token = n * 32 + t;
;                     const f32x4 a0 = acc[ai][bj][m][0], a1 = acc[ai][bj][m][1];
;                     u32x4 w; w.x = cvt_pk_bf16(gelu_tanh(a0[0]), gelu_tanh(a0[1])); w.y = cvt_pk_bf16(gelu_tanh(a0[2]), gelu_tanh(a0[3]));
;                     w.z = cvt_pk_bf16(gelu_tanh(a1[0]), gelu_tanh(a1[1])); w.w = cvt_pk_bf16(gelu_tanh(a1[2]), gelu_tanh(a1[3]));
;                     *(u32x4*)(Y + (size_t)token * 1024 + 16 * g + co) = w;
;                 }
;             }
;     }
	v_fmac_f32_e32 v35, v28, v35
	v_div_scale_f32 v28, vcc, 2.0, v27, 2.0
	v_mul_f32_e32 v36, v28, v35
	v_fma_f32 v37, -v33, v36, v28
	v_fmac_f32_e32 v36, v37, v35
	v_fma_f32 v28, -v33, v36, v28
	v_div_fmas_f32 v28, v28, v35, v36
	v_div_fixup_f32 v27, v28, v27, 2.0
	v_sub_f32_e32 v27, 1.0, v27
	v_mul_f32_e32 v28, 0.5, v29
	v_add_f32_e32 v27, 1.0, v27
	v_mul_f32_e32 v27, v28, v27
	v_mul_f32_e32 v28, 0x3d372713, v22
	v_mul_f32_e32 v28, v22, v28
	v_fma_f32 v28, v22, v28, v22
	v_mul_f32_e32 v28, 0x3f4c422a, v28
	v_add_f32_e32 v28, v28, v28
	v_mul_f32_e32 v28, 0x3fb8aa3b, v28
	v_exp_f32_e32 v28, v28
	v_or_b32_e32 v34, v171, v152
	v_ashrrev_i32_e32 v35, 31, v34
	v_cvt_pk_bf16_f32 v33, v26, v27
	v_add_f32_e32 v28, 1.0, v28
	v_div_scale_f32 v29, s[28:29], v28, v28, 2.0
	v_lshlrev_b64 v[26:27], 11, v[34:35]
	v_rcp_f32_e32 v34, v29
	v_lshl_add_u64 v[26:27], v[138:139], 0, v[26:27]
	global_store_dwordx4 v[26:27], v[30:33], off
	v_mul_f32_e32 v22, 0.5, v22
	v_fma_f32 v27, -v29, v34, 1.0
	v_fmac_f32_e32 v34, v27, v34
	v_div_scale_f32 v27, vcc, 2.0, v28, 2.0
	v_mul_f32_e32 v30, v27, v34
	v_fma_f32 v31, -v29, v30, v27
	v_fmac_f32_e32 v30, v31, v34
	v_fma_f32 v27, -v29, v30, v27
	v_mul_f32_e32 v29, 0x3d372713, v23
	v_mul_f32_e32 v29, v23, v29
	v_fma_f32 v29, v23, v29, v23
	v_mul_f32_e32 v29, 0x3f4c422a, v29
	v_add_f32_e32 v29, v29, v29
	v_mul_f32_e32 v29, 0x3fb8aa3b, v29
	v_exp_f32_e32 v29, v29
	v_div_fmas_f32 v27, v27, v34, v30
	v_div_fixup_f32 v27, v27, v28, 2.0
	v_sub_f32_e32 v27, 1.0, v27
	v_add_f32_e32 v28, 1.0, v29
	v_div_scale_f32 v29, s[28:29], v28, v28, 2.0
	v_rcp_f32_e32 v30, v29
	v_add_f32_e32 v27, 1.0, v27
	v_mul_f32_e32 v22, v22, v27
	v_mul_f32_e32 v23, 0.5, v23
	v_fma_f32 v27, -v29, v30, 1.0
	v_fmac_f32_e32 v30, v27, v30
	v_div_scale_f32 v27, vcc, 2.0, v28, 2.0
	v_mul_f32_e32 v31, v27, v30
	v_fma_f32 v32, -v29, v31, v27
	v_fmac_f32_e32 v31, v32, v30
	v_fma_f32 v27, -v29, v31, v27
	v_mul_f32_e32 v29, 0x3d372713, v24
	v_mul_f32_e32 v29, v24, v29
	v_fma_f32 v29, v24, v29, v24
	v_mul_f32_e32 v29, 0x3f4c422a, v29
	v_add_f32_e32 v29, v29, v29
	v_mul_f32_e32 v29, 0x3fb8aa3b, v29
	v_exp_f32_e32 v29, v29
	v_div_fmas_f32 v27, v27, v30, v31
	v_div_fixup_f32 v27, v27, v28, 2.0
	v_sub_f32_e32 v27, 1.0, v27
	v_add_f32_e32 v28, 1.0, v29
	v_div_scale_f32 v29, s[28:29], v28, v28, 2.0
	v_rcp_f32_e32 v30, v29
	v_add_f32_e32 v27, 1.0, v27
	v_mul_f32_e32 v23, v23, v27
	v_cvt_pk_bf16_f32 v22, v22, v23
	v_fma_f32 v23, -v29, v30, 1.0
	v_fmac_f32_e32 v30, v23, v30
	v_div_scale_f32 v23, vcc, 2.0, v28, 2.0
	v_mul_f32_e32 v27, v23, v30
	v_fma_f32 v31, -v29, v27, v23
	v_fmac_f32_e32 v27, v31, v30
	v_fma_f32 v23, -v29, v27, v23
	v_mul_f32_e32 v29, 0x3d372713, v25
	v_mul_f32_e32 v29, v25, v29
	v_fma_f32 v29, v25, v29, v25
	v_mul_f32_e32 v29, 0x3f4c422a, v29
	v_add_f32_e32 v29, v29, v29
	v_mul_f32_e32 v29, 0x3fb8aa3b, v29
	v_exp_f32_e32 v29, v29
	v_div_fmas_f32 v23, v23, v30, v27
	v_div_fixup_f32 v23, v23, v28, 2.0
	v_sub_f32_e32 v23, 1.0, v23
	v_add_f32_e32 v27, 1.0, v29
	v_div_scale_f32 v28, s[28:29], v27, v27, 2.0
	v_rcp_f32_e32 v29, v28
	v_mul_f32_e32 v24, 0.5, v24
	v_add_f32_e32 v23, 1.0, v23
	v_mul_f32_e32 v23, v24, v23
	v_fma_f32 v24, -v28, v29, 1.0
	v_fmac_f32_e32 v29, v24, v29
	v_div_scale_f32 v24, vcc, 2.0, v27, 2.0
	v_mul_f32_e32 v30, v24, v29
	v_fma_f32 v31, -v28, v30, v24
	v_fmac_f32_e32 v30, v31, v29
	v_fma_f32 v24, -v28, v30, v24
	v_mul_f32_e32 v28, 0x3d372713, v18
	v_mul_f32_e32 v28, v18, v28
	v_fma_f32 v28, v18, v28, v18
	v_mul_f32_e32 v28, 0x3f4c422a, v28
	v_add_f32_e32 v28, v28, v28
	v_mul_f32_e32 v28, 0x3fb8aa3b, v28
	v_exp_f32_e32 v28, v28
	v_div_fmas_f32 v24, v24, v29, v30
	v_div_fixup_f32 v24, v24, v27, 2.0
	v_sub_f32_e32 v24, 1.0, v24
	v_add_f32_e32 v27, 1.0, v28
	v_div_scale_f32 v28, s[28:29], v27, v27, 2.0
	v_rcp_f32_e32 v29, v28
	v_mul_f32_e32 v25, 0.5, v25
	v_add_f32_e32 v24, 1.0, v24
	v_mul_f32_e32 v24, v25, v24
	v_cvt_pk_bf16_f32 v23, v23, v24
	v_fma_f32 v24, -v28, v29, 1.0
	v_fmac_f32_e32 v29, v24, v29
	v_div_scale_f32 v24, vcc, 2.0, v27, 2.0
	v_mul_f32_e32 v25, v24, v29
	v_fma_f32 v30, -v28, v25, v24
	v_fmac_f32_e32 v25, v30, v29
	v_fma_f32 v24, -v28, v25, v24
	v_mul_f32_e32 v28, 0x3d372713, v19
	v_mul_f32_e32 v28, v19, v28
	v_fma_f32 v28, v19, v28, v19
	v_mul_f32_e32 v28, 0x3f4c422a, v28
	v_add_f32_e32 v28, v28, v28
	v_mul_f32_e32 v28, 0x3fb8aa3b, v28
	v_exp_f32_e32 v28, v28
	v_div_fmas_f32 v24, v24, v29, v25
	v_div_fixup_f32 v24, v24, v27, 2.0
	v_sub_f32_e32 v24, 1.0, v24
	v_add_f32_e32 v25, 1.0, v28
	v_div_scale_f32 v27, s[28:29], v25, v25, 2.0
	v_rcp_f32_e32 v28, v27
	v_mul_f32_e32 v18, 0.5, v18
	v_add_f32_e32 v24, 1.0, v24
	v_mul_f32_e32 v18, v18, v24
	v_fma_f32 v24, -v27, v28, 1.0
	v_fmac_f32_e32 v28, v24, v28
	v_div_scale_f32 v24, vcc, 2.0, v25, 2.0
	v_mul_f32_e32 v29, v24, v28
	v_fma_f32 v30, -v27, v29, v24
	v_fmac_f32_e32 v29, v30, v28
	v_fma_f32 v24, -v27, v29, v24
	v_mul_f32_e32 v27, 0x3d372713, v20
	v_mul_f32_e32 v27, v20, v27
	v_fma_f32 v27, v20, v27, v20
	v_mul_f32_e32 v27, 0x3f4c422a, v27
	v_add_f32_e32 v27, v27, v27
	v_mul_f32_e32 v27, 0x3fb8aa3b, v27
	v_exp_f32_e32 v27, v27
	v_div_fmas_f32 v24, v24, v28, v29
	v_div_fixup_f32 v24, v24, v25, 2.0
	v_sub_f32_e32 v24, 1.0, v24
	v_add_f32_e32 v25, 1.0, v27
	v_div_scale_f32 v27, s[28:29], v25, v25, 2.0
	v_rcp_f32_e32 v28, v27
	v_mul_f32_e32 v19, 0.5, v19
	v_add_f32_e32 v24, 1.0, v24
	v_mul_f32_e32 v19, v19, v24
	v_cvt_pk_bf16_f32 v24, v18, v19
	v_fma_f32 v18, -v27, v28, 1.0
	v_fmac_f32_e32 v28, v18, v28
	v_div_scale_f32 v18, vcc, 2.0, v25, 2.0
	v_mul_f32_e32 v19, v18, v28
	v_fma_f32 v29, -v27, v19, v18
	v_fmac_f32_e32 v19, v29, v28
	v_fma_f32 v18, -v27, v19, v18
; #define LAS __attribute__((address_space(3)))
; __device__ __forceinline__ unsigned cvt_pk_bf16(float lo, float hi) { unsigned r; asm volatile("v_cvt_pk_bf16_f32 %0, %1, %2" : "=v"(r) : "v"(lo), "v"(hi)); return r; }
; __device__ __forceinline__ float gelu_tanh(float x) { const float z = 0.7978845608f * (x + 0.044715f * x * x * x); const float th = 1.0f - 2.0f / (__expf(2.0f * z) + 1.0f); return 0.5f * x * (1.0f + th); }
;     __device__ __forceinline__ void operator()(const f32x4 (&acc)[2][2][4][2], const Unit& u, int ui, const LAS float* rtab, int wr, int wc, int fr, int fq) const {
;         const int g = u.pm; const int n0 = wr * 64 + fr; const int lc0 = (u.pn & 1) * 256 + wc * 32 + 8 * fq;
; #pragma unroll
;         for (int ai = 0; ai < 2; ++ai)
; #pragma unroll
;             for (int m = 0; m < 4; ++m) {
;                 const int n = n0 + ai * HALF + m * 16;
; #pragma unroll
;                 for (int bj = 0; bj < 2; ++bj) {
;                     const int lc = lc0 + bj * HALF, t = lc >> 4, co = lc & 15; const int token = n * 32 + t;
;                     const f32x4 a0 = acc[ai][bj][m][0], a1 = acc[ai][bj][m][1];
;                     u32x4 w; w.x = cvt_pk_bf16(gelu_tanh(a0[0]), gelu_tanh(a0[1])); w.y = cvt_pk_bf16(gelu_tanh(a0[2]), gelu_tanh(a0[3]));
;                     w.z = cvt_pk_bf16(gelu_tanh(a1[0]), gelu_tanh(a1[1])); w.w = cvt_pk_bf16(gelu_tanh(a1[2]), gelu_tanh(a1[3]));
;                     *(u32x4*)(Y + (size_t)token * 1024 + 16 * g + co) = w;
;                 }
;             }
;     }
	v_mul_f32_e32 v27, 0x3d372713, v21
	v_mul_f32_e32 v27, v21, v27
	v_fma_f32 v27, v21, v27, v21
	v_mul_f32_e32 v27, 0x3f4c422a, v27
	v_add_f32_e32 v27, v27, v27
	v_mul_f32_e32 v27, 0x3fb8aa3b, v27
	v_exp_f32_e32 v27, v27
	v_div_fmas_f32 v18, v18, v28, v19
	v_div_fixup_f32 v18, v18, v25, 2.0
	v_sub_f32_e32 v18, 1.0, v18
	v_add_f32_e32 v19, 1.0, v27
	v_div_scale_f32 v25, s[28:29], v19, v19, 2.0
	v_rcp_f32_e32 v27, v25
	v_mul_f32_e32 v20, 0.5, v20
	v_add_f32_e32 v18, 1.0, v18
	v_mul_f32_e32 v18, v20, v18
	v_fma_f32 v20, -v25, v27, 1.0
	v_fmac_f32_e32 v27, v20, v27
	v_div_scale_f32 v20, vcc, 2.0, v19, 2.0
	v_mul_f32_e32 v28, v20, v27
	v_fma_f32 v29, -v25, v28, v20
	v_fmac_f32_e32 v28, v29, v27
	v_fma_f32 v20, -v25, v28, v20
	v_div_fmas_f32 v20, v20, v27, v28
	v_div_fixup_f32 v19, v20, v19, 2.0
	v_sub_f32_e32 v19, 1.0, v19
	v_mul_f32_e32 v20, 0.5, v21
	v_add_f32_e32 v19, 1.0, v19
	v_mul_f32_e32 v19, v20, v19
	v_mul_f32_e32 v20, 0x3d372713, v14
	v_mul_f32_e32 v20, v14, v20
	v_fma_f32 v20, v14, v20, v14
	v_mul_f32_e32 v20, 0x3f4c422a, v20
	v_add_f32_e32 v20, v20, v20
	v_mul_f32_e32 v20, 0x3fb8aa3b, v20
	v_exp_f32_e32 v20, v20
	v_or_b32_e32 v26, v124, v152
	v_ashrrev_i32_e32 v27, 31, v26
	v_cvt_pk_bf16_f32 v25, v18, v19
	v_add_f32_e32 v20, 1.0, v20
	v_div_scale_f32 v21, s[28:29], v20, v20, 2.0
	v_lshlrev_b64 v[18:19], 11, v[26:27]
	v_rcp_f32_e32 v26, v21
	v_lshl_add_u64 v[18:19], v[138:139], 0, v[18:19]
	global_store_dwordx4 v[18:19], v[22:25], off
	v_mul_f32_e32 v14, 0.5, v14
	v_fma_f32 v19, -v21, v26, 1.0
	v_fmac_f32_e32 v26, v19, v26
	v_div_scale_f32 v19, vcc, 2.0, v20, 2.0
	v_mul_f32_e32 v22, v19, v26
	v_fma_f32 v23, -v21, v22, v19
	v_fmac_f32_e32 v22, v23, v26
	v_fma_f32 v19, -v21, v22, v19
	v_mul_f32_e32 v21, 0x3d372713, v15
	v_mul_f32_e32 v21, v15, v21
	v_fma_f32 v21, v15, v21, v15
	v_mul_f32_e32 v21, 0x3f4c422a, v21
	v_add_f32_e32 v21, v21, v21
	v_mul_f32_e32 v21, 0x3fb8aa3b, v21
	v_exp_f32_e32 v21, v21
	v_div_fmas_f32 v19, v19, v26, v22
	v_div_fixup_f32 v19, v19, v20, 2.0
	v_sub_f32_e32 v19, 1.0, v19
	v_add_f32_e32 v20, 1.0, v21
	v_div_scale_f32 v21, s[28:29], v20, v20, 2.0
	v_rcp_f32_e32 v22, v21
	v_add_f32_e32 v19, 1.0, v19
	v_mul_f32_e32 v14, v14, v19
	v_mul_f32_e32 v15, 0.5, v15
	v_fma_f32 v19, -v21, v22, 1.0
	v_fmac_f32_e32 v22, v19, v22
	v_div_scale_f32 v19, vcc, 2.0, v20, 2.0
	v_mul_f32_e32 v23, v19, v22
	v_fma_f32 v24, -v21, v23, v19
	v_fmac_f32_e32 v23, v24, v22
	v_fma_f32 v19, -v21, v23, v19
	v_mul_f32_e32 v21, 0x3d372713, v16
	v_mul_f32_e32 v21, v16, v21
	v_fma_f32 v21, v16, v21, v16
	v_mul_f32_e32 v21, 0x3f4c422a, v21
	v_add_f32_e32 v21, v21, v21
	v_mul_f32_e32 v21, 0x3fb8aa3b, v21
	v_exp_f32_e32 v21, v21
	v_div_fmas_f32 v19, v19, v22, v23
	v_div_fixup_f32 v19, v19, v20, 2.0
	v_sub_f32_e32 v19, 1.0, v19
	v_add_f32_e32 v20, 1.0, v21
	v_div_scale_f32 v21, s[28:29], v20, v20, 2.0
	v_rcp_f32_e32 v22, v21
	v_add_f32_e32 v19, 1.0, v19
	v_mul_f32_e32 v15, v15, v19
	v_cvt_pk_bf16_f32 v14, v14, v15
	v_fma_f32 v15, -v21, v22, 1.0
	v_fmac_f32_e32 v22, v15, v22
	v_div_scale_f32 v15, vcc, 2.0, v20, 2.0
	v_mul_f32_e32 v19, v15, v22
	v_fma_f32 v23, -v21, v19, v15
	v_fmac_f32_e32 v19, v23, v22
	v_fma_f32 v15, -v21, v19, v15
	v_mul_f32_e32 v21, 0x3d372713, v17
	v_mul_f32_e32 v21, v17, v21
	v_fma_f32 v21, v17, v21, v17
	v_mul_f32_e32 v21, 0x3f4c422a, v21
	v_add_f32_e32 v21, v21, v21
	v_mul_f32_e32 v21, 0x3fb8aa3b, v21
	v_exp_f32_e32 v21, v21
	v_div_fmas_f32 v15, v15, v22, v19
	v_div_fixup_f32 v15, v15, v20, 2.0
	v_sub_f32_e32 v15, 1.0, v15
	v_add_f32_e32 v19, 1.0, v21
	v_div_scale_f32 v20, s[28:29], v19, v19, 2.0
	v_rcp_f32_e32 v21, v20
	v_mul_f32_e32 v16, 0.5, v16
	v_add_f32_e32 v15, 1.0, v15
	v_mul_f32_e32 v15, v16, v15
	v_fma_f32 v16, -v20, v21, 1.0
	v_fmac_f32_e32 v21, v16, v21
	v_div_scale_f32 v16, vcc, 2.0, v19, 2.0
	v_mul_f32_e32 v22, v16, v21
	v_fma_f32 v23, -v20, v22, v16
	v_fmac_f32_e32 v22, v23, v21
	v_fma_f32 v16, -v20, v22, v16
	v_mul_f32_e32 v20, 0x3d372713, v10
	v_mul_f32_e32 v20, v10, v20
	v_fma_f32 v20, v10, v20, v10
	v_mul_f32_e32 v20, 0x3f4c422a, v20
	v_add_f32_e32 v20, v20, v20
	v_mul_f32_e32 v20, 0x3fb8aa3b, v20
	v_exp_f32_e32 v20, v20
	v_div_fmas_f32 v16, v16, v21, v22
	v_div_fixup_f32 v16, v16, v19, 2.0
	v_sub_f32_e32 v16, 1.0, v16
	v_add_f32_e32 v19, 1.0, v20
	v_div_scale_f32 v20, s[28:29], v19, v19, 2.0
	v_rcp_f32_e32 v21, v20
	v_mul_f32_e32 v17, 0.5, v17
	v_add_f32_e32 v16, 1.0, v16
	v_mul_f32_e32 v16, v17, v16
	v_cvt_pk_bf16_f32 v15, v15, v16
	v_fma_f32 v16, -v20, v21, 1.0
	v_fmac_f32_e32 v21, v16, v21
	v_div_scale_f32 v16, vcc, 2.0, v19, 2.0
	v_mul_f32_e32 v17, v16, v21
	v_fma_f32 v22, -v20, v17, v16
	v_fmac_f32_e32 v17, v22, v21
	v_fma_f32 v16, -v20, v17, v16
	v_mul_f32_e32 v20, 0x3d372713, v11
	v_mul_f32_e32 v20, v11, v20
	v_fma_f32 v20, v11, v20, v11
	v_mul_f32_e32 v20, 0x3f4c422a, v20
	v_add_f32_e32 v20, v20, v20
	v_mul_f32_e32 v20, 0x3fb8aa3b, v20
	v_exp_f32_e32 v20, v20
	v_div_fmas_f32 v16, v16, v21, v17
	v_div_fixup_f32 v16, v16, v19, 2.0
	v_sub_f32_e32 v16, 1.0, v16
	v_add_f32_e32 v17, 1.0, v20
	v_div_scale_f32 v19, s[28:29], v17, v17, 2.0
	v_rcp_f32_e32 v20, v19
	v_mul_f32_e32 v10, 0.5, v10
	v_add_f32_e32 v16, 1.0, v16
	v_mul_f32_e32 v10, v10, v16
	v_fma_f32 v16, -v19, v20, 1.0
	v_fmac_f32_e32 v20, v16, v20
	v_div_scale_f32 v16, vcc, 2.0, v17, 2.0
	v_mul_f32_e32 v21, v16, v20
	v_fma_f32 v22, -v19, v21, v16
	v_fmac_f32_e32 v21, v22, v20
	v_fma_f32 v16, -v19, v21, v16
	v_mul_f32_e32 v19, 0x3d372713, v12
	v_mul_f32_e32 v19, v12, v19
	v_fma_f32 v19, v12, v19, v12
	v_mul_f32_e32 v19, 0x3f4c422a, v19
	v_add_f32_e32 v19, v19, v19
	v_mul_f32_e32 v19, 0x3fb8aa3b, v19
	v_exp_f32_e32 v19, v19
	v_div_fmas_f32 v16, v16, v20, v21
; #define LAS __attribute__((address_space(3)))
; __device__ __forceinline__ unsigned cvt_pk_bf16(float lo, float hi) { unsigned r; asm volatile("v_cvt_pk_bf16_f32 %0, %1, %2" : "=v"(r) : "v"(lo), "v"(hi)); return r; }
; __device__ __forceinline__ float gelu_tanh(float x) { const float z = 0.7978845608f * (x + 0.044715f * x * x * x); const float th = 1.0f - 2.0f / (__expf(2.0f * z) + 1.0f); return 0.5f * x * (1.0f + th); }
;     __device__ __forceinline__ void operator()(const f32x4 (&acc)[2][2][4][2], const Unit& u, int ui, const LAS float* rtab, int wr, int wc, int fr, int fq) const {
;         const int g = u.pm; const int n0 = wr * 64 + fr; const int lc0 = (u.pn & 1) * 256 + wc * 32 + 8 * fq;
; #pragma unroll
;         for (int ai = 0; ai < 2; ++ai)
; #pragma unroll
;             for (int m = 0; m < 4; ++m) {
;                 const int n = n0 + ai * HALF + m * 16;
; #pragma unroll
;                 for (int bj = 0; bj < 2; ++bj) {
;                     const int lc = lc0 + bj * HALF, t = lc >> 4, co = lc & 15; const int token = n * 32 + t;
;                     const f32x4 a0 = acc[ai][bj][m][0], a1 = acc[ai][bj][m][1];
;                     u32x4 w; w.x = cvt_pk_bf16(gelu_tanh(a0[0]), gelu_tanh(a0[1])); w.y = cvt_pk_bf16(gelu_tanh(a0[2]), gelu_tanh(a0[3]));
;                     w.z = cvt_pk_bf16(gelu_tanh(a1[0]), gelu_tanh(a1[1])); w.w = cvt_pk_bf16(gelu_tanh(a1[2]), gelu_tanh(a1[3]));
;                     *(u32x4*)(Y + (size_t)token * 1024 + 16 * g + co) = w;
;                 }
;             }
;     }
	v_div_fixup_f32 v16, v16, v17, 2.0
	v_sub_f32_e32 v16, 1.0, v16
	v_add_f32_e32 v17, 1.0, v19
	v_div_scale_f32 v19, s[28:29], v17, v17, 2.0
	v_rcp_f32_e32 v20, v19
	v_mul_f32_e32 v11, 0.5, v11
	v_add_f32_e32 v16, 1.0, v16
	v_mul_f32_e32 v11, v11, v16
	v_cvt_pk_bf16_f32 v16, v10, v11
	v_fma_f32 v10, -v19, v20, 1.0
	v_fmac_f32_e32 v20, v10, v20
	v_div_scale_f32 v10, vcc, 2.0, v17, 2.0
	v_mul_f32_e32 v11, v10, v20
	v_fma_f32 v21, -v19, v11, v10
	v_fmac_f32_e32 v11, v21, v20
	v_fma_f32 v10, -v19, v11, v10
	v_mul_f32_e32 v19, 0x3d372713, v13
	v_mul_f32_e32 v19, v13, v19
	v_fma_f32 v19, v13, v19, v13
	v_mul_f32_e32 v19, 0x3f4c422a, v19
	v_add_f32_e32 v19, v19, v19
	v_mul_f32_e32 v19, 0x3fb8aa3b, v19
	v_exp_f32_e32 v19, v19
	v_div_fmas_f32 v10, v10, v20, v11
	v_div_fixup_f32 v10, v10, v17, 2.0
	v_sub_f32_e32 v10, 1.0, v10
	v_add_f32_e32 v11, 1.0, v19
	v_div_scale_f32 v17, s[28:29], v11, v11, 2.0
	v_rcp_f32_e32 v19, v17
	v_mul_f32_e32 v12, 0.5, v12
	v_add_f32_e32 v10, 1.0, v10
	v_mul_f32_e32 v10, v12, v10
	v_fma_f32 v12, -v17, v19, 1.0
	v_fmac_f32_e32 v19, v12, v19
	v_div_scale_f32 v12, vcc, 2.0, v11, 2.0
	v_mul_f32_e32 v20, v12, v19
	v_fma_f32 v21, -v17, v20, v12
	v_fmac_f32_e32 v20, v21, v19
	v_fma_f32 v12, -v17, v20, v12
	v_div_fmas_f32 v12, v12, v19, v20
	v_div_fixup_f32 v11, v12, v11, 2.0
	v_sub_f32_e32 v11, 1.0, v11
	v_mul_f32_e32 v12, 0.5, v13
	v_add_f32_e32 v11, 1.0, v11
	v_mul_f32_e32 v11, v12, v11
	v_mul_f32_e32 v12, 0x3d372713, v6
	v_mul_f32_e32 v12, v6, v12
	v_fma_f32 v12, v6, v12, v6
	v_mul_f32_e32 v12, 0x3f4c422a, v12
	v_add_f32_e32 v12, v12, v12
	v_mul_f32_e32 v12, 0x3fb8aa3b, v12
	v_exp_f32_e32 v12, v12
	v_or_b32_e32 v18, v171, v153
	v_ashrrev_i32_e32 v19, 31, v18
	v_cvt_pk_bf16_f32 v17, v10, v11
	v_add_f32_e32 v12, 1.0, v12
	v_div_scale_f32 v13, s[28:29], v12, v12, 2.0
	v_lshlrev_b64 v[10:11], 11, v[18:19]
	v_rcp_f32_e32 v18, v13
	v_lshl_add_u64 v[10:11], v[138:139], 0, v[10:11]
	global_store_dwordx4 v[10:11], v[14:17], off
	v_mul_f32_e32 v6, 0.5, v6
	v_fma_f32 v11, -v13, v18, 1.0
	v_fmac_f32_e32 v18, v11, v18
	v_div_scale_f32 v11, vcc, 2.0, v12, 2.0
	v_mul_f32_e32 v14, v11, v18
	v_fma_f32 v15, -v13, v14, v11
	v_fmac_f32_e32 v14, v15, v18
	v_fma_f32 v11, -v13, v14, v11
	v_mul_f32_e32 v13, 0x3d372713, v7
	v_mul_f32_e32 v13, v7, v13
	v_fma_f32 v13, v7, v13, v7
	v_mul_f32_e32 v13, 0x3f4c422a, v13
	v_add_f32_e32 v13, v13, v13
	v_mul_f32_e32 v13, 0x3fb8aa3b, v13
	v_exp_f32_e32 v13, v13
	v_div_fmas_f32 v11, v11, v18, v14
	v_div_fixup_f32 v11, v11, v12, 2.0
	v_sub_f32_e32 v11, 1.0, v11
	v_add_f32_e32 v12, 1.0, v13
	v_div_scale_f32 v13, s[28:29], v12, v12, 2.0
	v_rcp_f32_e32 v14, v13
	v_add_f32_e32 v11, 1.0, v11
	v_mul_f32_e32 v6, v6, v11
	v_mul_f32_e32 v7, 0.5, v7
	v_fma_f32 v11, -v13, v14, 1.0
	v_fmac_f32_e32 v14, v11, v14
	v_div_scale_f32 v11, vcc, 2.0, v12, 2.0
	v_mul_f32_e32 v15, v11, v14
	v_fma_f32 v16, -v13, v15, v11
	v_fmac_f32_e32 v15, v16, v14
	v_fma_f32 v11, -v13, v15, v11
	v_mul_f32_e32 v13, 0x3d372713, v8
	v_mul_f32_e32 v13, v8, v13
	v_fma_f32 v13, v8, v13, v8
	v_mul_f32_e32 v13, 0x3f4c422a, v13
	v_add_f32_e32 v13, v13, v13
	v_mul_f32_e32 v13, 0x3fb8aa3b, v13
	v_exp_f32_e32 v13, v13
	v_div_fmas_f32 v11, v11, v14, v15
	v_div_fixup_f32 v11, v11, v12, 2.0
	v_sub_f32_e32 v11, 1.0, v11
	v_add_f32_e32 v12, 1.0, v13
	v_div_scale_f32 v13, s[28:29], v12, v12, 2.0
	v_rcp_f32_e32 v14, v13
	v_add_f32_e32 v11, 1.0, v11
	v_mul_f32_e32 v7, v7, v11
	v_cvt_pk_bf16_f32 v6, v6, v7
	v_fma_f32 v7, -v13, v14, 1.0
	v_fmac_f32_e32 v14, v7, v14
	v_div_scale_f32 v7, vcc, 2.0, v12, 2.0
	v_mul_f32_e32 v11, v7, v14
	v_fma_f32 v15, -v13, v11, v7
	v_fmac_f32_e32 v11, v15, v14
	v_fma_f32 v7, -v13, v11, v7
	v_mul_f32_e32 v13, 0x3d372713, v9
	v_mul_f32_e32 v13, v9, v13
	v_fma_f32 v13, v9, v13, v9
	v_mul_f32_e32 v13, 0x3f4c422a, v13
	v_add_f32_e32 v13, v13, v13
	v_mul_f32_e32 v13, 0x3fb8aa3b, v13
	v_exp_f32_e32 v13, v13
	v_div_fmas_f32 v7, v7, v14, v11
; #define LAS __attribute__((address_space(3)))
; __device__ __forceinline__ unsigned cvt_pk_bf16(float lo, float hi) { unsigned r; asm volatile("v_cvt_pk_bf16_f32 %0, %1, %2" : "=v"(r) : "v"(lo), "v"(hi)); return r; }
; __device__ __forceinline__ float gelu_tanh(float x) { const float z = 0.7978845608f * (x + 0.044715f * x * x * x); const float th = 1.0f - 2.0f / (__expf(2.0f * z) + 1.0f); return 0.5f * x * (1.0f + th); }
; #define PG8_WAIT_V(n) asm volatile("s_waitcnt vmcnt(" #n ")" ::: "memory")
; #define PG8_BAR __builtin_amdgcn_s_barrier()
;     __device__ __forceinline__ void operator()(const f32x4 (&acc)[2][2][4][2], const Unit& u, int ui, const LAS float* rtab, int wr, int wc, int fr, int fq) const {
;         const int g = u.pm; const int n0 = wr * 64 + fr; const int lc0 = (u.pn & 1) * 256 + wc * 32 + 8 * fq;
; #pragma unroll
;         for (int ai = 0; ai < 2; ++ai)
; #pragma unroll
;             for (int m = 0; m < 4; ++m) {
;                 const int n = n0 + ai * HALF + m * 16;
; #pragma unroll
;                 for (int bj = 0; bj < 2; ++bj) {
;                     const int lc = lc0 + bj * HALF, t = lc >> 4, co = lc & 15; const int token = n * 32 + t;
;                     const f32x4 a0 = acc[ai][bj][m][0], a1 = acc[ai][bj][m][1];
;                     u32x4 w; w.x = cvt_pk_bf16(gelu_tanh(a0[0]), gelu_tanh(a0[1])); w.y = cvt_pk_bf16(gelu_tanh(a0[2]), gelu_tanh(a0[3]));
;                     w.z = cvt_pk_bf16(gelu_tanh(a1[0]), gelu_tanh(a1[1])); w.w = cvt_pk_bf16(gelu_tanh(a1[2]), gelu_tanh(a1[3]));
;                     *(u32x4*)(Y + (size_t)token * 1024 + 16 * g + co) = w;
;                 }
;             }
;     }
; template <class Epi, class Sched>
; __device__ __forceinline__ void gemm_phase(LAS unsigned char* lds, const Gemm g, const Sched& S, const Epi& E) {
;     ...
;     PG8_WAIT_V(0);
;     if (wr == 0) PG8_BAR;
	v_div_fixup_f32 v7, v7, v12, 2.0
	v_sub_f32_e32 v7, 1.0, v7
	v_add_f32_e32 v11, 1.0, v13
	v_div_scale_f32 v12, s[28:29], v11, v11, 2.0
	v_rcp_f32_e32 v13, v12
	v_mul_f32_e32 v8, 0.5, v8
	v_add_f32_e32 v7, 1.0, v7
	v_mul_f32_e32 v7, v8, v7
	v_fma_f32 v8, -v12, v13, 1.0
	v_fmac_f32_e32 v13, v8, v13
	v_div_scale_f32 v8, vcc, 2.0, v11, 2.0
	v_mul_f32_e32 v14, v8, v13
	v_fma_f32 v15, -v12, v14, v8
	v_fmac_f32_e32 v14, v15, v13
	v_fma_f32 v8, -v12, v14, v8
	v_mul_f32_e32 v12, 0x3d372713, v2
	v_mul_f32_e32 v12, v2, v12
	v_fma_f32 v12, v2, v12, v2
	v_mul_f32_e32 v12, 0x3f4c422a, v12
	v_add_f32_e32 v12, v12, v12
	v_mul_f32_e32 v12, 0x3fb8aa3b, v12
	v_exp_f32_e32 v12, v12
	v_div_fmas_f32 v8, v8, v13, v14
	v_div_fixup_f32 v8, v8, v11, 2.0
	v_sub_f32_e32 v8, 1.0, v8
	v_add_f32_e32 v11, 1.0, v12
	v_div_scale_f32 v12, s[28:29], v11, v11, 2.0
	v_rcp_f32_e32 v13, v12
	v_mul_f32_e32 v9, 0.5, v9
	v_add_f32_e32 v8, 1.0, v8
	v_mul_f32_e32 v8, v9, v8
	v_cvt_pk_bf16_f32 v7, v7, v8
	v_fma_f32 v8, -v12, v13, 1.0
	v_fmac_f32_e32 v13, v8, v13
	v_div_scale_f32 v8, vcc, 2.0, v11, 2.0
	v_mul_f32_e32 v9, v8, v13
	v_fma_f32 v14, -v12, v9, v8
	v_fmac_f32_e32 v9, v14, v13
	v_fma_f32 v8, -v12, v9, v8
	v_mul_f32_e32 v12, 0x3d372713, v3
	v_mul_f32_e32 v12, v3, v12
	v_fma_f32 v12, v3, v12, v3
	v_mul_f32_e32 v12, 0x3f4c422a, v12
	v_add_f32_e32 v12, v12, v12
	v_mul_f32_e32 v12, 0x3fb8aa3b, v12
	v_exp_f32_e32 v12, v12
	v_div_fmas_f32 v8, v8, v13, v9
	v_div_fixup_f32 v8, v8, v11, 2.0
	v_sub_f32_e32 v8, 1.0, v8
	v_add_f32_e32 v9, 1.0, v12
	v_div_scale_f32 v11, s[28:29], v9, v9, 2.0
	v_rcp_f32_e32 v12, v11
	v_mul_f32_e32 v2, 0.5, v2
	v_add_f32_e32 v8, 1.0, v8
	v_mul_f32_e32 v2, v2, v8
	v_fma_f32 v8, -v11, v12, 1.0
	v_fmac_f32_e32 v12, v8, v12
	v_div_scale_f32 v8, vcc, 2.0, v9, 2.0
	v_mul_f32_e32 v13, v8, v12
	v_fma_f32 v14, -v11, v13, v8
	v_fmac_f32_e32 v13, v14, v12
	v_fma_f32 v8, -v11, v13, v8
	v_mul_f32_e32 v11, 0x3d372713, v4
	v_mul_f32_e32 v11, v4, v11
	v_fma_f32 v11, v4, v11, v4
	v_mul_f32_e32 v11, 0x3f4c422a, v11
	v_add_f32_e32 v11, v11, v11
	v_mul_f32_e32 v11, 0x3fb8aa3b, v11
	v_exp_f32_e32 v11, v11
	v_div_fmas_f32 v8, v8, v12, v13
	v_div_fixup_f32 v8, v8, v9, 2.0
	v_sub_f32_e32 v8, 1.0, v8
	v_add_f32_e32 v9, 1.0, v11
	v_div_scale_f32 v11, s[28:29], v9, v9, 2.0
	v_rcp_f32_e32 v12, v11
	v_mul_f32_e32 v3, 0.5, v3
	v_add_f32_e32 v8, 1.0, v8
	v_mul_f32_e32 v3, v3, v8
	v_cvt_pk_bf16_f32 v8, v2, v3
	v_fma_f32 v2, -v11, v12, 1.0
	v_fmac_f32_e32 v12, v2, v12
	v_div_scale_f32 v2, vcc, 2.0, v9, 2.0
	v_mul_f32_e32 v3, v2, v12
	v_fma_f32 v13, -v11, v3, v2
	v_fmac_f32_e32 v3, v13, v12
	v_fma_f32 v2, -v11, v3, v2
	v_mul_f32_e32 v11, 0x3d372713, v5
	v_mul_f32_e32 v11, v5, v11
	v_fma_f32 v11, v5, v11, v5
	v_mul_f32_e32 v11, 0x3f4c422a, v11
	v_add_f32_e32 v11, v11, v11
	v_mul_f32_e32 v11, 0x3fb8aa3b, v11
	v_exp_f32_e32 v11, v11
	v_div_fmas_f32 v2, v2, v12, v3
	v_div_fixup_f32 v2, v2, v9, 2.0
	v_sub_f32_e32 v2, 1.0, v2
	v_add_f32_e32 v3, 1.0, v11
	v_div_scale_f32 v9, s[28:29], v3, v3, 2.0
	v_rcp_f32_e32 v11, v9
	v_mul_f32_e32 v4, 0.5, v4
	v_add_f32_e32 v2, 1.0, v2
	v_mul_f32_e32 v2, v4, v2
	v_fma_f32 v4, -v9, v11, 1.0
	v_fmac_f32_e32 v11, v4, v11
	v_div_scale_f32 v4, vcc, 2.0, v3, 2.0
	v_mul_f32_e32 v12, v4, v11
	v_fma_f32 v13, -v9, v12, v4
	v_fmac_f32_e32 v12, v13, v11
	v_fma_f32 v4, -v9, v12, v4
	v_div_fmas_f32 v4, v4, v11, v12
	v_div_fixup_f32 v3, v4, v3, 2.0
	v_sub_f32_e32 v3, 1.0, v3
	v_or_b32_e32 v10, v124, v153
	v_mul_f32_e32 v4, 0.5, v5
	v_add_f32_e32 v3, 1.0, v3
	v_mul_f32_e32 v3, v4, v3
	v_ashrrev_i32_e32 v11, 31, v10
	v_cvt_pk_bf16_f32 v9, v2, v3
	v_lshlrev_b64 v[2:3], 11, v[10:11]
	v_lshl_add_u64 v[2:3], v[138:139], 0, v[2:3]
	s_mov_b64 s[42:43], 0
	s_and_b64 vcc, exec, s[40:41]
	v_readlane_b32 s26, v254, 32
	global_store_dwordx4 v[2:3], v[6:9], off
	s_cbranch_vccz .LBB0_594
	s_waitcnt vmcnt(0)
	s_cmpk_gt_u32 s12, 0xff
	s_cbranch_scc1 .LBB0_599
	s_barrier

; #define PG8_STAGE(bufoff, gbase, voff) do { _Pragma("unroll") for (int _i = 0; _i < 2; ++_i) \
;         __builtin_amdgcn_global_load_lds((const unsigned*)((const char*)(gbase) + (voff)[_i]), (LAS unsigned*)(lds + (bufoff) + ldsw + _i * 8192), 16, 0, 0); } while (0)
; #define PG8_LDA(dst, b, h) do { _Pragma("unroll") for (int m = 0; m < 4; ++m) _Pragma("unroll") for (int k = 0; k < 2; ++k) dst[m][k] = *(const LAS bf16x8*)(lds + PG8_SA(b, h) + aoff + m * 2048 + k * 1024); } while (0)
; #define PG8_LDB(dst, b, h) do { _Pragma("unroll") for (int n = 0; n < 2; ++n) _Pragma("unroll") for (int k = 0; k < 2; ++k) dst[n][k] = *(const LAS bf16x8*)(lds + PG8_SB(b, h) + boff + n * 2048 + k * 1024); } while (0)
; #define PG8_MMA(ai, bj, At, Bt) do { __builtin_amdgcn_s_setprio(1); _Pragma("unroll") for (int m = 0; m < 4; ++m) _Pragma("unroll") for (int n = 0; n < 2; ++n) _Pragma("unroll") for (int k = 0; k < 2; ++k) \
;         acc[ai][bj][m][n] = __builtin_amdgcn_mfma_f32_16x16x32_bf16(Bt[n][k], At[m][k], acc[ai][bj][m][n], 0, 0, 0); __builtin_amdgcn_s_setprio(0); } while (0)
; #define PG8_WAIT_L(n) asm volatile("s_waitcnt lgkmcnt(" #n ")" ::: "memory")
; #define PG8_BAR __builtin_amdgcn_s_barrier()
; #define PG8_SCHED __builtin_amdgcn_sched_barrier(0)
; template <class Epi, class Sched>
; __device__ __forceinline__ void gemm_phase(LAS unsigned char* lds, const Gemm g, const Sched& S, const Epi& E) {
;     ...
;             PG8_LDB(B0, 0, 0); PG8_SCHED; PG8_LDA(At, 0, 0); PG8_STAGE(PG8_SA(1, 1), a1 + hstepA, voffA);
;             PG8_WAIT_L(8); PG8_BAR; PG8_WAIT_L(0); PG8_MMA(0, 0, At, B0); PG8_BAR; PG8_SCHED;
;             PG8_LDB(B1, 0, 1); PG8_STAGE(PG8_SB(0, 0), b2, voffB);
;             PG8_BAR; PG8_WAIT_L(0); PG8_MMA(0, 1, At, B1); PG8_BAR;
;             PG8_LDA(At, 0, 1); PG8_STAGE(PG8_SA(0, 0), a2, voffA);
;             PG8_BAR; PG8_WAIT_L(0); PG8_MMA(1, 0, At, B0); PG8_BAR; PG8_SCHED;
.LBB0_668:
	s_add_u32 s23, s20, 0xfffc0080
	s_addc_u32 s34, s21, -1
	s_add_i32 s43, 0, 0x10000
	v_add_u32_e32 v153, s43, v150
	ds_read_b128 v[142:145], v153
	ds_read_b128 v[146:149], v153 offset:1024
	ds_read_b128 v[170:173], v153 offset:2048
	ds_read_b128 v[174:177], v153 offset:3072
	s_cmp_eq_u32 s31, 12
	s_cselect_b32 s49, s24, s34
	s_cselect_b32 s48, s25, s23
	s_cselect_b32 s37, s1, s29
	s_cselect_b32 s36, s26, s28
	v_lshl_add_u64 v[198:199], s[20:21], 0, v[138:139]
	s_add_i32 m0, s52, 0xc000
	ds_read_b128 v[178:181], v152
	ds_read_b128 v[182:185], v152 offset:1024
	ds_read_b128 v[186:189], v152 offset:2048
	ds_read_b128 v[190:193], v152 offset:3072
	ds_read_b128 v[194:197], v152 offset:4096
	ds_read_b128 v[210:213], v152 offset:5120
	ds_read_b128 v[214:217], v152 offset:6144
	ds_read_b128 v[218:221], v152 offset:7168
	global_load_lds_dwordx4 v[198:199], off
	s_add_i32 m0, s52, 0xe000
	v_lshl_add_u64 v[198:199], s[20:21], 0, v[140:141]
	global_load_lds_dwordx4 v[198:199], off
	s_waitcnt lgkmcnt(8)
	s_barrier
	s_waitcnt lgkmcnt(0)
	v_mfma_f32_16x16x32_bf16 v[126:129], v[142:145], v[178:181], v[126:129]
	v_mfma_f32_16x16x32_bf16 v[122:125], v[170:173], v[178:181], v[122:125]
	v_mfma_f32_16x16x32_bf16 v[110:113], v[142:145], v[186:189], v[110:113]
	v_mfma_f32_16x16x32_bf16 v[106:109], v[170:173], v[186:189], v[106:109]
	v_mfma_f32_16x16x32_bf16 v[94:97], v[142:145], v[194:197], v[94:97]
	v_mfma_f32_16x16x32_bf16 v[90:93], v[170:173], v[194:197], v[90:93]
	v_mfma_f32_16x16x32_bf16 v[78:81], v[142:145], v[214:217], v[78:81]
	v_mfma_f32_16x16x32_bf16 v[74:77], v[170:173], v[214:217], v[74:77]
	v_mfma_f32_16x16x32_bf16 v[126:129], v[146:149], v[182:185], v[126:129]
	v_mfma_f32_16x16x32_bf16 v[122:125], v[174:177], v[182:185], v[122:125]
	v_mfma_f32_16x16x32_bf16 v[110:113], v[146:149], v[190:193], v[110:113]
	v_mfma_f32_16x16x32_bf16 v[106:109], v[174:177], v[190:193], v[106:109]
	v_mfma_f32_16x16x32_bf16 v[94:97], v[146:149], v[210:213], v[94:97]
	v_mfma_f32_16x16x32_bf16 v[90:93], v[174:177], v[210:213], v[90:93]
	v_mfma_f32_16x16x32_bf16 v[78:81], v[146:149], v[218:221], v[78:81]
	v_mfma_f32_16x16x32_bf16 v[74:77], v[174:177], v[218:221], v[74:77]
	s_barrier
	s_add_i32 s23, 0, 0x14000
	s_add_i32 s34, s43, s51
	v_add_u32_e32 v153, s23, v150
	v_lshl_add_u64 v[198:199], s[36:37], 0, v[134:135]
	s_mov_b32 m0, s34
	ds_read_b128 v[222:225], v153
	ds_read_b128 v[226:229], v153 offset:1024
	ds_read_b128 v[230:233], v153 offset:2048
	ds_read_b128 v[234:237], v153 offset:3072
	global_load_lds_dwordx4 v[198:199], off
	s_add_i32 m0, s34, 0x2000
	v_lshl_add_u64 v[238:239], s[36:37], 0, v[130:131]
	global_load_lds_dwordx4 v[238:239], off
	s_barrier
	s_waitcnt lgkmcnt(0)
	v_mfma_f32_16x16x32_bf16 v[118:121], v[222:225], v[178:181], v[118:121]
	v_mfma_f32_16x16x32_bf16 v[114:117], v[230:233], v[178:181], v[114:117]
	v_mfma_f32_16x16x32_bf16 v[102:105], v[222:225], v[186:189], v[102:105]
	v_mfma_f32_16x16x32_bf16 v[98:101], v[230:233], v[186:189], v[98:101]
	v_mfma_f32_16x16x32_bf16 v[86:89], v[222:225], v[194:197], v[86:89]
	v_mfma_f32_16x16x32_bf16 v[82:85], v[230:233], v[194:197], v[82:85]
	v_mfma_f32_16x16x32_bf16 v[70:73], v[222:225], v[214:217], v[70:73]
	v_mfma_f32_16x16x32_bf16 v[66:69], v[230:233], v[214:217], v[66:69]
	v_mfma_f32_16x16x32_bf16 v[118:121], v[226:229], v[182:185], v[118:121]
	v_mfma_f32_16x16x32_bf16 v[114:117], v[234:237], v[182:185], v[114:117]
	v_mfma_f32_16x16x32_bf16 v[102:105], v[226:229], v[190:193], v[102:105]
	v_mfma_f32_16x16x32_bf16 v[98:101], v[234:237], v[190:193], v[98:101]
	v_mfma_f32_16x16x32_bf16 v[86:89], v[226:229], v[210:213], v[86:89]
	v_mfma_f32_16x16x32_bf16 v[82:85], v[234:237], v[210:213], v[82:85]
	v_mfma_f32_16x16x32_bf16 v[70:73], v[226:229], v[218:221], v[70:73]
	v_mfma_f32_16x16x32_bf16 v[66:69], v[234:237], v[218:221], v[66:69]
	s_mov_b32 m0, s52
	v_lshl_add_u64 v[240:241], s[48:49], 0, v[136:137]
	s_barrier
	ds_read_b128 v[178:181], v152 offset:16384
	ds_read_b128 v[182:185], v152 offset:17408
	ds_read_b128 v[186:189], v152 offset:18432
	ds_read_b128 v[190:193], v152 offset:19456
	ds_read_b128 v[194:197], v152 offset:20480
	ds_read_b128 v[210:213], v152 offset:21504
	ds_read_b128 v[214:217], v152 offset:22528
	ds_read_b128 v[218:221], v152 offset:23552
	global_load_lds_dwordx4 v[240:241], off
	s_mov_b32 m0, s53
	v_lshl_add_u64 v[242:243], s[48:49], 0, v[132:133]
	global_load_lds_dwordx4 v[242:243], off
	s_barrier
	s_waitcnt lgkmcnt(0)
	v_mfma_f32_16x16x32_bf16 v[62:65], v[142:145], v[178:181], v[62:65]
	v_mfma_f32_16x16x32_bf16 v[58:61], v[170:173], v[178:181], v[58:61]
	v_mfma_f32_16x16x32_bf16 v[46:49], v[142:145], v[186:189], v[46:49]
	v_mfma_f32_16x16x32_bf16 v[42:45], v[170:173], v[186:189], v[42:45]
	v_mfma_f32_16x16x32_bf16 v[30:33], v[142:145], v[194:197], v[30:33]
	v_mfma_f32_16x16x32_bf16 v[26:29], v[170:173], v[194:197], v[26:29]
	v_mfma_f32_16x16x32_bf16 v[14:17], v[142:145], v[214:217], v[14:17]
	v_mfma_f32_16x16x32_bf16 v[10:13], v[170:173], v[214:217], v[10:13]
	v_mfma_f32_16x16x32_bf16 v[62:65], v[146:149], v[182:185], v[62:65]
	v_mfma_f32_16x16x32_bf16 v[58:61], v[174:177], v[182:185], v[58:61]
	v_mfma_f32_16x16x32_bf16 v[46:49], v[146:149], v[190:193], v[46:49]
	v_mfma_f32_16x16x32_bf16 v[42:45], v[174:177], v[190:193], v[42:45]
	v_mfma_f32_16x16x32_bf16 v[30:33], v[146:149], v[210:213], v[30:33]
	v_mfma_f32_16x16x32_bf16 v[26:29], v[174:177], v[210:213], v[26:29]
	v_mfma_f32_16x16x32_bf16 v[14:17], v[146:149], v[218:221], v[14:17]
	v_mfma_f32_16x16x32_bf16 v[10:13], v[174:177], v[218:221], v[10:13]
	s_barrier
; #define PG8_STAGE(bufoff, gbase, voff) do { _Pragma("unroll") for (int _i = 0; _i < 2; ++_i) \
;         __builtin_amdgcn_global_load_lds((const unsigned*)((const char*)(gbase) + (voff)[_i]), (LAS unsigned*)(lds + (bufoff) + ldsw + _i * 8192), 16, 0, 0); } while (0)
; #define PG8_LDA(dst, b, h) do { _Pragma("unroll") for (int m = 0; m < 4; ++m) _Pragma("unroll") for (int k = 0; k < 2; ++k) dst[m][k] = *(const LAS bf16x8*)(lds + PG8_SA(b, h) + aoff + m * 2048 + k * 1024); } while (0)
; #define PG8_LDB(dst, b, h) do { _Pragma("unroll") for (int n = 0; n < 2; ++n) _Pragma("unroll") for (int k = 0; k < 2; ++k) dst[n][k] = *(const LAS bf16x8*)(lds + PG8_SB(b, h) + boff + n * 2048 + k * 1024); } while (0)
; #define PG8_MMA(ai, bj, At, Bt) do { __builtin_amdgcn_s_setprio(1); _Pragma("unroll") for (int m = 0; m < 4; ++m) _Pragma("unroll") for (int n = 0; n < 2; ++n) _Pragma("unroll") for (int k = 0; k < 2; ++k) \
;         acc[ai][bj][m][n] = __builtin_amdgcn_mfma_f32_16x16x32_bf16(Bt[n][k], At[m][k], acc[ai][bj][m][n], 0, 0, 0); __builtin_amdgcn_s_setprio(0); } while (0)
; #define PG8_WAIT_V(n) asm volatile("s_waitcnt vmcnt(" #n ")" ::: "memory")
; #define PG8_WAIT_L(n) asm volatile("s_waitcnt lgkmcnt(" #n ")" ::: "memory")
; #define PG8_BAR __builtin_amdgcn_s_barrier()
; #define PG8_SCHED __builtin_amdgcn_sched_barrier(0)
; template <class Epi, class Sched>
; __device__ __forceinline__ void gemm_phase(LAS unsigned char* lds, const Gemm g, const Sched& S, const Epi& E) {
;     ...
;             PG8_STAGE(PG8_SB(0, 1), b2 + hstepB, voffB);
;             PG8_WAIT_V(6); PG8_BAR; PG8_MMA(1, 1, At, B1); PG8_BAR;
;             PG8_LDB(B0, 1, 0); PG8_SCHED; PG8_LDA(At, 1, 0); PG8_STAGE(PG8_SA(0, 1), a2 + hstepA, voffA);
;             PG8_WAIT_L(8); PG8_BAR; PG8_WAIT_L(0); PG8_MMA(0, 0, At, B0); PG8_BAR; PG8_SCHED;
;             PG8_LDB(B1, 1, 1); PG8_STAGE(PG8_SB(1, 0), b3, voffB);
;             PG8_BAR; PG8_WAIT_L(0); PG8_MMA(0, 1, At, B1); PG8_BAR;
;             PG8_LDA(At, 1, 1); PG8_STAGE(PG8_SA(1, 0), a3, voffA);
	s_add_u32 s66, s36, 0x40000
	s_addc_u32 s67, s37, 0
	s_add_i32 s23, s23, s51
	s_mov_b32 m0, s23
	v_lshl_add_u64 v[142:143], s[66:67], 0, v[134:135]
	global_load_lds_dwordx4 v[142:143], off
	s_add_i32 m0, s23, 0x2000
	v_lshl_add_u64 v[142:143], s[66:67], 0, v[130:131]
	global_load_lds_dwordx4 v[142:143], off
	s_waitcnt vmcnt(6)
	s_barrier
	v_mfma_f32_16x16x32_bf16 v[54:57], v[222:225], v[178:181], v[54:57]
	v_mfma_f32_16x16x32_bf16 v[50:53], v[230:233], v[178:181], v[50:53]
	v_mfma_f32_16x16x32_bf16 v[38:41], v[222:225], v[186:189], v[38:41]
	v_mfma_f32_16x16x32_bf16 v[34:37], v[230:233], v[186:189], v[34:37]
	v_mfma_f32_16x16x32_bf16 v[22:25], v[222:225], v[194:197], v[22:25]
	v_mfma_f32_16x16x32_bf16 v[18:21], v[230:233], v[194:197], v[18:21]
	v_mfma_f32_16x16x32_bf16 v[6:9], v[222:225], v[214:217], v[6:9]
	v_mfma_f32_16x16x32_bf16 v[2:5], v[230:233], v[214:217], v[2:5]
	v_mfma_f32_16x16x32_bf16 v[54:57], v[226:229], v[182:185], v[54:57]
	v_mfma_f32_16x16x32_bf16 v[50:53], v[234:237], v[182:185], v[50:53]
	v_mfma_f32_16x16x32_bf16 v[38:41], v[226:229], v[190:193], v[38:41]
	v_mfma_f32_16x16x32_bf16 v[34:37], v[234:237], v[190:193], v[34:37]
	v_mfma_f32_16x16x32_bf16 v[22:25], v[226:229], v[210:213], v[22:25]
	v_mfma_f32_16x16x32_bf16 v[18:21], v[234:237], v[210:213], v[18:21]
	v_mfma_f32_16x16x32_bf16 v[6:9], v[226:229], v[218:221], v[6:9]
	v_mfma_f32_16x16x32_bf16 v[2:5], v[234:237], v[218:221], v[2:5]
	s_add_i32 s23, 0, 0x18000
	v_add_u32_e32 v153, s23, v150
	s_barrier
	ds_read_b128 v[142:145], v153
	ds_read_b128 v[146:149], v153 offset:1024
	ds_read_b128 v[170:173], v153 offset:2048
	ds_read_b128 v[174:177], v153 offset:3072
	s_add_u32 s48, s48, 0x40000
	s_addc_u32 s49, s49, 0
	s_mov_b32 m0, s54
	v_lshl_add_u64 v[222:223], s[48:49], 0, v[136:137]
	ds_read_b128 v[178:181], v152 offset:32768
	ds_read_b128 v[182:185], v152 offset:33792
	ds_read_b128 v[186:189], v152 offset:34816
	ds_read_b128 v[190:193], v152 offset:35840
	ds_read_b128 v[194:197], v152 offset:36864
	ds_read_b128 v[210:213], v152 offset:37888
	ds_read_b128 v[214:217], v152 offset:38912
	ds_read_b128 v[218:221], v152 offset:39936
	global_load_lds_dwordx4 v[222:223], off
	s_mov_b32 m0, s55
	v_lshl_add_u64 v[222:223], s[48:49], 0, v[132:133]
	global_load_lds_dwordx4 v[222:223], off
	s_waitcnt lgkmcnt(8)
	s_barrier
	s_waitcnt lgkmcnt(0)
	v_mfma_f32_16x16x32_bf16 v[126:129], v[142:145], v[178:181], v[126:129]
	v_mfma_f32_16x16x32_bf16 v[122:125], v[170:173], v[178:181], v[122:125]
	v_mfma_f32_16x16x32_bf16 v[110:113], v[142:145], v[186:189], v[110:113]
	v_mfma_f32_16x16x32_bf16 v[106:109], v[170:173], v[186:189], v[106:109]
	v_mfma_f32_16x16x32_bf16 v[94:97], v[142:145], v[194:197], v[94:97]
	v_mfma_f32_16x16x32_bf16 v[90:93], v[170:173], v[194:197], v[90:93]
	v_mfma_f32_16x16x32_bf16 v[78:81], v[142:145], v[214:217], v[78:81]
	v_mfma_f32_16x16x32_bf16 v[74:77], v[170:173], v[214:217], v[74:77]
	v_mfma_f32_16x16x32_bf16 v[126:129], v[146:149], v[182:185], v[126:129]
	v_mfma_f32_16x16x32_bf16 v[122:125], v[174:177], v[182:185], v[122:125]
	v_mfma_f32_16x16x32_bf16 v[110:113], v[146:149], v[190:193], v[110:113]
	v_mfma_f32_16x16x32_bf16 v[106:109], v[174:177], v[190:193], v[106:109]
	v_mfma_f32_16x16x32_bf16 v[94:97], v[146:149], v[210:213], v[94:97]
	v_mfma_f32_16x16x32_bf16 v[90:93], v[174:177], v[210:213], v[90:93]
	v_mfma_f32_16x16x32_bf16 v[78:81], v[146:149], v[218:221], v[78:81]
	v_mfma_f32_16x16x32_bf16 v[74:77], v[174:177], v[218:221], v[74:77]
	s_barrier
	s_add_i32 s34, 0, 0x1c000
	s_add_i32 s23, s23, s51
	v_add_u32_e32 v153, s34, v150
	v_lshl_add_u64 v[198:199], v[198:199], 0, s[10:11]
	s_mov_b32 m0, s23
	ds_read_b128 v[222:225], v153
	ds_read_b128 v[226:229], v153 offset:1024
	ds_read_b128 v[230:233], v153 offset:2048
	ds_read_b128 v[234:237], v153 offset:3072
	global_load_lds_dwordx4 v[198:199], off
	s_add_i32 m0, s23, 0x2000
	v_lshl_add_u64 v[198:199], v[238:239], 0, s[10:11]
	global_load_lds_dwordx4 v[198:199], off
	s_barrier
	s_waitcnt lgkmcnt(0)
	v_mfma_f32_16x16x32_bf16 v[118:121], v[222:225], v[178:181], v[118:121]
	v_mfma_f32_16x16x32_bf16 v[114:117], v[230:233], v[178:181], v[114:117]
	v_mfma_f32_16x16x32_bf16 v[102:105], v[222:225], v[186:189], v[102:105]
	v_mfma_f32_16x16x32_bf16 v[98:101], v[230:233], v[186:189], v[98:101]
	v_mfma_f32_16x16x32_bf16 v[86:89], v[222:225], v[194:197], v[86:89]
	v_mfma_f32_16x16x32_bf16 v[82:85], v[230:233], v[194:197], v[82:85]
	v_mfma_f32_16x16x32_bf16 v[70:73], v[222:225], v[214:217], v[70:73]
	v_mfma_f32_16x16x32_bf16 v[66:69], v[230:233], v[214:217], v[66:69]
	v_mfma_f32_16x16x32_bf16 v[118:121], v[226:229], v[182:185], v[118:121]
	v_mfma_f32_16x16x32_bf16 v[114:117], v[234:237], v[182:185], v[114:117]
	v_mfma_f32_16x16x32_bf16 v[102:105], v[226:229], v[190:193], v[102:105]
	v_mfma_f32_16x16x32_bf16 v[98:101], v[234:237], v[190:193], v[98:101]
	v_mfma_f32_16x16x32_bf16 v[86:89], v[226:229], v[210:213], v[86:89]
	v_mfma_f32_16x16x32_bf16 v[82:85], v[234:237], v[210:213], v[82:85]
	v_mfma_f32_16x16x32_bf16 v[70:73], v[226:229], v[218:221], v[70:73]
	v_mfma_f32_16x16x32_bf16 v[66:69], v[234:237], v[218:221], v[66:69]
	s_mov_b32 m0, s56
	v_lshl_add_u64 v[198:199], v[240:241], 0, s[10:11]
	s_barrier
	ds_read_b128 v[178:181], v152 offset:49152
	ds_read_b128 v[182:185], v152 offset:50176
	ds_read_b128 v[186:189], v152 offset:51200
	ds_read_b128 v[190:193], v152 offset:52224
	ds_read_b128 v[194:197], v152 offset:53248
	ds_read_b128 v[210:213], v152 offset:54272
	ds_read_b128 v[214:217], v152 offset:55296
	ds_read_b128 v[218:221], v152 offset:56320
	global_load_lds_dwordx4 v[198:199], off
	s_mov_b32 m0, s57
	v_lshl_add_u64 v[198:199], v[242:243], 0, s[10:11]
	global_load_lds_dwordx4 v[198:199], off
	s_barrier
; #define LAS __attribute__((address_space(3)))
; __device__ __forceinline__ float bf_lo(unsigned w) { return __uint_as_float(w << 16); }
; __device__ __forceinline__ float bf_hi(unsigned w) { return __uint_as_float(w & 0xffff0000u); }
; #define PG8_STAGE(bufoff, gbase, voff) do { _Pragma("unroll") for (int _i = 0; _i < 2; ++_i) \
;         __builtin_amdgcn_global_load_lds((const unsigned*)((const char*)(gbase) + (voff)[_i]), (LAS unsigned*)(lds + (bufoff) + ldsw + _i * 8192), 16, 0, 0); } while (0)
; #define PG8_LDA(dst, b, h) do { _Pragma("unroll") for (int m = 0; m < 4; ++m) _Pragma("unroll") for (int k = 0; k < 2; ++k) dst[m][k] = *(const LAS bf16x8*)(lds + PG8_SA(b, h) + aoff + m * 2048 + k * 1024); } while (0)
; #define PG8_BAR __builtin_amdgcn_s_barrier()
;     __device__ __forceinline__ void operator()(const f32x4 (&acc)[2][2][4][2], const Unit& u, int ui, const LAS float* rtab, int wr, int wc, int fr, int fq) const {
;         const int row0 = u.pm * BM + wr * 64 + fr, col0 = u.pn * BM + wc * 32 + 8 * fq;
; #pragma unroll
;         for (int ai = 0; ai < 2; ++ai)
; #pragma unroll
;             for (int m = 0; m < 4; ++m) {
;                 const int row = row0 + ai * HALF + m * 16;
; #pragma unroll
;                 for (int bj = 0; bj < 2; ++bj) {
;                     const int col = col0 + bj * HALF; const u32x4 yv = *(const u32x4*)(Y + (size_t)row * 1024 + col);
;                     const f32x4 a0 = acc[ai][bj][m][0], a1 = acc[ai][bj][m][1]; float o[8];
;                     const float yy[8] = {bf_lo(yv.x), bf_hi(yv.x), bf_lo(yv.y), bf_hi(yv.y), bf_lo(yv.z), bf_hi(yv.z), bf_lo(yv.w), bf_hi(yv.w)};
; #pragma unroll
;                     for (int e = 0; e < 4; ++e) { o[e] = yy[e] / (1.0f + __expf(-a0[e])); o[4 + e] = yy[4 + e] / (1.0f + __expf(-a1[e])); }
; template <class Epi, class Sched>
; __device__ __forceinline__ void gemm_phase(LAS unsigned char* lds, const Gemm g, const Sched& S, const Epi& E) {
;     ...
;             PG8_BAR; PG8_WAIT_L(0); PG8_MMA(0, 1, At, B1); PG8_BAR;
;             PG8_LDA(At, 1, 1); PG8_STAGE(PG8_SA(1, 0), a3, voffA);
;             PG8_BAR; PG8_WAIT_L(0); PG8_MMA(1, 0, At, B0); PG8_BAR; PG8_SCHED;
;             PG8_STAGE(PG8_SB(1, 1), b3 + hstepB, voffB);
;             PG8_WAIT_V(6); PG8_BAR; PG8_MMA(1, 1, At, B1); PG8_BAR;
;         }
;         E(acc, cur, ui, (const LAS float*)(lds + STAGE_BYTES), wr, wc, fr, fq);
	s_waitcnt lgkmcnt(0)
	v_mfma_f32_16x16x32_bf16 v[62:65], v[142:145], v[178:181], v[62:65]
	v_mfma_f32_16x16x32_bf16 v[58:61], v[170:173], v[178:181], v[58:61]
	v_mfma_f32_16x16x32_bf16 v[46:49], v[142:145], v[186:189], v[46:49]
	v_mfma_f32_16x16x32_bf16 v[42:45], v[170:173], v[186:189], v[42:45]
	v_mfma_f32_16x16x32_bf16 v[30:33], v[142:145], v[194:197], v[30:33]
	v_mfma_f32_16x16x32_bf16 v[26:29], v[170:173], v[194:197], v[26:29]
	v_mfma_f32_16x16x32_bf16 v[14:17], v[142:145], v[214:217], v[14:17]
	v_mfma_f32_16x16x32_bf16 v[10:13], v[170:173], v[214:217], v[10:13]
	v_mfma_f32_16x16x32_bf16 v[62:65], v[146:149], v[182:185], v[62:65]
	v_mfma_f32_16x16x32_bf16 v[58:61], v[174:177], v[182:185], v[58:61]
	v_mfma_f32_16x16x32_bf16 v[46:49], v[146:149], v[190:193], v[46:49]
	v_mfma_f32_16x16x32_bf16 v[42:45], v[174:177], v[190:193], v[42:45]
	v_mfma_f32_16x16x32_bf16 v[30:33], v[146:149], v[210:213], v[30:33]
	v_mfma_f32_16x16x32_bf16 v[26:29], v[174:177], v[210:213], v[26:29]
	v_mfma_f32_16x16x32_bf16 v[14:17], v[146:149], v[218:221], v[14:17]
	v_mfma_f32_16x16x32_bf16 v[10:13], v[174:177], v[218:221], v[10:13]
	s_barrier
	s_add_u32 s36, s36, 0x40080
	s_addc_u32 s37, s37, 0
	s_add_i32 s23, s34, s51
	s_mov_b32 m0, s23
	v_lshl_add_u64 v[142:143], s[36:37], 0, v[134:135]
	global_load_lds_dwordx4 v[142:143], off
	s_add_i32 m0, s23, 0x2000
	v_lshl_add_u64 v[142:143], s[36:37], 0, v[130:131]
	global_load_lds_dwordx4 v[142:143], off
	s_waitcnt vmcnt(6)
	s_barrier
	v_mfma_f32_16x16x32_bf16 v[54:57], v[222:225], v[178:181], v[54:57]
	v_mfma_f32_16x16x32_bf16 v[50:53], v[230:233], v[178:181], v[50:53]
	v_mfma_f32_16x16x32_bf16 v[38:41], v[222:225], v[186:189], v[38:41]
	v_mfma_f32_16x16x32_bf16 v[34:37], v[230:233], v[186:189], v[34:37]
	v_mfma_f32_16x16x32_bf16 v[22:25], v[222:225], v[194:197], v[22:25]
	v_mfma_f32_16x16x32_bf16 v[18:21], v[230:233], v[194:197], v[18:21]
	v_mfma_f32_16x16x32_bf16 v[6:9], v[222:225], v[214:217], v[6:9]
	v_mfma_f32_16x16x32_bf16 v[2:5], v[230:233], v[214:217], v[2:5]
	v_mfma_f32_16x16x32_bf16 v[54:57], v[226:229], v[182:185], v[54:57]
	v_mfma_f32_16x16x32_bf16 v[50:53], v[234:237], v[182:185], v[50:53]
	v_mfma_f32_16x16x32_bf16 v[38:41], v[226:229], v[190:193], v[38:41]
	v_mfma_f32_16x16x32_bf16 v[34:37], v[234:237], v[190:193], v[34:37]
	v_mfma_f32_16x16x32_bf16 v[22:25], v[226:229], v[210:213], v[22:25]
	v_mfma_f32_16x16x32_bf16 v[18:21], v[234:237], v[210:213], v[18:21]
	v_mfma_f32_16x16x32_bf16 v[6:9], v[226:229], v[218:221], v[6:9]
	v_mfma_f32_16x16x32_bf16 v[2:5], v[234:237], v[218:221], v[2:5]
	s_add_i32 s31, s31, 2
	s_add_u32 s20, s20, 0x100
	s_addc_u32 s21, s21, 0
	s_add_u32 s28, s28, 0x100
	s_addc_u32 s29, s29, 0
	s_cmp_gt_u32 s31, 13
	s_barrier
	s_cbranch_scc0 .LBB0_668
	v_lshl_add_u32 v144, s13, 8, v1
	v_lshl_or_b32 v142, s12, 8, v151
	v_ashrrev_i32_e32 v145, 31, v144
	v_lshlrev_b64 v[146:147], 11, v[144:145]
	v_ashrrev_i32_e32 v143, 31, v142
	v_lshl_add_u64 v[146:147], s[86:87], 0, v[146:147]
	v_lshlrev_b64 v[142:143], 1, v[142:143]
	v_lshl_add_u64 v[146:147], v[146:147], 0, v[142:143]
	global_load_dwordx4 v[170:173], v[146:147], off
	v_mul_f32_e32 v126, 0xbfb8aa3b, v126
	v_exp_f32_e32 v126, v126
	v_lshlrev_b64 v[148:149], 12, v[144:145]
	v_mul_f32_e32 v122, 0xbfb8aa3b, v122
	v_exp_f32_e32 v122, v122
	v_add_f32_e32 v126, 1.0, v126
	v_mul_f32_e32 v127, 0xbfb8aa3b, v127
	v_exp_f32_e32 v127, v127
	v_add_f32_e32 v122, 1.0, v122
	v_mul_f32_e32 v123, 0xbfb8aa3b, v123
	v_exp_f32_e32 v123, v123
	v_add_f32_e32 v127, 1.0, v127
	v_mul_f32_e32 v128, 0xbfb8aa3b, v128
	v_exp_f32_e32 v128, v128
	v_add_f32_e32 v123, 1.0, v123
	v_mul_f32_e32 v124, 0xbfb8aa3b, v124
	v_exp_f32_e32 v124, v124
	v_add_f32_e32 v128, 1.0, v128
	v_mul_f32_e32 v118, 0xbfb8aa3b, v118
	v_exp_f32_e32 v118, v118
	v_add_f32_e32 v124, 1.0, v124
	v_mul_f32_e32 v114, 0xbfb8aa3b, v114
	v_exp_f32_e32 v114, v114
	v_add_f32_e32 v118, 1.0, v118
	v_mul_f32_e32 v119, 0xbfb8aa3b, v119
	v_exp_f32_e32 v119, v119
	v_add_f32_e32 v114, 1.0, v114
	v_mul_f32_e32 v115, 0xbfb8aa3b, v115
	v_exp_f32_e32 v115, v115
	v_add_f32_e32 v119, 1.0, v119
	v_mul_f32_e32 v120, 0xbfb8aa3b, v120
	v_exp_f32_e32 v120, v120
	v_add_f32_e32 v115, 1.0, v115
	v_mul_f32_e32 v116, 0xbfb8aa3b, v116
	v_exp_f32_e32 v116, v116
	v_add_f32_e32 v120, 1.0, v120
	v_mul_f32_e32 v110, 0xbfb8aa3b, v110
	v_exp_f32_e32 v110, v110
	v_add_f32_e32 v116, 1.0, v116
	v_mul_f32_e32 v106, 0xbfb8aa3b, v106
	v_exp_f32_e32 v106, v106
	v_add_f32_e32 v110, 1.0, v110
	v_mul_f32_e32 v111, 0xbfb8aa3b, v111
	v_exp_f32_e32 v111, v111
	v_add_f32_e32 v106, 1.0, v106
	v_mul_f32_e32 v107, 0xbfb8aa3b, v107
	v_exp_f32_e32 v107, v107
	v_add_f32_e32 v111, 1.0, v111
	v_mul_f32_e32 v112, 0xbfb8aa3b, v112
	v_exp_f32_e32 v112, v112
	v_add_f32_e32 v107, 1.0, v107
	v_mul_f32_e32 v108, 0xbfb8aa3b, v108
	v_exp_f32_e32 v108, v108
	v_add_f32_e32 v112, 1.0, v112
	v_mul_f32_e32 v102, 0xbfb8aa3b, v102
	v_exp_f32_e32 v102, v102
	v_add_f32_e32 v108, 1.0, v108
	v_mul_f32_e32 v98, 0xbfb8aa3b, v98
	v_exp_f32_e32 v98, v98
	v_add_f32_e32 v102, 1.0, v102
	v_mul_f32_e32 v99, 0xbfb8aa3b, v99
	v_exp_f32_e32 v99, v99
	v_add_f32_e32 v98, 1.0, v98
	v_mul_f32_e32 v100, 0xbfb8aa3b, v100
	v_exp_f32_e32 v100, v100
	v_add_f32_e32 v99, 1.0, v99
	v_mul_f32_e32 v101, 0xbfb8aa3b, v101
	v_exp_f32_e32 v101, v101
	v_add_f32_e32 v100, 1.0, v100
	v_mul_f32_e32 v94, 0xbfb8aa3b, v94
	v_exp_f32_e32 v94, v94
	v_add_f32_e32 v101, 1.0, v101
	v_mul_f32_e32 v90, 0xbfb8aa3b, v90
	v_exp_f32_e32 v90, v90
	v_add_f32_e32 v94, 1.0, v94
	v_mul_f32_e32 v95, 0xbfb8aa3b, v95
	v_exp_f32_e32 v95, v95
	v_add_f32_e32 v90, 1.0, v90
	v_mul_f32_e32 v91, 0xbfb8aa3b, v91
	s_waitcnt vmcnt(0)
; #define LAS __attribute__((address_space(3)))
; __device__ __forceinline__ unsigned cvt_pk_bf16(float lo, float hi) { unsigned r; asm volatile("v_cvt_pk_bf16_f32 %0, %1, %2" : "=v"(r) : "v"(lo), "v"(hi)); return r; }
; __device__ __forceinline__ float bf_lo(unsigned w) { return __uint_as_float(w << 16); }
; __device__ __forceinline__ float bf_hi(unsigned w) { return __uint_as_float(w & 0xffff0000u); }
;     __device__ __forceinline__ void operator()(const f32x4 (&acc)[2][2][4][2], const Unit& u, int ui, const LAS float* rtab, int wr, int wc, int fr, int fq) const {
;         const int row0 = u.pm * BM + wr * 64 + fr, col0 = u.pn * BM + wc * 32 + 8 * fq;
; #pragma unroll
;         for (int ai = 0; ai < 2; ++ai)
; #pragma unroll
;             for (int m = 0; m < 4; ++m) {
;                 const int row = row0 + ai * HALF + m * 16;
; #pragma unroll
;                 for (int bj = 0; bj < 2; ++bj) {
;                     const int col = col0 + bj * HALF; const u32x4 yv = *(const u32x4*)(Y + (size_t)row * 1024 + col);
;                     const f32x4 a0 = acc[ai][bj][m][0], a1 = acc[ai][bj][m][1]; float o[8];
;                     const float yy[8] = {bf_lo(yv.x), bf_hi(yv.x), bf_lo(yv.y), bf_hi(yv.y), bf_lo(yv.z), bf_hi(yv.z), bf_lo(yv.w), bf_hi(yv.w)};
; #pragma unroll
;                     for (int e = 0; e < 4; ++e) { o[e] = yy[e] / (1.0f + __expf(-a0[e])); o[4 + e] = yy[4 + e] / (1.0f + __expf(-a1[e])); }
;                     u32x4 w; w.x = cvt_pk_bf16(o[0], o[1]); w.y = cvt_pk_bf16(o[2], o[3]); w.z = cvt_pk_bf16(o[4], o[5]); w.w = cvt_pk_bf16(o[6], o[7]);
;                     *(u32x4*)(MG + (size_t)row * DM + 1024 + col) = w;
	v_lshlrev_b32_e32 v174, 16, v170
	v_lshlrev_b32_e32 v162, 16, v173
	v_and_b32_e32 v145, 0xffff0000, v173
	v_div_scale_f32 v173, s[12:13], v126, v126, v174
	v_rcp_f32_e32 v176, v173
	v_lshlrev_b32_e32 v175, 16, v171
	v_and_b32_e32 v153, 0xffff0000, v171
	v_lshlrev_b32_e32 v171, 16, v172
	v_fma_f32 v177, -v173, v176, 1.0
	v_fmac_f32_e32 v176, v177, v176
	v_div_scale_f32 v177, vcc, v174, v126, v174
	v_mul_f32_e32 v178, v177, v176
	v_fma_f32 v179, -v173, v178, v177
	v_fmac_f32_e32 v178, v179, v176
	v_fma_f32 v173, -v173, v178, v177
	v_div_fmas_f32 v173, v173, v176, v178
	v_div_fixup_f32 v126, v173, v126, v174
	v_div_scale_f32 v173, s[12:13], v122, v122, v171
	v_rcp_f32_e32 v174, v173
	v_and_b32_e32 v170, 0xffff0000, v170
	v_and_b32_e32 v172, 0xffff0000, v172
	v_add_f32_e32 v95, 1.0, v95
	v_fma_f32 v176, -v173, v174, 1.0
	v_fmac_f32_e32 v174, v176, v174
	v_div_scale_f32 v176, vcc, v171, v122, v171
	v_mul_f32_e32 v177, v176, v174
	v_fma_f32 v178, -v173, v177, v176
	v_fmac_f32_e32 v177, v178, v174
	v_fma_f32 v173, -v173, v177, v176
	v_div_fmas_f32 v173, v173, v174, v177
	v_div_fixup_f32 v122, v173, v122, v171
	v_div_scale_f32 v171, s[12:13], v127, v127, v170
	v_rcp_f32_e32 v173, v171
	v_exp_f32_e32 v91, v91
	v_mul_f32_e32 v96, 0xbfb8aa3b, v96
	v_exp_f32_e32 v96, v96
	v_fma_f32 v174, -v171, v173, 1.0
	v_fmac_f32_e32 v173, v174, v173
	v_div_scale_f32 v174, vcc, v170, v127, v170
	v_mul_f32_e32 v176, v174, v173
	v_fma_f32 v177, -v171, v176, v174
	v_fmac_f32_e32 v176, v177, v173
	v_fma_f32 v171, -v171, v176, v174
	v_div_fmas_f32 v171, v171, v173, v176
	v_div_fixup_f32 v127, v171, v127, v170
	v_div_scale_f32 v170, s[12:13], v123, v123, v172
	v_rcp_f32_e32 v171, v170
	v_add_f32_e32 v91, 1.0, v91
	v_add_f32_e32 v96, 1.0, v96
	v_mul_f32_e32 v92, 0xbfb8aa3b, v92
	v_fma_f32 v173, -v170, v171, 1.0
	v_fmac_f32_e32 v171, v173, v171
	v_div_scale_f32 v173, vcc, v172, v123, v172
	v_mul_f32_e32 v174, v173, v171
	v_fma_f32 v176, -v170, v174, v173
	v_fmac_f32_e32 v174, v176, v171
	v_fma_f32 v170, -v170, v174, v173
	v_div_fmas_f32 v170, v170, v171, v174
	v_div_fixup_f32 v123, v170, v123, v172
	v_div_scale_f32 v170, s[12:13], v128, v128, v175
	v_rcp_f32_e32 v171, v170
	v_exp_f32_e32 v92, v92
	v_mul_f32_e32 v86, 0xbfb8aa3b, v86
	v_exp_f32_e32 v86, v86
	v_fma_f32 v172, -v170, v171, 1.0
	v_fmac_f32_e32 v171, v172, v171
	v_div_scale_f32 v172, vcc, v175, v128, v175
	v_mul_f32_e32 v173, v172, v171
	v_fma_f32 v174, -v170, v173, v172
	v_fmac_f32_e32 v173, v174, v171
	v_fma_f32 v170, -v170, v173, v172
	v_div_fmas_f32 v170, v170, v171, v173
	v_div_fixup_f32 v128, v170, v128, v175
	v_div_scale_f32 v170, s[12:13], v124, v124, v162
	v_rcp_f32_e32 v171, v170
	v_add_f32_e32 v92, 1.0, v92
	v_add_f32_e32 v86, 1.0, v86
	v_mul_f32_e32 v82, 0xbfb8aa3b, v82
	v_fma_f32 v172, -v170, v171, 1.0
	v_fmac_f32_e32 v171, v172, v171
	v_div_scale_f32 v172, vcc, v162, v124, v162
	v_mul_f32_e32 v173, v172, v171
	v_fma_f32 v174, -v170, v173, v172
	v_fmac_f32_e32 v173, v174, v171
	v_fma_f32 v170, -v170, v173, v172
	v_div_fmas_f32 v170, v170, v171, v173
	v_div_fixup_f32 v162, v170, v124, v162
	v_mul_f32_e32 v124, 0xbfb8aa3b, v129
	v_exp_f32_e32 v124, v124
	v_exp_f32_e32 v82, v82
	v_mul_f32_e32 v83, 0xbfb8aa3b, v83
	v_exp_f32_e32 v83, v83
	v_add_f32_e32 v124, 1.0, v124
	v_div_scale_f32 v129, s[12:13], v124, v124, v153
	v_rcp_f32_e32 v170, v129
	v_add_f32_e32 v82, 1.0, v82
	v_add_f32_e32 v83, 1.0, v83
	v_mul_f32_e32 v84, 0xbfb8aa3b, v84
	v_fma_f32 v171, -v129, v170, 1.0
	v_fmac_f32_e32 v170, v171, v170
	v_div_scale_f32 v171, vcc, v153, v124, v153
	v_mul_f32_e32 v172, v171, v170
	v_fma_f32 v173, -v129, v172, v171
	v_fmac_f32_e32 v172, v173, v170
	v_fma_f32 v129, -v129, v172, v171
	v_div_fmas_f32 v129, v129, v170, v172
	v_div_fixup_f32 v129, v129, v124, v153
	v_mul_f32_e32 v124, 0xbfb8aa3b, v125
	v_exp_f32_e32 v124, v124
	v_exp_f32_e32 v84, v84
	v_mul_f32_e32 v85, 0xbfb8aa3b, v85
	v_exp_f32_e32 v85, v85
	v_add_f32_e32 v124, 1.0, v124
	v_div_scale_f32 v125, s[12:13], v124, v124, v145
	v_rcp_f32_e32 v153, v125
	v_add_f32_e32 v84, 1.0, v84
	v_add_f32_e32 v85, 1.0, v85
	v_mul_f32_e32 v78, 0xbfb8aa3b, v78
	v_fma_f32 v170, -v125, v153, 1.0
	v_fmac_f32_e32 v153, v170, v153
	v_div_scale_f32 v170, vcc, v145, v124, v145
	v_mul_f32_e32 v171, v170, v153
	v_fma_f32 v172, -v125, v171, v170
	v_fmac_f32_e32 v171, v172, v153
	v_fma_f32 v125, -v125, v171, v170
	v_div_fmas_f32 v125, v125, v153, v171
	v_div_fixup_f32 v145, v125, v124, v145
	v_cvt_pk_bf16_f32 v124, v126, v127
	v_cvt_pk_bf16_f32 v125, v128, v129
	v_cvt_pk_bf16_f32 v126, v122, v123
	v_lshl_add_u64 v[122:123], s[88:89], 0, v[148:149]
	v_cvt_pk_bf16_f32 v127, v162, v145
	v_lshl_add_u64 v[122:123], v[122:123], 0, v[142:143]
	global_store_dwordx4 v[122:123], v[124:127], off offset:2048
	global_load_dwordx4 v[124:127], v[146:147], off offset:256
	v_exp_f32_e32 v78, v78
	v_mul_f32_e32 v74, 0xbfb8aa3b, v74
	v_exp_f32_e32 v74, v74
	v_mul_f32_e32 v79, 0xbfb8aa3b, v79
	v_add_f32_e32 v78, 1.0, v78
	v_exp_f32_e32 v79, v79
	v_add_f32_e32 v74, 1.0, v74
	v_mul_f32_e32 v75, 0xbfb8aa3b, v75
	v_exp_f32_e32 v75, v75
	v_add_f32_e32 v79, 1.0, v79
	v_mul_f32_e32 v80, 0xbfb8aa3b, v80
	v_exp_f32_e32 v80, v80
	v_add_f32_e32 v75, 1.0, v75
	v_mul_f32_e32 v76, 0xbfb8aa3b, v76
	v_exp_f32_e32 v76, v76
	v_add_f32_e32 v80, 1.0, v80
	v_mul_f32_e32 v70, 0xbfb8aa3b, v70
	v_exp_f32_e32 v70, v70
	v_add_f32_e32 v76, 1.0, v76
	v_mul_f32_e32 v66, 0xbfb8aa3b, v66
	v_exp_f32_e32 v66, v66
	v_add_f32_e32 v70, 1.0, v70
	v_mul_f32_e32 v67, 0xbfb8aa3b, v67
	v_exp_f32_e32 v67, v67
	v_add_f32_e32 v66, 1.0, v66
	v_mul_f32_e32 v68, 0xbfb8aa3b, v68
	v_exp_f32_e32 v68, v68
	v_add_f32_e32 v67, 1.0, v67
; __device__ __forceinline__ unsigned cvt_pk_bf16(float lo, float hi) { unsigned r; asm volatile("v_cvt_pk_bf16_f32 %0, %1, %2" : "=v"(r) : "v"(lo), "v"(hi)); return r; }
; __device__ __forceinline__ float bf_lo(unsigned w) { return __uint_as_float(w << 16); }
; __device__ __forceinline__ float bf_hi(unsigned w) { return __uint_as_float(w & 0xffff0000u); }
;     __device__ __forceinline__ void operator()(const f32x4 (&acc)[2][2][4][2], const Unit& u, int ui, const LAS float* rtab, int wr, int wc, int fr, int fq) const {
;         const int row0 = u.pm * BM + wr * 64 + fr, col0 = u.pn * BM + wc * 32 + 8 * fq;
; #pragma unroll
;         for (int ai = 0; ai < 2; ++ai)
; #pragma unroll
;             for (int m = 0; m < 4; ++m) {
;                 const int row = row0 + ai * HALF + m * 16;
; #pragma unroll
;                 for (int bj = 0; bj < 2; ++bj) {
;                     const int col = col0 + bj * HALF; const u32x4 yv = *(const u32x4*)(Y + (size_t)row * 1024 + col);
;                     const f32x4 a0 = acc[ai][bj][m][0], a1 = acc[ai][bj][m][1]; float o[8];
;                     const float yy[8] = {bf_lo(yv.x), bf_hi(yv.x), bf_lo(yv.y), bf_hi(yv.y), bf_lo(yv.z), bf_hi(yv.z), bf_lo(yv.w), bf_hi(yv.w)};
; #pragma unroll
;                     for (int e = 0; e < 4; ++e) { o[e] = yy[e] / (1.0f + __expf(-a0[e])); o[4 + e] = yy[4 + e] / (1.0f + __expf(-a1[e])); }
;                     u32x4 w; w.x = cvt_pk_bf16(o[0], o[1]); w.y = cvt_pk_bf16(o[2], o[3]); w.z = cvt_pk_bf16(o[4], o[5]); w.w = cvt_pk_bf16(o[6], o[7]);
;                     *(u32x4*)(MG + (size_t)row * DM + 1024 + col) = w;
	v_mul_f32_e32 v69, 0xbfb8aa3b, v69
	v_exp_f32_e32 v69, v69
	v_add_f32_e32 v68, 1.0, v68
	v_mul_f32_e32 v62, 0xbfb8aa3b, v62
	v_exp_f32_e32 v62, v62
	v_add_f32_e32 v69, 1.0, v69
	v_mul_f32_e32 v58, 0xbfb8aa3b, v58
	v_exp_f32_e32 v58, v58
	v_add_f32_e32 v62, 1.0, v62
	v_mul_f32_e32 v63, 0xbfb8aa3b, v63
	v_exp_f32_e32 v63, v63
	v_add_f32_e32 v58, 1.0, v58
	v_mul_f32_e32 v59, 0xbfb8aa3b, v59
	v_exp_f32_e32 v59, v59
	v_add_f32_e32 v63, 1.0, v63
	v_mul_f32_e32 v64, 0xbfb8aa3b, v64
	v_exp_f32_e32 v64, v64
	v_add_f32_e32 v59, 1.0, v59
	v_mul_f32_e32 v60, 0xbfb8aa3b, v60
	v_exp_f32_e32 v60, v60
	v_add_f32_e32 v64, 1.0, v64
	v_mul_f32_e32 v54, 0xbfb8aa3b, v54
	v_exp_f32_e32 v54, v54
	v_add_f32_e32 v60, 1.0, v60
	v_mul_f32_e32 v50, 0xbfb8aa3b, v50
	v_exp_f32_e32 v50, v50
	v_add_f32_e32 v54, 1.0, v54
	v_mul_f32_e32 v51, 0xbfb8aa3b, v51
	v_exp_f32_e32 v51, v51
	v_add_f32_e32 v50, 1.0, v50
	v_mul_f32_e32 v52, 0xbfb8aa3b, v52
	v_exp_f32_e32 v52, v52
	v_add_f32_e32 v51, 1.0, v51
	v_mul_f32_e32 v53, 0xbfb8aa3b, v53
	v_exp_f32_e32 v53, v53
	v_add_f32_e32 v52, 1.0, v52
	v_mul_f32_e32 v46, 0xbfb8aa3b, v46
	v_exp_f32_e32 v46, v46
	v_add_f32_e32 v53, 1.0, v53
	v_mul_f32_e32 v42, 0xbfb8aa3b, v42
	v_exp_f32_e32 v42, v42
	v_add_f32_e32 v46, 1.0, v46
	v_mul_f32_e32 v47, 0xbfb8aa3b, v47
	v_exp_f32_e32 v47, v47
	v_add_f32_e32 v42, 1.0, v42
	v_mul_f32_e32 v43, 0xbfb8aa3b, v43
	v_exp_f32_e32 v43, v43
	v_add_f32_e32 v47, 1.0, v47
	v_mul_f32_e32 v48, 0xbfb8aa3b, v48
	v_exp_f32_e32 v48, v48
	v_add_f32_e32 v43, 1.0, v43
	s_waitcnt vmcnt(0)
	v_lshlrev_b32_e32 v128, 16, v124
	v_and_b32_e32 v129, 0xffff0000, v124
	v_lshlrev_b32_e32 v146, 16, v126
	v_and_b32_e32 v147, 0xffff0000, v126
	v_lshlrev_b32_e32 v126, 16, v127
	v_and_b32_e32 v124, 0xffff0000, v127
	v_div_scale_f32 v127, s[12:13], v118, v118, v128
	v_rcp_f32_e32 v148, v127
	v_lshlrev_b32_e32 v145, 16, v125
	v_and_b32_e32 v125, 0xffff0000, v125
	v_add_f32_e32 v48, 1.0, v48
	v_fma_f32 v149, -v127, v148, 1.0
	v_fmac_f32_e32 v148, v149, v148
	v_div_scale_f32 v149, vcc, v128, v118, v128
	v_mul_f32_e32 v153, v149, v148
	v_fma_f32 v162, -v127, v153, v149
	v_fmac_f32_e32 v153, v162, v148
	v_fma_f32 v127, -v127, v153, v149
	v_div_fmas_f32 v127, v127, v148, v153
	v_div_fixup_f32 v118, v127, v118, v128
	v_div_scale_f32 v127, s[12:13], v114, v114, v146
	v_rcp_f32_e32 v128, v127
	v_mul_f32_e32 v44, 0xbfb8aa3b, v44
	v_exp_f32_e32 v44, v44
	v_mul_f32_e32 v38, 0xbfb8aa3b, v38
	v_fma_f32 v148, -v127, v128, 1.0
	v_fmac_f32_e32 v128, v148, v128
	v_div_scale_f32 v148, vcc, v146, v114, v146
	v_mul_f32_e32 v149, v148, v128
	v_fma_f32 v153, -v127, v149, v148
	v_fmac_f32_e32 v149, v153, v128
	v_fma_f32 v127, -v127, v149, v148
	v_div_fmas_f32 v127, v127, v128, v149
	v_div_fixup_f32 v114, v127, v114, v146
	v_div_scale_f32 v127, s[12:13], v119, v119, v129
	v_rcp_f32_e32 v128, v127
	v_add_f32_e32 v44, 1.0, v44
	v_exp_f32_e32 v38, v38
	v_mul_f32_e32 v34, 0xbfb8aa3b, v34
	v_fma_f32 v146, -v127, v128, 1.0
	v_fmac_f32_e32 v128, v146, v128
	v_div_scale_f32 v146, vcc, v129, v119, v129
	v_mul_f32_e32 v148, v146, v128
	v_fma_f32 v149, -v127, v148, v146
	v_fmac_f32_e32 v148, v149, v128
	v_fma_f32 v127, -v127, v148, v146
	v_div_fmas_f32 v127, v127, v128, v148
	v_div_fixup_f32 v119, v127, v119, v129
	v_div_scale_f32 v127, s[12:13], v115, v115, v147
	v_rcp_f32_e32 v128, v127
	v_add_f32_e32 v38, 1.0, v38
	v_exp_f32_e32 v34, v34
	v_mul_f32_e32 v35, 0xbfb8aa3b, v35
	v_fma_f32 v129, -v127, v128, 1.0
	v_fmac_f32_e32 v128, v129, v128
	v_div_scale_f32 v129, vcc, v147, v115, v147
	v_mul_f32_e32 v146, v129, v128
	v_fma_f32 v148, -v127, v146, v129
	v_fmac_f32_e32 v146, v148, v128
	v_fma_f32 v127, -v127, v146, v129
	v_div_fmas_f32 v127, v127, v128, v146
	v_div_fixup_f32 v115, v127, v115, v147
	v_div_scale_f32 v127, s[12:13], v120, v120, v145
	v_rcp_f32_e32 v128, v127
	v_add_f32_e32 v34, 1.0, v34
	v_exp_f32_e32 v35, v35
	v_mul_f32_e32 v36, 0xbfb8aa3b, v36
	v_fma_f32 v129, -v127, v128, 1.0
	v_fmac_f32_e32 v128, v129, v128
	v_div_scale_f32 v129, vcc, v145, v120, v145
	v_mul_f32_e32 v146, v129, v128
	v_fma_f32 v147, -v127, v146, v129
	v_fmac_f32_e32 v146, v147, v128
	v_fma_f32 v127, -v127, v146, v129
	v_div_fmas_f32 v127, v127, v128, v146
	v_div_fixup_f32 v120, v127, v120, v145
	v_div_scale_f32 v127, s[12:13], v116, v116, v126
	v_rcp_f32_e32 v128, v127
	v_add_f32_e32 v35, 1.0, v35
	v_exp_f32_e32 v36, v36
	v_mul_f32_e32 v37, 0xbfb8aa3b, v37
	v_fma_f32 v129, -v127, v128, 1.0
	v_fmac_f32_e32 v128, v129, v128
	v_div_scale_f32 v129, vcc, v126, v116, v126
	v_mul_f32_e32 v145, v129, v128
	v_fma_f32 v146, -v127, v145, v129
	v_fmac_f32_e32 v145, v146, v128
	v_fma_f32 v127, -v127, v145, v129
	v_div_fmas_f32 v127, v127, v128, v145
	v_div_fixup_f32 v126, v127, v116, v126
	v_mul_f32_e32 v116, 0xbfb8aa3b, v121
	v_exp_f32_e32 v116, v116
	v_add_f32_e32 v36, 1.0, v36
	v_exp_f32_e32 v37, v37
	v_mul_f32_e32 v30, 0xbfb8aa3b, v30
	v_add_f32_e32 v116, 1.0, v116
	v_div_scale_f32 v121, s[12:13], v116, v116, v125
	v_rcp_f32_e32 v127, v121
	v_add_f32_e32 v37, 1.0, v37
	v_exp_f32_e32 v30, v30
	v_mul_f32_e32 v26, 0xbfb8aa3b, v26
	v_fma_f32 v128, -v121, v127, 1.0
	v_fmac_f32_e32 v127, v128, v127
	v_div_scale_f32 v128, vcc, v125, v116, v125
	v_mul_f32_e32 v129, v128, v127
	v_fma_f32 v145, -v121, v129, v128
	v_fmac_f32_e32 v129, v145, v127
	v_fma_f32 v121, -v121, v129, v128
	v_div_fmas_f32 v121, v121, v127, v129
	v_div_fixup_f32 v121, v121, v116, v125
	v_mul_f32_e32 v116, 0xbfb8aa3b, v117
	v_exp_f32_e32 v116, v116
	v_add_f32_e32 v30, 1.0, v30
	v_exp_f32_e32 v26, v26
	v_mul_f32_e32 v31, 0xbfb8aa3b, v31
	v_add_f32_e32 v116, 1.0, v116
	v_div_scale_f32 v117, s[12:13], v116, v116, v124
	v_rcp_f32_e32 v125, v117
; __device__ __forceinline__ unsigned cvt_pk_bf16(float lo, float hi) { unsigned r; asm volatile("v_cvt_pk_bf16_f32 %0, %1, %2" : "=v"(r) : "v"(lo), "v"(hi)); return r; }
; __device__ __forceinline__ float bf_lo(unsigned w) { return __uint_as_float(w << 16); }
; __device__ __forceinline__ float bf_hi(unsigned w) { return __uint_as_float(w & 0xffff0000u); }
;     __device__ __forceinline__ void operator()(const f32x4 (&acc)[2][2][4][2], const Unit& u, int ui, const LAS float* rtab, int wr, int wc, int fr, int fq) const {
;     ...
;                 const int row = row0 + ai * HALF + m * 16;
; #pragma unroll
;                 for (int bj = 0; bj < 2; ++bj) {
;                     const int col = col0 + bj * HALF; const u32x4 yv = *(const u32x4*)(Y + (size_t)row * 1024 + col);
;                     const f32x4 a0 = acc[ai][bj][m][0], a1 = acc[ai][bj][m][1]; float o[8];
;                     const float yy[8] = {bf_lo(yv.x), bf_hi(yv.x), bf_lo(yv.y), bf_hi(yv.y), bf_lo(yv.z), bf_hi(yv.z), bf_lo(yv.w), bf_hi(yv.w)};
; #pragma unroll
;                     for (int e = 0; e < 4; ++e) { o[e] = yy[e] / (1.0f + __expf(-a0[e])); o[4 + e] = yy[4 + e] / (1.0f + __expf(-a1[e])); }
;                     u32x4 w; w.x = cvt_pk_bf16(o[0], o[1]); w.y = cvt_pk_bf16(o[2], o[3]); w.z = cvt_pk_bf16(o[4], o[5]); w.w = cvt_pk_bf16(o[6], o[7]);
;                     *(u32x4*)(MG + (size_t)row * DM + 1024 + col) = w;
	v_add_f32_e32 v26, 1.0, v26
	v_exp_f32_e32 v31, v31
	v_mul_f32_e32 v27, 0xbfb8aa3b, v27
	v_fma_f32 v127, -v117, v125, 1.0
	v_fmac_f32_e32 v125, v127, v125
	v_div_scale_f32 v127, vcc, v124, v116, v124
	v_mul_f32_e32 v128, v127, v125
	v_fma_f32 v129, -v117, v128, v127
	v_fmac_f32_e32 v128, v129, v125
	v_fma_f32 v117, -v117, v128, v127
	v_div_fmas_f32 v117, v117, v125, v128
	v_div_fixup_f32 v124, v117, v116, v124
	v_cvt_pk_bf16_f32 v116, v118, v119
	v_cvt_pk_bf16_f32 v117, v120, v121
	v_cvt_pk_bf16_f32 v118, v114, v115
	v_or_b32_e32 v114, 16, v144
	v_cvt_pk_bf16_f32 v119, v126, v124
	v_ashrrev_i32_e32 v115, 31, v114
	global_store_dwordx4 v[122:123], v[116:119], off offset:2304
	v_add_f32_e32 v31, 1.0, v31
	v_exp_f32_e32 v27, v27
	v_lshlrev_b64 v[118:119], 11, v[114:115]
	v_lshlrev_b64 v[116:117], 12, v[114:115]
	v_lshl_add_u64 v[114:115], s[86:87], 0, v[118:119]
	v_lshl_add_u64 v[114:115], v[114:115], 0, v[142:143]
	global_load_dwordx4 v[118:121], v[114:115], off
	v_add_f32_e32 v27, 1.0, v27
	v_mul_f32_e32 v32, 0xbfb8aa3b, v32
	v_exp_f32_e32 v32, v32
	v_mul_f32_e32 v28, 0xbfb8aa3b, v28
	v_exp_f32_e32 v28, v28
	v_mul_f32_e32 v22, 0xbfb8aa3b, v22
	v_add_f32_e32 v32, 1.0, v32
	v_exp_f32_e32 v22, v22
	v_add_f32_e32 v28, 1.0, v28
	v_mul_f32_e32 v18, 0xbfb8aa3b, v18
	v_exp_f32_e32 v18, v18
	v_add_f32_e32 v22, 1.0, v22
	v_mul_f32_e32 v19, 0xbfb8aa3b, v19
	v_exp_f32_e32 v19, v19
	v_add_f32_e32 v18, 1.0, v18
	v_mul_f32_e32 v20, 0xbfb8aa3b, v20
	v_exp_f32_e32 v20, v20
	v_add_f32_e32 v19, 1.0, v19
	v_mul_f32_e32 v21, 0xbfb8aa3b, v21
	v_exp_f32_e32 v21, v21
	v_add_f32_e32 v20, 1.0, v20
	v_mul_f32_e32 v14, 0xbfb8aa3b, v14
	v_exp_f32_e32 v14, v14
	v_add_f32_e32 v21, 1.0, v21
	v_mul_f32_e32 v10, 0xbfb8aa3b, v10
	v_exp_f32_e32 v10, v10
	v_add_f32_e32 v14, 1.0, v14
	v_mul_f32_e32 v15, 0xbfb8aa3b, v15
	v_exp_f32_e32 v15, v15
	v_add_f32_e32 v10, 1.0, v10
	v_mul_f32_e32 v11, 0xbfb8aa3b, v11
	v_exp_f32_e32 v11, v11
	v_add_f32_e32 v15, 1.0, v15
	v_mul_f32_e32 v16, 0xbfb8aa3b, v16
	v_exp_f32_e32 v16, v16
	v_add_f32_e32 v11, 1.0, v11
	v_mul_f32_e32 v12, 0xbfb8aa3b, v12
	v_exp_f32_e32 v12, v12
	v_add_f32_e32 v16, 1.0, v16
	v_mul_f32_e32 v6, 0xbfb8aa3b, v6
	v_exp_f32_e32 v6, v6
	v_add_f32_e32 v12, 1.0, v12
	v_mul_f32_e32 v2, 0xbfb8aa3b, v2
	v_exp_f32_e32 v2, v2
	v_add_f32_e32 v6, 1.0, v6
	v_mul_f32_e32 v3, 0xbfb8aa3b, v3
	v_exp_f32_e32 v3, v3
	v_add_f32_e32 v2, 1.0, v2
	v_mul_f32_e32 v4, 0xbfb8aa3b, v4
	v_exp_f32_e32 v4, v4
	v_add_f32_e32 v3, 1.0, v3
	v_mul_f32_e32 v5, 0xbfb8aa3b, v5
	v_exp_f32_e32 v5, v5
	v_add_f32_e32 v4, 1.0, v4
	s_mov_b64 s[36:37], s[46:47]
	s_mov_b64 s[20:21], s[44:45]
	v_add_f32_e32 v5, 1.0, v5
	s_waitcnt vmcnt(0)
	v_lshlrev_b32_e32 v122, 16, v118
	v_and_b32_e32 v123, 0xffff0000, v118
	v_lshlrev_b32_e32 v126, 16, v121
	v_and_b32_e32 v118, 0xffff0000, v121
	v_div_scale_f32 v121, s[12:13], v110, v110, v122
	v_rcp_f32_e32 v127, v121
	v_lshlrev_b32_e32 v125, 16, v120
	v_and_b32_e32 v120, 0xffff0000, v120
	v_lshlrev_b32_e32 v124, 16, v119
	v_fma_f32 v128, -v121, v127, 1.0
	v_fmac_f32_e32 v127, v128, v127
	v_div_scale_f32 v128, vcc, v122, v110, v122
	v_mul_f32_e32 v129, v128, v127
	v_fma_f32 v145, -v121, v129, v128
	v_fmac_f32_e32 v129, v145, v127
	v_fma_f32 v121, -v121, v129, v128
	v_div_fmas_f32 v121, v121, v127, v129
	v_div_fixup_f32 v110, v121, v110, v122
	v_div_scale_f32 v121, s[12:13], v106, v106, v125
	v_rcp_f32_e32 v122, v121
	v_and_b32_e32 v119, 0xffff0000, v119
	v_fma_f32 v127, -v121, v122, 1.0
	v_fmac_f32_e32 v122, v127, v122
	v_div_scale_f32 v127, vcc, v125, v106, v125
	v_mul_f32_e32 v128, v127, v122
	v_fma_f32 v129, -v121, v128, v127
	v_fmac_f32_e32 v128, v129, v122
	v_fma_f32 v121, -v121, v128, v127
	v_div_fmas_f32 v121, v121, v122, v128
	v_div_fixup_f32 v106, v121, v106, v125
	v_div_scale_f32 v121, s[12:13], v111, v111, v123
	v_rcp_f32_e32 v122, v121
	s_nop 0
	v_fma_f32 v125, -v121, v122, 1.0
	v_fmac_f32_e32 v122, v125, v122
	v_div_scale_f32 v125, vcc, v123, v111, v123
	v_mul_f32_e32 v127, v125, v122
	v_fma_f32 v128, -v121, v127, v125
	v_fmac_f32_e32 v127, v128, v122
	v_fma_f32 v121, -v121, v127, v125
	v_div_fmas_f32 v121, v121, v122, v127
	v_div_fixup_f32 v111, v121, v111, v123
	v_div_scale_f32 v121, s[12:13], v107, v107, v120
	v_rcp_f32_e32 v122, v121
	s_nop 0
	v_fma_f32 v123, -v121, v122, 1.0
	v_fmac_f32_e32 v122, v123, v122
	v_div_scale_f32 v123, vcc, v120, v107, v120
	v_mul_f32_e32 v125, v123, v122
	v_fma_f32 v127, -v121, v125, v123
	v_fmac_f32_e32 v125, v127, v122
	v_fma_f32 v121, -v121, v125, v123
	v_div_fmas_f32 v121, v121, v122, v125
	v_div_fixup_f32 v107, v121, v107, v120
	v_div_scale_f32 v120, s[12:13], v112, v112, v124
	v_rcp_f32_e32 v121, v120
	s_nop 0
	v_fma_f32 v122, -v120, v121, 1.0
	v_fmac_f32_e32 v121, v122, v121
	v_div_scale_f32 v122, vcc, v124, v112, v124
	v_mul_f32_e32 v123, v122, v121
	v_fma_f32 v125, -v120, v123, v122
	v_fmac_f32_e32 v123, v125, v121
	v_fma_f32 v120, -v120, v123, v122
	v_div_fmas_f32 v120, v120, v121, v123
	v_div_fixup_f32 v112, v120, v112, v124
	v_div_scale_f32 v120, s[12:13], v108, v108, v126
	v_rcp_f32_e32 v121, v120
	s_nop 0
	v_fma_f32 v122, -v120, v121, 1.0
	v_fmac_f32_e32 v121, v122, v121
	v_div_scale_f32 v122, vcc, v126, v108, v126
	v_mul_f32_e32 v123, v122, v121
	v_fma_f32 v124, -v120, v123, v122
	v_fmac_f32_e32 v123, v124, v121
	v_fma_f32 v120, -v120, v123, v122
	v_div_fmas_f32 v120, v120, v121, v123
	v_div_fixup_f32 v120, v120, v108, v126
	v_mul_f32_e32 v108, 0xbfb8aa3b, v113
	v_exp_f32_e32 v108, v108
	s_nop 0
	v_add_f32_e32 v108, 1.0, v108
	v_div_scale_f32 v113, s[12:13], v108, v108, v119
	v_rcp_f32_e32 v121, v113
	s_nop 0
	v_fma_f32 v122, -v113, v121, 1.0
	v_fmac_f32_e32 v121, v122, v121
	v_div_scale_f32 v122, vcc, v119, v108, v119
	v_mul_f32_e32 v123, v122, v121
	v_fma_f32 v124, -v113, v123, v122
	v_fmac_f32_e32 v123, v124, v121
	v_fma_f32 v113, -v113, v123, v122
	v_div_fmas_f32 v113, v113, v121, v123
	v_div_fixup_f32 v113, v113, v108, v119
	v_mul_f32_e32 v108, 0xbfb8aa3b, v109
	v_exp_f32_e32 v108, v108
	s_nop 0
	v_add_f32_e32 v108, 1.0, v108
	v_div_scale_f32 v109, s[12:13], v108, v108, v118
	v_rcp_f32_e32 v119, v109
	s_nop 0
	v_fma_f32 v121, -v109, v119, 1.0
	v_fmac_f32_e32 v119, v121, v119
	v_div_scale_f32 v121, vcc, v118, v108, v118
	v_mul_f32_e32 v122, v121, v119
	v_fma_f32 v123, -v109, v122, v121
	v_fmac_f32_e32 v122, v123, v119
	v_fma_f32 v109, -v109, v122, v121
	v_div_fmas_f32 v109, v109, v119, v122
	v_div_fixup_f32 v118, v109, v108, v118
	v_cvt_pk_bf16_f32 v108, v110, v111
	v_cvt_pk_bf16_f32 v109, v112, v113
	v_cvt_pk_bf16_f32 v110, v106, v107
	v_lshl_add_u64 v[106:107], s[88:89], 0, v[116:117]
	v_cvt_pk_bf16_f32 v111, v120, v118
	v_lshl_add_u64 v[106:107], v[106:107], 0, v[142:143]
	global_store_dwordx4 v[106:107], v[108:111], off offset:2048
	global_load_dwordx4 v[108:111], v[114:115], off offset:256
	s_waitcnt vmcnt(0)
; __device__ __forceinline__ unsigned cvt_pk_bf16(float lo, float hi) { unsigned r; asm volatile("v_cvt_pk_bf16_f32 %0, %1, %2" : "=v"(r) : "v"(lo), "v"(hi)); return r; }
; __device__ __forceinline__ float bf_lo(unsigned w) { return __uint_as_float(w << 16); }
; __device__ __forceinline__ float bf_hi(unsigned w) { return __uint_as_float(w & 0xffff0000u); }
;     __device__ __forceinline__ void operator()(const f32x4 (&acc)[2][2][4][2], const Unit& u, int ui, const LAS float* rtab, int wr, int wc, int fr, int fq) const {
;     ...
;                 const int row = row0 + ai * HALF + m * 16;
; #pragma unroll
;                 for (int bj = 0; bj < 2; ++bj) {
;                     const int col = col0 + bj * HALF; const u32x4 yv = *(const u32x4*)(Y + (size_t)row * 1024 + col);
;                     const f32x4 a0 = acc[ai][bj][m][0], a1 = acc[ai][bj][m][1]; float o[8];
;                     const float yy[8] = {bf_lo(yv.x), bf_hi(yv.x), bf_lo(yv.y), bf_hi(yv.y), bf_lo(yv.z), bf_hi(yv.z), bf_lo(yv.w), bf_hi(yv.w)};
; #pragma unroll
;                     for (int e = 0; e < 4; ++e) { o[e] = yy[e] / (1.0f + __expf(-a0[e])); o[4 + e] = yy[4 + e] / (1.0f + __expf(-a1[e])); }
;                     u32x4 w; w.x = cvt_pk_bf16(o[0], o[1]); w.y = cvt_pk_bf16(o[2], o[3]); w.z = cvt_pk_bf16(o[4], o[5]); w.w = cvt_pk_bf16(o[6], o[7]);
;                     *(u32x4*)(MG + (size_t)row * DM + 1024 + col) = w;
	v_lshlrev_b32_e32 v112, 16, v108
	v_and_b32_e32 v113, 0xffff0000, v108
	v_lshlrev_b32_e32 v116, 16, v111
	v_and_b32_e32 v108, 0xffff0000, v111
	v_div_scale_f32 v111, s[12:13], v102, v102, v112
	v_rcp_f32_e32 v117, v111
	v_lshlrev_b32_e32 v115, 16, v110
	v_and_b32_e32 v110, 0xffff0000, v110
	v_lshlrev_b32_e32 v114, 16, v109
	v_fma_f32 v118, -v111, v117, 1.0
	v_fmac_f32_e32 v117, v118, v117
	v_div_scale_f32 v118, vcc, v112, v102, v112
	v_mul_f32_e32 v119, v118, v117
	v_fma_f32 v120, -v111, v119, v118
	v_fmac_f32_e32 v119, v120, v117
	v_fma_f32 v111, -v111, v119, v118
	v_div_fmas_f32 v111, v111, v117, v119
	v_div_fixup_f32 v102, v111, v102, v112
	v_div_scale_f32 v111, s[12:13], v98, v98, v115
	v_rcp_f32_e32 v112, v111
	v_and_b32_e32 v109, 0xffff0000, v109
	v_fma_f32 v117, -v111, v112, 1.0
	v_fmac_f32_e32 v112, v117, v112
	v_div_scale_f32 v117, vcc, v115, v98, v115
	v_mul_f32_e32 v118, v117, v112
	v_fma_f32 v119, -v111, v118, v117
	v_fmac_f32_e32 v118, v119, v112
	v_fma_f32 v111, -v111, v118, v117
	v_div_fmas_f32 v111, v111, v112, v118
	v_div_fixup_f32 v111, v111, v98, v115
	v_mul_f32_e32 v98, 0xbfb8aa3b, v103
	v_exp_f32_e32 v98, v98
	s_nop 0
	v_add_f32_e32 v98, 1.0, v98
	v_div_scale_f32 v103, s[12:13], v98, v98, v113
	v_rcp_f32_e32 v112, v103
	s_nop 0
	v_fma_f32 v115, -v103, v112, 1.0
	v_fmac_f32_e32 v112, v115, v112
	v_div_scale_f32 v115, vcc, v113, v98, v113
	v_mul_f32_e32 v117, v115, v112
	v_fma_f32 v118, -v103, v117, v115
	v_fmac_f32_e32 v117, v118, v112
	v_fma_f32 v103, -v103, v117, v115
	v_div_fmas_f32 v103, v103, v112, v117
	v_div_fixup_f32 v98, v103, v98, v113
	v_div_scale_f32 v103, s[12:13], v99, v99, v110
	v_rcp_f32_e32 v112, v103
	v_cvt_pk_bf16_f32 v98, v102, v98
	s_nop 0
	v_fma_f32 v113, -v103, v112, 1.0
	v_fmac_f32_e32 v112, v113, v112
	v_div_scale_f32 v113, vcc, v110, v99, v110
	v_mul_f32_e32 v115, v113, v112
	v_fma_f32 v117, -v103, v115, v113
	v_fmac_f32_e32 v115, v117, v112
	v_fma_f32 v103, -v103, v115, v113
	v_div_fmas_f32 v103, v103, v112, v115
	v_div_fixup_f32 v103, v103, v99, v110
	v_mul_f32_e32 v99, 0xbfb8aa3b, v104
	v_exp_f32_e32 v99, v99
	s_nop 0
	v_add_f32_e32 v99, 1.0, v99
	v_div_scale_f32 v104, s[12:13], v99, v99, v114
	v_rcp_f32_e32 v110, v104
	s_nop 0
	v_fma_f32 v112, -v104, v110, 1.0
	v_fmac_f32_e32 v110, v112, v110
	v_div_scale_f32 v112, vcc, v114, v99, v114
	v_mul_f32_e32 v113, v112, v110
	v_fma_f32 v115, -v104, v113, v112
	v_fmac_f32_e32 v113, v115, v110
	v_fma_f32 v104, -v104, v113, v112
	v_div_fmas_f32 v104, v104, v110, v113
	v_div_fixup_f32 v99, v104, v99, v114
	v_div_scale_f32 v104, s[12:13], v100, v100, v116
	v_rcp_f32_e32 v110, v104
	s_nop 0
	v_fma_f32 v112, -v104, v110, 1.0
	v_fmac_f32_e32 v110, v112, v110
	v_div_scale_f32 v112, vcc, v116, v100, v116
	v_mul_f32_e32 v113, v112, v110
	v_fma_f32 v114, -v104, v113, v112
	v_fmac_f32_e32 v113, v114, v110
	v_fma_f32 v104, -v104, v113, v112
	v_div_fmas_f32 v104, v104, v110, v113
	v_div_fixup_f32 v104, v104, v100, v116
	v_mul_f32_e32 v100, 0xbfb8aa3b, v105
	v_exp_f32_e32 v100, v100
	s_nop 0
	v_add_f32_e32 v100, 1.0, v100
	v_div_scale_f32 v105, s[12:13], v100, v100, v109
	v_rcp_f32_e32 v110, v105
	s_nop 0
	v_fma_f32 v112, -v105, v110, 1.0
	v_fmac_f32_e32 v110, v112, v110
	v_div_scale_f32 v112, vcc, v109, v100, v109
	v_mul_f32_e32 v113, v112, v110
	v_fma_f32 v114, -v105, v113, v112
	v_fmac_f32_e32 v113, v114, v110
	v_fma_f32 v105, -v105, v113, v112
	v_div_fmas_f32 v105, v105, v110, v113
	v_div_fixup_f32 v100, v105, v100, v109
	v_div_scale_f32 v105, s[12:13], v101, v101, v108
	v_rcp_f32_e32 v109, v105
	v_cvt_pk_bf16_f32 v99, v99, v100
	v_cvt_pk_bf16_f32 v100, v111, v103
	s_nop 0
	v_fma_f32 v110, -v105, v109, 1.0
	v_fmac_f32_e32 v109, v110, v109
	v_div_scale_f32 v110, vcc, v108, v101, v108
	v_mul_f32_e32 v112, v110, v109
	v_fma_f32 v113, -v105, v112, v110
	v_fmac_f32_e32 v112, v113, v109
	v_fma_f32 v105, -v105, v112, v110
	v_div_fmas_f32 v105, v105, v109, v112
	v_div_fixup_f32 v101, v105, v101, v108
	v_cvt_pk_bf16_f32 v101, v104, v101
	global_store_dwordx4 v[106:107], v[98:101], off offset:2304
	s_nop 1
	v_or_b32_e32 v98, 32, v144
	v_ashrrev_i32_e32 v99, 31, v98
	v_lshlrev_b64 v[102:103], 11, v[98:99]
	v_lshlrev_b64 v[100:101], 12, v[98:99]
	v_lshl_add_u64 v[98:99], s[86:87], 0, v[102:103]
	v_lshl_add_u64 v[98:99], v[98:99], 0, v[142:143]
	global_load_dwordx4 v[102:105], v[98:99], off
	s_waitcnt vmcnt(0)
; __device__ __forceinline__ unsigned cvt_pk_bf16(float lo, float hi) { unsigned r; asm volatile("v_cvt_pk_bf16_f32 %0, %1, %2" : "=v"(r) : "v"(lo), "v"(hi)); return r; }
; __device__ __forceinline__ float bf_lo(unsigned w) { return __uint_as_float(w << 16); }
; __device__ __forceinline__ float bf_hi(unsigned w) { return __uint_as_float(w & 0xffff0000u); }
;     __device__ __forceinline__ void operator()(const f32x4 (&acc)[2][2][4][2], const Unit& u, int ui, const LAS float* rtab, int wr, int wc, int fr, int fq) const {
;     ...
;                 const int row = row0 + ai * HALF + m * 16;
; #pragma unroll
;                 for (int bj = 0; bj < 2; ++bj) {
;                     const int col = col0 + bj * HALF; const u32x4 yv = *(const u32x4*)(Y + (size_t)row * 1024 + col);
;                     const f32x4 a0 = acc[ai][bj][m][0], a1 = acc[ai][bj][m][1]; float o[8];
;                     const float yy[8] = {bf_lo(yv.x), bf_hi(yv.x), bf_lo(yv.y), bf_hi(yv.y), bf_lo(yv.z), bf_hi(yv.z), bf_lo(yv.w), bf_hi(yv.w)};
; #pragma unroll
;                     for (int e = 0; e < 4; ++e) { o[e] = yy[e] / (1.0f + __expf(-a0[e])); o[4 + e] = yy[4 + e] / (1.0f + __expf(-a1[e])); }
;                     u32x4 w; w.x = cvt_pk_bf16(o[0], o[1]); w.y = cvt_pk_bf16(o[2], o[3]); w.z = cvt_pk_bf16(o[4], o[5]); w.w = cvt_pk_bf16(o[6], o[7]);
;                     *(u32x4*)(MG + (size_t)row * DM + 1024 + col) = w;
	v_lshlrev_b32_e32 v106, 16, v102
	v_and_b32_e32 v107, 0xffff0000, v102
	v_lshlrev_b32_e32 v110, 16, v105
	v_and_b32_e32 v102, 0xffff0000, v105
	v_div_scale_f32 v105, s[12:13], v94, v94, v106
	v_rcp_f32_e32 v111, v105
	v_lshlrev_b32_e32 v109, 16, v104
	v_and_b32_e32 v104, 0xffff0000, v104
	v_lshlrev_b32_e32 v108, 16, v103
	v_fma_f32 v112, -v105, v111, 1.0
	v_fmac_f32_e32 v111, v112, v111
	v_div_scale_f32 v112, vcc, v106, v94, v106
	v_mul_f32_e32 v113, v112, v111
	v_fma_f32 v114, -v105, v113, v112
	v_fmac_f32_e32 v113, v114, v111
	v_fma_f32 v105, -v105, v113, v112
	v_div_fmas_f32 v105, v105, v111, v113
	v_div_fixup_f32 v94, v105, v94, v106
	v_div_scale_f32 v105, s[12:13], v90, v90, v109
	v_rcp_f32_e32 v106, v105
	v_and_b32_e32 v103, 0xffff0000, v103
	v_fma_f32 v111, -v105, v106, 1.0
	v_fmac_f32_e32 v106, v111, v106
	v_div_scale_f32 v111, vcc, v109, v90, v109
	v_mul_f32_e32 v112, v111, v106
	v_fma_f32 v113, -v105, v112, v111
	v_fmac_f32_e32 v112, v113, v106
	v_fma_f32 v105, -v105, v112, v111
	v_div_fmas_f32 v105, v105, v106, v112
	v_div_fixup_f32 v90, v105, v90, v109
	v_div_scale_f32 v105, s[12:13], v95, v95, v107
	v_rcp_f32_e32 v106, v105
	s_nop 0
	v_fma_f32 v109, -v105, v106, 1.0
	v_fmac_f32_e32 v106, v109, v106
	v_div_scale_f32 v109, vcc, v107, v95, v107
	v_mul_f32_e32 v111, v109, v106
	v_fma_f32 v112, -v105, v111, v109
	v_fmac_f32_e32 v111, v112, v106
	v_fma_f32 v105, -v105, v111, v109
	v_div_fmas_f32 v105, v105, v106, v111
	v_div_fixup_f32 v95, v105, v95, v107
	v_div_scale_f32 v105, s[12:13], v91, v91, v104
	v_rcp_f32_e32 v106, v105
	s_nop 0
	v_fma_f32 v107, -v105, v106, 1.0
	v_fmac_f32_e32 v106, v107, v106
	v_div_scale_f32 v107, vcc, v104, v91, v104
	v_mul_f32_e32 v109, v107, v106
	v_fma_f32 v111, -v105, v109, v107
	v_fmac_f32_e32 v109, v111, v106
	v_fma_f32 v105, -v105, v109, v107
	v_div_fmas_f32 v105, v105, v106, v109
	v_div_fixup_f32 v91, v105, v91, v104
	v_div_scale_f32 v104, s[12:13], v96, v96, v108
	v_rcp_f32_e32 v105, v104
	s_nop 0
	v_fma_f32 v106, -v104, v105, 1.0
	v_fmac_f32_e32 v105, v106, v105
	v_div_scale_f32 v106, vcc, v108, v96, v108
	v_mul_f32_e32 v107, v106, v105
	v_fma_f32 v109, -v104, v107, v106
	v_fmac_f32_e32 v107, v109, v105
	v_fma_f32 v104, -v104, v107, v106
	v_div_fmas_f32 v104, v104, v105, v107
	v_div_fixup_f32 v96, v104, v96, v108
	v_div_scale_f32 v104, s[12:13], v92, v92, v110
	v_rcp_f32_e32 v105, v104
	s_nop 0
	v_fma_f32 v106, -v104, v105, 1.0
	v_fmac_f32_e32 v105, v106, v105
	v_div_scale_f32 v106, vcc, v110, v92, v110
	v_mul_f32_e32 v107, v106, v105
	v_fma_f32 v108, -v104, v107, v106
	v_fmac_f32_e32 v107, v108, v105
	v_fma_f32 v104, -v104, v107, v106
	v_div_fmas_f32 v104, v104, v105, v107
	v_div_fixup_f32 v104, v104, v92, v110
	v_mul_f32_e32 v92, 0xbfb8aa3b, v97
	v_exp_f32_e32 v92, v92
	s_nop 0
	v_add_f32_e32 v92, 1.0, v92
	v_div_scale_f32 v97, s[12:13], v92, v92, v103
	v_rcp_f32_e32 v105, v97
	s_nop 0
	v_fma_f32 v106, -v97, v105, 1.0
	v_fmac_f32_e32 v105, v106, v105
	v_div_scale_f32 v106, vcc, v103, v92, v103
	v_mul_f32_e32 v107, v106, v105
	v_fma_f32 v108, -v97, v107, v106
	v_fmac_f32_e32 v107, v108, v105
	v_fma_f32 v97, -v97, v107, v106
	v_div_fmas_f32 v97, v97, v105, v107
	v_div_fixup_f32 v97, v97, v92, v103
	v_mul_f32_e32 v92, 0xbfb8aa3b, v93
	v_exp_f32_e32 v92, v92
	s_nop 0
	v_add_f32_e32 v92, 1.0, v92
	v_div_scale_f32 v93, s[12:13], v92, v92, v102
	v_rcp_f32_e32 v103, v93
	s_nop 0
	v_fma_f32 v105, -v93, v103, 1.0
	v_fmac_f32_e32 v103, v105, v103
	v_div_scale_f32 v105, vcc, v102, v92, v102
	v_mul_f32_e32 v106, v105, v103
	v_fma_f32 v107, -v93, v106, v105
	v_fmac_f32_e32 v106, v107, v103
	v_fma_f32 v93, -v93, v106, v105
	v_div_fmas_f32 v93, v93, v103, v106
	v_div_fixup_f32 v102, v93, v92, v102
	v_cvt_pk_bf16_f32 v92, v94, v95
	v_cvt_pk_bf16_f32 v93, v96, v97
	v_cvt_pk_bf16_f32 v94, v90, v91
	v_lshl_add_u64 v[90:91], s[88:89], 0, v[100:101]
	v_cvt_pk_bf16_f32 v95, v104, v102
	v_lshl_add_u64 v[90:91], v[90:91], 0, v[142:143]
	global_store_dwordx4 v[90:91], v[92:95], off offset:2048
	global_load_dwordx4 v[92:95], v[98:99], off offset:256
	s_waitcnt vmcnt(0)
	v_lshlrev_b32_e32 v96, 16, v92
	v_and_b32_e32 v97, 0xffff0000, v92
	v_lshlrev_b32_e32 v100, 16, v95
	v_and_b32_e32 v92, 0xffff0000, v95
	v_div_scale_f32 v95, s[12:13], v86, v86, v96
	v_rcp_f32_e32 v101, v95
	v_lshlrev_b32_e32 v99, 16, v94
	v_and_b32_e32 v94, 0xffff0000, v94
	v_lshlrev_b32_e32 v98, 16, v93
	v_fma_f32 v102, -v95, v101, 1.0
	v_fmac_f32_e32 v101, v102, v101
	v_div_scale_f32 v102, vcc, v96, v86, v96
	v_mul_f32_e32 v103, v102, v101
	v_fma_f32 v104, -v95, v103, v102
	v_fmac_f32_e32 v103, v104, v101
	v_fma_f32 v95, -v95, v103, v102
	v_div_fmas_f32 v95, v95, v101, v103
	v_div_fixup_f32 v86, v95, v86, v96
	v_div_scale_f32 v95, s[12:13], v82, v82, v99
	v_rcp_f32_e32 v96, v95
	v_and_b32_e32 v93, 0xffff0000, v93
	v_fma_f32 v101, -v95, v96, 1.0
	v_fmac_f32_e32 v96, v101, v96
	v_div_scale_f32 v101, vcc, v99, v82, v99
	v_mul_f32_e32 v102, v101, v96
	v_fma_f32 v103, -v95, v102, v101
	v_fmac_f32_e32 v102, v103, v96
	v_fma_f32 v95, -v95, v102, v101
	v_div_fmas_f32 v95, v95, v96, v102
	v_div_fixup_f32 v95, v95, v82, v99
	v_mul_f32_e32 v82, 0xbfb8aa3b, v87
	v_exp_f32_e32 v82, v82
	s_nop 0
	v_add_f32_e32 v82, 1.0, v82
	v_div_scale_f32 v87, s[12:13], v82, v82, v97
	v_rcp_f32_e32 v96, v87
	s_nop 0
	v_fma_f32 v99, -v87, v96, 1.0
	v_fmac_f32_e32 v96, v99, v96
	v_div_scale_f32 v99, vcc, v97, v82, v97
	v_mul_f32_e32 v101, v99, v96
	v_fma_f32 v102, -v87, v101, v99
	v_fmac_f32_e32 v101, v102, v96
	v_fma_f32 v87, -v87, v101, v99
	v_div_fmas_f32 v87, v87, v96, v101
	v_div_fixup_f32 v82, v87, v82, v97
	v_div_scale_f32 v87, s[12:13], v83, v83, v94
	v_rcp_f32_e32 v96, v87
; __device__ __forceinline__ unsigned cvt_pk_bf16(float lo, float hi) { unsigned r; asm volatile("v_cvt_pk_bf16_f32 %0, %1, %2" : "=v"(r) : "v"(lo), "v"(hi)); return r; }
; __device__ __forceinline__ float bf_lo(unsigned w) { return __uint_as_float(w << 16); }
; __device__ __forceinline__ float bf_hi(unsigned w) { return __uint_as_float(w & 0xffff0000u); }
;     __device__ __forceinline__ void operator()(const f32x4 (&acc)[2][2][4][2], const Unit& u, int ui, const LAS float* rtab, int wr, int wc, int fr, int fq) const {
;     ...
;                 const int row = row0 + ai * HALF + m * 16;
; #pragma unroll
;                 for (int bj = 0; bj < 2; ++bj) {
;                     const int col = col0 + bj * HALF; const u32x4 yv = *(const u32x4*)(Y + (size_t)row * 1024 + col);
;                     const f32x4 a0 = acc[ai][bj][m][0], a1 = acc[ai][bj][m][1]; float o[8];
;                     const float yy[8] = {bf_lo(yv.x), bf_hi(yv.x), bf_lo(yv.y), bf_hi(yv.y), bf_lo(yv.z), bf_hi(yv.z), bf_lo(yv.w), bf_hi(yv.w)};
; #pragma unroll
;                     for (int e = 0; e < 4; ++e) { o[e] = yy[e] / (1.0f + __expf(-a0[e])); o[4 + e] = yy[4 + e] / (1.0f + __expf(-a1[e])); }
;                     u32x4 w; w.x = cvt_pk_bf16(o[0], o[1]); w.y = cvt_pk_bf16(o[2], o[3]); w.z = cvt_pk_bf16(o[4], o[5]); w.w = cvt_pk_bf16(o[6], o[7]);
;                     *(u32x4*)(MG + (size_t)row * DM + 1024 + col) = w;
	v_cvt_pk_bf16_f32 v82, v86, v82
	s_nop 0
	v_fma_f32 v97, -v87, v96, 1.0
	v_fmac_f32_e32 v96, v97, v96
	v_div_scale_f32 v97, vcc, v94, v83, v94
	v_mul_f32_e32 v99, v97, v96
	v_fma_f32 v101, -v87, v99, v97
	v_fmac_f32_e32 v99, v101, v96
	v_fma_f32 v87, -v87, v99, v97
	v_div_fmas_f32 v87, v87, v96, v99
	v_div_fixup_f32 v87, v87, v83, v94
	v_mul_f32_e32 v83, 0xbfb8aa3b, v88
	v_exp_f32_e32 v83, v83
	s_nop 0
	v_add_f32_e32 v83, 1.0, v83
	v_div_scale_f32 v88, s[12:13], v83, v83, v98
	v_rcp_f32_e32 v94, v88
	s_nop 0
	v_fma_f32 v96, -v88, v94, 1.0
	v_fmac_f32_e32 v94, v96, v94
	v_div_scale_f32 v96, vcc, v98, v83, v98
	v_mul_f32_e32 v97, v96, v94
	v_fma_f32 v99, -v88, v97, v96
	v_fmac_f32_e32 v97, v99, v94
	v_fma_f32 v88, -v88, v97, v96
	v_div_fmas_f32 v88, v88, v94, v97
	v_div_fixup_f32 v83, v88, v83, v98
	v_div_scale_f32 v88, s[12:13], v84, v84, v100
	v_rcp_f32_e32 v94, v88
	s_nop 0
	v_fma_f32 v96, -v88, v94, 1.0
	v_fmac_f32_e32 v94, v96, v94
	v_div_scale_f32 v96, vcc, v100, v84, v100
	v_mul_f32_e32 v97, v96, v94
	v_fma_f32 v98, -v88, v97, v96
	v_fmac_f32_e32 v97, v98, v94
	v_fma_f32 v88, -v88, v97, v96
	v_div_fmas_f32 v88, v88, v94, v97
	v_div_fixup_f32 v88, v88, v84, v100
	v_mul_f32_e32 v84, 0xbfb8aa3b, v89
	v_exp_f32_e32 v84, v84
	s_nop 0
	v_add_f32_e32 v84, 1.0, v84
	v_div_scale_f32 v89, s[12:13], v84, v84, v93
	v_rcp_f32_e32 v94, v89
	s_nop 0
	v_fma_f32 v96, -v89, v94, 1.0
	v_fmac_f32_e32 v94, v96, v94
	v_div_scale_f32 v96, vcc, v93, v84, v93
	v_mul_f32_e32 v97, v96, v94
	v_fma_f32 v98, -v89, v97, v96
	v_fmac_f32_e32 v97, v98, v94
	v_fma_f32 v89, -v89, v97, v96
	v_div_fmas_f32 v89, v89, v94, v97
	v_div_fixup_f32 v84, v89, v84, v93
	v_div_scale_f32 v89, s[12:13], v85, v85, v92
	v_rcp_f32_e32 v93, v89
	v_cvt_pk_bf16_f32 v83, v83, v84
	v_cvt_pk_bf16_f32 v84, v95, v87
	s_nop 0
	v_fma_f32 v94, -v89, v93, 1.0
	v_fmac_f32_e32 v93, v94, v93
	v_div_scale_f32 v94, vcc, v92, v85, v92
	v_mul_f32_e32 v96, v94, v93
	v_fma_f32 v97, -v89, v96, v94
	v_fmac_f32_e32 v96, v97, v93
	v_fma_f32 v89, -v89, v96, v94
	v_div_fmas_f32 v89, v89, v93, v96
	v_div_fixup_f32 v85, v89, v85, v92
	v_cvt_pk_bf16_f32 v85, v88, v85
	global_store_dwordx4 v[90:91], v[82:85], off offset:2304
	s_nop 1
	v_or_b32_e32 v82, 48, v144
	v_ashrrev_i32_e32 v83, 31, v82
	v_lshlrev_b64 v[86:87], 11, v[82:83]
	v_lshlrev_b64 v[84:85], 12, v[82:83]
	v_lshl_add_u64 v[82:83], s[86:87], 0, v[86:87]
	v_lshl_add_u64 v[82:83], v[82:83], 0, v[142:143]
	global_load_dwordx4 v[86:89], v[82:83], off
	s_waitcnt vmcnt(0)
	v_lshlrev_b32_e32 v90, 16, v86
	v_and_b32_e32 v91, 0xffff0000, v86
	v_lshlrev_b32_e32 v94, 16, v89
	v_and_b32_e32 v86, 0xffff0000, v89
	v_div_scale_f32 v89, s[12:13], v78, v78, v90
	v_rcp_f32_e32 v95, v89
	v_lshlrev_b32_e32 v93, 16, v88
	v_and_b32_e32 v88, 0xffff0000, v88
	v_lshlrev_b32_e32 v92, 16, v87
	v_fma_f32 v96, -v89, v95, 1.0
	v_fmac_f32_e32 v95, v96, v95
	v_div_scale_f32 v96, vcc, v90, v78, v90
	v_mul_f32_e32 v97, v96, v95
	v_fma_f32 v98, -v89, v97, v96
	v_fmac_f32_e32 v97, v98, v95
	v_fma_f32 v89, -v89, v97, v96
	v_div_fmas_f32 v89, v89, v95, v97
	v_div_fixup_f32 v78, v89, v78, v90
	v_div_scale_f32 v89, s[12:13], v74, v74, v93
	v_rcp_f32_e32 v90, v89
	v_and_b32_e32 v87, 0xffff0000, v87
	v_fma_f32 v95, -v89, v90, 1.0
	v_fmac_f32_e32 v90, v95, v90
	v_div_scale_f32 v95, vcc, v93, v74, v93
	v_mul_f32_e32 v96, v95, v90
	v_fma_f32 v97, -v89, v96, v95
	v_fmac_f32_e32 v96, v97, v90
	v_fma_f32 v89, -v89, v96, v95
	v_div_fmas_f32 v89, v89, v90, v96
	v_div_fixup_f32 v74, v89, v74, v93
	v_div_scale_f32 v89, s[12:13], v79, v79, v91
	v_rcp_f32_e32 v90, v89
	s_nop 0
	v_fma_f32 v93, -v89, v90, 1.0
	v_fmac_f32_e32 v90, v93, v90
	v_div_scale_f32 v93, vcc, v91, v79, v91
	v_mul_f32_e32 v95, v93, v90
	v_fma_f32 v96, -v89, v95, v93
	v_fmac_f32_e32 v95, v96, v90
	v_fma_f32 v89, -v89, v95, v93
	v_div_fmas_f32 v89, v89, v90, v95
	v_div_fixup_f32 v79, v89, v79, v91
	v_div_scale_f32 v89, s[12:13], v75, v75, v88
	v_rcp_f32_e32 v90, v89
	s_nop 0
	v_fma_f32 v91, -v89, v90, 1.0
	v_fmac_f32_e32 v90, v91, v90
	v_div_scale_f32 v91, vcc, v88, v75, v88
	v_mul_f32_e32 v93, v91, v90
	v_fma_f32 v95, -v89, v93, v91
	v_fmac_f32_e32 v93, v95, v90
	v_fma_f32 v89, -v89, v93, v91
	v_div_fmas_f32 v89, v89, v90, v93
	v_div_fixup_f32 v75, v89, v75, v88
	v_div_scale_f32 v88, s[12:13], v80, v80, v92
	v_rcp_f32_e32 v89, v88
	s_nop 0
	v_fma_f32 v90, -v88, v89, 1.0
	v_fmac_f32_e32 v89, v90, v89
	v_div_scale_f32 v90, vcc, v92, v80, v92
	v_mul_f32_e32 v91, v90, v89
	v_fma_f32 v93, -v88, v91, v90
	v_fmac_f32_e32 v91, v93, v89
	v_fma_f32 v88, -v88, v91, v90
	v_div_fmas_f32 v88, v88, v89, v91
	v_div_fixup_f32 v80, v88, v80, v92
	v_div_scale_f32 v88, s[12:13], v76, v76, v94
	v_rcp_f32_e32 v89, v88
	s_nop 0
	v_fma_f32 v90, -v88, v89, 1.0
	v_fmac_f32_e32 v89, v90, v89
	v_div_scale_f32 v90, vcc, v94, v76, v94
	v_mul_f32_e32 v91, v90, v89
	v_fma_f32 v92, -v88, v91, v90
	v_fmac_f32_e32 v91, v92, v89
	v_fma_f32 v88, -v88, v91, v90
	v_div_fmas_f32 v88, v88, v89, v91
	v_div_fixup_f32 v88, v88, v76, v94
	v_mul_f32_e32 v76, 0xbfb8aa3b, v81
	v_exp_f32_e32 v76, v76
	s_nop 0
	v_add_f32_e32 v76, 1.0, v76
	v_div_scale_f32 v81, s[12:13], v76, v76, v87
	v_rcp_f32_e32 v89, v81
	s_nop 0
	v_fma_f32 v90, -v81, v89, 1.0
	v_fmac_f32_e32 v89, v90, v89
	v_div_scale_f32 v90, vcc, v87, v76, v87
	v_mul_f32_e32 v91, v90, v89
	v_fma_f32 v92, -v81, v91, v90
	v_fmac_f32_e32 v91, v92, v89
	v_fma_f32 v81, -v81, v91, v90
	v_div_fmas_f32 v81, v81, v89, v91
	v_div_fixup_f32 v81, v81, v76, v87
	v_mul_f32_e32 v76, 0xbfb8aa3b, v77
	v_exp_f32_e32 v76, v76
	s_nop 0
	v_add_f32_e32 v76, 1.0, v76
	v_div_scale_f32 v77, s[12:13], v76, v76, v86
	v_rcp_f32_e32 v87, v77
	s_nop 0
	v_fma_f32 v89, -v77, v87, 1.0
	v_fmac_f32_e32 v87, v89, v87
	v_div_scale_f32 v89, vcc, v86, v76, v86
	v_mul_f32_e32 v90, v89, v87
	v_fma_f32 v91, -v77, v90, v89
	v_fmac_f32_e32 v90, v91, v87
	v_fma_f32 v77, -v77, v90, v89
	v_div_fmas_f32 v77, v77, v87, v90
	v_div_fixup_f32 v86, v77, v76, v86
	v_cvt_pk_bf16_f32 v76, v78, v79
	v_cvt_pk_bf16_f32 v77, v80, v81
	v_cvt_pk_bf16_f32 v78, v74, v75
	v_lshl_add_u64 v[74:75], s[88:89], 0, v[84:85]
	v_cvt_pk_bf16_f32 v79, v88, v86
	v_lshl_add_u64 v[74:75], v[74:75], 0, v[142:143]
	global_store_dwordx4 v[74:75], v[76:79], off offset:2048
	global_load_dwordx4 v[76:79], v[82:83], off offset:256
	s_waitcnt vmcnt(0)
; __device__ __forceinline__ unsigned cvt_pk_bf16(float lo, float hi) { unsigned r; asm volatile("v_cvt_pk_bf16_f32 %0, %1, %2" : "=v"(r) : "v"(lo), "v"(hi)); return r; }
; __device__ __forceinline__ float bf_lo(unsigned w) { return __uint_as_float(w << 16); }
; __device__ __forceinline__ float bf_hi(unsigned w) { return __uint_as_float(w & 0xffff0000u); }
;     __device__ __forceinline__ void operator()(const f32x4 (&acc)[2][2][4][2], const Unit& u, int ui, const LAS float* rtab, int wr, int wc, int fr, int fq) const {
;     ...
;                 const int row = row0 + ai * HALF + m * 16;
; #pragma unroll
;                 for (int bj = 0; bj < 2; ++bj) {
;                     const int col = col0 + bj * HALF; const u32x4 yv = *(const u32x4*)(Y + (size_t)row * 1024 + col);
;                     const f32x4 a0 = acc[ai][bj][m][0], a1 = acc[ai][bj][m][1]; float o[8];
;                     const float yy[8] = {bf_lo(yv.x), bf_hi(yv.x), bf_lo(yv.y), bf_hi(yv.y), bf_lo(yv.z), bf_hi(yv.z), bf_lo(yv.w), bf_hi(yv.w)};
; #pragma unroll
;                     for (int e = 0; e < 4; ++e) { o[e] = yy[e] / (1.0f + __expf(-a0[e])); o[4 + e] = yy[4 + e] / (1.0f + __expf(-a1[e])); }
;                     u32x4 w; w.x = cvt_pk_bf16(o[0], o[1]); w.y = cvt_pk_bf16(o[2], o[3]); w.z = cvt_pk_bf16(o[4], o[5]); w.w = cvt_pk_bf16(o[6], o[7]);
;                     *(u32x4*)(MG + (size_t)row * DM + 1024 + col) = w;
	v_lshlrev_b32_e32 v80, 16, v76
	v_and_b32_e32 v81, 0xffff0000, v76
	v_lshlrev_b32_e32 v84, 16, v79
	v_and_b32_e32 v76, 0xffff0000, v79
	v_div_scale_f32 v79, s[12:13], v70, v70, v80
	v_rcp_f32_e32 v85, v79
	v_lshlrev_b32_e32 v83, 16, v78
	v_and_b32_e32 v78, 0xffff0000, v78
	v_lshlrev_b32_e32 v82, 16, v77
	v_fma_f32 v86, -v79, v85, 1.0
	v_fmac_f32_e32 v85, v86, v85
	v_div_scale_f32 v86, vcc, v80, v70, v80
	v_mul_f32_e32 v87, v86, v85
	v_fma_f32 v88, -v79, v87, v86
	v_fmac_f32_e32 v87, v88, v85
	v_fma_f32 v79, -v79, v87, v86
	v_div_fmas_f32 v79, v79, v85, v87
	v_div_fixup_f32 v70, v79, v70, v80
	v_div_scale_f32 v79, s[12:13], v66, v66, v83
	v_rcp_f32_e32 v80, v79
	v_and_b32_e32 v77, 0xffff0000, v77
	v_fma_f32 v85, -v79, v80, 1.0
	v_fmac_f32_e32 v80, v85, v80
	v_div_scale_f32 v85, vcc, v83, v66, v83
	v_mul_f32_e32 v86, v85, v80
	v_fma_f32 v87, -v79, v86, v85
	v_fmac_f32_e32 v86, v87, v80
	v_fma_f32 v79, -v79, v86, v85
	v_div_fmas_f32 v79, v79, v80, v86
	v_div_fixup_f32 v79, v79, v66, v83
	v_mul_f32_e32 v66, 0xbfb8aa3b, v71
	v_exp_f32_e32 v66, v66
	s_nop 0
	v_add_f32_e32 v66, 1.0, v66
	v_div_scale_f32 v71, s[12:13], v66, v66, v81
	v_rcp_f32_e32 v80, v71
	s_nop 0
	v_fma_f32 v83, -v71, v80, 1.0
	v_fmac_f32_e32 v80, v83, v80
	v_div_scale_f32 v83, vcc, v81, v66, v81
	v_mul_f32_e32 v85, v83, v80
	v_fma_f32 v86, -v71, v85, v83
	v_fmac_f32_e32 v85, v86, v80
	v_fma_f32 v71, -v71, v85, v83
	v_div_fmas_f32 v71, v71, v80, v85
	v_div_fixup_f32 v66, v71, v66, v81
	v_div_scale_f32 v71, s[12:13], v67, v67, v78
	v_rcp_f32_e32 v80, v71
	v_cvt_pk_bf16_f32 v66, v70, v66
	s_nop 0
	v_fma_f32 v81, -v71, v80, 1.0
	v_fmac_f32_e32 v80, v81, v80
	v_div_scale_f32 v81, vcc, v78, v67, v78
	v_mul_f32_e32 v83, v81, v80
	v_fma_f32 v85, -v71, v83, v81
	v_fmac_f32_e32 v83, v85, v80
	v_fma_f32 v71, -v71, v83, v81
	v_div_fmas_f32 v71, v71, v80, v83
	v_div_fixup_f32 v71, v71, v67, v78
	v_mul_f32_e32 v67, 0xbfb8aa3b, v72
	v_exp_f32_e32 v67, v67
	s_nop 0
	v_add_f32_e32 v67, 1.0, v67
	v_div_scale_f32 v72, s[12:13], v67, v67, v82
	v_rcp_f32_e32 v78, v72
	s_nop 0
	v_fma_f32 v80, -v72, v78, 1.0
	v_fmac_f32_e32 v78, v80, v78
	v_div_scale_f32 v80, vcc, v82, v67, v82
	v_mul_f32_e32 v81, v80, v78
	v_fma_f32 v83, -v72, v81, v80
	v_fmac_f32_e32 v81, v83, v78
	v_fma_f32 v72, -v72, v81, v80
	v_div_fmas_f32 v72, v72, v78, v81
	v_div_fixup_f32 v67, v72, v67, v82
	v_div_scale_f32 v72, s[12:13], v68, v68, v84
	v_rcp_f32_e32 v78, v72
	s_nop 0
	v_fma_f32 v80, -v72, v78, 1.0
	v_fmac_f32_e32 v78, v80, v78
	v_div_scale_f32 v80, vcc, v84, v68, v84
	v_mul_f32_e32 v81, v80, v78
	v_fma_f32 v82, -v72, v81, v80
	v_fmac_f32_e32 v81, v82, v78
	v_fma_f32 v72, -v72, v81, v80
	v_div_fmas_f32 v72, v72, v78, v81
	v_div_fixup_f32 v72, v72, v68, v84
	v_mul_f32_e32 v68, 0xbfb8aa3b, v73
	v_exp_f32_e32 v68, v68
	s_nop 0
	v_add_f32_e32 v68, 1.0, v68
	v_div_scale_f32 v73, s[12:13], v68, v68, v77
	v_rcp_f32_e32 v78, v73
	s_nop 0
	v_fma_f32 v80, -v73, v78, 1.0
	v_fmac_f32_e32 v78, v80, v78
	v_div_scale_f32 v80, vcc, v77, v68, v77
	v_mul_f32_e32 v81, v80, v78
	v_fma_f32 v82, -v73, v81, v80
	v_fmac_f32_e32 v81, v82, v78
	v_fma_f32 v73, -v73, v81, v80
	v_div_fmas_f32 v73, v73, v78, v81
	v_div_fixup_f32 v68, v73, v68, v77
	v_div_scale_f32 v73, s[12:13], v69, v69, v76
	v_rcp_f32_e32 v77, v73
	v_cvt_pk_bf16_f32 v67, v67, v68
	v_cvt_pk_bf16_f32 v68, v79, v71
	s_nop 0
	v_fma_f32 v78, -v73, v77, 1.0
	v_fmac_f32_e32 v77, v78, v77
	v_div_scale_f32 v78, vcc, v76, v69, v76
	v_mul_f32_e32 v80, v78, v77
	v_fma_f32 v81, -v73, v80, v78
	v_fmac_f32_e32 v80, v81, v77
	v_fma_f32 v73, -v73, v80, v78
	v_div_fmas_f32 v73, v73, v77, v80
	v_div_fixup_f32 v69, v73, v69, v76
	v_cvt_pk_bf16_f32 v69, v72, v69
	global_store_dwordx4 v[74:75], v[66:69], off offset:2304
	s_nop 1
	v_add_u32_e32 v66, 0x80, v144
	v_ashrrev_i32_e32 v67, 31, v66
	v_lshlrev_b64 v[70:71], 11, v[66:67]
	v_lshlrev_b64 v[68:69], 12, v[66:67]
	v_lshl_add_u64 v[66:67], s[86:87], 0, v[70:71]
	v_lshl_add_u64 v[66:67], v[66:67], 0, v[142:143]
	global_load_dwordx4 v[70:73], v[66:67], off
	s_waitcnt vmcnt(0)
	v_lshlrev_b32_e32 v74, 16, v70
	v_and_b32_e32 v75, 0xffff0000, v70
	v_lshlrev_b32_e32 v78, 16, v73
	v_and_b32_e32 v70, 0xffff0000, v73
	v_div_scale_f32 v73, s[12:13], v62, v62, v74
	v_rcp_f32_e32 v79, v73
	v_lshlrev_b32_e32 v77, 16, v72
	v_and_b32_e32 v72, 0xffff0000, v72
	v_lshlrev_b32_e32 v76, 16, v71
	v_fma_f32 v80, -v73, v79, 1.0
	v_fmac_f32_e32 v79, v80, v79
	v_div_scale_f32 v80, vcc, v74, v62, v74
	v_mul_f32_e32 v81, v80, v79
	v_fma_f32 v82, -v73, v81, v80
	v_fmac_f32_e32 v81, v82, v79
	v_fma_f32 v73, -v73, v81, v80
	v_div_fmas_f32 v73, v73, v79, v81
	v_div_fixup_f32 v62, v73, v62, v74
	v_div_scale_f32 v73, s[12:13], v58, v58, v77
	v_rcp_f32_e32 v74, v73
	v_and_b32_e32 v71, 0xffff0000, v71
	v_fma_f32 v79, -v73, v74, 1.0
	v_fmac_f32_e32 v74, v79, v74
	v_div_scale_f32 v79, vcc, v77, v58, v77
	v_mul_f32_e32 v80, v79, v74
	v_fma_f32 v81, -v73, v80, v79
	v_fmac_f32_e32 v80, v81, v74
	v_fma_f32 v73, -v73, v80, v79
	v_div_fmas_f32 v73, v73, v74, v80
	v_div_fixup_f32 v58, v73, v58, v77
	v_div_scale_f32 v73, s[12:13], v63, v63, v75
	v_rcp_f32_e32 v74, v73
	s_nop 0
	v_fma_f32 v77, -v73, v74, 1.0
	v_fmac_f32_e32 v74, v77, v74
	v_div_scale_f32 v77, vcc, v75, v63, v75
	v_mul_f32_e32 v79, v77, v74
	v_fma_f32 v80, -v73, v79, v77
	v_fmac_f32_e32 v79, v80, v74
	v_fma_f32 v73, -v73, v79, v77
	v_div_fmas_f32 v73, v73, v74, v79
	v_div_fixup_f32 v63, v73, v63, v75
	v_div_scale_f32 v73, s[12:13], v59, v59, v72
	v_rcp_f32_e32 v74, v73
	s_nop 0
	v_fma_f32 v75, -v73, v74, 1.0
	v_fmac_f32_e32 v74, v75, v74
	v_div_scale_f32 v75, vcc, v72, v59, v72
	v_mul_f32_e32 v77, v75, v74
	v_fma_f32 v79, -v73, v77, v75
; __device__ __forceinline__ unsigned cvt_pk_bf16(float lo, float hi) { unsigned r; asm volatile("v_cvt_pk_bf16_f32 %0, %1, %2" : "=v"(r) : "v"(lo), "v"(hi)); return r; }
; __device__ __forceinline__ float bf_lo(unsigned w) { return __uint_as_float(w << 16); }
; __device__ __forceinline__ float bf_hi(unsigned w) { return __uint_as_float(w & 0xffff0000u); }
;     __device__ __forceinline__ void operator()(const f32x4 (&acc)[2][2][4][2], const Unit& u, int ui, const LAS float* rtab, int wr, int wc, int fr, int fq) const {
;     ...
;                 const int row = row0 + ai * HALF + m * 16;
; #pragma unroll
;                 for (int bj = 0; bj < 2; ++bj) {
;                     const int col = col0 + bj * HALF; const u32x4 yv = *(const u32x4*)(Y + (size_t)row * 1024 + col);
;                     const f32x4 a0 = acc[ai][bj][m][0], a1 = acc[ai][bj][m][1]; float o[8];
;                     const float yy[8] = {bf_lo(yv.x), bf_hi(yv.x), bf_lo(yv.y), bf_hi(yv.y), bf_lo(yv.z), bf_hi(yv.z), bf_lo(yv.w), bf_hi(yv.w)};
; #pragma unroll
;                     for (int e = 0; e < 4; ++e) { o[e] = yy[e] / (1.0f + __expf(-a0[e])); o[4 + e] = yy[4 + e] / (1.0f + __expf(-a1[e])); }
;                     u32x4 w; w.x = cvt_pk_bf16(o[0], o[1]); w.y = cvt_pk_bf16(o[2], o[3]); w.z = cvt_pk_bf16(o[4], o[5]); w.w = cvt_pk_bf16(o[6], o[7]);
;                     *(u32x4*)(MG + (size_t)row * DM + 1024 + col) = w;
	v_fmac_f32_e32 v77, v79, v74
	v_fma_f32 v73, -v73, v77, v75
	v_div_fmas_f32 v73, v73, v74, v77
	v_div_fixup_f32 v59, v73, v59, v72
	v_div_scale_f32 v72, s[12:13], v64, v64, v76
	v_rcp_f32_e32 v73, v72
	s_nop 0
	v_fma_f32 v74, -v72, v73, 1.0
	v_fmac_f32_e32 v73, v74, v73
	v_div_scale_f32 v74, vcc, v76, v64, v76
	v_mul_f32_e32 v75, v74, v73
	v_fma_f32 v77, -v72, v75, v74
	v_fmac_f32_e32 v75, v77, v73
	v_fma_f32 v72, -v72, v75, v74
	v_div_fmas_f32 v72, v72, v73, v75
	v_div_fixup_f32 v64, v72, v64, v76
	v_div_scale_f32 v72, s[12:13], v60, v60, v78
	v_rcp_f32_e32 v73, v72
	s_nop 0
	v_fma_f32 v74, -v72, v73, 1.0
	v_fmac_f32_e32 v73, v74, v73
	v_div_scale_f32 v74, vcc, v78, v60, v78
	v_mul_f32_e32 v75, v74, v73
	v_fma_f32 v76, -v72, v75, v74
	v_fmac_f32_e32 v75, v76, v73
	v_fma_f32 v72, -v72, v75, v74
	v_div_fmas_f32 v72, v72, v73, v75
	v_div_fixup_f32 v72, v72, v60, v78
	v_mul_f32_e32 v60, 0xbfb8aa3b, v65
	v_exp_f32_e32 v60, v60
	s_nop 0
	v_add_f32_e32 v60, 1.0, v60
	v_div_scale_f32 v65, s[12:13], v60, v60, v71
	v_rcp_f32_e32 v73, v65
	s_nop 0
	v_fma_f32 v74, -v65, v73, 1.0
	v_fmac_f32_e32 v73, v74, v73
	v_div_scale_f32 v74, vcc, v71, v60, v71
	v_mul_f32_e32 v75, v74, v73
	v_fma_f32 v76, -v65, v75, v74
	v_fmac_f32_e32 v75, v76, v73
	v_fma_f32 v65, -v65, v75, v74
	v_div_fmas_f32 v65, v65, v73, v75
	v_div_fixup_f32 v65, v65, v60, v71
	v_mul_f32_e32 v60, 0xbfb8aa3b, v61
	v_exp_f32_e32 v60, v60
	s_nop 0
	v_add_f32_e32 v60, 1.0, v60
	v_div_scale_f32 v61, s[12:13], v60, v60, v70
	v_rcp_f32_e32 v71, v61
	s_nop 0
	v_fma_f32 v73, -v61, v71, 1.0
	v_fmac_f32_e32 v71, v73, v71
	v_div_scale_f32 v73, vcc, v70, v60, v70
	v_mul_f32_e32 v74, v73, v71
	v_fma_f32 v75, -v61, v74, v73
	v_fmac_f32_e32 v74, v75, v71
	v_fma_f32 v61, -v61, v74, v73
	v_div_fmas_f32 v61, v61, v71, v74
	v_div_fixup_f32 v70, v61, v60, v70
	v_cvt_pk_bf16_f32 v60, v62, v63
	v_cvt_pk_bf16_f32 v61, v64, v65
	v_cvt_pk_bf16_f32 v62, v58, v59
	v_lshl_add_u64 v[58:59], s[88:89], 0, v[68:69]
	v_cvt_pk_bf16_f32 v63, v72, v70
	v_lshl_add_u64 v[58:59], v[58:59], 0, v[142:143]
	global_store_dwordx4 v[58:59], v[60:63], off offset:2048
	global_load_dwordx4 v[60:63], v[66:67], off offset:256
	s_waitcnt vmcnt(0)
	v_lshlrev_b32_e32 v64, 16, v60
	v_and_b32_e32 v65, 0xffff0000, v60
	v_lshlrev_b32_e32 v68, 16, v63
	v_and_b32_e32 v60, 0xffff0000, v63
	v_div_scale_f32 v63, s[12:13], v54, v54, v64
	v_rcp_f32_e32 v69, v63
	v_lshlrev_b32_e32 v67, 16, v62
	v_and_b32_e32 v62, 0xffff0000, v62
	v_lshlrev_b32_e32 v66, 16, v61
	v_fma_f32 v70, -v63, v69, 1.0
	v_fmac_f32_e32 v69, v70, v69
	v_div_scale_f32 v70, vcc, v64, v54, v64
	v_mul_f32_e32 v71, v70, v69
	v_fma_f32 v72, -v63, v71, v70
	v_fmac_f32_e32 v71, v72, v69
	v_fma_f32 v63, -v63, v71, v70
	v_div_fmas_f32 v63, v63, v69, v71
	v_div_fixup_f32 v54, v63, v54, v64
	v_div_scale_f32 v63, s[12:13], v50, v50, v67
	v_rcp_f32_e32 v64, v63
	v_and_b32_e32 v61, 0xffff0000, v61
	v_fma_f32 v69, -v63, v64, 1.0
	v_fmac_f32_e32 v64, v69, v64
	v_div_scale_f32 v69, vcc, v67, v50, v67
	v_mul_f32_e32 v70, v69, v64
	v_fma_f32 v71, -v63, v70, v69
	v_fmac_f32_e32 v70, v71, v64
	v_fma_f32 v63, -v63, v70, v69
	v_div_fmas_f32 v63, v63, v64, v70
	v_div_fixup_f32 v63, v63, v50, v67
	v_mul_f32_e32 v50, 0xbfb8aa3b, v55
	v_exp_f32_e32 v50, v50
	s_nop 0
	v_add_f32_e32 v50, 1.0, v50
	v_div_scale_f32 v55, s[12:13], v50, v50, v65
	v_rcp_f32_e32 v64, v55
	s_nop 0
	v_fma_f32 v67, -v55, v64, 1.0
	v_fmac_f32_e32 v64, v67, v64
	v_div_scale_f32 v67, vcc, v65, v50, v65
	v_mul_f32_e32 v69, v67, v64
	v_fma_f32 v70, -v55, v69, v67
	v_fmac_f32_e32 v69, v70, v64
	v_fma_f32 v55, -v55, v69, v67
	v_div_fmas_f32 v55, v55, v64, v69
	v_div_fixup_f32 v50, v55, v50, v65
	v_div_scale_f32 v55, s[12:13], v51, v51, v62
	v_rcp_f32_e32 v64, v55
	v_cvt_pk_bf16_f32 v50, v54, v50
	s_nop 0
	v_fma_f32 v65, -v55, v64, 1.0
	v_fmac_f32_e32 v64, v65, v64
	v_div_scale_f32 v65, vcc, v62, v51, v62
	v_mul_f32_e32 v67, v65, v64
	v_fma_f32 v69, -v55, v67, v65
	v_fmac_f32_e32 v67, v69, v64
	v_fma_f32 v55, -v55, v67, v65
	v_div_fmas_f32 v55, v55, v64, v67
	v_div_fixup_f32 v55, v55, v51, v62
	v_mul_f32_e32 v51, 0xbfb8aa3b, v56
	v_exp_f32_e32 v51, v51
	s_nop 0
	v_add_f32_e32 v51, 1.0, v51
	v_div_scale_f32 v56, s[12:13], v51, v51, v66
	v_rcp_f32_e32 v62, v56
	s_nop 0
	v_fma_f32 v64, -v56, v62, 1.0
	v_fmac_f32_e32 v62, v64, v62
	v_div_scale_f32 v64, vcc, v66, v51, v66
	v_mul_f32_e32 v65, v64, v62
	v_fma_f32 v67, -v56, v65, v64
	v_fmac_f32_e32 v65, v67, v62
	v_fma_f32 v56, -v56, v65, v64
	v_div_fmas_f32 v56, v56, v62, v65
	v_div_fixup_f32 v51, v56, v51, v66
	v_div_scale_f32 v56, s[12:13], v52, v52, v68
	v_rcp_f32_e32 v62, v56
	s_nop 0
	v_fma_f32 v64, -v56, v62, 1.0
	v_fmac_f32_e32 v62, v64, v62
	v_div_scale_f32 v64, vcc, v68, v52, v68
	v_mul_f32_e32 v65, v64, v62
	v_fma_f32 v66, -v56, v65, v64
	v_fmac_f32_e32 v65, v66, v62
	v_fma_f32 v56, -v56, v65, v64
	v_div_fmas_f32 v56, v56, v62, v65
	v_div_fixup_f32 v56, v56, v52, v68
	v_mul_f32_e32 v52, 0xbfb8aa3b, v57
	v_exp_f32_e32 v52, v52
	s_nop 0
	v_add_f32_e32 v52, 1.0, v52
	v_div_scale_f32 v57, s[12:13], v52, v52, v61
	v_rcp_f32_e32 v62, v57
	s_nop 0
	v_fma_f32 v64, -v57, v62, 1.0
	v_fmac_f32_e32 v62, v64, v62
	v_div_scale_f32 v64, vcc, v61, v52, v61
	v_mul_f32_e32 v65, v64, v62
	v_fma_f32 v66, -v57, v65, v64
	v_fmac_f32_e32 v65, v66, v62
	v_fma_f32 v57, -v57, v65, v64
	v_div_fmas_f32 v57, v57, v62, v65
	v_div_fixup_f32 v52, v57, v52, v61
	v_div_scale_f32 v57, s[12:13], v53, v53, v60
	v_rcp_f32_e32 v61, v57
	v_cvt_pk_bf16_f32 v51, v51, v52
	v_cvt_pk_bf16_f32 v52, v63, v55
	s_nop 0
	v_fma_f32 v62, -v57, v61, 1.0
	v_fmac_f32_e32 v61, v62, v61
	v_div_scale_f32 v62, vcc, v60, v53, v60
	v_mul_f32_e32 v64, v62, v61
	v_fma_f32 v65, -v57, v64, v62
	v_fmac_f32_e32 v64, v65, v61
	v_fma_f32 v57, -v57, v64, v62
	v_div_fmas_f32 v57, v57, v61, v64
	v_div_fixup_f32 v53, v57, v53, v60
	v_cvt_pk_bf16_f32 v53, v56, v53
	global_store_dwordx4 v[58:59], v[50:53], off offset:2304
	s_nop 1
	v_add_u32_e32 v50, 0x90, v144
	v_ashrrev_i32_e32 v51, 31, v50
	v_lshlrev_b64 v[54:55], 11, v[50:51]
	v_lshlrev_b64 v[52:53], 12, v[50:51]
	v_lshl_add_u64 v[50:51], s[86:87], 0, v[54:55]
	v_lshl_add_u64 v[50:51], v[50:51], 0, v[142:143]
	global_load_dwordx4 v[54:57], v[50:51], off
	s_waitcnt vmcnt(0)
; __device__ __forceinline__ unsigned cvt_pk_bf16(float lo, float hi) { unsigned r; asm volatile("v_cvt_pk_bf16_f32 %0, %1, %2" : "=v"(r) : "v"(lo), "v"(hi)); return r; }
; __device__ __forceinline__ float bf_lo(unsigned w) { return __uint_as_float(w << 16); }
; __device__ __forceinline__ float bf_hi(unsigned w) { return __uint_as_float(w & 0xffff0000u); }
;     __device__ __forceinline__ void operator()(const f32x4 (&acc)[2][2][4][2], const Unit& u, int ui, const LAS float* rtab, int wr, int wc, int fr, int fq) const {
;     ...
;                 const int row = row0 + ai * HALF + m * 16;
; #pragma unroll
;                 for (int bj = 0; bj < 2; ++bj) {
;                     const int col = col0 + bj * HALF; const u32x4 yv = *(const u32x4*)(Y + (size_t)row * 1024 + col);
;                     const f32x4 a0 = acc[ai][bj][m][0], a1 = acc[ai][bj][m][1]; float o[8];
;                     const float yy[8] = {bf_lo(yv.x), bf_hi(yv.x), bf_lo(yv.y), bf_hi(yv.y), bf_lo(yv.z), bf_hi(yv.z), bf_lo(yv.w), bf_hi(yv.w)};
; #pragma unroll
;                     for (int e = 0; e < 4; ++e) { o[e] = yy[e] / (1.0f + __expf(-a0[e])); o[4 + e] = yy[4 + e] / (1.0f + __expf(-a1[e])); }
;                     u32x4 w; w.x = cvt_pk_bf16(o[0], o[1]); w.y = cvt_pk_bf16(o[2], o[3]); w.z = cvt_pk_bf16(o[4], o[5]); w.w = cvt_pk_bf16(o[6], o[7]);
;                     *(u32x4*)(MG + (size_t)row * DM + 1024 + col) = w;
	v_lshlrev_b32_e32 v58, 16, v54
	v_and_b32_e32 v59, 0xffff0000, v54
	v_lshlrev_b32_e32 v62, 16, v57
	v_and_b32_e32 v54, 0xffff0000, v57
	v_div_scale_f32 v57, s[12:13], v46, v46, v58
	v_rcp_f32_e32 v63, v57
	v_lshlrev_b32_e32 v61, 16, v56
	v_and_b32_e32 v56, 0xffff0000, v56
	v_lshlrev_b32_e32 v60, 16, v55
	v_fma_f32 v64, -v57, v63, 1.0
	v_fmac_f32_e32 v63, v64, v63
	v_div_scale_f32 v64, vcc, v58, v46, v58
	v_mul_f32_e32 v65, v64, v63
	v_fma_f32 v66, -v57, v65, v64
	v_fmac_f32_e32 v65, v66, v63
	v_fma_f32 v57, -v57, v65, v64
	v_div_fmas_f32 v57, v57, v63, v65
	v_div_fixup_f32 v46, v57, v46, v58
	v_div_scale_f32 v57, s[12:13], v42, v42, v61
	v_rcp_f32_e32 v58, v57
	v_and_b32_e32 v55, 0xffff0000, v55
	v_fma_f32 v63, -v57, v58, 1.0
	v_fmac_f32_e32 v58, v63, v58
	v_div_scale_f32 v63, vcc, v61, v42, v61
	v_mul_f32_e32 v64, v63, v58
	v_fma_f32 v65, -v57, v64, v63
	v_fmac_f32_e32 v64, v65, v58
	v_fma_f32 v57, -v57, v64, v63
	v_div_fmas_f32 v57, v57, v58, v64
	v_div_fixup_f32 v42, v57, v42, v61
	v_div_scale_f32 v57, s[12:13], v47, v47, v59
	v_rcp_f32_e32 v58, v57
	s_nop 0
	v_fma_f32 v61, -v57, v58, 1.0
	v_fmac_f32_e32 v58, v61, v58
	v_div_scale_f32 v61, vcc, v59, v47, v59
	v_mul_f32_e32 v63, v61, v58
	v_fma_f32 v64, -v57, v63, v61
	v_fmac_f32_e32 v63, v64, v58
	v_fma_f32 v57, -v57, v63, v61
	v_div_fmas_f32 v57, v57, v58, v63
	v_div_fixup_f32 v47, v57, v47, v59
	v_div_scale_f32 v57, s[12:13], v43, v43, v56
	v_rcp_f32_e32 v58, v57
	s_nop 0
	v_fma_f32 v59, -v57, v58, 1.0
	v_fmac_f32_e32 v58, v59, v58
	v_div_scale_f32 v59, vcc, v56, v43, v56
	v_mul_f32_e32 v61, v59, v58
	v_fma_f32 v63, -v57, v61, v59
	v_fmac_f32_e32 v61, v63, v58
	v_fma_f32 v57, -v57, v61, v59
	v_div_fmas_f32 v57, v57, v58, v61
	v_div_fixup_f32 v43, v57, v43, v56
	v_div_scale_f32 v56, s[12:13], v48, v48, v60
	v_rcp_f32_e32 v57, v56
	s_nop 0
	v_fma_f32 v58, -v56, v57, 1.0
	v_fmac_f32_e32 v57, v58, v57
	v_div_scale_f32 v58, vcc, v60, v48, v60
	v_mul_f32_e32 v59, v58, v57
	v_fma_f32 v61, -v56, v59, v58
	v_fmac_f32_e32 v59, v61, v57
	v_fma_f32 v56, -v56, v59, v58
	v_div_fmas_f32 v56, v56, v57, v59
	v_div_fixup_f32 v48, v56, v48, v60
	v_div_scale_f32 v56, s[12:13], v44, v44, v62
	v_rcp_f32_e32 v57, v56
	s_nop 0
	v_fma_f32 v58, -v56, v57, 1.0
	v_fmac_f32_e32 v57, v58, v57
	v_div_scale_f32 v58, vcc, v62, v44, v62
	v_mul_f32_e32 v59, v58, v57
	v_fma_f32 v60, -v56, v59, v58
	v_fmac_f32_e32 v59, v60, v57
	v_fma_f32 v56, -v56, v59, v58
	v_div_fmas_f32 v56, v56, v57, v59
	v_div_fixup_f32 v56, v56, v44, v62
	v_mul_f32_e32 v44, 0xbfb8aa3b, v49
	v_exp_f32_e32 v44, v44
	s_nop 0
	v_add_f32_e32 v44, 1.0, v44
	v_div_scale_f32 v49, s[12:13], v44, v44, v55
	v_rcp_f32_e32 v57, v49
	s_nop 0
	v_fma_f32 v58, -v49, v57, 1.0
	v_fmac_f32_e32 v57, v58, v57
	v_div_scale_f32 v58, vcc, v55, v44, v55
	v_mul_f32_e32 v59, v58, v57
	v_fma_f32 v60, -v49, v59, v58
	v_fmac_f32_e32 v59, v60, v57
	v_fma_f32 v49, -v49, v59, v58
	v_div_fmas_f32 v49, v49, v57, v59
	v_div_fixup_f32 v49, v49, v44, v55
	v_mul_f32_e32 v44, 0xbfb8aa3b, v45
	v_exp_f32_e32 v44, v44
	s_nop 0
	v_add_f32_e32 v44, 1.0, v44
	v_div_scale_f32 v45, s[12:13], v44, v44, v54
	v_rcp_f32_e32 v55, v45
	s_nop 0
	v_fma_f32 v57, -v45, v55, 1.0
	v_fmac_f32_e32 v55, v57, v55
	v_div_scale_f32 v57, vcc, v54, v44, v54
	v_mul_f32_e32 v58, v57, v55
	v_fma_f32 v59, -v45, v58, v57
	v_fmac_f32_e32 v58, v59, v55
	v_fma_f32 v45, -v45, v58, v57
	v_div_fmas_f32 v45, v45, v55, v58
	v_div_fixup_f32 v54, v45, v44, v54
	v_cvt_pk_bf16_f32 v44, v46, v47
	v_cvt_pk_bf16_f32 v45, v48, v49
	v_cvt_pk_bf16_f32 v46, v42, v43
	v_lshl_add_u64 v[42:43], s[88:89], 0, v[52:53]
	v_cvt_pk_bf16_f32 v47, v56, v54
	v_lshl_add_u64 v[42:43], v[42:43], 0, v[142:143]
	global_store_dwordx4 v[42:43], v[44:47], off offset:2048
	global_load_dwordx4 v[44:47], v[50:51], off offset:256
	s_waitcnt vmcnt(0)
	v_lshlrev_b32_e32 v48, 16, v44
	v_and_b32_e32 v49, 0xffff0000, v44
	v_lshlrev_b32_e32 v52, 16, v47
	v_and_b32_e32 v44, 0xffff0000, v47
	v_div_scale_f32 v47, s[12:13], v38, v38, v48
	v_rcp_f32_e32 v53, v47
	v_lshlrev_b32_e32 v51, 16, v46
	v_and_b32_e32 v46, 0xffff0000, v46
	v_lshlrev_b32_e32 v50, 16, v45
	v_fma_f32 v54, -v47, v53, 1.0
	v_fmac_f32_e32 v53, v54, v53
	v_div_scale_f32 v54, vcc, v48, v38, v48
	v_mul_f32_e32 v55, v54, v53
	v_fma_f32 v56, -v47, v55, v54
	v_fmac_f32_e32 v55, v56, v53
	v_fma_f32 v47, -v47, v55, v54
	v_div_fmas_f32 v47, v47, v53, v55
	v_div_fixup_f32 v38, v47, v38, v48
	v_div_scale_f32 v47, s[12:13], v34, v34, v51
	v_rcp_f32_e32 v48, v47
	v_and_b32_e32 v45, 0xffff0000, v45
	v_fma_f32 v53, -v47, v48, 1.0
	v_fmac_f32_e32 v48, v53, v48
	v_div_scale_f32 v53, vcc, v51, v34, v51
	v_mul_f32_e32 v54, v53, v48
	v_fma_f32 v55, -v47, v54, v53
	v_fmac_f32_e32 v54, v55, v48
	v_fma_f32 v47, -v47, v54, v53
	v_div_fmas_f32 v47, v47, v48, v54
	v_div_fixup_f32 v47, v47, v34, v51
	v_mul_f32_e32 v34, 0xbfb8aa3b, v39
	v_exp_f32_e32 v34, v34
	s_nop 0
	v_add_f32_e32 v34, 1.0, v34
	v_div_scale_f32 v39, s[12:13], v34, v34, v49
	v_rcp_f32_e32 v48, v39
	s_nop 0
	v_fma_f32 v51, -v39, v48, 1.0
	v_fmac_f32_e32 v48, v51, v48
	v_div_scale_f32 v51, vcc, v49, v34, v49
	v_mul_f32_e32 v53, v51, v48
	v_fma_f32 v54, -v39, v53, v51
	v_fmac_f32_e32 v53, v54, v48
	v_fma_f32 v39, -v39, v53, v51
	v_div_fmas_f32 v39, v39, v48, v53
	v_div_fixup_f32 v34, v39, v34, v49
	v_div_scale_f32 v39, s[12:13], v35, v35, v46
	v_rcp_f32_e32 v48, v39
	v_cvt_pk_bf16_f32 v34, v38, v34
	s_nop 0
	v_fma_f32 v49, -v39, v48, 1.0
	v_fmac_f32_e32 v48, v49, v48
	v_div_scale_f32 v49, vcc, v46, v35, v46
	v_mul_f32_e32 v51, v49, v48
	v_fma_f32 v53, -v39, v51, v49
	v_fmac_f32_e32 v51, v53, v48
	v_fma_f32 v39, -v39, v51, v49
	v_div_fmas_f32 v39, v39, v48, v51
; __device__ __forceinline__ unsigned cvt_pk_bf16(float lo, float hi) { unsigned r; asm volatile("v_cvt_pk_bf16_f32 %0, %1, %2" : "=v"(r) : "v"(lo), "v"(hi)); return r; }
; __device__ __forceinline__ float bf_lo(unsigned w) { return __uint_as_float(w << 16); }
; __device__ __forceinline__ float bf_hi(unsigned w) { return __uint_as_float(w & 0xffff0000u); }
;     __device__ __forceinline__ void operator()(const f32x4 (&acc)[2][2][4][2], const Unit& u, int ui, const LAS float* rtab, int wr, int wc, int fr, int fq) const {
;     ...
;                 const int row = row0 + ai * HALF + m * 16;
; #pragma unroll
;                 for (int bj = 0; bj < 2; ++bj) {
;                     const int col = col0 + bj * HALF; const u32x4 yv = *(const u32x4*)(Y + (size_t)row * 1024 + col);
;                     const f32x4 a0 = acc[ai][bj][m][0], a1 = acc[ai][bj][m][1]; float o[8];
;                     const float yy[8] = {bf_lo(yv.x), bf_hi(yv.x), bf_lo(yv.y), bf_hi(yv.y), bf_lo(yv.z), bf_hi(yv.z), bf_lo(yv.w), bf_hi(yv.w)};
; #pragma unroll
;                     for (int e = 0; e < 4; ++e) { o[e] = yy[e] / (1.0f + __expf(-a0[e])); o[4 + e] = yy[4 + e] / (1.0f + __expf(-a1[e])); }
;                     u32x4 w; w.x = cvt_pk_bf16(o[0], o[1]); w.y = cvt_pk_bf16(o[2], o[3]); w.z = cvt_pk_bf16(o[4], o[5]); w.w = cvt_pk_bf16(o[6], o[7]);
;                     *(u32x4*)(MG + (size_t)row * DM + 1024 + col) = w;
	v_div_fixup_f32 v39, v39, v35, v46
	v_mul_f32_e32 v35, 0xbfb8aa3b, v40
	v_exp_f32_e32 v35, v35
	s_nop 0
	v_add_f32_e32 v35, 1.0, v35
	v_div_scale_f32 v40, s[12:13], v35, v35, v50
	v_rcp_f32_e32 v46, v40
	s_nop 0
	v_fma_f32 v48, -v40, v46, 1.0
	v_fmac_f32_e32 v46, v48, v46
	v_div_scale_f32 v48, vcc, v50, v35, v50
	v_mul_f32_e32 v49, v48, v46
	v_fma_f32 v51, -v40, v49, v48
	v_fmac_f32_e32 v49, v51, v46
	v_fma_f32 v40, -v40, v49, v48
	v_div_fmas_f32 v40, v40, v46, v49
	v_div_fixup_f32 v35, v40, v35, v50
	v_div_scale_f32 v40, s[12:13], v36, v36, v52
	v_rcp_f32_e32 v46, v40
	s_nop 0
	v_fma_f32 v48, -v40, v46, 1.0
	v_fmac_f32_e32 v46, v48, v46
	v_div_scale_f32 v48, vcc, v52, v36, v52
	v_mul_f32_e32 v49, v48, v46
	v_fma_f32 v50, -v40, v49, v48
	v_fmac_f32_e32 v49, v50, v46
	v_fma_f32 v40, -v40, v49, v48
	v_div_fmas_f32 v40, v40, v46, v49
	v_div_fixup_f32 v40, v40, v36, v52
	v_mul_f32_e32 v36, 0xbfb8aa3b, v41
	v_exp_f32_e32 v36, v36
	s_nop 0
	v_add_f32_e32 v36, 1.0, v36
	v_div_scale_f32 v41, s[12:13], v36, v36, v45
	v_rcp_f32_e32 v46, v41
	s_nop 0
	v_fma_f32 v48, -v41, v46, 1.0
	v_fmac_f32_e32 v46, v48, v46
	v_div_scale_f32 v48, vcc, v45, v36, v45
	v_mul_f32_e32 v49, v48, v46
	v_fma_f32 v50, -v41, v49, v48
	v_fmac_f32_e32 v49, v50, v46
	v_fma_f32 v41, -v41, v49, v48
	v_div_fmas_f32 v41, v41, v46, v49
	v_div_fixup_f32 v36, v41, v36, v45
	v_div_scale_f32 v41, s[12:13], v37, v37, v44
	v_rcp_f32_e32 v45, v41
	v_cvt_pk_bf16_f32 v35, v35, v36
	v_cvt_pk_bf16_f32 v36, v47, v39
	s_nop 0
	v_fma_f32 v46, -v41, v45, 1.0
	v_fmac_f32_e32 v45, v46, v45
	v_div_scale_f32 v46, vcc, v44, v37, v44
	v_mul_f32_e32 v48, v46, v45
	v_fma_f32 v49, -v41, v48, v46
	v_fmac_f32_e32 v48, v49, v45
	v_fma_f32 v41, -v41, v48, v46
	v_div_fmas_f32 v41, v41, v45, v48
	v_div_fixup_f32 v37, v41, v37, v44
	v_cvt_pk_bf16_f32 v37, v40, v37
	global_store_dwordx4 v[42:43], v[34:37], off offset:2304
	s_nop 1
	v_add_u32_e32 v34, 0xa0, v144
	v_ashrrev_i32_e32 v35, 31, v34
	v_lshlrev_b64 v[38:39], 11, v[34:35]
	v_lshlrev_b64 v[36:37], 12, v[34:35]
	v_lshl_add_u64 v[34:35], s[86:87], 0, v[38:39]
	v_lshl_add_u64 v[34:35], v[34:35], 0, v[142:143]
	global_load_dwordx4 v[38:41], v[34:35], off
	s_waitcnt vmcnt(0)
	v_lshlrev_b32_e32 v42, 16, v38
	v_and_b32_e32 v43, 0xffff0000, v38
	v_lshlrev_b32_e32 v46, 16, v41
	v_and_b32_e32 v38, 0xffff0000, v41
	v_div_scale_f32 v41, s[12:13], v30, v30, v42
	v_rcp_f32_e32 v47, v41
	v_lshlrev_b32_e32 v45, 16, v40
	v_and_b32_e32 v40, 0xffff0000, v40
	v_lshlrev_b32_e32 v44, 16, v39
	v_fma_f32 v48, -v41, v47, 1.0
	v_fmac_f32_e32 v47, v48, v47
	v_div_scale_f32 v48, vcc, v42, v30, v42
	v_mul_f32_e32 v49, v48, v47
	v_fma_f32 v50, -v41, v49, v48
	v_fmac_f32_e32 v49, v50, v47
	v_fma_f32 v41, -v41, v49, v48
	v_div_fmas_f32 v41, v41, v47, v49
	v_div_fixup_f32 v30, v41, v30, v42
	v_div_scale_f32 v41, s[12:13], v26, v26, v45
	v_rcp_f32_e32 v42, v41
	v_and_b32_e32 v39, 0xffff0000, v39
	v_fma_f32 v47, -v41, v42, 1.0
	v_fmac_f32_e32 v42, v47, v42
	v_div_scale_f32 v47, vcc, v45, v26, v45
	v_mul_f32_e32 v48, v47, v42
	v_fma_f32 v49, -v41, v48, v47
	v_fmac_f32_e32 v48, v49, v42
	v_fma_f32 v41, -v41, v48, v47
	v_div_fmas_f32 v41, v41, v42, v48
	v_div_fixup_f32 v26, v41, v26, v45
	v_div_scale_f32 v41, s[12:13], v31, v31, v43
	v_rcp_f32_e32 v42, v41
	s_nop 0
	v_fma_f32 v45, -v41, v42, 1.0
	v_fmac_f32_e32 v42, v45, v42
	v_div_scale_f32 v45, vcc, v43, v31, v43
	v_mul_f32_e32 v47, v45, v42
	v_fma_f32 v48, -v41, v47, v45
	v_fmac_f32_e32 v47, v48, v42
	v_fma_f32 v41, -v41, v47, v45
	v_div_fmas_f32 v41, v41, v42, v47
	v_div_fixup_f32 v31, v41, v31, v43
	v_div_scale_f32 v41, s[12:13], v27, v27, v40
	v_rcp_f32_e32 v42, v41
	s_nop 0
	v_fma_f32 v43, -v41, v42, 1.0
	v_fmac_f32_e32 v42, v43, v42
	v_div_scale_f32 v43, vcc, v40, v27, v40
	v_mul_f32_e32 v45, v43, v42
	v_fma_f32 v47, -v41, v45, v43
	v_fmac_f32_e32 v45, v47, v42
	v_fma_f32 v41, -v41, v45, v43
	v_div_fmas_f32 v41, v41, v42, v45
	v_div_fixup_f32 v27, v41, v27, v40
	v_div_scale_f32 v40, s[12:13], v32, v32, v44
	v_rcp_f32_e32 v41, v40
	s_nop 0
	v_fma_f32 v42, -v40, v41, 1.0
	v_fmac_f32_e32 v41, v42, v41
	v_div_scale_f32 v42, vcc, v44, v32, v44
	v_mul_f32_e32 v43, v42, v41
	v_fma_f32 v45, -v40, v43, v42
	v_fmac_f32_e32 v43, v45, v41
	v_fma_f32 v40, -v40, v43, v42
	v_div_fmas_f32 v40, v40, v41, v43
	v_div_fixup_f32 v32, v40, v32, v44
	v_div_scale_f32 v40, s[12:13], v28, v28, v46
	v_rcp_f32_e32 v41, v40
	s_nop 0
	v_fma_f32 v42, -v40, v41, 1.0
	v_fmac_f32_e32 v41, v42, v41
	v_div_scale_f32 v42, vcc, v46, v28, v46
	v_mul_f32_e32 v43, v42, v41
	v_fma_f32 v44, -v40, v43, v42
	v_fmac_f32_e32 v43, v44, v41
	v_fma_f32 v40, -v40, v43, v42
	v_div_fmas_f32 v40, v40, v41, v43
	v_div_fixup_f32 v40, v40, v28, v46
	v_mul_f32_e32 v28, 0xbfb8aa3b, v33
	v_exp_f32_e32 v28, v28
	s_nop 0
	v_add_f32_e32 v28, 1.0, v28
	v_div_scale_f32 v33, s[12:13], v28, v28, v39
	v_rcp_f32_e32 v41, v33
	s_nop 0
	v_fma_f32 v42, -v33, v41, 1.0
	v_fmac_f32_e32 v41, v42, v41
	v_div_scale_f32 v42, vcc, v39, v28, v39
	v_mul_f32_e32 v43, v42, v41
	v_fma_f32 v44, -v33, v43, v42
	v_fmac_f32_e32 v43, v44, v41
	v_fma_f32 v33, -v33, v43, v42
	v_div_fmas_f32 v33, v33, v41, v43
	v_div_fixup_f32 v33, v33, v28, v39
	v_mul_f32_e32 v28, 0xbfb8aa3b, v29
	v_exp_f32_e32 v28, v28
	s_nop 0
	v_add_f32_e32 v28, 1.0, v28
	v_div_scale_f32 v29, s[12:13], v28, v28, v38
	v_rcp_f32_e32 v39, v29
	s_nop 0
	v_fma_f32 v41, -v29, v39, 1.0
	v_fmac_f32_e32 v39, v41, v39
	v_div_scale_f32 v41, vcc, v38, v28, v38
	v_mul_f32_e32 v42, v41, v39
	v_fma_f32 v43, -v29, v42, v41
	v_fmac_f32_e32 v42, v43, v39
	v_fma_f32 v29, -v29, v42, v41
	v_div_fmas_f32 v29, v29, v39, v42
	v_div_fixup_f32 v38, v29, v28, v38
	v_cvt_pk_bf16_f32 v28, v30, v31
	v_cvt_pk_bf16_f32 v29, v32, v33
	v_cvt_pk_bf16_f32 v30, v26, v27
	v_lshl_add_u64 v[26:27], s[88:89], 0, v[36:37]
	v_cvt_pk_bf16_f32 v31, v40, v38
	v_lshl_add_u64 v[26:27], v[26:27], 0, v[142:143]
	global_store_dwordx4 v[26:27], v[28:31], off offset:2048
	global_load_dwordx4 v[28:31], v[34:35], off offset:256
	s_waitcnt vmcnt(0)
; __device__ __forceinline__ unsigned cvt_pk_bf16(float lo, float hi) { unsigned r; asm volatile("v_cvt_pk_bf16_f32 %0, %1, %2" : "=v"(r) : "v"(lo), "v"(hi)); return r; }
; __device__ __forceinline__ float bf_lo(unsigned w) { return __uint_as_float(w << 16); }
; __device__ __forceinline__ float bf_hi(unsigned w) { return __uint_as_float(w & 0xffff0000u); }
;     __device__ __forceinline__ void operator()(const f32x4 (&acc)[2][2][4][2], const Unit& u, int ui, const LAS float* rtab, int wr, int wc, int fr, int fq) const {
;     ...
;                 const int row = row0 + ai * HALF + m * 16;
; #pragma unroll
;                 for (int bj = 0; bj < 2; ++bj) {
;                     const int col = col0 + bj * HALF; const u32x4 yv = *(const u32x4*)(Y + (size_t)row * 1024 + col);
;                     const f32x4 a0 = acc[ai][bj][m][0], a1 = acc[ai][bj][m][1]; float o[8];
;                     const float yy[8] = {bf_lo(yv.x), bf_hi(yv.x), bf_lo(yv.y), bf_hi(yv.y), bf_lo(yv.z), bf_hi(yv.z), bf_lo(yv.w), bf_hi(yv.w)};
; #pragma unroll
;                     for (int e = 0; e < 4; ++e) { o[e] = yy[e] / (1.0f + __expf(-a0[e])); o[4 + e] = yy[4 + e] / (1.0f + __expf(-a1[e])); }
;                     u32x4 w; w.x = cvt_pk_bf16(o[0], o[1]); w.y = cvt_pk_bf16(o[2], o[3]); w.z = cvt_pk_bf16(o[4], o[5]); w.w = cvt_pk_bf16(o[6], o[7]);
;                     *(u32x4*)(MG + (size_t)row * DM + 1024 + col) = w;
	v_lshlrev_b32_e32 v32, 16, v28
	v_and_b32_e32 v33, 0xffff0000, v28
	v_lshlrev_b32_e32 v36, 16, v31
	v_and_b32_e32 v28, 0xffff0000, v31
	v_div_scale_f32 v31, s[12:13], v22, v22, v32
	v_rcp_f32_e32 v37, v31
	v_lshlrev_b32_e32 v35, 16, v30
	v_and_b32_e32 v30, 0xffff0000, v30
	v_lshlrev_b32_e32 v34, 16, v29
	v_fma_f32 v38, -v31, v37, 1.0
	v_fmac_f32_e32 v37, v38, v37
	v_div_scale_f32 v38, vcc, v32, v22, v32
	v_mul_f32_e32 v39, v38, v37
	v_fma_f32 v40, -v31, v39, v38
	v_fmac_f32_e32 v39, v40, v37
	v_fma_f32 v31, -v31, v39, v38
	v_div_fmas_f32 v31, v31, v37, v39
	v_div_fixup_f32 v22, v31, v22, v32
	v_div_scale_f32 v31, s[12:13], v18, v18, v35
	v_rcp_f32_e32 v32, v31
	v_and_b32_e32 v29, 0xffff0000, v29
	v_fma_f32 v37, -v31, v32, 1.0
	v_fmac_f32_e32 v32, v37, v32
	v_div_scale_f32 v37, vcc, v35, v18, v35
	v_mul_f32_e32 v38, v37, v32
	v_fma_f32 v39, -v31, v38, v37
	v_fmac_f32_e32 v38, v39, v32
	v_fma_f32 v31, -v31, v38, v37
	v_div_fmas_f32 v31, v31, v32, v38
	v_div_fixup_f32 v31, v31, v18, v35
	v_mul_f32_e32 v18, 0xbfb8aa3b, v23
	v_exp_f32_e32 v18, v18
	s_nop 0
	v_add_f32_e32 v18, 1.0, v18
	v_div_scale_f32 v23, s[12:13], v18, v18, v33
	v_rcp_f32_e32 v32, v23
	s_nop 0
	v_fma_f32 v35, -v23, v32, 1.0
	v_fmac_f32_e32 v32, v35, v32
	v_div_scale_f32 v35, vcc, v33, v18, v33
	v_mul_f32_e32 v37, v35, v32
	v_fma_f32 v38, -v23, v37, v35
	v_fmac_f32_e32 v37, v38, v32
	v_fma_f32 v23, -v23, v37, v35
	v_div_fmas_f32 v23, v23, v32, v37
	v_div_fixup_f32 v18, v23, v18, v33
	v_div_scale_f32 v23, s[12:13], v19, v19, v30
	v_rcp_f32_e32 v32, v23
	v_cvt_pk_bf16_f32 v18, v22, v18
	s_nop 0
	v_fma_f32 v33, -v23, v32, 1.0
	v_fmac_f32_e32 v32, v33, v32
	v_div_scale_f32 v33, vcc, v30, v19, v30
	v_mul_f32_e32 v35, v33, v32
	v_fma_f32 v37, -v23, v35, v33
	v_fmac_f32_e32 v35, v37, v32
	v_fma_f32 v23, -v23, v35, v33
	v_div_fmas_f32 v23, v23, v32, v35
	v_div_fixup_f32 v23, v23, v19, v30
	v_mul_f32_e32 v19, 0xbfb8aa3b, v24
	v_exp_f32_e32 v19, v19
	s_nop 0
	v_add_f32_e32 v19, 1.0, v19
	v_div_scale_f32 v24, s[12:13], v19, v19, v34
	v_rcp_f32_e32 v30, v24
	s_nop 0
	v_fma_f32 v32, -v24, v30, 1.0
	v_fmac_f32_e32 v30, v32, v30
	v_div_scale_f32 v32, vcc, v34, v19, v34
	v_mul_f32_e32 v33, v32, v30
	v_fma_f32 v35, -v24, v33, v32
	v_fmac_f32_e32 v33, v35, v30
	v_fma_f32 v24, -v24, v33, v32
	v_div_fmas_f32 v24, v24, v30, v33
	v_div_fixup_f32 v19, v24, v19, v34
	v_div_scale_f32 v24, s[12:13], v20, v20, v36
	v_rcp_f32_e32 v30, v24
	s_nop 0
	v_fma_f32 v32, -v24, v30, 1.0
	v_fmac_f32_e32 v30, v32, v30
	v_div_scale_f32 v32, vcc, v36, v20, v36
	v_mul_f32_e32 v33, v32, v30
	v_fma_f32 v34, -v24, v33, v32
	v_fmac_f32_e32 v33, v34, v30
	v_fma_f32 v24, -v24, v33, v32
	v_div_fmas_f32 v24, v24, v30, v33
	v_div_fixup_f32 v24, v24, v20, v36
	v_mul_f32_e32 v20, 0xbfb8aa3b, v25
	v_exp_f32_e32 v20, v20
	s_nop 0
	v_add_f32_e32 v20, 1.0, v20
	v_div_scale_f32 v25, s[12:13], v20, v20, v29
	v_rcp_f32_e32 v30, v25
	s_nop 0
	v_fma_f32 v32, -v25, v30, 1.0
	v_fmac_f32_e32 v30, v32, v30
	v_div_scale_f32 v32, vcc, v29, v20, v29
	v_mul_f32_e32 v33, v32, v30
	v_fma_f32 v34, -v25, v33, v32
	v_fmac_f32_e32 v33, v34, v30
	v_fma_f32 v25, -v25, v33, v32
	v_div_fmas_f32 v25, v25, v30, v33
	v_div_fixup_f32 v20, v25, v20, v29
	v_div_scale_f32 v25, s[12:13], v21, v21, v28
	v_rcp_f32_e32 v29, v25
	v_cvt_pk_bf16_f32 v19, v19, v20
	v_cvt_pk_bf16_f32 v20, v31, v23
	s_nop 0
	v_fma_f32 v30, -v25, v29, 1.0
	v_fmac_f32_e32 v29, v30, v29
	v_div_scale_f32 v30, vcc, v28, v21, v28
	v_mul_f32_e32 v32, v30, v29
	v_fma_f32 v33, -v25, v32, v30
	v_fmac_f32_e32 v32, v33, v29
	v_fma_f32 v25, -v25, v32, v30
	v_div_fmas_f32 v25, v25, v29, v32
	v_div_fixup_f32 v21, v25, v21, v28
	v_cvt_pk_bf16_f32 v21, v24, v21
	global_store_dwordx4 v[26:27], v[18:21], off offset:2304
	s_nop 1
	v_add_u32_e32 v18, 0xb0, v144
	v_ashrrev_i32_e32 v19, 31, v18
	v_lshlrev_b64 v[22:23], 11, v[18:19]
	v_lshlrev_b64 v[20:21], 12, v[18:19]
	v_lshl_add_u64 v[18:19], s[86:87], 0, v[22:23]
	v_lshl_add_u64 v[18:19], v[18:19], 0, v[142:143]
	global_load_dwordx4 v[22:25], v[18:19], off
	s_waitcnt vmcnt(0)
	v_lshlrev_b32_e32 v26, 16, v22
	v_and_b32_e32 v27, 0xffff0000, v22
	v_lshlrev_b32_e32 v30, 16, v25
	v_and_b32_e32 v22, 0xffff0000, v25
	v_div_scale_f32 v25, s[12:13], v14, v14, v26
	v_rcp_f32_e32 v31, v25
	v_lshlrev_b32_e32 v29, 16, v24
	v_and_b32_e32 v24, 0xffff0000, v24
	v_lshlrev_b32_e32 v28, 16, v23
	v_fma_f32 v32, -v25, v31, 1.0
	v_fmac_f32_e32 v31, v32, v31
	v_div_scale_f32 v32, vcc, v26, v14, v26
	v_mul_f32_e32 v33, v32, v31
	v_fma_f32 v34, -v25, v33, v32
	v_fmac_f32_e32 v33, v34, v31
	v_fma_f32 v25, -v25, v33, v32
	v_div_fmas_f32 v25, v25, v31, v33
	v_div_fixup_f32 v14, v25, v14, v26
	v_div_scale_f32 v25, s[12:13], v10, v10, v29
	v_rcp_f32_e32 v26, v25
	v_and_b32_e32 v23, 0xffff0000, v23
	v_fma_f32 v31, -v25, v26, 1.0
	v_fmac_f32_e32 v26, v31, v26
	v_div_scale_f32 v31, vcc, v29, v10, v29
	v_mul_f32_e32 v32, v31, v26
	v_fma_f32 v33, -v25, v32, v31
	v_fmac_f32_e32 v32, v33, v26
	v_fma_f32 v25, -v25, v32, v31
	v_div_fmas_f32 v25, v25, v26, v32
	v_div_fixup_f32 v10, v25, v10, v29
	v_div_scale_f32 v25, s[12:13], v15, v15, v27
	v_rcp_f32_e32 v26, v25
	s_nop 0
	v_fma_f32 v29, -v25, v26, 1.0
	v_fmac_f32_e32 v26, v29, v26
	v_div_scale_f32 v29, vcc, v27, v15, v27
	v_mul_f32_e32 v31, v29, v26
	v_fma_f32 v32, -v25, v31, v29
	v_fmac_f32_e32 v31, v32, v26
	v_fma_f32 v25, -v25, v31, v29
	v_div_fmas_f32 v25, v25, v26, v31
	v_div_fixup_f32 v15, v25, v15, v27
	v_div_scale_f32 v25, s[12:13], v11, v11, v24
	v_rcp_f32_e32 v26, v25
	s_nop 0
	v_fma_f32 v27, -v25, v26, 1.0
	v_fmac_f32_e32 v26, v27, v26
	v_div_scale_f32 v27, vcc, v24, v11, v24
	v_mul_f32_e32 v29, v27, v26
	v_fma_f32 v31, -v25, v29, v27
; __device__ __forceinline__ unsigned cvt_pk_bf16(float lo, float hi) { unsigned r; asm volatile("v_cvt_pk_bf16_f32 %0, %1, %2" : "=v"(r) : "v"(lo), "v"(hi)); return r; }
; __device__ __forceinline__ float bf_lo(unsigned w) { return __uint_as_float(w << 16); }
; __device__ __forceinline__ float bf_hi(unsigned w) { return __uint_as_float(w & 0xffff0000u); }
; #define PG8_WAIT_V(n) asm volatile("s_waitcnt vmcnt(" #n ")" ::: "memory")
; #define PG8_BAR __builtin_amdgcn_s_barrier()
;     __device__ __forceinline__ void operator()(const f32x4 (&acc)[2][2][4][2], const Unit& u, int ui, const LAS float* rtab, int wr, int wc, int fr, int fq) const {
;     ...
;                 const int row = row0 + ai * HALF + m * 16;
; #pragma unroll
;                 for (int bj = 0; bj < 2; ++bj) {
;                     const int col = col0 + bj * HALF; const u32x4 yv = *(const u32x4*)(Y + (size_t)row * 1024 + col);
;                     const f32x4 a0 = acc[ai][bj][m][0], a1 = acc[ai][bj][m][1]; float o[8];
;                     const float yy[8] = {bf_lo(yv.x), bf_hi(yv.x), bf_lo(yv.y), bf_hi(yv.y), bf_lo(yv.z), bf_hi(yv.z), bf_lo(yv.w), bf_hi(yv.w)};
; #pragma unroll
;                     for (int e = 0; e < 4; ++e) { o[e] = yy[e] / (1.0f + __expf(-a0[e])); o[4 + e] = yy[4 + e] / (1.0f + __expf(-a1[e])); }
;                     u32x4 w; w.x = cvt_pk_bf16(o[0], o[1]); w.y = cvt_pk_bf16(o[2], o[3]); w.z = cvt_pk_bf16(o[4], o[5]); w.w = cvt_pk_bf16(o[6], o[7]);
;                     *(u32x4*)(MG + (size_t)row * DM + 1024 + col) = w;
; template <class Epi, class Sched>
; __device__ __forceinline__ void gemm_phase(LAS unsigned char* lds, const Gemm g, const Sched& S, const Epi& E) {
;     ...
;         if (!has_next) break;
;     ...
;     PG8_WAIT_V(0);
;     if (wr == 0) PG8_BAR;
;     PG8_BAR;
	v_fmac_f32_e32 v29, v31, v26
	v_fma_f32 v25, -v25, v29, v27
	v_div_fmas_f32 v25, v25, v26, v29
	v_div_fixup_f32 v11, v25, v11, v24
	v_div_scale_f32 v24, s[12:13], v16, v16, v28
	v_rcp_f32_e32 v25, v24
	s_nop 0
	v_fma_f32 v26, -v24, v25, 1.0
	v_fmac_f32_e32 v25, v26, v25
	v_div_scale_f32 v26, vcc, v28, v16, v28
	v_mul_f32_e32 v27, v26, v25
	v_fma_f32 v29, -v24, v27, v26
	v_fmac_f32_e32 v27, v29, v25
	v_fma_f32 v24, -v24, v27, v26
	v_div_fmas_f32 v24, v24, v25, v27
	v_div_fixup_f32 v16, v24, v16, v28
	v_div_scale_f32 v24, s[12:13], v12, v12, v30
	v_rcp_f32_e32 v25, v24
	s_nop 0
	v_fma_f32 v26, -v24, v25, 1.0
	v_fmac_f32_e32 v25, v26, v25
	v_div_scale_f32 v26, vcc, v30, v12, v30
	v_mul_f32_e32 v27, v26, v25
	v_fma_f32 v28, -v24, v27, v26
	v_fmac_f32_e32 v27, v28, v25
	v_fma_f32 v24, -v24, v27, v26
	v_div_fmas_f32 v24, v24, v25, v27
	v_div_fixup_f32 v24, v24, v12, v30
	v_mul_f32_e32 v12, 0xbfb8aa3b, v17
	v_exp_f32_e32 v12, v12
	s_nop 0
	v_add_f32_e32 v12, 1.0, v12
	v_div_scale_f32 v17, s[12:13], v12, v12, v23
	v_rcp_f32_e32 v25, v17
	s_nop 0
	v_fma_f32 v26, -v17, v25, 1.0
	v_fmac_f32_e32 v25, v26, v25
	v_div_scale_f32 v26, vcc, v23, v12, v23
	v_mul_f32_e32 v27, v26, v25
	v_fma_f32 v28, -v17, v27, v26
	v_fmac_f32_e32 v27, v28, v25
	v_fma_f32 v17, -v17, v27, v26
	v_div_fmas_f32 v17, v17, v25, v27
	v_div_fixup_f32 v17, v17, v12, v23
	v_mul_f32_e32 v12, 0xbfb8aa3b, v13
	v_exp_f32_e32 v12, v12
	s_nop 0
	v_add_f32_e32 v12, 1.0, v12
	v_div_scale_f32 v13, s[12:13], v12, v12, v22
	v_rcp_f32_e32 v23, v13
	s_nop 0
	v_fma_f32 v25, -v13, v23, 1.0
	v_fmac_f32_e32 v23, v25, v23
	v_div_scale_f32 v25, vcc, v22, v12, v22
	v_mul_f32_e32 v26, v25, v23
	v_fma_f32 v27, -v13, v26, v25
	v_fmac_f32_e32 v26, v27, v23
	v_fma_f32 v13, -v13, v26, v25
	v_div_fmas_f32 v13, v13, v23, v26
	v_div_fixup_f32 v22, v13, v12, v22
	v_cvt_pk_bf16_f32 v12, v14, v15
	v_cvt_pk_bf16_f32 v13, v16, v17
	v_cvt_pk_bf16_f32 v14, v10, v11
	v_lshl_add_u64 v[10:11], s[88:89], 0, v[20:21]
	v_cvt_pk_bf16_f32 v15, v24, v22
	v_lshl_add_u64 v[10:11], v[10:11], 0, v[142:143]
	global_store_dwordx4 v[10:11], v[12:15], off offset:2048
	global_load_dwordx4 v[12:15], v[18:19], off offset:256
	s_waitcnt vmcnt(0)
	v_lshlrev_b32_e32 v16, 16, v12
	v_and_b32_e32 v17, 0xffff0000, v12
	v_lshlrev_b32_e32 v20, 16, v15
	v_and_b32_e32 v12, 0xffff0000, v15
	v_div_scale_f32 v15, s[12:13], v6, v6, v16
	v_rcp_f32_e32 v21, v15
	v_lshlrev_b32_e32 v19, 16, v14
	v_and_b32_e32 v14, 0xffff0000, v14
	v_lshlrev_b32_e32 v18, 16, v13
	v_fma_f32 v22, -v15, v21, 1.0
	v_fmac_f32_e32 v21, v22, v21
	v_div_scale_f32 v22, vcc, v16, v6, v16
	v_mul_f32_e32 v23, v22, v21
	v_fma_f32 v24, -v15, v23, v22
	v_fmac_f32_e32 v23, v24, v21
	v_fma_f32 v15, -v15, v23, v22
	v_div_fmas_f32 v15, v15, v21, v23
	v_div_fixup_f32 v6, v15, v6, v16
	v_div_scale_f32 v15, s[12:13], v2, v2, v19
	v_rcp_f32_e32 v16, v15
	v_and_b32_e32 v13, 0xffff0000, v13
	v_fma_f32 v21, -v15, v16, 1.0
	v_fmac_f32_e32 v16, v21, v16
	v_div_scale_f32 v21, vcc, v19, v2, v19
	v_mul_f32_e32 v22, v21, v16
	v_fma_f32 v23, -v15, v22, v21
	v_fmac_f32_e32 v22, v23, v16
	v_fma_f32 v15, -v15, v22, v21
	v_div_fmas_f32 v15, v15, v16, v22
	v_div_fixup_f32 v15, v15, v2, v19
	v_mul_f32_e32 v2, 0xbfb8aa3b, v7
	v_exp_f32_e32 v2, v2
	s_nop 0
	v_add_f32_e32 v2, 1.0, v2
	v_div_scale_f32 v7, s[12:13], v2, v2, v17
	v_rcp_f32_e32 v16, v7
	s_nop 0
	v_fma_f32 v19, -v7, v16, 1.0
	v_fmac_f32_e32 v16, v19, v16
	v_div_scale_f32 v19, vcc, v17, v2, v17
	v_mul_f32_e32 v21, v19, v16
	v_fma_f32 v22, -v7, v21, v19
	v_fmac_f32_e32 v21, v22, v16
	v_fma_f32 v7, -v7, v21, v19
	v_div_fmas_f32 v7, v7, v16, v21
	v_div_fixup_f32 v2, v7, v2, v17
	v_div_scale_f32 v7, s[12:13], v3, v3, v14
	v_rcp_f32_e32 v16, v7
	v_cvt_pk_bf16_f32 v2, v6, v2
	s_nop 0
	v_fma_f32 v17, -v7, v16, 1.0
	v_fmac_f32_e32 v16, v17, v16
	v_div_scale_f32 v17, vcc, v14, v3, v14
	v_mul_f32_e32 v19, v17, v16
	v_fma_f32 v21, -v7, v19, v17
	v_fmac_f32_e32 v19, v21, v16
	v_fma_f32 v7, -v7, v19, v17
	v_div_fmas_f32 v7, v7, v16, v19
	v_div_fixup_f32 v7, v7, v3, v14
	v_mul_f32_e32 v3, 0xbfb8aa3b, v8
	v_exp_f32_e32 v3, v3
	s_nop 0
	v_add_f32_e32 v3, 1.0, v3
	v_div_scale_f32 v8, s[12:13], v3, v3, v18
	v_rcp_f32_e32 v14, v8
	s_nop 0
	v_fma_f32 v16, -v8, v14, 1.0
	v_fmac_f32_e32 v14, v16, v14
	v_div_scale_f32 v16, vcc, v18, v3, v18
	v_mul_f32_e32 v17, v16, v14
	v_fma_f32 v19, -v8, v17, v16
	v_fmac_f32_e32 v17, v19, v14
	v_fma_f32 v8, -v8, v17, v16
	v_div_fmas_f32 v8, v8, v14, v17
	v_div_fixup_f32 v3, v8, v3, v18
	v_div_scale_f32 v8, s[12:13], v4, v4, v20
	v_rcp_f32_e32 v14, v8
	s_nop 0
	v_fma_f32 v16, -v8, v14, 1.0
	v_fmac_f32_e32 v14, v16, v14
	v_div_scale_f32 v16, vcc, v20, v4, v20
	v_mul_f32_e32 v17, v16, v14
	v_fma_f32 v18, -v8, v17, v16
	v_fmac_f32_e32 v17, v18, v14
	v_fma_f32 v8, -v8, v17, v16
	v_div_fmas_f32 v8, v8, v14, v17
	v_div_fixup_f32 v8, v8, v4, v20
	v_mul_f32_e32 v4, 0xbfb8aa3b, v9
	v_exp_f32_e32 v4, v4
	s_nop 0
	v_add_f32_e32 v4, 1.0, v4
	v_div_scale_f32 v9, s[12:13], v4, v4, v13
	v_rcp_f32_e32 v14, v9
	s_nop 0
	v_fma_f32 v16, -v9, v14, 1.0
	v_fmac_f32_e32 v14, v16, v14
	v_div_scale_f32 v16, vcc, v13, v4, v13
	v_mul_f32_e32 v17, v16, v14
	v_fma_f32 v18, -v9, v17, v16
	v_fmac_f32_e32 v17, v18, v14
	v_fma_f32 v9, -v9, v17, v16
	v_div_fmas_f32 v9, v9, v14, v17
	v_div_fixup_f32 v4, v9, v4, v13
	v_div_scale_f32 v9, s[12:13], v5, v5, v12
	v_rcp_f32_e32 v13, v9
	s_mov_b32 s12, s0
	s_mov_b32 s13, s42
	v_cvt_pk_bf16_f32 v3, v3, v4
	v_fma_f32 v14, -v9, v13, 1.0
	v_fmac_f32_e32 v13, v14, v13
	v_div_scale_f32 v14, vcc, v12, v5, v12
	v_mul_f32_e32 v16, v14, v13
	v_fma_f32 v17, -v9, v16, v14
	v_fmac_f32_e32 v16, v17, v13
	v_fma_f32 v9, -v9, v16, v14
	v_div_fmas_f32 v9, v9, v13, v16
	v_div_fixup_f32 v5, v9, v5, v12
	s_and_b64 vcc, exec, s[40:41]
	v_cvt_pk_bf16_f32 v4, v15, v7
	v_cvt_pk_bf16_f32 v5, v8, v5
	global_store_dwordx4 v[10:11], v[2:5], off offset:2304
	s_cbranch_vccz .LBB0_661
	s_waitcnt vmcnt(0)
	s_cmpk_gt_u32 s27, 0xff
	s_cbranch_scc1 .LBB0_672
	s_barrier

; #define PG8_STAGE(bufoff, gbase, voff) do { _Pragma("unroll") for (int _i = 0; _i < 2; ++_i) \
;         __builtin_amdgcn_global_load_lds((const unsigned*)((const char*)(gbase) + (voff)[_i]), (LAS unsigned*)(lds + (bufoff) + ldsw + _i * 8192), 16, 0, 0); } while (0)
; #define PG8_LDA(dst, b, h) do { _Pragma("unroll") for (int m = 0; m < 4; ++m) _Pragma("unroll") for (int k = 0; k < 2; ++k) dst[m][k] = *(const LAS bf16x8*)(lds + PG8_SA(b, h) + aoff + m * 2048 + k * 1024); } while (0)
; #define PG8_LDB(dst, b, h) do { _Pragma("unroll") for (int n = 0; n < 2; ++n) _Pragma("unroll") for (int k = 0; k < 2; ++k) dst[n][k] = *(const LAS bf16x8*)(lds + PG8_SB(b, h) + boff + n * 2048 + k * 1024); } while (0)
; #define PG8_MMA(ai, bj, At, Bt) do { __builtin_amdgcn_s_setprio(1); _Pragma("unroll") for (int m = 0; m < 4; ++m) _Pragma("unroll") for (int n = 0; n < 2; ++n) _Pragma("unroll") for (int k = 0; k < 2; ++k) \
;         acc[ai][bj][m][n] = __builtin_amdgcn_mfma_f32_16x16x32_bf16(Bt[n][k], At[m][k], acc[ai][bj][m][n], 0, 0, 0); __builtin_amdgcn_s_setprio(0); } while (0)
; #define PG8_WAIT_V(n) asm volatile("s_waitcnt vmcnt(" #n ")" ::: "memory")
; #define PG8_WAIT_L(n) asm volatile("s_waitcnt lgkmcnt(" #n ")" ::: "memory")
; #define PG8_BAR __builtin_amdgcn_s_barrier()
; #define PG8_SCHED __builtin_amdgcn_sched_barrier(0)
; template <class Epi, class Sched>
; __device__ __forceinline__ void gemm_phase(LAS unsigned char* lds, const Gemm g, const Sched& S, const Epi& E) {
;     ...
;             const char* a1 = cA + (size_t)(t + 1) * kstep;
;             const char* a2 = last ? nA : cA + (size_t)(t + 2) * kstep; const char* b2 = last ? nB : cB + (size_t)(t + 2) * kstep;
;             const char* a3 = a2 + kstep; const char* b3 = b2 + kstep;
;             PG8_LDB(B0, 0, 0); PG8_SCHED; PG8_LDA(At, 0, 0); PG8_STAGE(PG8_SA(1, 1), a1 + hstepA, voffA);
;             PG8_WAIT_L(8); PG8_BAR; PG8_WAIT_L(0); PG8_MMA(0, 0, At, B0); PG8_BAR; PG8_SCHED;
;             PG8_LDB(B1, 0, 1); PG8_STAGE(PG8_SB(0, 0), b2, voffB);
;             PG8_BAR; PG8_WAIT_L(0); PG8_MMA(0, 1, At, B1); PG8_BAR;
;             PG8_LDA(At, 0, 1); PG8_STAGE(PG8_SA(0, 0), a2, voffA);
;             PG8_BAR; PG8_WAIT_L(0); PG8_MMA(1, 0, At, B0); PG8_BAR; PG8_SCHED;
;             PG8_STAGE(PG8_SB(0, 1), b2 + hstepB, voffB);
;             PG8_WAIT_V(6); PG8_BAR; PG8_MMA(1, 1, At, B1); PG8_BAR;
.LBB0_738:
	s_add_u32 s23, s48, 0xfff80080
	s_addc_u32 s50, s49, -1
	s_add_i32 s67, 0, 0x10000
	v_add_u32_e32 v142, s67, v162
	ds_read_b128 v[130:133], v142
	ds_read_b128 v[134:137], v142 offset:1024
	ds_read_b128 v[138:141], v142 offset:2048
	ds_read_b128 v[142:145], v142 offset:3072
	s_cmp_eq_u32 s66, 28
	s_cselect_b32 s53, s35, s50
	s_cselect_b32 s52, s59, s23
	s_cselect_b32 s51, s21, s71
	s_cselect_b32 s50, s68, s70
	v_lshl_add_u64 v[198:199], s[48:49], 0, v[178:179]
	s_add_i32 m0, s26, 0xc000
	ds_read_b128 v[146:149], v210
	ds_read_b128 v[150:153], v210 offset:1024
	ds_read_b128 v[182:185], v210 offset:2048
	ds_read_b128 v[186:189], v210 offset:3072
	ds_read_b128 v[190:193], v210 offset:4096
	ds_read_b128 v[194:197], v210 offset:5120
	ds_read_b128 v[212:215], v210 offset:6144
	ds_read_b128 v[216:219], v210 offset:7168
	global_load_lds_dwordx4 v[198:199], off
	s_add_i32 m0, s26, 0xe000
	v_lshl_add_u64 v[198:199], s[48:49], 0, v[180:181]
	global_load_lds_dwordx4 v[198:199], off
	s_waitcnt lgkmcnt(8)
	s_barrier
	s_waitcnt lgkmcnt(0)
	v_mfma_f32_16x16x32_bf16 v[126:129], v[130:133], v[146:149], v[126:129]
	v_mfma_f32_16x16x32_bf16 v[122:125], v[138:141], v[146:149], v[122:125]
	v_mfma_f32_16x16x32_bf16 v[110:113], v[130:133], v[182:185], v[110:113]
	v_mfma_f32_16x16x32_bf16 v[106:109], v[138:141], v[182:185], v[106:109]
	v_mfma_f32_16x16x32_bf16 v[94:97], v[130:133], v[190:193], v[94:97]
	v_mfma_f32_16x16x32_bf16 v[90:93], v[138:141], v[190:193], v[90:93]
	v_mfma_f32_16x16x32_bf16 v[78:81], v[130:133], v[212:215], v[78:81]
	v_mfma_f32_16x16x32_bf16 v[74:77], v[138:141], v[212:215], v[74:77]
	v_mfma_f32_16x16x32_bf16 v[126:129], v[134:137], v[150:153], v[126:129]
	v_mfma_f32_16x16x32_bf16 v[122:125], v[142:145], v[150:153], v[122:125]
	v_mfma_f32_16x16x32_bf16 v[110:113], v[134:137], v[186:189], v[110:113]
	v_mfma_f32_16x16x32_bf16 v[106:109], v[142:145], v[186:189], v[106:109]
	v_mfma_f32_16x16x32_bf16 v[94:97], v[134:137], v[194:197], v[94:97]
	v_mfma_f32_16x16x32_bf16 v[90:93], v[142:145], v[194:197], v[90:93]
	v_mfma_f32_16x16x32_bf16 v[78:81], v[134:137], v[216:219], v[78:81]
	v_mfma_f32_16x16x32_bf16 v[74:77], v[142:145], v[216:219], v[74:77]
	s_barrier
	s_add_i32 s23, 0, 0x14000
	v_add_u32_e32 v198, s23, v162
	s_add_i32 s67, s67, s25
	ds_read_b128 v[220:223], v198
	ds_read_b128 v[224:227], v198 offset:1024
	ds_read_b128 v[228:231], v198 offset:2048
	ds_read_b128 v[232:235], v198 offset:3072
	v_lshl_add_u64 v[198:199], s[50:51], 0, v[174:175]
	s_mov_b32 m0, s67
	v_lshl_add_u64 v[236:237], s[50:51], 0, v[170:171]
	global_load_lds_dwordx4 v[198:199], off
	s_add_i32 m0, s67, 0x2000
	s_nop 0
	global_load_lds_dwordx4 v[236:237], off
	s_barrier
	s_waitcnt lgkmcnt(0)
	v_mfma_f32_16x16x32_bf16 v[118:121], v[220:223], v[146:149], v[118:121]
	v_mfma_f32_16x16x32_bf16 v[114:117], v[228:231], v[146:149], v[114:117]
	v_mfma_f32_16x16x32_bf16 v[102:105], v[220:223], v[182:185], v[102:105]
	v_mfma_f32_16x16x32_bf16 v[98:101], v[228:231], v[182:185], v[98:101]
	v_mfma_f32_16x16x32_bf16 v[86:89], v[220:223], v[190:193], v[86:89]
	v_mfma_f32_16x16x32_bf16 v[82:85], v[228:231], v[190:193], v[82:85]
	v_mfma_f32_16x16x32_bf16 v[70:73], v[220:223], v[212:215], v[70:73]
	v_mfma_f32_16x16x32_bf16 v[66:69], v[228:231], v[212:215], v[66:69]
	v_mfma_f32_16x16x32_bf16 v[118:121], v[224:227], v[150:153], v[118:121]
	v_mfma_f32_16x16x32_bf16 v[114:117], v[232:235], v[150:153], v[114:117]
	v_mfma_f32_16x16x32_bf16 v[102:105], v[224:227], v[186:189], v[102:105]
	v_mfma_f32_16x16x32_bf16 v[98:101], v[232:235], v[186:189], v[98:101]
	v_mfma_f32_16x16x32_bf16 v[86:89], v[224:227], v[194:197], v[86:89]
	v_mfma_f32_16x16x32_bf16 v[82:85], v[232:235], v[194:197], v[82:85]
	v_mfma_f32_16x16x32_bf16 v[70:73], v[224:227], v[216:219], v[70:73]
	v_mfma_f32_16x16x32_bf16 v[66:69], v[232:235], v[216:219], v[66:69]
	s_mov_b32 m0, s26
	v_lshl_add_u64 v[238:239], s[52:53], 0, v[176:177]
	s_barrier
	ds_read_b128 v[146:149], v210 offset:16384
	ds_read_b128 v[150:153], v210 offset:17408
	ds_read_b128 v[182:185], v210 offset:18432
	ds_read_b128 v[186:189], v210 offset:19456
	ds_read_b128 v[190:193], v210 offset:20480
	ds_read_b128 v[194:197], v210 offset:21504
	ds_read_b128 v[212:215], v210 offset:22528
	ds_read_b128 v[216:219], v210 offset:23552
	global_load_lds_dwordx4 v[238:239], off
	s_mov_b32 m0, s27
	v_lshl_add_u64 v[240:241], s[52:53], 0, v[172:173]
	global_load_lds_dwordx4 v[240:241], off
	s_barrier
	s_waitcnt lgkmcnt(0)
	v_mfma_f32_16x16x32_bf16 v[62:65], v[130:133], v[146:149], v[62:65]
	v_mfma_f32_16x16x32_bf16 v[58:61], v[138:141], v[146:149], v[58:61]
	v_mfma_f32_16x16x32_bf16 v[46:49], v[130:133], v[182:185], v[46:49]
	v_mfma_f32_16x16x32_bf16 v[42:45], v[138:141], v[182:185], v[42:45]
	v_mfma_f32_16x16x32_bf16 v[30:33], v[130:133], v[190:193], v[30:33]
	v_mfma_f32_16x16x32_bf16 v[26:29], v[138:141], v[190:193], v[26:29]
	v_mfma_f32_16x16x32_bf16 v[14:17], v[130:133], v[212:215], v[14:17]
	v_mfma_f32_16x16x32_bf16 v[10:13], v[138:141], v[212:215], v[10:13]
	v_mfma_f32_16x16x32_bf16 v[62:65], v[134:137], v[150:153], v[62:65]
	v_mfma_f32_16x16x32_bf16 v[58:61], v[142:145], v[150:153], v[58:61]
	v_mfma_f32_16x16x32_bf16 v[46:49], v[134:137], v[186:189], v[46:49]
	v_mfma_f32_16x16x32_bf16 v[42:45], v[142:145], v[186:189], v[42:45]
	v_mfma_f32_16x16x32_bf16 v[30:33], v[134:137], v[194:197], v[30:33]
	v_mfma_f32_16x16x32_bf16 v[26:29], v[142:145], v[194:197], v[26:29]
	v_mfma_f32_16x16x32_bf16 v[14:17], v[134:137], v[216:219], v[14:17]
	v_mfma_f32_16x16x32_bf16 v[10:13], v[142:145], v[216:219], v[10:13]
	s_barrier
; #define PG8_STAGE(bufoff, gbase, voff) do { _Pragma("unroll") for (int _i = 0; _i < 2; ++_i) \
;         __builtin_amdgcn_global_load_lds((const unsigned*)((const char*)(gbase) + (voff)[_i]), (LAS unsigned*)(lds + (bufoff) + ldsw + _i * 8192), 16, 0, 0); } while (0)
; #define PG8_LDA(dst, b, h) do { _Pragma("unroll") for (int m = 0; m < 4; ++m) _Pragma("unroll") for (int k = 0; k < 2; ++k) dst[m][k] = *(const LAS bf16x8*)(lds + PG8_SA(b, h) + aoff + m * 2048 + k * 1024); } while (0)
; #define PG8_LDB(dst, b, h) do { _Pragma("unroll") for (int n = 0; n < 2; ++n) _Pragma("unroll") for (int k = 0; k < 2; ++k) dst[n][k] = *(const LAS bf16x8*)(lds + PG8_SB(b, h) + boff + n * 2048 + k * 1024); } while (0)
; #define PG8_MMA(ai, bj, At, Bt) do { __builtin_amdgcn_s_setprio(1); _Pragma("unroll") for (int m = 0; m < 4; ++m) _Pragma("unroll") for (int n = 0; n < 2; ++n) _Pragma("unroll") for (int k = 0; k < 2; ++k) \
;         acc[ai][bj][m][n] = __builtin_amdgcn_mfma_f32_16x16x32_bf16(Bt[n][k], At[m][k], acc[ai][bj][m][n], 0, 0, 0); __builtin_amdgcn_s_setprio(0); } while (0)
; #define PG8_WAIT_V(n) asm volatile("s_waitcnt vmcnt(" #n ")" ::: "memory")
; #define PG8_WAIT_L(n) asm volatile("s_waitcnt lgkmcnt(" #n ")" ::: "memory")
; #define PG8_BAR __builtin_amdgcn_s_barrier()
; #define PG8_SCHED __builtin_amdgcn_sched_barrier(0)
; template <class Epi, class Sched>
; __device__ __forceinline__ void gemm_phase(LAS unsigned char* lds, const Gemm g, const Sched& S, const Epi& E) {
;     ...
;             PG8_STAGE(PG8_SB(0, 1), b2 + hstepB, voffB);
;             PG8_WAIT_V(6); PG8_BAR; PG8_MMA(1, 1, At, B1); PG8_BAR;
;             PG8_LDB(B0, 1, 0); PG8_SCHED; PG8_LDA(At, 1, 0); PG8_STAGE(PG8_SA(0, 1), a2 + hstepA, voffA);
;             PG8_WAIT_L(8); PG8_BAR; PG8_WAIT_L(0); PG8_MMA(0, 0, At, B0); PG8_BAR; PG8_SCHED;
;             PG8_LDB(B1, 1, 1); PG8_STAGE(PG8_SB(1, 0), b3, voffB);
;             PG8_BAR; PG8_WAIT_L(0); PG8_MMA(0, 1, At, B1); PG8_BAR;
;             PG8_LDA(At, 1, 1); PG8_STAGE(PG8_SA(1, 0), a3, voffA);
;             PG8_BAR; PG8_WAIT_L(0); PG8_MMA(1, 0, At, B0); PG8_BAR; PG8_SCHED;
	s_add_u32 s84, s50, 0x80000
	s_addc_u32 s85, s51, 0
	s_add_i32 s23, s23, s25
	s_mov_b32 m0, s23
	v_lshl_add_u64 v[130:131], s[84:85], 0, v[174:175]
	global_load_lds_dwordx4 v[130:131], off
	s_add_i32 m0, s23, 0x2000
	v_lshl_add_u64 v[130:131], s[84:85], 0, v[170:171]
	global_load_lds_dwordx4 v[130:131], off
	s_waitcnt vmcnt(6)
	s_barrier
	v_mfma_f32_16x16x32_bf16 v[54:57], v[220:223], v[146:149], v[54:57]
	v_mfma_f32_16x16x32_bf16 v[50:53], v[228:231], v[146:149], v[50:53]
	v_mfma_f32_16x16x32_bf16 v[38:41], v[220:223], v[182:185], v[38:41]
	v_mfma_f32_16x16x32_bf16 v[34:37], v[228:231], v[182:185], v[34:37]
	v_mfma_f32_16x16x32_bf16 v[22:25], v[220:223], v[190:193], v[22:25]
	v_mfma_f32_16x16x32_bf16 v[18:21], v[228:231], v[190:193], v[18:21]
	v_mfma_f32_16x16x32_bf16 v[6:9], v[220:223], v[212:215], v[6:9]
	v_mfma_f32_16x16x32_bf16 v[2:5], v[228:231], v[212:215], v[2:5]
	v_mfma_f32_16x16x32_bf16 v[54:57], v[224:227], v[150:153], v[54:57]
	v_mfma_f32_16x16x32_bf16 v[50:53], v[232:235], v[150:153], v[50:53]
	v_mfma_f32_16x16x32_bf16 v[38:41], v[224:227], v[186:189], v[38:41]
	v_mfma_f32_16x16x32_bf16 v[34:37], v[232:235], v[186:189], v[34:37]
	v_mfma_f32_16x16x32_bf16 v[22:25], v[224:227], v[194:197], v[22:25]
	v_mfma_f32_16x16x32_bf16 v[18:21], v[232:235], v[194:197], v[18:21]
	v_mfma_f32_16x16x32_bf16 v[6:9], v[224:227], v[216:219], v[6:9]
	v_mfma_f32_16x16x32_bf16 v[2:5], v[232:235], v[216:219], v[2:5]
	s_add_i32 s23, 0, 0x18000
	v_add_u32_e32 v142, s23, v162
	s_barrier
	ds_read_b128 v[130:133], v142
	ds_read_b128 v[134:137], v142 offset:1024
	ds_read_b128 v[138:141], v142 offset:2048
	ds_read_b128 v[142:145], v142 offset:3072
	s_add_u32 s52, s52, 0x80000
	s_addc_u32 s53, s53, 0
	s_mov_b32 m0, s31
	v_lshl_add_u64 v[220:221], s[52:53], 0, v[176:177]
	ds_read_b128 v[146:149], v210 offset:32768
	ds_read_b128 v[150:153], v210 offset:33792
	ds_read_b128 v[182:185], v210 offset:34816
	ds_read_b128 v[186:189], v210 offset:35840
	ds_read_b128 v[190:193], v210 offset:36864
	ds_read_b128 v[194:197], v210 offset:37888
	ds_read_b128 v[212:215], v210 offset:38912
	ds_read_b128 v[216:219], v210 offset:39936
	global_load_lds_dwordx4 v[220:221], off
	s_mov_b32 m0, s54
	v_lshl_add_u64 v[220:221], s[52:53], 0, v[172:173]
	global_load_lds_dwordx4 v[220:221], off
	s_waitcnt lgkmcnt(8)
	s_barrier
	s_waitcnt lgkmcnt(0)
	v_mfma_f32_16x16x32_bf16 v[126:129], v[130:133], v[146:149], v[126:129]
	v_mfma_f32_16x16x32_bf16 v[122:125], v[138:141], v[146:149], v[122:125]
	v_mfma_f32_16x16x32_bf16 v[110:113], v[130:133], v[182:185], v[110:113]
	v_mfma_f32_16x16x32_bf16 v[106:109], v[138:141], v[182:185], v[106:109]
	v_mfma_f32_16x16x32_bf16 v[94:97], v[130:133], v[190:193], v[94:97]
	v_mfma_f32_16x16x32_bf16 v[90:93], v[138:141], v[190:193], v[90:93]
	v_mfma_f32_16x16x32_bf16 v[78:81], v[130:133], v[212:215], v[78:81]
	v_mfma_f32_16x16x32_bf16 v[74:77], v[138:141], v[212:215], v[74:77]
	v_mfma_f32_16x16x32_bf16 v[126:129], v[134:137], v[150:153], v[126:129]
	v_mfma_f32_16x16x32_bf16 v[122:125], v[142:145], v[150:153], v[122:125]
	v_mfma_f32_16x16x32_bf16 v[110:113], v[134:137], v[186:189], v[110:113]
	v_mfma_f32_16x16x32_bf16 v[106:109], v[142:145], v[186:189], v[106:109]
	v_mfma_f32_16x16x32_bf16 v[94:97], v[134:137], v[194:197], v[94:97]
	v_mfma_f32_16x16x32_bf16 v[90:93], v[142:145], v[194:197], v[90:93]
	v_mfma_f32_16x16x32_bf16 v[78:81], v[134:137], v[216:219], v[78:81]
	v_mfma_f32_16x16x32_bf16 v[74:77], v[142:145], v[216:219], v[74:77]
	s_barrier
	s_add_i32 s52, 0, 0x1c000
	s_add_i32 s23, s23, s25
	v_add_u32_e32 v211, s52, v162
	v_lshl_add_u64 v[198:199], v[198:199], 0, s[10:11]
	s_mov_b32 m0, s23
	ds_read_b128 v[220:223], v211
	ds_read_b128 v[224:227], v211 offset:1024
	ds_read_b128 v[228:231], v211 offset:2048
	ds_read_b128 v[232:235], v211 offset:3072
	global_load_lds_dwordx4 v[198:199], off
	s_add_i32 m0, s23, 0x2000
	v_lshl_add_u64 v[198:199], v[236:237], 0, s[10:11]
	global_load_lds_dwordx4 v[198:199], off
	s_barrier
	s_waitcnt lgkmcnt(0)
	v_mfma_f32_16x16x32_bf16 v[118:121], v[220:223], v[146:149], v[118:121]
	v_mfma_f32_16x16x32_bf16 v[114:117], v[228:231], v[146:149], v[114:117]
	v_mfma_f32_16x16x32_bf16 v[102:105], v[220:223], v[182:185], v[102:105]
	v_mfma_f32_16x16x32_bf16 v[98:101], v[228:231], v[182:185], v[98:101]
	v_mfma_f32_16x16x32_bf16 v[86:89], v[220:223], v[190:193], v[86:89]
	v_mfma_f32_16x16x32_bf16 v[82:85], v[228:231], v[190:193], v[82:85]
	v_mfma_f32_16x16x32_bf16 v[70:73], v[220:223], v[212:215], v[70:73]
	v_mfma_f32_16x16x32_bf16 v[66:69], v[228:231], v[212:215], v[66:69]
	v_mfma_f32_16x16x32_bf16 v[118:121], v[224:227], v[150:153], v[118:121]
	v_mfma_f32_16x16x32_bf16 v[114:117], v[232:235], v[150:153], v[114:117]
	v_mfma_f32_16x16x32_bf16 v[102:105], v[224:227], v[186:189], v[102:105]
	v_mfma_f32_16x16x32_bf16 v[98:101], v[232:235], v[186:189], v[98:101]
	v_mfma_f32_16x16x32_bf16 v[86:89], v[224:227], v[194:197], v[86:89]
	v_mfma_f32_16x16x32_bf16 v[82:85], v[232:235], v[194:197], v[82:85]
	v_mfma_f32_16x16x32_bf16 v[70:73], v[224:227], v[216:219], v[70:73]
	v_mfma_f32_16x16x32_bf16 v[66:69], v[232:235], v[216:219], v[66:69]
	s_mov_b32 m0, s28
	v_lshl_add_u64 v[198:199], v[238:239], 0, s[10:11]
	s_barrier
	ds_read_b128 v[146:149], v210 offset:49152
	ds_read_b128 v[150:153], v210 offset:50176
	ds_read_b128 v[182:185], v210 offset:51200
	ds_read_b128 v[186:189], v210 offset:52224
	ds_read_b128 v[190:193], v210 offset:53248
	ds_read_b128 v[194:197], v210 offset:54272
	ds_read_b128 v[212:215], v210 offset:55296
	ds_read_b128 v[216:219], v210 offset:56320
	global_load_lds_dwordx4 v[198:199], off
	s_mov_b32 m0, s29
	v_lshl_add_u64 v[198:199], v[240:241], 0, s[10:11]
	global_load_lds_dwordx4 v[198:199], off
	s_barrier
; #define PG8_STAGE(bufoff, gbase, voff) do { _Pragma("unroll") for (int _i = 0; _i < 2; ++_i) \
;         __builtin_amdgcn_global_load_lds((const unsigned*)((const char*)(gbase) + (voff)[_i]), (LAS unsigned*)(lds + (bufoff) + ldsw + _i * 8192), 16, 0, 0); } while (0)
; #define PG8_MMA(ai, bj, At, Bt) do { __builtin_amdgcn_s_setprio(1); _Pragma("unroll") for (int m = 0; m < 4; ++m) _Pragma("unroll") for (int n = 0; n < 2; ++n) _Pragma("unroll") for (int k = 0; k < 2; ++k) \
;         acc[ai][bj][m][n] = __builtin_amdgcn_mfma_f32_16x16x32_bf16(Bt[n][k], At[m][k], acc[ai][bj][m][n], 0, 0, 0); __builtin_amdgcn_s_setprio(0); } while (0)
; #define PG8_WAIT_V(n) asm volatile("s_waitcnt vmcnt(" #n ")" ::: "memory")
; #define PG8_WAIT_L(n) asm volatile("s_waitcnt lgkmcnt(" #n ")" ::: "memory")
; #define PG8_BAR __builtin_amdgcn_s_barrier()
; #define PG8_SCHED __builtin_amdgcn_sched_barrier(0)
; template <class Epi, class Sched>
; __device__ __forceinline__ void gemm_phase(LAS unsigned char* lds, const Gemm g, const Sched& S, const Epi& E) {
;     ...
;             PG8_BAR; PG8_WAIT_L(0); PG8_MMA(1, 0, At, B0); PG8_BAR; PG8_SCHED;
;             PG8_STAGE(PG8_SB(1, 1), b3 + hstepB, voffB);
;             PG8_WAIT_V(6); PG8_BAR; PG8_MMA(1, 1, At, B1); PG8_BAR;
;         }
	s_waitcnt lgkmcnt(0)
	v_mfma_f32_16x16x32_bf16 v[62:65], v[130:133], v[146:149], v[62:65]
	v_mfma_f32_16x16x32_bf16 v[58:61], v[138:141], v[146:149], v[58:61]
	v_mfma_f32_16x16x32_bf16 v[46:49], v[130:133], v[182:185], v[46:49]
	v_mfma_f32_16x16x32_bf16 v[42:45], v[138:141], v[182:185], v[42:45]
	v_mfma_f32_16x16x32_bf16 v[30:33], v[130:133], v[190:193], v[30:33]
	v_mfma_f32_16x16x32_bf16 v[26:29], v[138:141], v[190:193], v[26:29]
	v_mfma_f32_16x16x32_bf16 v[14:17], v[130:133], v[212:215], v[14:17]
	v_mfma_f32_16x16x32_bf16 v[10:13], v[138:141], v[212:215], v[10:13]
	v_mfma_f32_16x16x32_bf16 v[62:65], v[134:137], v[150:153], v[62:65]
	v_mfma_f32_16x16x32_bf16 v[58:61], v[142:145], v[150:153], v[58:61]
	v_mfma_f32_16x16x32_bf16 v[46:49], v[134:137], v[186:189], v[46:49]
	v_mfma_f32_16x16x32_bf16 v[42:45], v[142:145], v[186:189], v[42:45]
	v_mfma_f32_16x16x32_bf16 v[30:33], v[134:137], v[194:197], v[30:33]
	v_mfma_f32_16x16x32_bf16 v[26:29], v[142:145], v[194:197], v[26:29]
	v_mfma_f32_16x16x32_bf16 v[14:17], v[134:137], v[216:219], v[14:17]
	v_mfma_f32_16x16x32_bf16 v[10:13], v[142:145], v[216:219], v[10:13]
	s_barrier
	s_add_u32 s50, s50, 0x80080
	s_addc_u32 s51, s51, 0
	s_add_i32 s23, s52, s25
	s_mov_b32 m0, s23
	v_lshl_add_u64 v[130:131], s[50:51], 0, v[174:175]
	global_load_lds_dwordx4 v[130:131], off
	s_add_i32 m0, s23, 0x2000
	v_lshl_add_u64 v[130:131], s[50:51], 0, v[170:171]
	global_load_lds_dwordx4 v[130:131], off
	s_waitcnt vmcnt(6)
	s_barrier
	v_mfma_f32_16x16x32_bf16 v[54:57], v[220:223], v[146:149], v[54:57]
	v_mfma_f32_16x16x32_bf16 v[50:53], v[228:231], v[146:149], v[50:53]
	v_mfma_f32_16x16x32_bf16 v[38:41], v[220:223], v[182:185], v[38:41]
	v_mfma_f32_16x16x32_bf16 v[34:37], v[228:231], v[182:185], v[34:37]
	v_mfma_f32_16x16x32_bf16 v[22:25], v[220:223], v[190:193], v[22:25]
	v_mfma_f32_16x16x32_bf16 v[18:21], v[228:231], v[190:193], v[18:21]
	v_mfma_f32_16x16x32_bf16 v[6:9], v[220:223], v[212:215], v[6:9]
	v_mfma_f32_16x16x32_bf16 v[2:5], v[228:231], v[212:215], v[2:5]
	v_mfma_f32_16x16x32_bf16 v[54:57], v[224:227], v[150:153], v[54:57]
	v_mfma_f32_16x16x32_bf16 v[50:53], v[232:235], v[150:153], v[50:53]
	v_mfma_f32_16x16x32_bf16 v[38:41], v[224:227], v[186:189], v[38:41]
	v_mfma_f32_16x16x32_bf16 v[34:37], v[232:235], v[186:189], v[34:37]
	v_mfma_f32_16x16x32_bf16 v[22:25], v[224:227], v[194:197], v[22:25]
	v_mfma_f32_16x16x32_bf16 v[18:21], v[232:235], v[194:197], v[18:21]
	v_mfma_f32_16x16x32_bf16 v[6:9], v[224:227], v[216:219], v[6:9]
	v_mfma_f32_16x16x32_bf16 v[2:5], v[232:235], v[216:219], v[2:5]
	s_add_i32 s66, s66, 2
	s_add_u32 s48, s48, 0x100
	s_addc_u32 s49, s49, 0
	s_add_u32 s70, s70, 0x100
	s_addc_u32 s71, s71, 0
	s_cmp_gt_u32 s66, 29
	s_barrier
	s_cbranch_scc0 .LBB0_738
; __device__ __forceinline__ unsigned cvt_pk_bf16(float lo, float hi) { unsigned r; asm volatile("v_cvt_pk_bf16_f32 %0, %1, %2" : "=v"(r) : "v"(lo), "v"(hi)); return r; }
; __device__ __forceinline__ float bf_lo(unsigned w) { return __uint_as_float(w << 16); }
; __device__ __forceinline__ float bf_hi(unsigned w) { return __uint_as_float(w & 0xffff0000u); }
;     __device__ __forceinline__ void operator()(const f32x4 (&acc)[2][2][4][2], const Unit& u, int ui, const LAS float* rtab, int wr, int wc, int fr, int fq) const {
;         const int row0 = u.pm * BM + wr * 64 + fr, col0 = u.pn * BM + wc * 32 + 8 * fq;
; #pragma unroll
;         for (int ai = 0; ai < 2; ++ai) {
;             u32x4 xv[4][2];
; #pragma unroll
;             for (int m = 0; m < 4; ++m)
; #pragma unroll
;                 for (int bj = 0; bj < 2; ++bj) xv[m][bj] = *(const u32x4*)(XB + (size_t)(row0 + ai * HALF + m * 16) * DM + col0 + bj * HALF);
; #pragma unroll
;             for (int m = 0; m < 4; ++m) { const int row = row0 + ai * HALF + m * 16; float ss = 0.f;
; #pragma unroll
;                 for (int bj = 0; bj < 2; ++bj) {
;                     const f32x4 a0 = acc[ai][bj][m][0], a1 = acc[ai][bj][m][1]; const u32x4 xo = xv[m][bj]; u32x4 w;
;                     w.x = cvt_pk_bf16(bf_lo(xo.x) + a0[0], bf_hi(xo.x) + a0[1]); w.y = cvt_pk_bf16(bf_lo(xo.y) + a0[2], bf_hi(xo.y) + a0[3]);
;                     w.z = cvt_pk_bf16(bf_lo(xo.z) + a1[0], bf_hi(xo.z) + a1[1]); w.w = cvt_pk_bf16(bf_lo(xo.w) + a1[2], bf_hi(xo.w) + a1[3]);
;                     *(u32x4*)(XB + (size_t)row * DM + col0 + bj * HALF) = w;
; #pragma unroll
;                     for (int e = 0; e < 4; ++e) { const float lo = bf_lo(w[e]), hi = bf_hi(w[e]); ss += lo * lo + hi * hi; }
;                 }
;                 ss += __shfl_xor(ss, 16); ss += __shfl_xor(ss, 32);
;                 if (fq == 0) ssq_next[(size_t)row * 32 + (u.pn & 7) * 4 + wc] = ss; }
	v_lshl_or_b32 v182, s57, 8, v209
	v_lshl_add_u32 v186, s58, 8, v1
	v_ashrrev_i32_e32 v183, 31, v182
	v_lshlrev_b64 v[130:131], 1, v[182:183]
	v_ashrrev_i32_e32 v187, 31, v186
	v_lshl_add_u64 v[184:185], s[74:75], 0, v[130:131]
	v_lshlrev_b64 v[132:133], 12, v[186:187]
	v_lshl_add_u64 v[134:135], v[184:185], 0, v[132:133]
	global_load_dwordx4 v[212:215], v[134:135], off
	global_load_dwordx4 v[216:219], v[134:135], off offset:256
	v_or_b32_e32 v196, 16, v186
	v_or_b32_e32 v192, 32, v186
	v_or_b32_e32 v188, 48, v186
	v_ashrrev_i32_e32 v197, 31, v196
	v_ashrrev_i32_e32 v193, 31, v192
	v_ashrrev_i32_e32 v189, 31, v188
	v_lshlrev_b64 v[198:199], 12, v[196:197]
	v_lshlrev_b64 v[194:195], 12, v[192:193]
	v_lshlrev_b64 v[190:191], 12, v[188:189]
	v_lshl_add_u64 v[132:133], s[74:75], 0, v[132:133]
	v_lshl_add_u64 v[134:135], v[184:185], 0, v[198:199]
	v_lshl_add_u64 v[136:137], v[184:185], 0, v[194:195]
	v_lshl_add_u64 v[220:221], v[184:185], 0, v[190:191]
	v_lshl_add_u64 v[222:223], v[132:133], 0, v[130:131]
	global_load_dwordx4 v[150:153], v[134:135], off
	global_load_dwordx4 v[146:149], v[134:135], off offset:256
	global_load_dwordx4 v[142:145], v[136:137], off
	global_load_dwordx4 v[138:141], v[136:137], off offset:256
	s_nop 0
	global_load_dwordx4 v[134:137], v[220:221], off
	global_load_dwordx4 v[130:133], v[220:221], off offset:256
	s_lshl_b32 s21, s57, 2
	s_and_b32 s21, s21, 28
	s_waitcnt vmcnt(0)
	v_lshlrev_b32_e32 v211, 16, v212
	v_and_b32_e32 v212, 0xffff0000, v212
	v_lshlrev_b32_e32 v220, 16, v213
	v_and_b32_e32 v213, 0xffff0000, v213
	v_lshlrev_b32_e32 v221, 16, v214
	v_and_b32_e32 v214, 0xffff0000, v214
	v_lshlrev_b32_e32 v227, 16, v218
	v_and_b32_e32 v218, 0xffff0000, v218
	v_lshlrev_b32_e32 v224, 16, v215
	v_and_b32_e32 v215, 0xffff0000, v215
	v_lshlrev_b32_e32 v228, 16, v219
	v_and_b32_e32 v219, 0xffff0000, v219
	v_add_f32_e32 v126, v126, v211
	v_add_f32_e32 v127, v127, v212
	v_add_f32_e32 v128, v128, v220
	v_add_f32_e32 v129, v129, v213
	v_add_f32_e32 v122, v122, v221
	v_add_f32_e32 v123, v123, v214
	v_add_f32_e32 v211, v114, v227
	v_add_f32_e32 v212, v115, v218
	v_cvt_pk_bf16_f32 v114, v126, v127
	v_cvt_pk_bf16_f32 v115, v128, v129
	v_add_f32_e32 v124, v124, v224
	v_add_f32_e32 v125, v125, v215
	v_add_f32_e32 v213, v116, v228
	v_add_f32_e32 v214, v117, v219
	v_cvt_pk_bf16_f32 v116, v122, v123
	v_cvt_pk_bf16_f32 v117, v124, v125
	global_store_dwordx4 v[222:223], v[114:117], off
	v_lshlrev_b32_e32 v122, 16, v114
	v_lshlrev_b32_e32 v123, 16, v115
	v_and_b32_e32 v114, 0xffff0000, v114
	v_and_b32_e32 v115, 0xffff0000, v115
	v_lshlrev_b32_e32 v225, 16, v216
	v_lshlrev_b32_e32 v124, 16, v116
	v_and_b32_e32 v116, 0xffff0000, v116
	v_mul_f32_e32 v114, v114, v114
	v_mul_f32_e32 v115, v115, v115
	v_and_b32_e32 v216, 0xffff0000, v216
	v_add_f32_e32 v118, v118, v225
	v_lshlrev_b32_e32 v125, 16, v117
	v_and_b32_e32 v117, 0xffff0000, v117
	v_mul_f32_e32 v116, v116, v116
	v_fmac_f32_e32 v114, v122, v122
	v_fmac_f32_e32 v115, v123, v123
	v_lshlrev_b32_e32 v226, 16, v217
	v_and_b32_e32 v217, 0xffff0000, v217
	v_add_f32_e32 v119, v119, v216
	v_cvt_pk_bf16_f32 v118, v118, v119
	v_mul_f32_e32 v117, v117, v117
	v_and_b32_e32 v127, 0xffff0000, v118
	v_fmac_f32_e32 v116, v124, v124
	v_add_f32_e32 v114, v114, v115
	v_add_f32_e32 v120, v120, v226
	v_add_f32_e32 v121, v121, v217
	v_cvt_pk_bf16_f32 v119, v120, v121
	v_lshlrev_b32_e32 v126, 16, v118
	v_fmac_f32_e32 v117, v125, v125
	v_mul_f32_e32 v122, v127, v127
	v_add_f32_e32 v114, v114, v116
	v_and_b32_e32 v116, 0xffff0000, v119
	v_fmac_f32_e32 v122, v126, v126
	v_add_f32_e32 v114, v114, v117
	v_lshlrev_b32_e32 v115, 16, v119
	v_mul_f32_e32 v116, v116, v116
	v_add_f32_e32 v114, v114, v122
	v_fmac_f32_e32 v116, v115, v115
	v_cvt_pk_bf16_f32 v120, v211, v212
	v_add_f32_e32 v114, v114, v116
	v_and_b32_e32 v116, 0xffff0000, v120
	v_lshlrev_b32_e32 v115, 16, v120
	v_mul_f32_e32 v116, v116, v116
	v_fmac_f32_e32 v116, v115, v115
	v_cvt_pk_bf16_f32 v121, v213, v214
	v_add_f32_e32 v114, v114, v116
	v_and_b32_e32 v116, 0xffff0000, v121
	v_lshlrev_b32_e32 v115, 16, v121
	v_mul_f32_e32 v116, v116, v116
	v_fmac_f32_e32 v116, v115, v115
	v_add_f32_e32 v115, v114, v116
	v_and_b32_e32 v116, 64, v207
	v_xor_b32_e32 v114, 16, v207
	v_add_u32_e32 v117, 64, v116
	v_cmp_lt_i32_e32 vcc, v114, v117
	global_store_dwordx4 v[222:223], v[118:121], off offset:256
	s_nop 0
	v_cndmask_b32_e32 v114, v207, v114, vcc
	v_lshlrev_b32_e32 v114, 2, v114
	ds_bpermute_b32 v116, v114, v115
	s_waitcnt lgkmcnt(0)
	v_add_f32_e32 v116, v115, v116
	v_xor_b32_e32 v115, 32, v207
	v_cmp_lt_i32_e32 vcc, v115, v117
	s_nop 1
	v_cndmask_b32_e32 v115, v207, v115, vcc
	v_lshlrev_b32_e32 v115, 2, v115
	ds_bpermute_b32 v117, v115, v116
	s_and_saveexec_b64 s[48:49], s[42:43]
	s_cbranch_execz .LBB0_741
	s_waitcnt lgkmcnt(0)
	v_add_f32_e32 v118, v116, v117
	v_lshlrev_b64 v[116:117], 7, v[186:187]
	v_lshl_add_u64 v[116:117], s[0:1], 0, v[116:117]
	s_lshl_b32 s68, s21, 2
	v_lshl_add_u64 v[116:117], v[116:117], 0, s[68:69]
	s_lshl_b32 s68, s55, 2
	v_lshl_add_u64 v[116:117], v[116:117], 0, s[68:69]
	global_store_dword v[116:117], v118, off

; #define PG8_STAGE(bufoff, gbase, voff) do { _Pragma("unroll") for (int _i = 0; _i < 2; ++_i) \
;         __builtin_amdgcn_global_load_lds((const unsigned*)((const char*)(gbase) + (voff)[_i]), (LAS unsigned*)(lds + (bufoff) + ldsw + _i * 8192), 16, 0, 0); } while (0)
; #define PG8_LDA(dst, b, h) do { _Pragma("unroll") for (int m = 0; m < 4; ++m) _Pragma("unroll") for (int k = 0; k < 2; ++k) dst[m][k] = *(const LAS bf16x8*)(lds + PG8_SA(b, h) + aoff + m * 2048 + k * 1024); } while (0)
; #define PG8_LDB(dst, b, h) do { _Pragma("unroll") for (int n = 0; n < 2; ++n) _Pragma("unroll") for (int k = 0; k < 2; ++k) dst[n][k] = *(const LAS bf16x8*)(lds + PG8_SB(b, h) + boff + n * 2048 + k * 1024); } while (0)
; #define PG8_MMA(ai, bj, At, Bt) do { __builtin_amdgcn_s_setprio(1); _Pragma("unroll") for (int m = 0; m < 4; ++m) _Pragma("unroll") for (int n = 0; n < 2; ++n) _Pragma("unroll") for (int k = 0; k < 2; ++k) \
;         acc[ai][bj][m][n] = __builtin_amdgcn_mfma_f32_16x16x32_bf16(Bt[n][k], At[m][k], acc[ai][bj][m][n], 0, 0, 0); __builtin_amdgcn_s_setprio(0); } while (0)
; #define PG8_WAIT_V(n) asm volatile("s_waitcnt vmcnt(" #n ")" ::: "memory")
; #define PG8_WAIT_L(n) asm volatile("s_waitcnt lgkmcnt(" #n ")" ::: "memory")
; #define PG8_BAR __builtin_amdgcn_s_barrier()
; #define PG8_SCHED __builtin_amdgcn_sched_barrier(0)
; template <class Epi, class Sched>
; __device__ __forceinline__ void gemm_phase(LAS unsigned char* lds, const Gemm g, const Sched& S, const Epi& E) {
;     ...
;             const char* a1 = cA + (size_t)(t + 1) * kstep;
;             const char* a2 = last ? nA : cA + (size_t)(t + 2) * kstep; const char* b2 = last ? nB : cB + (size_t)(t + 2) * kstep;
;             const char* a3 = a2 + kstep; const char* b3 = b2 + kstep;
;             PG8_LDB(B0, 0, 0); PG8_SCHED; PG8_LDA(At, 0, 0); PG8_STAGE(PG8_SA(1, 1), a1 + hstepA, voffA);
;             PG8_WAIT_L(8); PG8_BAR; PG8_WAIT_L(0); PG8_MMA(0, 0, At, B0); PG8_BAR; PG8_SCHED;
;             PG8_LDB(B1, 0, 1); PG8_STAGE(PG8_SB(0, 0), b2, voffB);
;             PG8_BAR; PG8_WAIT_L(0); PG8_MMA(0, 1, At, B1); PG8_BAR;
;             PG8_LDA(At, 0, 1); PG8_STAGE(PG8_SA(0, 0), a2, voffA);
;             PG8_BAR; PG8_WAIT_L(0); PG8_MMA(1, 0, At, B0); PG8_BAR; PG8_SCHED;
;             PG8_STAGE(PG8_SB(0, 1), b2 + hstepB, voffB);
;             PG8_WAIT_V(6); PG8_BAR; PG8_MMA(1, 1, At, B1); PG8_BAR;
.LBB0_830:
	s_add_u32 s23, s44, 0xfff80080
	s_addc_u32 s46, s45, -1
	s_add_i32 s67, 0, 0x10000
	v_add_u32_e32 v162, s67, v142
	ds_read_b128 v[146:149], v162
	ds_read_b128 v[150:153], v162 offset:1024
	ds_read_b128 v[170:173], v162 offset:2048
	ds_read_b128 v[174:177], v162 offset:3072
	s_cmp_eq_u32 s66, 28
	s_cselect_b32 s49, s21, s46
	s_cselect_b32 s48, s56, s23
	s_cselect_b32 s47, s1, s59
	s_cselect_b32 s46, s57, s58
	v_lshl_add_u64 v[198:199], s[44:45], 0, v[138:139]
	s_add_i32 m0, s27, 0xc000
	ds_read_b128 v[178:181], v145
	ds_read_b128 v[182:185], v145 offset:1024
	ds_read_b128 v[186:189], v145 offset:2048
	ds_read_b128 v[190:193], v145 offset:3072
	ds_read_b128 v[194:197], v145 offset:4096
	ds_read_b128 v[210:213], v145 offset:5120
	ds_read_b128 v[214:217], v145 offset:6144
	ds_read_b128 v[218:221], v145 offset:7168
	global_load_lds_dwordx4 v[198:199], off
	s_add_i32 m0, s27, 0xe000
	v_lshl_add_u64 v[198:199], s[44:45], 0, v[140:141]
	global_load_lds_dwordx4 v[198:199], off
	s_waitcnt lgkmcnt(8)
	s_barrier
	s_waitcnt lgkmcnt(0)
	v_mfma_f32_16x16x32_bf16 v[126:129], v[146:149], v[178:181], v[126:129]
	v_mfma_f32_16x16x32_bf16 v[122:125], v[170:173], v[178:181], v[122:125]
	v_mfma_f32_16x16x32_bf16 v[110:113], v[146:149], v[186:189], v[110:113]
	v_mfma_f32_16x16x32_bf16 v[106:109], v[170:173], v[186:189], v[106:109]
	v_mfma_f32_16x16x32_bf16 v[94:97], v[146:149], v[194:197], v[94:97]
	v_mfma_f32_16x16x32_bf16 v[90:93], v[170:173], v[194:197], v[90:93]
	v_mfma_f32_16x16x32_bf16 v[78:81], v[146:149], v[214:217], v[78:81]
	v_mfma_f32_16x16x32_bf16 v[74:77], v[170:173], v[214:217], v[74:77]
	v_mfma_f32_16x16x32_bf16 v[126:129], v[150:153], v[182:185], v[126:129]
	v_mfma_f32_16x16x32_bf16 v[122:125], v[174:177], v[182:185], v[122:125]
	v_mfma_f32_16x16x32_bf16 v[110:113], v[150:153], v[190:193], v[110:113]
	v_mfma_f32_16x16x32_bf16 v[106:109], v[174:177], v[190:193], v[106:109]
	v_mfma_f32_16x16x32_bf16 v[94:97], v[150:153], v[210:213], v[94:97]
	v_mfma_f32_16x16x32_bf16 v[90:93], v[174:177], v[210:213], v[90:93]
	v_mfma_f32_16x16x32_bf16 v[78:81], v[150:153], v[218:221], v[78:81]
	v_mfma_f32_16x16x32_bf16 v[74:77], v[174:177], v[218:221], v[74:77]
	s_barrier
	s_add_i32 s23, 0, 0x14000
	s_add_i32 s67, s67, s26
	v_add_u32_e32 v162, s23, v142
	v_lshl_add_u64 v[198:199], s[46:47], 0, v[134:135]
	s_mov_b32 m0, s67
	ds_read_b128 v[222:225], v162
	ds_read_b128 v[226:229], v162 offset:1024
	ds_read_b128 v[230:233], v162 offset:2048
	ds_read_b128 v[234:237], v162 offset:3072
	global_load_lds_dwordx4 v[198:199], off
	s_add_i32 m0, s67, 0x2000
	v_lshl_add_u64 v[238:239], s[46:47], 0, v[130:131]
	global_load_lds_dwordx4 v[238:239], off
	s_barrier
	s_waitcnt lgkmcnt(0)
	v_mfma_f32_16x16x32_bf16 v[118:121], v[222:225], v[178:181], v[118:121]
	v_mfma_f32_16x16x32_bf16 v[114:117], v[230:233], v[178:181], v[114:117]
	v_mfma_f32_16x16x32_bf16 v[102:105], v[222:225], v[186:189], v[102:105]
	v_mfma_f32_16x16x32_bf16 v[98:101], v[230:233], v[186:189], v[98:101]
	v_mfma_f32_16x16x32_bf16 v[86:89], v[222:225], v[194:197], v[86:89]
	v_mfma_f32_16x16x32_bf16 v[82:85], v[230:233], v[194:197], v[82:85]
	v_mfma_f32_16x16x32_bf16 v[70:73], v[222:225], v[214:217], v[70:73]
	v_mfma_f32_16x16x32_bf16 v[66:69], v[230:233], v[214:217], v[66:69]
	v_mfma_f32_16x16x32_bf16 v[118:121], v[226:229], v[182:185], v[118:121]
	v_mfma_f32_16x16x32_bf16 v[114:117], v[234:237], v[182:185], v[114:117]
	v_mfma_f32_16x16x32_bf16 v[102:105], v[226:229], v[190:193], v[102:105]
	v_mfma_f32_16x16x32_bf16 v[98:101], v[234:237], v[190:193], v[98:101]
	v_mfma_f32_16x16x32_bf16 v[86:89], v[226:229], v[210:213], v[86:89]
	v_mfma_f32_16x16x32_bf16 v[82:85], v[234:237], v[210:213], v[82:85]
	v_mfma_f32_16x16x32_bf16 v[70:73], v[226:229], v[218:221], v[70:73]
	v_mfma_f32_16x16x32_bf16 v[66:69], v[234:237], v[218:221], v[66:69]
	s_mov_b32 m0, s27
	v_lshl_add_u64 v[240:241], s[48:49], 0, v[136:137]
	s_barrier
	ds_read_b128 v[178:181], v145 offset:16384
	ds_read_b128 v[182:185], v145 offset:17408
	ds_read_b128 v[186:189], v145 offset:18432
	ds_read_b128 v[190:193], v145 offset:19456
	ds_read_b128 v[194:197], v145 offset:20480
	ds_read_b128 v[210:213], v145 offset:21504
	ds_read_b128 v[214:217], v145 offset:22528
	ds_read_b128 v[218:221], v145 offset:23552
	global_load_lds_dwordx4 v[240:241], off
	s_mov_b32 m0, s28
	v_lshl_add_u64 v[242:243], s[48:49], 0, v[132:133]
	global_load_lds_dwordx4 v[242:243], off
	s_barrier
	s_waitcnt lgkmcnt(0)
	v_mfma_f32_16x16x32_bf16 v[62:65], v[146:149], v[178:181], v[62:65]
	v_mfma_f32_16x16x32_bf16 v[58:61], v[170:173], v[178:181], v[58:61]
	v_mfma_f32_16x16x32_bf16 v[46:49], v[146:149], v[186:189], v[46:49]
	v_mfma_f32_16x16x32_bf16 v[42:45], v[170:173], v[186:189], v[42:45]
	v_mfma_f32_16x16x32_bf16 v[30:33], v[146:149], v[194:197], v[30:33]
	v_mfma_f32_16x16x32_bf16 v[26:29], v[170:173], v[194:197], v[26:29]
	v_mfma_f32_16x16x32_bf16 v[14:17], v[146:149], v[214:217], v[14:17]
	v_mfma_f32_16x16x32_bf16 v[10:13], v[170:173], v[214:217], v[10:13]
	v_mfma_f32_16x16x32_bf16 v[62:65], v[150:153], v[182:185], v[62:65]
	v_mfma_f32_16x16x32_bf16 v[58:61], v[174:177], v[182:185], v[58:61]
	v_mfma_f32_16x16x32_bf16 v[46:49], v[150:153], v[190:193], v[46:49]
	v_mfma_f32_16x16x32_bf16 v[42:45], v[174:177], v[190:193], v[42:45]
	v_mfma_f32_16x16x32_bf16 v[30:33], v[150:153], v[210:213], v[30:33]
	v_mfma_f32_16x16x32_bf16 v[26:29], v[174:177], v[210:213], v[26:29]
	v_mfma_f32_16x16x32_bf16 v[14:17], v[150:153], v[218:221], v[14:17]
	v_mfma_f32_16x16x32_bf16 v[10:13], v[174:177], v[218:221], v[10:13]
	s_barrier
; #define PG8_STAGE(bufoff, gbase, voff) do { _Pragma("unroll") for (int _i = 0; _i < 2; ++_i) \
;         __builtin_amdgcn_global_load_lds((const unsigned*)((const char*)(gbase) + (voff)[_i]), (LAS unsigned*)(lds + (bufoff) + ldsw + _i * 8192), 16, 0, 0); } while (0)
; #define PG8_LDA(dst, b, h) do { _Pragma("unroll") for (int m = 0; m < 4; ++m) _Pragma("unroll") for (int k = 0; k < 2; ++k) dst[m][k] = *(const LAS bf16x8*)(lds + PG8_SA(b, h) + aoff + m * 2048 + k * 1024); } while (0)
; #define PG8_LDB(dst, b, h) do { _Pragma("unroll") for (int n = 0; n < 2; ++n) _Pragma("unroll") for (int k = 0; k < 2; ++k) dst[n][k] = *(const LAS bf16x8*)(lds + PG8_SB(b, h) + boff + n * 2048 + k * 1024); } while (0)
; #define PG8_MMA(ai, bj, At, Bt) do { __builtin_amdgcn_s_setprio(1); _Pragma("unroll") for (int m = 0; m < 4; ++m) _Pragma("unroll") for (int n = 0; n < 2; ++n) _Pragma("unroll") for (int k = 0; k < 2; ++k) \
;         acc[ai][bj][m][n] = __builtin_amdgcn_mfma_f32_16x16x32_bf16(Bt[n][k], At[m][k], acc[ai][bj][m][n], 0, 0, 0); __builtin_amdgcn_s_setprio(0); } while (0)
; #define PG8_WAIT_V(n) asm volatile("s_waitcnt vmcnt(" #n ")" ::: "memory")
; #define PG8_WAIT_L(n) asm volatile("s_waitcnt lgkmcnt(" #n ")" ::: "memory")
; #define PG8_BAR __builtin_amdgcn_s_barrier()
; #define PG8_SCHED __builtin_amdgcn_sched_barrier(0)
; template <class Epi, class Sched>
; __device__ __forceinline__ void gemm_phase(LAS unsigned char* lds, const Gemm g, const Sched& S, const Epi& E) {
;     ...
;             PG8_STAGE(PG8_SB(0, 1), b2 + hstepB, voffB);
;             PG8_WAIT_V(6); PG8_BAR; PG8_MMA(1, 1, At, B1); PG8_BAR;
;             PG8_LDB(B0, 1, 0); PG8_SCHED; PG8_LDA(At, 1, 0); PG8_STAGE(PG8_SA(0, 1), a2 + hstepA, voffA);
;             PG8_WAIT_L(8); PG8_BAR; PG8_WAIT_L(0); PG8_MMA(0, 0, At, B0); PG8_BAR; PG8_SCHED;
;             PG8_LDB(B1, 1, 1); PG8_STAGE(PG8_SB(1, 0), b3, voffB);
;             PG8_BAR; PG8_WAIT_L(0); PG8_MMA(0, 1, At, B1); PG8_BAR;
;             PG8_LDA(At, 1, 1); PG8_STAGE(PG8_SA(1, 0), a3, voffA);
;             PG8_BAR; PG8_WAIT_L(0); PG8_MMA(1, 0, At, B0); PG8_BAR; PG8_SCHED;
	s_add_u32 s70, s46, 0x80000
	s_addc_u32 s71, s47, 0
	s_add_i32 s23, s23, s26
	s_mov_b32 m0, s23
	v_lshl_add_u64 v[146:147], s[70:71], 0, v[134:135]
	global_load_lds_dwordx4 v[146:147], off
	s_add_i32 m0, s23, 0x2000
	v_lshl_add_u64 v[146:147], s[70:71], 0, v[130:131]
	global_load_lds_dwordx4 v[146:147], off
	s_waitcnt vmcnt(6)
	s_barrier
	v_mfma_f32_16x16x32_bf16 v[54:57], v[222:225], v[178:181], v[54:57]
	v_mfma_f32_16x16x32_bf16 v[50:53], v[230:233], v[178:181], v[50:53]
	v_mfma_f32_16x16x32_bf16 v[38:41], v[222:225], v[186:189], v[38:41]
	v_mfma_f32_16x16x32_bf16 v[34:37], v[230:233], v[186:189], v[34:37]
	v_mfma_f32_16x16x32_bf16 v[22:25], v[222:225], v[194:197], v[22:25]
	v_mfma_f32_16x16x32_bf16 v[18:21], v[230:233], v[194:197], v[18:21]
	v_mfma_f32_16x16x32_bf16 v[6:9], v[222:225], v[214:217], v[6:9]
	v_mfma_f32_16x16x32_bf16 v[2:5], v[230:233], v[214:217], v[2:5]
	v_mfma_f32_16x16x32_bf16 v[54:57], v[226:229], v[182:185], v[54:57]
	v_mfma_f32_16x16x32_bf16 v[50:53], v[234:237], v[182:185], v[50:53]
	v_mfma_f32_16x16x32_bf16 v[38:41], v[226:229], v[190:193], v[38:41]
	v_mfma_f32_16x16x32_bf16 v[34:37], v[234:237], v[190:193], v[34:37]
	v_mfma_f32_16x16x32_bf16 v[22:25], v[226:229], v[210:213], v[22:25]
	v_mfma_f32_16x16x32_bf16 v[18:21], v[234:237], v[210:213], v[18:21]
	v_mfma_f32_16x16x32_bf16 v[6:9], v[226:229], v[218:221], v[6:9]
	v_mfma_f32_16x16x32_bf16 v[2:5], v[234:237], v[218:221], v[2:5]
	s_add_i32 s23, 0, 0x18000
	v_add_u32_e32 v162, s23, v142
	s_barrier
	ds_read_b128 v[146:149], v162
	ds_read_b128 v[150:153], v162 offset:1024
	ds_read_b128 v[170:173], v162 offset:2048
	ds_read_b128 v[174:177], v162 offset:3072
	s_add_u32 s48, s48, 0x80000
	s_addc_u32 s49, s49, 0
	s_mov_b32 m0, s29
	v_lshl_add_u64 v[222:223], s[48:49], 0, v[136:137]
	ds_read_b128 v[178:181], v145 offset:32768
	ds_read_b128 v[182:185], v145 offset:33792
	ds_read_b128 v[186:189], v145 offset:34816
	ds_read_b128 v[190:193], v145 offset:35840
	ds_read_b128 v[194:197], v145 offset:36864
	ds_read_b128 v[210:213], v145 offset:37888
	ds_read_b128 v[214:217], v145 offset:38912
	ds_read_b128 v[218:221], v145 offset:39936
	global_load_lds_dwordx4 v[222:223], off
	s_mov_b32 m0, s31
	v_lshl_add_u64 v[222:223], s[48:49], 0, v[132:133]
	global_load_lds_dwordx4 v[222:223], off
	s_waitcnt lgkmcnt(8)
	s_barrier
	s_waitcnt lgkmcnt(0)
	v_mfma_f32_16x16x32_bf16 v[126:129], v[146:149], v[178:181], v[126:129]
	v_mfma_f32_16x16x32_bf16 v[122:125], v[170:173], v[178:181], v[122:125]
	v_mfma_f32_16x16x32_bf16 v[110:113], v[146:149], v[186:189], v[110:113]
	v_mfma_f32_16x16x32_bf16 v[106:109], v[170:173], v[186:189], v[106:109]
	v_mfma_f32_16x16x32_bf16 v[94:97], v[146:149], v[194:197], v[94:97]
	v_mfma_f32_16x16x32_bf16 v[90:93], v[170:173], v[194:197], v[90:93]
	v_mfma_f32_16x16x32_bf16 v[78:81], v[146:149], v[214:217], v[78:81]
	v_mfma_f32_16x16x32_bf16 v[74:77], v[170:173], v[214:217], v[74:77]
	v_mfma_f32_16x16x32_bf16 v[126:129], v[150:153], v[182:185], v[126:129]
	v_mfma_f32_16x16x32_bf16 v[122:125], v[174:177], v[182:185], v[122:125]
	v_mfma_f32_16x16x32_bf16 v[110:113], v[150:153], v[190:193], v[110:113]
	v_mfma_f32_16x16x32_bf16 v[106:109], v[174:177], v[190:193], v[106:109]
	v_mfma_f32_16x16x32_bf16 v[94:97], v[150:153], v[210:213], v[94:97]
	v_mfma_f32_16x16x32_bf16 v[90:93], v[174:177], v[210:213], v[90:93]
	v_mfma_f32_16x16x32_bf16 v[78:81], v[150:153], v[218:221], v[78:81]
	v_mfma_f32_16x16x32_bf16 v[74:77], v[174:177], v[218:221], v[74:77]
	s_barrier
	s_add_i32 s48, 0, 0x1c000
	s_add_i32 s23, s23, s26
	v_add_u32_e32 v162, s48, v142
	v_lshl_add_u64 v[198:199], v[198:199], 0, s[10:11]
	s_mov_b32 m0, s23
	ds_read_b128 v[222:225], v162
	ds_read_b128 v[226:229], v162 offset:1024
	ds_read_b128 v[230:233], v162 offset:2048
	ds_read_b128 v[234:237], v162 offset:3072
	global_load_lds_dwordx4 v[198:199], off
	s_add_i32 m0, s23, 0x2000
	v_lshl_add_u64 v[198:199], v[238:239], 0, s[10:11]
	global_load_lds_dwordx4 v[198:199], off
	s_barrier
	s_waitcnt lgkmcnt(0)
	v_mfma_f32_16x16x32_bf16 v[118:121], v[222:225], v[178:181], v[118:121]
	v_mfma_f32_16x16x32_bf16 v[114:117], v[230:233], v[178:181], v[114:117]
	v_mfma_f32_16x16x32_bf16 v[102:105], v[222:225], v[186:189], v[102:105]
	v_mfma_f32_16x16x32_bf16 v[98:101], v[230:233], v[186:189], v[98:101]
	v_mfma_f32_16x16x32_bf16 v[86:89], v[222:225], v[194:197], v[86:89]
	v_mfma_f32_16x16x32_bf16 v[82:85], v[230:233], v[194:197], v[82:85]
	v_mfma_f32_16x16x32_bf16 v[70:73], v[222:225], v[214:217], v[70:73]
	v_mfma_f32_16x16x32_bf16 v[66:69], v[230:233], v[214:217], v[66:69]
	v_mfma_f32_16x16x32_bf16 v[118:121], v[226:229], v[182:185], v[118:121]
	v_mfma_f32_16x16x32_bf16 v[114:117], v[234:237], v[182:185], v[114:117]
	v_mfma_f32_16x16x32_bf16 v[102:105], v[226:229], v[190:193], v[102:105]
	v_mfma_f32_16x16x32_bf16 v[98:101], v[234:237], v[190:193], v[98:101]
	v_mfma_f32_16x16x32_bf16 v[86:89], v[226:229], v[210:213], v[86:89]
	v_mfma_f32_16x16x32_bf16 v[82:85], v[234:237], v[210:213], v[82:85]
	v_mfma_f32_16x16x32_bf16 v[70:73], v[226:229], v[218:221], v[70:73]
	v_mfma_f32_16x16x32_bf16 v[66:69], v[234:237], v[218:221], v[66:69]
	s_mov_b32 m0, s50
	v_lshl_add_u64 v[198:199], v[240:241], 0, s[10:11]
	s_barrier
	ds_read_b128 v[178:181], v145 offset:49152
	ds_read_b128 v[182:185], v145 offset:50176
	ds_read_b128 v[186:189], v145 offset:51200
	ds_read_b128 v[190:193], v145 offset:52224
	ds_read_b128 v[194:197], v145 offset:53248
	ds_read_b128 v[210:213], v145 offset:54272
	ds_read_b128 v[214:217], v145 offset:55296
	ds_read_b128 v[218:221], v145 offset:56320
	global_load_lds_dwordx4 v[198:199], off
	s_mov_b32 m0, s51
	v_lshl_add_u64 v[198:199], v[242:243], 0, s[10:11]
	global_load_lds_dwordx4 v[198:199], off
	s_barrier
; __device__ __forceinline__ unsigned cvt_pk_bf16(float lo, float hi) { unsigned r; asm volatile("v_cvt_pk_bf16_f32 %0, %1, %2" : "=v"(r) : "v"(lo), "v"(hi)); return r; }
; #define PG8_STAGE(bufoff, gbase, voff) do { _Pragma("unroll") for (int _i = 0; _i < 2; ++_i) \
;         __builtin_amdgcn_global_load_lds((const unsigned*)((const char*)(gbase) + (voff)[_i]), (LAS unsigned*)(lds + (bufoff) + ldsw + _i * 8192), 16, 0, 0); } while (0)
; #define PG8_MMA(ai, bj, At, Bt) do { __builtin_amdgcn_s_setprio(1); _Pragma("unroll") for (int m = 0; m < 4; ++m) _Pragma("unroll") for (int n = 0; n < 2; ++n) _Pragma("unroll") for (int k = 0; k < 2; ++k) \
;         acc[ai][bj][m][n] = __builtin_amdgcn_mfma_f32_16x16x32_bf16(Bt[n][k], At[m][k], acc[ai][bj][m][n], 0, 0, 0); __builtin_amdgcn_s_setprio(0); } while (0)
; #define PG8_WAIT_V(n) asm volatile("s_waitcnt vmcnt(" #n ")" ::: "memory")
; #define PG8_WAIT_L(n) asm volatile("s_waitcnt lgkmcnt(" #n ")" ::: "memory")
;     __device__ __forceinline__ void operator()(const f32x4 (&acc)[2][2][4][2], const Unit& u, int ui, const LAS float* rtab, int wr, int wc, int fr, int fq) const {
;         const int row0 = u.pm * BM + wr * 64 + fr, col0 = u.pn * BM + wc * 32 + 8 * fq;
; #pragma unroll
;         for (int ai = 0; ai < 2; ++ai)
; #pragma unroll
;             for (int m = 0; m < 4; ++m) {
;                 const int row = row0 + ai * HALF + m * 16; const float rs = rtab[ui * 256 + wr * 64 + fr + ai * HALF + m * 16];
; #pragma unroll
;                 for (int bj = 0; bj < 2; ++bj) {
;                     f32x4 v0 = acc[ai][bj][m][0] * rs, v1 = acc[ai][bj][m][1] * rs;
; #pragma unroll
;                     for (int e = 0; e < 4; ++e) { const float a = fmaxf(v0[e], 0.f), b = fmaxf(v1[e], 0.f); v0[e] = a * a; v1[e] = b * b; }
;                     u32x4 w; w.x = cvt_pk_bf16(v0[0], v0[1]); w.y = cvt_pk_bf16(v0[2], v0[3]); w.z = cvt_pk_bf16(v1[0], v1[1]); w.w = cvt_pk_bf16(v1[2], v1[3]);
;                     *(u32x4*)(H + (size_t)row * DFF + col0 + bj * HALF) = w;
; template <class Epi, class Sched>
; __device__ __forceinline__ void gemm_phase(LAS unsigned char* lds, const Gemm g, const Sched& S, const Epi& E) {
;     ...
;             PG8_BAR; PG8_WAIT_L(0); PG8_MMA(1, 0, At, B0); PG8_BAR; PG8_SCHED;
;             PG8_STAGE(PG8_SB(1, 1), b3 + hstepB, voffB);
;             PG8_WAIT_V(6); PG8_BAR; PG8_MMA(1, 1, At, B1); PG8_BAR;
	s_waitcnt lgkmcnt(0)
	v_mfma_f32_16x16x32_bf16 v[62:65], v[146:149], v[178:181], v[62:65]
	v_mfma_f32_16x16x32_bf16 v[58:61], v[170:173], v[178:181], v[58:61]
	v_mfma_f32_16x16x32_bf16 v[46:49], v[146:149], v[186:189], v[46:49]
	v_mfma_f32_16x16x32_bf16 v[42:45], v[170:173], v[186:189], v[42:45]
	v_mfma_f32_16x16x32_bf16 v[30:33], v[146:149], v[194:197], v[30:33]
	v_mfma_f32_16x16x32_bf16 v[26:29], v[170:173], v[194:197], v[26:29]
	v_mfma_f32_16x16x32_bf16 v[14:17], v[146:149], v[214:217], v[14:17]
	v_mfma_f32_16x16x32_bf16 v[10:13], v[170:173], v[214:217], v[10:13]
	v_mfma_f32_16x16x32_bf16 v[62:65], v[150:153], v[182:185], v[62:65]
	v_mfma_f32_16x16x32_bf16 v[58:61], v[174:177], v[182:185], v[58:61]
	v_mfma_f32_16x16x32_bf16 v[46:49], v[150:153], v[190:193], v[46:49]
	v_mfma_f32_16x16x32_bf16 v[42:45], v[174:177], v[190:193], v[42:45]
	v_mfma_f32_16x16x32_bf16 v[30:33], v[150:153], v[210:213], v[30:33]
	v_mfma_f32_16x16x32_bf16 v[26:29], v[174:177], v[210:213], v[26:29]
	v_mfma_f32_16x16x32_bf16 v[14:17], v[150:153], v[218:221], v[14:17]
	v_mfma_f32_16x16x32_bf16 v[10:13], v[174:177], v[218:221], v[10:13]
	s_barrier
	s_add_u32 s46, s46, 0x80080
	s_addc_u32 s47, s47, 0
	s_add_i32 s23, s48, s26
	s_mov_b32 m0, s23
	v_lshl_add_u64 v[146:147], s[46:47], 0, v[134:135]
	global_load_lds_dwordx4 v[146:147], off
	s_add_i32 m0, s23, 0x2000
	v_lshl_add_u64 v[146:147], s[46:47], 0, v[130:131]
	global_load_lds_dwordx4 v[146:147], off
	s_waitcnt vmcnt(6)
	s_barrier
	v_mfma_f32_16x16x32_bf16 v[54:57], v[222:225], v[178:181], v[54:57]
	v_mfma_f32_16x16x32_bf16 v[50:53], v[230:233], v[178:181], v[50:53]
	v_mfma_f32_16x16x32_bf16 v[38:41], v[222:225], v[186:189], v[38:41]
	v_mfma_f32_16x16x32_bf16 v[34:37], v[230:233], v[186:189], v[34:37]
	v_mfma_f32_16x16x32_bf16 v[22:25], v[222:225], v[194:197], v[22:25]
	v_mfma_f32_16x16x32_bf16 v[18:21], v[230:233], v[194:197], v[18:21]
	v_mfma_f32_16x16x32_bf16 v[6:9], v[222:225], v[214:217], v[6:9]
	v_mfma_f32_16x16x32_bf16 v[2:5], v[230:233], v[214:217], v[2:5]
	v_mfma_f32_16x16x32_bf16 v[54:57], v[226:229], v[182:185], v[54:57]
	v_mfma_f32_16x16x32_bf16 v[50:53], v[234:237], v[182:185], v[50:53]
	v_mfma_f32_16x16x32_bf16 v[38:41], v[226:229], v[190:193], v[38:41]
	v_mfma_f32_16x16x32_bf16 v[34:37], v[234:237], v[190:193], v[34:37]
	v_mfma_f32_16x16x32_bf16 v[22:25], v[226:229], v[210:213], v[22:25]
	v_mfma_f32_16x16x32_bf16 v[18:21], v[234:237], v[210:213], v[18:21]
	v_mfma_f32_16x16x32_bf16 v[6:9], v[226:229], v[218:221], v[6:9]
	v_mfma_f32_16x16x32_bf16 v[2:5], v[234:237], v[218:221], v[2:5]
	s_add_i32 s66, s66, 2
	s_add_u32 s44, s44, 0x100
	s_addc_u32 s45, s45, 0
	s_add_u32 s58, s58, 0x100
	s_addc_u32 s59, s59, 0
	s_cmp_gt_u32 s66, 29
	s_barrier
	s_cbranch_scc0 .LBB0_830
	v_lshl_add_u32 v146, s55, 10, v143
	ds_read_b32 v150, v146
	v_lshl_add_u32 v148, s54, 8, v1
	v_lshl_or_b32 v152, s53, 8, v144
	v_ashrrev_i32_e32 v149, 31, v148
	v_ashrrev_i32_e32 v153, 31, v152
	s_waitcnt lgkmcnt(0)
	v_pk_mul_f32 v[124:125], v[124:125], v[150:151] op_sel_hi:[1,0]
	v_pk_mul_f32 v[128:129], v[128:129], v[150:151] op_sel_hi:[1,0]
	v_pk_mul_f32 v[126:127], v[126:127], v[150:151] op_sel_hi:[1,0]
	v_pk_mul_f32 v[122:123], v[122:123], v[150:151] op_sel_hi:[1,0]
	v_max_f32_e32 v124, 0, v124
	v_max_f32_e32 v126, 0, v126
	v_max_f32_e32 v122, 0, v122
	v_max_f32_e32 v123, 0, v123
	v_max_f32_e32 v128, 0, v128
	v_mul_f32_e32 v147, v124, v124
	v_max_f32_e32 v124, 0, v129
	v_lshlrev_b64 v[170:171], 14, v[148:149]
	v_mul_f32_e32 v126, v126, v126
	v_mul_f32_e32 v122, v122, v122
	v_max_f32_e32 v127, 0, v127
	v_mul_f32_e32 v123, v123, v123
	v_mul_f32_e32 v128, v128, v128
	v_max_f32_e32 v125, 0, v125
	v_mul_f32_e32 v129, v124, v124
	v_mul_f32_e32 v127, v127, v127
	v_mul_f32_e32 v149, v125, v125
	v_cvt_pk_bf16_f32 v124, v126, v127
	v_cvt_pk_bf16_f32 v125, v128, v129
	v_cvt_pk_bf16_f32 v126, v122, v123
	v_lshl_add_u64 v[122:123], s[72:73], 0, v[170:171]
	v_lshlrev_b64 v[128:129], 1, v[152:153]
	v_pk_mul_f32 v[116:117], v[116:117], v[150:151] op_sel_hi:[1,0]
	v_pk_mul_f32 v[114:115], v[114:115], v[150:151] op_sel_hi:[1,0]
	v_lshl_add_u64 v[122:123], v[122:123], 0, v[128:129]
	v_pk_mul_f32 v[120:121], v[120:121], v[150:151] op_sel_hi:[1,0]
	v_pk_mul_f32 v[118:119], v[118:119], v[150:151] op_sel_hi:[1,0]
	v_max_f32_e32 v114, 0, v114
	v_max_f32_e32 v115, 0, v115
	v_max_f32_e32 v116, 0, v116
	v_cvt_pk_bf16_f32 v127, v147, v149
	global_store_dwordx4 v[122:123], v[124:127], off
	v_max_f32_e32 v118, 0, v118
	v_max_f32_e32 v117, 0, v117
	v_mul_f32_e32 v124, v114, v114
	v_max_f32_e32 v114, 0, v119
	v_mul_f32_e32 v119, v115, v115
	v_max_f32_e32 v115, 0, v120
	v_mul_f32_e32 v120, v116, v116
	v_max_f32_e32 v116, 0, v121
	v_mul_f32_e32 v118, v118, v118
	v_mul_f32_e32 v114, v114, v114
	v_mul_f32_e32 v115, v115, v115
	v_mul_f32_e32 v116, v116, v116
	v_mul_f32_e32 v117, v117, v117
	v_cvt_pk_bf16_f32 v114, v118, v114
	v_cvt_pk_bf16_f32 v115, v115, v116
	v_cvt_pk_bf16_f32 v116, v124, v119
	v_cvt_pk_bf16_f32 v117, v120, v117
	ds_read_b32 v118, v146 offset:64
	global_store_dwordx4 v[122:123], v[114:117], off offset:256
	s_mov_b32 s1, 0x200000
	s_mov_b64 s[44:45], 0x240000
	v_or_b32_e32 v114, 16, v148
	s_waitcnt lgkmcnt(0)
; __device__ __forceinline__ unsigned cvt_pk_bf16(float lo, float hi) { unsigned r; asm volatile("v_cvt_pk_bf16_f32 %0, %1, %2" : "=v"(r) : "v"(lo), "v"(hi)); return r; }
;     __device__ __forceinline__ void operator()(const f32x4 (&acc)[2][2][4][2], const Unit& u, int ui, const LAS float* rtab, int wr, int wc, int fr, int fq) const {
;     ...
;         for (int ai = 0; ai < 2; ++ai)
; #pragma unroll
;             for (int m = 0; m < 4; ++m) {
;                 const int row = row0 + ai * HALF + m * 16; const float rs = rtab[ui * 256 + wr * 64 + fr + ai * HALF + m * 16];
; #pragma unroll
;                 for (int bj = 0; bj < 2; ++bj) {
;                     f32x4 v0 = acc[ai][bj][m][0] * rs, v1 = acc[ai][bj][m][1] * rs;
; #pragma unroll
;                     for (int e = 0; e < 4; ++e) { const float a = fmaxf(v0[e], 0.f), b = fmaxf(v1[e], 0.f); v0[e] = a * a; v1[e] = b * b; }
;                     u32x4 w; w.x = cvt_pk_bf16(v0[0], v0[1]); w.y = cvt_pk_bf16(v0[2], v0[3]); w.z = cvt_pk_bf16(v1[0], v1[1]); w.w = cvt_pk_bf16(v1[2], v1[3]);
;                     *(u32x4*)(H + (size_t)row * DFF + col0 + bj * HALF) = w;
;                 }
	v_pk_mul_f32 v[108:109], v[108:109], v[118:119] op_sel_hi:[1,0]
	v_pk_mul_f32 v[106:107], v[106:107], v[118:119] op_sel_hi:[1,0]
	v_pk_mul_f32 v[112:113], v[112:113], v[118:119] op_sel_hi:[1,0]
	v_pk_mul_f32 v[110:111], v[110:111], v[118:119] op_sel_hi:[1,0]
	v_max_f32_e32 v106, 0, v106
	v_max_f32_e32 v107, 0, v107
	v_max_f32_e32 v108, 0, v108
	v_ashrrev_i32_e32 v115, 31, v114
	v_max_f32_e32 v110, 0, v110
	v_mul_f32_e32 v116, v106, v106
	v_max_f32_e32 v106, 0, v111
	v_mul_f32_e32 v111, v107, v107
	v_max_f32_e32 v107, 0, v112
	v_mul_f32_e32 v112, v108, v108
	v_max_f32_e32 v108, 0, v113
	v_lshlrev_b64 v[114:115], 14, v[114:115]
	v_mul_f32_e32 v110, v110, v110
	v_mul_f32_e32 v106, v106, v106
	v_mul_f32_e32 v107, v107, v107
	v_mul_f32_e32 v108, v108, v108
	v_max_f32_e32 v109, 0, v109
	v_cvt_pk_bf16_f32 v106, v110, v106
	v_cvt_pk_bf16_f32 v107, v107, v108
	v_cvt_pk_bf16_f32 v108, v116, v111
	v_lshl_add_u64 v[110:111], s[72:73], 0, v[114:115]
	v_pk_mul_f32 v[100:101], v[100:101], v[118:119] op_sel_hi:[1,0]
	v_pk_mul_f32 v[98:99], v[98:99], v[118:119] op_sel_hi:[1,0]
	v_mul_f32_e32 v109, v109, v109
	v_lshl_add_u64 v[110:111], v[110:111], 0, v[128:129]
	v_pk_mul_f32 v[104:105], v[104:105], v[118:119] op_sel_hi:[1,0]
	v_pk_mul_f32 v[102:103], v[102:103], v[118:119] op_sel_hi:[1,0]
	v_max_f32_e32 v98, 0, v98
	v_max_f32_e32 v99, 0, v99
	v_max_f32_e32 v100, 0, v100
	v_cvt_pk_bf16_f32 v109, v112, v109
	global_store_dwordx4 v[110:111], v[106:109], off
	v_max_f32_e32 v102, 0, v102
	v_max_f32_e32 v101, 0, v101
	v_mul_f32_e32 v106, v98, v98
	v_max_f32_e32 v98, 0, v103
	v_mul_f32_e32 v103, v99, v99
	v_max_f32_e32 v99, 0, v104
	v_mul_f32_e32 v104, v100, v100
	v_max_f32_e32 v100, 0, v105
	v_mul_f32_e32 v102, v102, v102
	v_mul_f32_e32 v98, v98, v98
	v_mul_f32_e32 v99, v99, v99
	v_mul_f32_e32 v100, v100, v100
	v_mul_f32_e32 v101, v101, v101
	v_cvt_pk_bf16_f32 v98, v102, v98
	v_cvt_pk_bf16_f32 v99, v99, v100
	v_cvt_pk_bf16_f32 v100, v106, v103
	v_cvt_pk_bf16_f32 v101, v104, v101
	ds_read_b32 v102, v146 offset:128
	global_store_dwordx4 v[110:111], v[98:101], off offset:256
	s_mov_b32 s54, s20
	s_mov_b32 s53, s0
	v_or_b32_e32 v98, 32, v148
	s_waitcnt lgkmcnt(0)
	v_pk_mul_f32 v[92:93], v[92:93], v[102:103] op_sel_hi:[1,0]
	v_pk_mul_f32 v[90:91], v[90:91], v[102:103] op_sel_hi:[1,0]
	v_pk_mul_f32 v[96:97], v[96:97], v[102:103] op_sel_hi:[1,0]
	v_pk_mul_f32 v[94:95], v[94:95], v[102:103] op_sel_hi:[1,0]
	v_max_f32_e32 v90, 0, v90
	v_max_f32_e32 v91, 0, v91
	v_max_f32_e32 v92, 0, v92
	v_ashrrev_i32_e32 v99, 31, v98
	v_max_f32_e32 v94, 0, v94
	v_mul_f32_e32 v100, v90, v90
	v_max_f32_e32 v90, 0, v95
	v_mul_f32_e32 v95, v91, v91
	v_max_f32_e32 v91, 0, v96
	v_mul_f32_e32 v96, v92, v92
	v_max_f32_e32 v92, 0, v97
	v_lshlrev_b64 v[98:99], 14, v[98:99]
	v_mul_f32_e32 v94, v94, v94
	v_mul_f32_e32 v90, v90, v90
	v_mul_f32_e32 v91, v91, v91
	v_mul_f32_e32 v92, v92, v92
	v_max_f32_e32 v93, 0, v93
	v_cvt_pk_bf16_f32 v90, v94, v90
	v_cvt_pk_bf16_f32 v91, v91, v92
	v_cvt_pk_bf16_f32 v92, v100, v95
	v_lshl_add_u64 v[94:95], s[72:73], 0, v[98:99]
	v_pk_mul_f32 v[84:85], v[84:85], v[102:103] op_sel_hi:[1,0]
	v_pk_mul_f32 v[82:83], v[82:83], v[102:103] op_sel_hi:[1,0]
	v_mul_f32_e32 v93, v93, v93
	v_lshl_add_u64 v[94:95], v[94:95], 0, v[128:129]
	v_pk_mul_f32 v[88:89], v[88:89], v[102:103] op_sel_hi:[1,0]
	v_pk_mul_f32 v[86:87], v[86:87], v[102:103] op_sel_hi:[1,0]
	v_max_f32_e32 v82, 0, v82
	v_max_f32_e32 v83, 0, v83
	v_max_f32_e32 v84, 0, v84
	v_cvt_pk_bf16_f32 v93, v96, v93
	global_store_dwordx4 v[94:95], v[90:93], off
	v_max_f32_e32 v86, 0, v86
	v_max_f32_e32 v85, 0, v85
	v_mul_f32_e32 v90, v82, v82
	v_max_f32_e32 v82, 0, v87
	v_mul_f32_e32 v87, v83, v83
	v_max_f32_e32 v83, 0, v88
	v_mul_f32_e32 v88, v84, v84
	v_max_f32_e32 v84, 0, v89
	v_mul_f32_e32 v86, v86, v86
	v_mul_f32_e32 v82, v82, v82
	v_mul_f32_e32 v83, v83, v83
	v_mul_f32_e32 v84, v84, v84
	v_mul_f32_e32 v85, v85, v85
	v_cvt_pk_bf16_f32 v82, v86, v82
	v_cvt_pk_bf16_f32 v83, v83, v84
	v_cvt_pk_bf16_f32 v84, v90, v87
	v_cvt_pk_bf16_f32 v85, v88, v85
	ds_read_b32 v86, v146 offset:192
	global_store_dwordx4 v[94:95], v[82:85], off offset:256
	s_mov_b64 s[46:47], s[36:37]
	s_mov_b32 s55, s52
	v_or_b32_e32 v82, 48, v148
	s_waitcnt lgkmcnt(0)
	v_pk_mul_f32 v[76:77], v[76:77], v[86:87] op_sel_hi:[1,0]
	v_pk_mul_f32 v[74:75], v[74:75], v[86:87] op_sel_hi:[1,0]
	v_pk_mul_f32 v[80:81], v[80:81], v[86:87] op_sel_hi:[1,0]
	v_pk_mul_f32 v[78:79], v[78:79], v[86:87] op_sel_hi:[1,0]
	v_max_f32_e32 v74, 0, v74
	v_max_f32_e32 v75, 0, v75
	v_max_f32_e32 v76, 0, v76
	v_ashrrev_i32_e32 v83, 31, v82
	v_max_f32_e32 v78, 0, v78
	v_mul_f32_e32 v84, v74, v74
	v_max_f32_e32 v74, 0, v79
	v_mul_f32_e32 v79, v75, v75
	v_max_f32_e32 v75, 0, v80
	v_mul_f32_e32 v80, v76, v76
	v_max_f32_e32 v76, 0, v81
	v_lshlrev_b64 v[82:83], 14, v[82:83]
	v_mul_f32_e32 v78, v78, v78
	v_mul_f32_e32 v74, v74, v74
	v_mul_f32_e32 v75, v75, v75
	v_mul_f32_e32 v76, v76, v76
	v_max_f32_e32 v77, 0, v77
	v_cvt_pk_bf16_f32 v74, v78, v74
	v_cvt_pk_bf16_f32 v75, v75, v76
	v_cvt_pk_bf16_f32 v76, v84, v79
	v_lshl_add_u64 v[78:79], s[72:73], 0, v[82:83]
	v_pk_mul_f32 v[68:69], v[68:69], v[86:87] op_sel_hi:[1,0]
	v_pk_mul_f32 v[66:67], v[66:67], v[86:87] op_sel_hi:[1,0]
	v_mul_f32_e32 v77, v77, v77
	v_lshl_add_u64 v[78:79], v[78:79], 0, v[128:129]
	v_pk_mul_f32 v[72:73], v[72:73], v[86:87] op_sel_hi:[1,0]
	v_pk_mul_f32 v[70:71], v[70:71], v[86:87] op_sel_hi:[1,0]
	v_max_f32_e32 v66, 0, v66
	v_max_f32_e32 v67, 0, v67
	v_max_f32_e32 v68, 0, v68
	v_cvt_pk_bf16_f32 v77, v80, v77
	global_store_dwordx4 v[78:79], v[74:77], off
	v_max_f32_e32 v70, 0, v70
	v_max_f32_e32 v69, 0, v69
	v_mul_f32_e32 v74, v66, v66
	v_max_f32_e32 v66, 0, v71
	v_mul_f32_e32 v71, v67, v67
	v_max_f32_e32 v67, 0, v72
	v_mul_f32_e32 v72, v68, v68
	v_max_f32_e32 v68, 0, v73
	v_mul_f32_e32 v70, v70, v70
	v_mul_f32_e32 v66, v66, v66
	v_mul_f32_e32 v67, v67, v67
	v_mul_f32_e32 v68, v68, v68
	v_mul_f32_e32 v69, v69, v69
	v_cvt_pk_bf16_f32 v66, v70, v66
	v_cvt_pk_bf16_f32 v67, v67, v68
	v_cvt_pk_bf16_f32 v68, v74, v71
	v_cvt_pk_bf16_f32 v69, v72, v69
	ds_read_b32 v70, v146 offset:512
	global_store_dwordx4 v[78:79], v[66:69], off offset:256
	s_waitcnt lgkmcnt(0)
; __device__ __forceinline__ unsigned cvt_pk_bf16(float lo, float hi) { unsigned r; asm volatile("v_cvt_pk_bf16_f32 %0, %1, %2" : "=v"(r) : "v"(lo), "v"(hi)); return r; }
;     __device__ __forceinline__ void operator()(const f32x4 (&acc)[2][2][4][2], const Unit& u, int ui, const LAS float* rtab, int wr, int wc, int fr, int fq) const {
;     ...
;         for (int ai = 0; ai < 2; ++ai)
; #pragma unroll
;             for (int m = 0; m < 4; ++m) {
;                 const int row = row0 + ai * HALF + m * 16; const float rs = rtab[ui * 256 + wr * 64 + fr + ai * HALF + m * 16];
; #pragma unroll
;                 for (int bj = 0; bj < 2; ++bj) {
;                     f32x4 v0 = acc[ai][bj][m][0] * rs, v1 = acc[ai][bj][m][1] * rs;
; #pragma unroll
;                     for (int e = 0; e < 4; ++e) { const float a = fmaxf(v0[e], 0.f), b = fmaxf(v1[e], 0.f); v0[e] = a * a; v1[e] = b * b; }
;                     u32x4 w; w.x = cvt_pk_bf16(v0[0], v0[1]); w.y = cvt_pk_bf16(v0[2], v0[3]); w.z = cvt_pk_bf16(v1[0], v1[1]); w.w = cvt_pk_bf16(v1[2], v1[3]);
;                     *(u32x4*)(H + (size_t)row * DFF + col0 + bj * HALF) = w;
;                 }
	v_pk_mul_f32 v[58:59], v[58:59], v[70:71] op_sel_hi:[1,0]
	v_pk_mul_f32 v[62:63], v[62:63], v[70:71] op_sel_hi:[1,0]
	v_pk_mul_f32 v[60:61], v[60:61], v[70:71] op_sel_hi:[1,0]
	v_max_f32_e32 v58, 0, v58
	v_pk_mul_f32 v[64:65], v[64:65], v[70:71] op_sel_hi:[1,0]
	v_max_f32_e32 v62, 0, v62
	v_mul_f32_e32 v66, v58, v58
	v_max_f32_e32 v58, 0, v63
	v_max_f32_e32 v59, 0, v59
	v_max_f32_e32 v60, 0, v60
	v_mul_f32_e32 v62, v62, v62
	v_mul_f32_e32 v58, v58, v58
	v_mul_f32_e32 v63, v59, v59
	v_max_f32_e32 v59, 0, v64
	v_mul_f32_e32 v64, v60, v60
	v_max_f32_e32 v60, 0, v65
	v_mul_f32_e32 v59, v59, v59
	v_max_f32_e32 v61, 0, v61
	v_mul_f32_e32 v60, v60, v60
	v_cvt_pk_bf16_f32 v58, v62, v58
	v_add_co_u32_e32 v62, vcc, s1, v122
	v_pk_mul_f32 v[52:53], v[52:53], v[70:71] op_sel_hi:[1,0]
	v_pk_mul_f32 v[50:51], v[50:51], v[70:71] op_sel_hi:[1,0]
	v_mul_f32_e32 v61, v61, v61
	v_cvt_pk_bf16_f32 v59, v59, v60
	v_cvt_pk_bf16_f32 v60, v66, v63
	v_addc_co_u32_e32 v63, vcc, 0, v123, vcc
	v_pk_mul_f32 v[56:57], v[56:57], v[70:71] op_sel_hi:[1,0]
	v_pk_mul_f32 v[54:55], v[54:55], v[70:71] op_sel_hi:[1,0]
	v_max_f32_e32 v50, 0, v50
	v_max_f32_e32 v51, 0, v51
	v_max_f32_e32 v52, 0, v52
	v_cvt_pk_bf16_f32 v61, v64, v61
	global_store_dwordx4 v[62:63], v[58:61], off
	v_max_f32_e32 v54, 0, v54
	v_max_f32_e32 v53, 0, v53
	v_mul_f32_e32 v58, v50, v50
	v_max_f32_e32 v50, 0, v55
	v_mul_f32_e32 v55, v51, v51
	v_max_f32_e32 v51, 0, v56
	v_mul_f32_e32 v56, v52, v52
	v_max_f32_e32 v52, 0, v57
	v_mul_f32_e32 v54, v54, v54
	v_mul_f32_e32 v50, v50, v50
	v_mul_f32_e32 v51, v51, v51
	v_mul_f32_e32 v52, v52, v52
	v_mul_f32_e32 v53, v53, v53
	v_cvt_pk_bf16_f32 v50, v54, v50
	v_cvt_pk_bf16_f32 v51, v51, v52
	v_cvt_pk_bf16_f32 v52, v58, v55
	v_cvt_pk_bf16_f32 v53, v56, v53
	ds_read_b32 v54, v146 offset:576
	v_lshl_add_u64 v[56:57], v[122:123], 0, s[84:85]
	global_store_dwordx4 v[56:57], v[50:53], off offset:256
	s_mov_b32 s1, 0x240000
	s_waitcnt lgkmcnt(0)
	v_pk_mul_f32 v[42:43], v[42:43], v[54:55] op_sel_hi:[1,0]
	v_pk_mul_f32 v[46:47], v[46:47], v[54:55] op_sel_hi:[1,0]
	v_pk_mul_f32 v[44:45], v[44:45], v[54:55] op_sel_hi:[1,0]
	v_max_f32_e32 v42, 0, v42
	v_pk_mul_f32 v[48:49], v[48:49], v[54:55] op_sel_hi:[1,0]
	v_max_f32_e32 v46, 0, v46
	v_mul_f32_e32 v50, v42, v42
	v_max_f32_e32 v42, 0, v47
	v_max_f32_e32 v43, 0, v43
	v_max_f32_e32 v44, 0, v44
	v_mul_f32_e32 v46, v46, v46
	v_mul_f32_e32 v42, v42, v42
	v_mul_f32_e32 v47, v43, v43
	v_max_f32_e32 v43, 0, v48
	v_mul_f32_e32 v48, v44, v44
	v_max_f32_e32 v44, 0, v49
	v_mul_f32_e32 v43, v43, v43
	v_max_f32_e32 v45, 0, v45
	v_mul_f32_e32 v44, v44, v44
	v_cvt_pk_bf16_f32 v42, v46, v42
	v_add_co_u32_e32 v46, vcc, s1, v122
	v_pk_mul_f32 v[36:37], v[36:37], v[54:55] op_sel_hi:[1,0]
	v_pk_mul_f32 v[34:35], v[34:35], v[54:55] op_sel_hi:[1,0]
	v_mul_f32_e32 v45, v45, v45
	v_cvt_pk_bf16_f32 v43, v43, v44
	v_cvt_pk_bf16_f32 v44, v50, v47
	v_addc_co_u32_e32 v47, vcc, 0, v123, vcc
	v_pk_mul_f32 v[40:41], v[40:41], v[54:55] op_sel_hi:[1,0]
	v_pk_mul_f32 v[38:39], v[38:39], v[54:55] op_sel_hi:[1,0]
	v_max_f32_e32 v34, 0, v34
	v_max_f32_e32 v35, 0, v35
	v_max_f32_e32 v36, 0, v36
	v_cvt_pk_bf16_f32 v45, v48, v45
	global_store_dwordx4 v[46:47], v[42:45], off
	v_max_f32_e32 v38, 0, v38
	v_max_f32_e32 v37, 0, v37
	v_mul_f32_e32 v42, v34, v34
	v_max_f32_e32 v34, 0, v39
	v_mul_f32_e32 v39, v35, v35
	v_max_f32_e32 v35, 0, v40
	v_mul_f32_e32 v40, v36, v36
	v_max_f32_e32 v36, 0, v41
	v_mul_f32_e32 v38, v38, v38
	v_mul_f32_e32 v34, v34, v34
	v_mul_f32_e32 v35, v35, v35
	v_mul_f32_e32 v36, v36, v36
	v_mul_f32_e32 v37, v37, v37
	v_cvt_pk_bf16_f32 v34, v38, v34
	v_cvt_pk_bf16_f32 v35, v35, v36
	v_cvt_pk_bf16_f32 v36, v42, v39
	v_cvt_pk_bf16_f32 v37, v40, v37
	ds_read_b32 v38, v146 offset:640
	v_lshl_add_u64 v[40:41], v[122:123], 0, s[44:45]
	global_store_dwordx4 v[40:41], v[34:37], off offset:256
	s_mov_b32 s1, 0x280000
	s_mov_b64 s[44:45], 0x280000
	s_waitcnt lgkmcnt(0)
; __device__ __forceinline__ unsigned cvt_pk_bf16(float lo, float hi) { unsigned r; asm volatile("v_cvt_pk_bf16_f32 %0, %1, %2" : "=v"(r) : "v"(lo), "v"(hi)); return r; }
; #define PG8_WAIT_V(n) asm volatile("s_waitcnt vmcnt(" #n ")" ::: "memory")
; #define PG8_BAR __builtin_amdgcn_s_barrier()
;     __device__ __forceinline__ void operator()(const f32x4 (&acc)[2][2][4][2], const Unit& u, int ui, const LAS float* rtab, int wr, int wc, int fr, int fq) const {
;     ...
;         for (int ai = 0; ai < 2; ++ai)
; #pragma unroll
;             for (int m = 0; m < 4; ++m) {
;                 const int row = row0 + ai * HALF + m * 16; const float rs = rtab[ui * 256 + wr * 64 + fr + ai * HALF + m * 16];
; #pragma unroll
;                 for (int bj = 0; bj < 2; ++bj) {
;                     f32x4 v0 = acc[ai][bj][m][0] * rs, v1 = acc[ai][bj][m][1] * rs;
; #pragma unroll
;                     for (int e = 0; e < 4; ++e) { const float a = fmaxf(v0[e], 0.f), b = fmaxf(v1[e], 0.f); v0[e] = a * a; v1[e] = b * b; }
;                     u32x4 w; w.x = cvt_pk_bf16(v0[0], v0[1]); w.y = cvt_pk_bf16(v0[2], v0[3]); w.z = cvt_pk_bf16(v1[0], v1[1]); w.w = cvt_pk_bf16(v1[2], v1[3]);
;                     *(u32x4*)(H + (size_t)row * DFF + col0 + bj * HALF) = w;
;                 }
; template <class Epi, class Sched>
; __device__ __forceinline__ void gemm_phase(LAS unsigned char* lds, const Gemm g, const Sched& S, const Epi& E) {
;     ...
;         if (!has_next) break;
;     ...
;     PG8_WAIT_V(0);
;     if (wr == 0) PG8_BAR;
;     PG8_BAR;
	v_pk_mul_f32 v[26:27], v[26:27], v[38:39] op_sel_hi:[1,0]
	v_pk_mul_f32 v[30:31], v[30:31], v[38:39] op_sel_hi:[1,0]
	v_pk_mul_f32 v[28:29], v[28:29], v[38:39] op_sel_hi:[1,0]
	v_max_f32_e32 v26, 0, v26
	v_pk_mul_f32 v[32:33], v[32:33], v[38:39] op_sel_hi:[1,0]
	v_max_f32_e32 v30, 0, v30
	v_mul_f32_e32 v34, v26, v26
	v_max_f32_e32 v26, 0, v31
	v_max_f32_e32 v27, 0, v27
	v_max_f32_e32 v28, 0, v28
	v_mul_f32_e32 v30, v30, v30
	v_mul_f32_e32 v26, v26, v26
	v_mul_f32_e32 v31, v27, v27
	v_max_f32_e32 v27, 0, v32
	v_mul_f32_e32 v32, v28, v28
	v_max_f32_e32 v28, 0, v33
	v_mul_f32_e32 v27, v27, v27
	v_max_f32_e32 v29, 0, v29
	v_mul_f32_e32 v28, v28, v28
	v_cvt_pk_bf16_f32 v26, v30, v26
	v_add_co_u32_e32 v30, vcc, s1, v122
	v_pk_mul_f32 v[20:21], v[20:21], v[38:39] op_sel_hi:[1,0]
	v_pk_mul_f32 v[18:19], v[18:19], v[38:39] op_sel_hi:[1,0]
	v_mul_f32_e32 v29, v29, v29
	v_cvt_pk_bf16_f32 v27, v27, v28
	v_cvt_pk_bf16_f32 v28, v34, v31
	v_addc_co_u32_e32 v31, vcc, 0, v123, vcc
	v_pk_mul_f32 v[24:25], v[24:25], v[38:39] op_sel_hi:[1,0]
	v_pk_mul_f32 v[22:23], v[22:23], v[38:39] op_sel_hi:[1,0]
	v_max_f32_e32 v18, 0, v18
	v_max_f32_e32 v19, 0, v19
	v_max_f32_e32 v20, 0, v20
	v_cvt_pk_bf16_f32 v29, v32, v29
	global_store_dwordx4 v[30:31], v[26:29], off
	v_max_f32_e32 v22, 0, v22
	v_max_f32_e32 v21, 0, v21
	v_mul_f32_e32 v26, v18, v18
	v_max_f32_e32 v18, 0, v23
	v_mul_f32_e32 v23, v19, v19
	v_max_f32_e32 v19, 0, v24
	v_mul_f32_e32 v24, v20, v20
	v_max_f32_e32 v20, 0, v25
	v_mul_f32_e32 v22, v22, v22
	v_mul_f32_e32 v18, v18, v18
	v_mul_f32_e32 v19, v19, v19
	v_mul_f32_e32 v20, v20, v20
	v_mul_f32_e32 v21, v21, v21
	v_cvt_pk_bf16_f32 v18, v22, v18
	v_cvt_pk_bf16_f32 v19, v19, v20
	v_cvt_pk_bf16_f32 v20, v26, v23
	v_cvt_pk_bf16_f32 v21, v24, v21
	ds_read_b32 v22, v146 offset:704
	v_lshl_add_u64 v[24:25], v[122:123], 0, s[44:45]
	global_store_dwordx4 v[24:25], v[18:21], off offset:256
	s_mov_b32 s1, 0x2c0000
	s_mov_b64 s[44:45], 0x2c0000
	s_waitcnt lgkmcnt(0)
	v_pk_mul_f32 v[12:13], v[12:13], v[22:23] op_sel_hi:[1,0]
	v_pk_mul_f32 v[10:11], v[10:11], v[22:23] op_sel_hi:[1,0]
	v_pk_mul_f32 v[16:17], v[16:17], v[22:23] op_sel_hi:[1,0]
	v_pk_mul_f32 v[14:15], v[14:15], v[22:23] op_sel_hi:[1,0]
	v_max_f32_e32 v10, 0, v10
	v_max_f32_e32 v11, 0, v11
	v_max_f32_e32 v12, 0, v12
	v_mul_f32_e32 v18, v10, v10
	v_max_f32_e32 v10, 0, v15
	v_mul_f32_e32 v15, v11, v11
	v_max_f32_e32 v11, 0, v16
	v_mul_f32_e32 v16, v12, v12
	v_max_f32_e32 v12, 0, v17
	v_max_f32_e32 v13, 0, v13
	v_max_f32_e32 v14, 0, v14
	v_mul_f32_e32 v10, v10, v10
	v_mul_f32_e32 v11, v11, v11
	v_mul_f32_e32 v12, v12, v12
	v_mul_f32_e32 v13, v13, v13
	v_mul_f32_e32 v14, v14, v14
	v_cvt_pk_bf16_f32 v10, v14, v10
	v_cvt_pk_bf16_f32 v11, v11, v12
	v_cvt_pk_bf16_f32 v12, v18, v15
	v_cvt_pk_bf16_f32 v13, v16, v13
	v_add_co_u32_e32 v16, vcc, s1, v122
	v_pk_mul_f32 v[4:5], v[4:5], v[22:23] op_sel_hi:[1,0]
	v_pk_mul_f32 v[2:3], v[2:3], v[22:23] op_sel_hi:[1,0]
	v_addc_co_u32_e32 v17, vcc, 0, v123, vcc
	v_pk_mul_f32 v[8:9], v[8:9], v[22:23] op_sel_hi:[1,0]
	v_pk_mul_f32 v[6:7], v[6:7], v[22:23] op_sel_hi:[1,0]
	v_max_f32_e32 v2, 0, v2
	v_max_f32_e32 v3, 0, v3
	v_max_f32_e32 v4, 0, v4
	global_store_dwordx4 v[16:17], v[10:13], off
	v_max_f32_e32 v5, 0, v5
	v_lshl_add_u64 v[14:15], v[122:123], 0, s[44:45]
	v_mul_f32_e32 v10, v2, v2
	v_max_f32_e32 v2, 0, v7
	v_mul_f32_e32 v7, v3, v3
	v_max_f32_e32 v3, 0, v8
	v_mul_f32_e32 v8, v4, v4
	v_max_f32_e32 v4, 0, v9
	v_max_f32_e32 v6, 0, v6
	v_mul_f32_e32 v2, v2, v2
	v_mul_f32_e32 v3, v3, v3
	v_mul_f32_e32 v4, v4, v4
	v_mul_f32_e32 v5, v5, v5
	s_and_b64 vcc, exec, s[42:43]
	s_mov_b64 s[44:45], s[34:35]
	v_mul_f32_e32 v6, v6, v6
	v_cvt_pk_bf16_f32 v2, v6, v2
	v_cvt_pk_bf16_f32 v3, v3, v4
	v_cvt_pk_bf16_f32 v4, v10, v7
	v_cvt_pk_bf16_f32 v5, v8, v5
	global_store_dwordx4 v[14:15], v[2:5], off offset:256
	s_cbranch_vccz .LBB0_823
	s_waitcnt vmcnt(0)
	s_cmpk_gt_u32 s13, 0xff
	s_cbranch_scc1 .LBB0_834
	s_barrier

; #define PG8_STAGE(bufoff, gbase, voff) do { _Pragma("unroll") for (int _i = 0; _i < 2; ++_i) \
;         __builtin_amdgcn_global_load_lds((const unsigned*)((const char*)(gbase) + (voff)[_i]), (LAS unsigned*)(lds + (bufoff) + ldsw + _i * 8192), 16, 0, 0); } while (0)
; #define PG8_LDA(dst, b, h) do { _Pragma("unroll") for (int m = 0; m < 4; ++m) _Pragma("unroll") for (int k = 0; k < 2; ++k) dst[m][k] = *(const LAS bf16x8*)(lds + PG8_SA(b, h) + aoff + m * 2048 + k * 1024); } while (0)
; #define PG8_LDB(dst, b, h) do { _Pragma("unroll") for (int n = 0; n < 2; ++n) _Pragma("unroll") for (int k = 0; k < 2; ++k) dst[n][k] = *(const LAS bf16x8*)(lds + PG8_SB(b, h) + boff + n * 2048 + k * 1024); } while (0)
; #define PG8_MMA(ai, bj, At, Bt) do { __builtin_amdgcn_s_setprio(1); _Pragma("unroll") for (int m = 0; m < 4; ++m) _Pragma("unroll") for (int n = 0; n < 2; ++n) _Pragma("unroll") for (int k = 0; k < 2; ++k) \
;         acc[ai][bj][m][n] = __builtin_amdgcn_mfma_f32_16x16x32_bf16(Bt[n][k], At[m][k], acc[ai][bj][m][n], 0, 0, 0); __builtin_amdgcn_s_setprio(0); } while (0)
; #define PG8_WAIT_V(n) asm volatile("s_waitcnt vmcnt(" #n ")" ::: "memory")
; #define PG8_WAIT_L(n) asm volatile("s_waitcnt lgkmcnt(" #n ")" ::: "memory")
; #define PG8_BAR __builtin_amdgcn_s_barrier()
; #define PG8_SCHED __builtin_amdgcn_sched_barrier(0)
; template <class Epi, class Sched>
; __device__ __forceinline__ void gemm_phase(LAS unsigned char* lds, const Gemm g, const Sched& S, const Epi& E) {
;     ...
;             const char* a1 = cA + (size_t)(t + 1) * kstep;
;             const char* a2 = last ? nA : cA + (size_t)(t + 2) * kstep; const char* b2 = last ? nB : cB + (size_t)(t + 2) * kstep;
;             const char* a3 = a2 + kstep; const char* b3 = b2 + kstep;
;             PG8_LDB(B0, 0, 0); PG8_SCHED; PG8_LDA(At, 0, 0); PG8_STAGE(PG8_SA(1, 1), a1 + hstepA, voffA);
;             PG8_WAIT_L(8); PG8_BAR; PG8_WAIT_L(0); PG8_MMA(0, 0, At, B0); PG8_BAR; PG8_SCHED;
;             PG8_LDB(B1, 0, 1); PG8_STAGE(PG8_SB(0, 0), b2, voffB);
;             PG8_BAR; PG8_WAIT_L(0); PG8_MMA(0, 1, At, B1); PG8_BAR;
;             PG8_LDA(At, 0, 1); PG8_STAGE(PG8_SA(0, 0), a2, voffA);
;             PG8_BAR; PG8_WAIT_L(0); PG8_MMA(1, 0, At, B0); PG8_BAR; PG8_SCHED;
;             PG8_STAGE(PG8_SB(0, 1), b2 + hstepB, voffB);
;             PG8_WAIT_V(6); PG8_BAR; PG8_MMA(1, 1, At, B1); PG8_BAR;
.LBB0_899:
	s_add_u32 s23, s44, 0xffe00080
	s_addc_u32 s46, s45, -1
	s_add_i32 s67, 0, 0x10000
	v_add_u32_e32 v142, s67, v162
	ds_read_b128 v[130:133], v142
	ds_read_b128 v[134:137], v142 offset:1024
	ds_read_b128 v[138:141], v142 offset:2048
	ds_read_b128 v[142:145], v142 offset:3072
	s_cmpk_eq_i32 s66, 0x7c
	s_cselect_b32 s49, s25, s46
	s_cselect_b32 s48, s57, s23
	s_cselect_b32 s47, s21, s68
	s_cselect_b32 s46, s58, s59
	v_lshl_add_u64 v[198:199], s[44:45], 0, v[178:179]
	s_add_i32 m0, s31, 0xc000
	ds_read_b128 v[146:149], v210
	ds_read_b128 v[150:153], v210 offset:1024
	ds_read_b128 v[182:185], v210 offset:2048
	ds_read_b128 v[186:189], v210 offset:3072
	ds_read_b128 v[190:193], v210 offset:4096
	ds_read_b128 v[194:197], v210 offset:5120
	ds_read_b128 v[212:215], v210 offset:6144
	ds_read_b128 v[216:219], v210 offset:7168
	global_load_lds_dwordx4 v[198:199], off
	s_add_i32 m0, s31, 0xe000
	v_lshl_add_u64 v[198:199], s[44:45], 0, v[180:181]
	global_load_lds_dwordx4 v[198:199], off
	s_waitcnt lgkmcnt(8)
	s_barrier
	s_waitcnt lgkmcnt(0)
	v_mfma_f32_16x16x32_bf16 v[126:129], v[130:133], v[146:149], v[126:129]
	v_mfma_f32_16x16x32_bf16 v[122:125], v[138:141], v[146:149], v[122:125]
	v_mfma_f32_16x16x32_bf16 v[110:113], v[130:133], v[182:185], v[110:113]
	v_mfma_f32_16x16x32_bf16 v[106:109], v[138:141], v[182:185], v[106:109]
	v_mfma_f32_16x16x32_bf16 v[94:97], v[130:133], v[190:193], v[94:97]
	v_mfma_f32_16x16x32_bf16 v[90:93], v[138:141], v[190:193], v[90:93]
	v_mfma_f32_16x16x32_bf16 v[78:81], v[130:133], v[212:215], v[78:81]
	v_mfma_f32_16x16x32_bf16 v[74:77], v[138:141], v[212:215], v[74:77]
	v_mfma_f32_16x16x32_bf16 v[126:129], v[134:137], v[150:153], v[126:129]
	v_mfma_f32_16x16x32_bf16 v[122:125], v[142:145], v[150:153], v[122:125]
	v_mfma_f32_16x16x32_bf16 v[110:113], v[134:137], v[186:189], v[110:113]
	v_mfma_f32_16x16x32_bf16 v[106:109], v[142:145], v[186:189], v[106:109]
	v_mfma_f32_16x16x32_bf16 v[94:97], v[134:137], v[194:197], v[94:97]
	v_mfma_f32_16x16x32_bf16 v[90:93], v[142:145], v[194:197], v[90:93]
	v_mfma_f32_16x16x32_bf16 v[78:81], v[134:137], v[216:219], v[78:81]
	v_mfma_f32_16x16x32_bf16 v[74:77], v[142:145], v[216:219], v[74:77]
	s_barrier
	s_add_i32 s23, 0, 0x14000
	v_add_u32_e32 v198, s23, v162
	s_add_i32 s67, s67, s27
	ds_read_b128 v[220:223], v198
	ds_read_b128 v[224:227], v198 offset:1024
	ds_read_b128 v[228:231], v198 offset:2048
	ds_read_b128 v[232:235], v198 offset:3072
	v_lshl_add_u64 v[198:199], s[46:47], 0, v[174:175]
	s_mov_b32 m0, s67
	v_lshl_add_u64 v[236:237], s[46:47], 0, v[170:171]
	global_load_lds_dwordx4 v[198:199], off
	s_add_i32 m0, s67, 0x2000
	s_nop 0
	global_load_lds_dwordx4 v[236:237], off
	s_barrier
	s_waitcnt lgkmcnt(0)
	v_mfma_f32_16x16x32_bf16 v[118:121], v[220:223], v[146:149], v[118:121]
	v_mfma_f32_16x16x32_bf16 v[114:117], v[228:231], v[146:149], v[114:117]
	v_mfma_f32_16x16x32_bf16 v[102:105], v[220:223], v[182:185], v[102:105]
	v_mfma_f32_16x16x32_bf16 v[98:101], v[228:231], v[182:185], v[98:101]
	v_mfma_f32_16x16x32_bf16 v[86:89], v[220:223], v[190:193], v[86:89]
	v_mfma_f32_16x16x32_bf16 v[82:85], v[228:231], v[190:193], v[82:85]
	v_mfma_f32_16x16x32_bf16 v[70:73], v[220:223], v[212:215], v[70:73]
	v_mfma_f32_16x16x32_bf16 v[66:69], v[228:231], v[212:215], v[66:69]
	v_mfma_f32_16x16x32_bf16 v[118:121], v[224:227], v[150:153], v[118:121]
	v_mfma_f32_16x16x32_bf16 v[114:117], v[232:235], v[150:153], v[114:117]
	v_mfma_f32_16x16x32_bf16 v[102:105], v[224:227], v[186:189], v[102:105]
	v_mfma_f32_16x16x32_bf16 v[98:101], v[232:235], v[186:189], v[98:101]
	v_mfma_f32_16x16x32_bf16 v[86:89], v[224:227], v[194:197], v[86:89]
	v_mfma_f32_16x16x32_bf16 v[82:85], v[232:235], v[194:197], v[82:85]
	v_mfma_f32_16x16x32_bf16 v[70:73], v[224:227], v[216:219], v[70:73]
	v_mfma_f32_16x16x32_bf16 v[66:69], v[232:235], v[216:219], v[66:69]
	s_mov_b32 m0, s31
	v_lshl_add_u64 v[238:239], s[48:49], 0, v[176:177]
	s_barrier
	ds_read_b128 v[146:149], v210 offset:16384
	ds_read_b128 v[150:153], v210 offset:17408
	ds_read_b128 v[182:185], v210 offset:18432
	ds_read_b128 v[186:189], v210 offset:19456
	ds_read_b128 v[190:193], v210 offset:20480
	ds_read_b128 v[194:197], v210 offset:21504
	ds_read_b128 v[212:215], v210 offset:22528
	ds_read_b128 v[216:219], v210 offset:23552
	global_load_lds_dwordx4 v[238:239], off
	s_mov_b32 m0, s50
	v_lshl_add_u64 v[240:241], s[48:49], 0, v[172:173]
	global_load_lds_dwordx4 v[240:241], off
	s_barrier
	s_waitcnt lgkmcnt(0)
	v_mfma_f32_16x16x32_bf16 v[62:65], v[130:133], v[146:149], v[62:65]
	v_mfma_f32_16x16x32_bf16 v[58:61], v[138:141], v[146:149], v[58:61]
	v_mfma_f32_16x16x32_bf16 v[46:49], v[130:133], v[182:185], v[46:49]
	v_mfma_f32_16x16x32_bf16 v[42:45], v[138:141], v[182:185], v[42:45]
	v_mfma_f32_16x16x32_bf16 v[30:33], v[130:133], v[190:193], v[30:33]
	v_mfma_f32_16x16x32_bf16 v[26:29], v[138:141], v[190:193], v[26:29]
	v_mfma_f32_16x16x32_bf16 v[14:17], v[130:133], v[212:215], v[14:17]
	v_mfma_f32_16x16x32_bf16 v[10:13], v[138:141], v[212:215], v[10:13]
	v_mfma_f32_16x16x32_bf16 v[62:65], v[134:137], v[150:153], v[62:65]
	v_mfma_f32_16x16x32_bf16 v[58:61], v[142:145], v[150:153], v[58:61]
	v_mfma_f32_16x16x32_bf16 v[46:49], v[134:137], v[186:189], v[46:49]
	v_mfma_f32_16x16x32_bf16 v[42:45], v[142:145], v[186:189], v[42:45]
	v_mfma_f32_16x16x32_bf16 v[30:33], v[134:137], v[194:197], v[30:33]
	v_mfma_f32_16x16x32_bf16 v[26:29], v[142:145], v[194:197], v[26:29]
	v_mfma_f32_16x16x32_bf16 v[14:17], v[134:137], v[216:219], v[14:17]
	v_mfma_f32_16x16x32_bf16 v[10:13], v[142:145], v[216:219], v[10:13]
	s_barrier
; #define PG8_STAGE(bufoff, gbase, voff) do { _Pragma("unroll") for (int _i = 0; _i < 2; ++_i) \
;         __builtin_amdgcn_global_load_lds((const unsigned*)((const char*)(gbase) + (voff)[_i]), (LAS unsigned*)(lds + (bufoff) + ldsw + _i * 8192), 16, 0, 0); } while (0)
; #define PG8_LDA(dst, b, h) do { _Pragma("unroll") for (int m = 0; m < 4; ++m) _Pragma("unroll") for (int k = 0; k < 2; ++k) dst[m][k] = *(const LAS bf16x8*)(lds + PG8_SA(b, h) + aoff + m * 2048 + k * 1024); } while (0)
; #define PG8_LDB(dst, b, h) do { _Pragma("unroll") for (int n = 0; n < 2; ++n) _Pragma("unroll") for (int k = 0; k < 2; ++k) dst[n][k] = *(const LAS bf16x8*)(lds + PG8_SB(b, h) + boff + n * 2048 + k * 1024); } while (0)
; #define PG8_MMA(ai, bj, At, Bt) do { __builtin_amdgcn_s_setprio(1); _Pragma("unroll") for (int m = 0; m < 4; ++m) _Pragma("unroll") for (int n = 0; n < 2; ++n) _Pragma("unroll") for (int k = 0; k < 2; ++k) \
;         acc[ai][bj][m][n] = __builtin_amdgcn_mfma_f32_16x16x32_bf16(Bt[n][k], At[m][k], acc[ai][bj][m][n], 0, 0, 0); __builtin_amdgcn_s_setprio(0); } while (0)
; #define PG8_WAIT_V(n) asm volatile("s_waitcnt vmcnt(" #n ")" ::: "memory")
; #define PG8_WAIT_L(n) asm volatile("s_waitcnt lgkmcnt(" #n ")" ::: "memory")
; #define PG8_BAR __builtin_amdgcn_s_barrier()
; #define PG8_SCHED __builtin_amdgcn_sched_barrier(0)
; template <class Epi, class Sched>
; __device__ __forceinline__ void gemm_phase(LAS unsigned char* lds, const Gemm g, const Sched& S, const Epi& E) {
;     ...
;             PG8_STAGE(PG8_SB(0, 1), b2 + hstepB, voffB);
;             PG8_WAIT_V(6); PG8_BAR; PG8_MMA(1, 1, At, B1); PG8_BAR;
;             PG8_LDB(B0, 1, 0); PG8_SCHED; PG8_LDA(At, 1, 0); PG8_STAGE(PG8_SA(0, 1), a2 + hstepA, voffA);
;             PG8_WAIT_L(8); PG8_BAR; PG8_WAIT_L(0); PG8_MMA(0, 0, At, B0); PG8_BAR; PG8_SCHED;
;             PG8_LDB(B1, 1, 1); PG8_STAGE(PG8_SB(1, 0), b3, voffB);
;             PG8_BAR; PG8_WAIT_L(0); PG8_MMA(0, 1, At, B1); PG8_BAR;
;             PG8_LDA(At, 1, 1); PG8_STAGE(PG8_SA(1, 0), a3, voffA);
;             PG8_BAR; PG8_WAIT_L(0); PG8_MMA(1, 0, At, B0); PG8_BAR; PG8_SCHED;
	s_add_u32 s70, s46, 0x200000
	s_addc_u32 s71, s47, 0
	s_add_i32 s23, s23, s27
	s_mov_b32 m0, s23
	v_lshl_add_u64 v[130:131], s[70:71], 0, v[174:175]
	global_load_lds_dwordx4 v[130:131], off
	s_add_i32 m0, s23, 0x2000
	v_lshl_add_u64 v[130:131], s[70:71], 0, v[170:171]
	global_load_lds_dwordx4 v[130:131], off
	s_waitcnt vmcnt(6)
	s_barrier
	v_mfma_f32_16x16x32_bf16 v[54:57], v[220:223], v[146:149], v[54:57]
	v_mfma_f32_16x16x32_bf16 v[50:53], v[228:231], v[146:149], v[50:53]
	v_mfma_f32_16x16x32_bf16 v[38:41], v[220:223], v[182:185], v[38:41]
	v_mfma_f32_16x16x32_bf16 v[34:37], v[228:231], v[182:185], v[34:37]
	v_mfma_f32_16x16x32_bf16 v[22:25], v[220:223], v[190:193], v[22:25]
	v_mfma_f32_16x16x32_bf16 v[18:21], v[228:231], v[190:193], v[18:21]
	v_mfma_f32_16x16x32_bf16 v[6:9], v[220:223], v[212:215], v[6:9]
	v_mfma_f32_16x16x32_bf16 v[2:5], v[228:231], v[212:215], v[2:5]
	v_mfma_f32_16x16x32_bf16 v[54:57], v[224:227], v[150:153], v[54:57]
	v_mfma_f32_16x16x32_bf16 v[50:53], v[232:235], v[150:153], v[50:53]
	v_mfma_f32_16x16x32_bf16 v[38:41], v[224:227], v[186:189], v[38:41]
	v_mfma_f32_16x16x32_bf16 v[34:37], v[232:235], v[186:189], v[34:37]
	v_mfma_f32_16x16x32_bf16 v[22:25], v[224:227], v[194:197], v[22:25]
	v_mfma_f32_16x16x32_bf16 v[18:21], v[232:235], v[194:197], v[18:21]
	v_mfma_f32_16x16x32_bf16 v[6:9], v[224:227], v[216:219], v[6:9]
	v_mfma_f32_16x16x32_bf16 v[2:5], v[232:235], v[216:219], v[2:5]
	s_add_i32 s23, 0, 0x18000
	v_add_u32_e32 v142, s23, v162
	s_barrier
	ds_read_b128 v[130:133], v142
	ds_read_b128 v[134:137], v142 offset:1024
	ds_read_b128 v[138:141], v142 offset:2048
	ds_read_b128 v[142:145], v142 offset:3072
	s_add_u32 s48, s48, 0x200000
	s_addc_u32 s49, s49, 0
	s_mov_b32 m0, s51
	v_lshl_add_u64 v[220:221], s[48:49], 0, v[176:177]
	ds_read_b128 v[146:149], v210 offset:32768
	ds_read_b128 v[150:153], v210 offset:33792
	ds_read_b128 v[182:185], v210 offset:34816
	ds_read_b128 v[186:189], v210 offset:35840
	ds_read_b128 v[190:193], v210 offset:36864
	ds_read_b128 v[194:197], v210 offset:37888
	ds_read_b128 v[212:215], v210 offset:38912
	ds_read_b128 v[216:219], v210 offset:39936
	global_load_lds_dwordx4 v[220:221], off
	s_mov_b32 m0, s52
	v_lshl_add_u64 v[220:221], s[48:49], 0, v[172:173]
	global_load_lds_dwordx4 v[220:221], off
	s_waitcnt lgkmcnt(8)
	s_barrier
	s_waitcnt lgkmcnt(0)
	v_mfma_f32_16x16x32_bf16 v[126:129], v[130:133], v[146:149], v[126:129]
	v_mfma_f32_16x16x32_bf16 v[122:125], v[138:141], v[146:149], v[122:125]
	v_mfma_f32_16x16x32_bf16 v[110:113], v[130:133], v[182:185], v[110:113]
	v_mfma_f32_16x16x32_bf16 v[106:109], v[138:141], v[182:185], v[106:109]
	v_mfma_f32_16x16x32_bf16 v[94:97], v[130:133], v[190:193], v[94:97]
	v_mfma_f32_16x16x32_bf16 v[90:93], v[138:141], v[190:193], v[90:93]
	v_mfma_f32_16x16x32_bf16 v[78:81], v[130:133], v[212:215], v[78:81]
	v_mfma_f32_16x16x32_bf16 v[74:77], v[138:141], v[212:215], v[74:77]
	v_mfma_f32_16x16x32_bf16 v[126:129], v[134:137], v[150:153], v[126:129]
	v_mfma_f32_16x16x32_bf16 v[122:125], v[142:145], v[150:153], v[122:125]
	v_mfma_f32_16x16x32_bf16 v[110:113], v[134:137], v[186:189], v[110:113]
	v_mfma_f32_16x16x32_bf16 v[106:109], v[142:145], v[186:189], v[106:109]
	v_mfma_f32_16x16x32_bf16 v[94:97], v[134:137], v[194:197], v[94:97]
	v_mfma_f32_16x16x32_bf16 v[90:93], v[142:145], v[194:197], v[90:93]
	v_mfma_f32_16x16x32_bf16 v[78:81], v[134:137], v[216:219], v[78:81]
	v_mfma_f32_16x16x32_bf16 v[74:77], v[142:145], v[216:219], v[74:77]
	s_barrier
	s_add_i32 s48, 0, 0x1c000
	s_add_i32 s23, s23, s27
	v_add_u32_e32 v211, s48, v162
	v_lshl_add_u64 v[198:199], v[198:199], 0, s[10:11]
	s_mov_b32 m0, s23
	ds_read_b128 v[220:223], v211
	ds_read_b128 v[224:227], v211 offset:1024
	ds_read_b128 v[228:231], v211 offset:2048
	ds_read_b128 v[232:235], v211 offset:3072
	global_load_lds_dwordx4 v[198:199], off
	s_add_i32 m0, s23, 0x2000
	v_lshl_add_u64 v[198:199], v[236:237], 0, s[10:11]
	global_load_lds_dwordx4 v[198:199], off
	s_barrier
	s_waitcnt lgkmcnt(0)
	v_mfma_f32_16x16x32_bf16 v[118:121], v[220:223], v[146:149], v[118:121]
	v_mfma_f32_16x16x32_bf16 v[114:117], v[228:231], v[146:149], v[114:117]
	v_mfma_f32_16x16x32_bf16 v[102:105], v[220:223], v[182:185], v[102:105]
	v_mfma_f32_16x16x32_bf16 v[98:101], v[228:231], v[182:185], v[98:101]
	v_mfma_f32_16x16x32_bf16 v[86:89], v[220:223], v[190:193], v[86:89]
	v_mfma_f32_16x16x32_bf16 v[82:85], v[228:231], v[190:193], v[82:85]
	v_mfma_f32_16x16x32_bf16 v[70:73], v[220:223], v[212:215], v[70:73]
	v_mfma_f32_16x16x32_bf16 v[66:69], v[228:231], v[212:215], v[66:69]
	v_mfma_f32_16x16x32_bf16 v[118:121], v[224:227], v[150:153], v[118:121]
	v_mfma_f32_16x16x32_bf16 v[114:117], v[232:235], v[150:153], v[114:117]
	v_mfma_f32_16x16x32_bf16 v[102:105], v[224:227], v[186:189], v[102:105]
	v_mfma_f32_16x16x32_bf16 v[98:101], v[232:235], v[186:189], v[98:101]
	v_mfma_f32_16x16x32_bf16 v[86:89], v[224:227], v[194:197], v[86:89]
	v_mfma_f32_16x16x32_bf16 v[82:85], v[232:235], v[194:197], v[82:85]
	v_mfma_f32_16x16x32_bf16 v[70:73], v[224:227], v[216:219], v[70:73]
	v_mfma_f32_16x16x32_bf16 v[66:69], v[232:235], v[216:219], v[66:69]
	s_mov_b32 m0, s28
	v_lshl_add_u64 v[198:199], v[238:239], 0, s[10:11]
	s_barrier
	ds_read_b128 v[146:149], v210 offset:49152
	ds_read_b128 v[150:153], v210 offset:50176
	ds_read_b128 v[182:185], v210 offset:51200
	ds_read_b128 v[186:189], v210 offset:52224
	ds_read_b128 v[190:193], v210 offset:53248
	ds_read_b128 v[194:197], v210 offset:54272
	ds_read_b128 v[212:215], v210 offset:55296
	ds_read_b128 v[216:219], v210 offset:56320
	global_load_lds_dwordx4 v[198:199], off
	s_mov_b32 m0, s29
	v_lshl_add_u64 v[198:199], v[240:241], 0, s[10:11]
	global_load_lds_dwordx4 v[198:199], off
	s_barrier
; #define PG8_STAGE(bufoff, gbase, voff) do { _Pragma("unroll") for (int _i = 0; _i < 2; ++_i) \
;         __builtin_amdgcn_global_load_lds((const unsigned*)((const char*)(gbase) + (voff)[_i]), (LAS unsigned*)(lds + (bufoff) + ldsw + _i * 8192), 16, 0, 0); } while (0)
; #define PG8_MMA(ai, bj, At, Bt) do { __builtin_amdgcn_s_setprio(1); _Pragma("unroll") for (int m = 0; m < 4; ++m) _Pragma("unroll") for (int n = 0; n < 2; ++n) _Pragma("unroll") for (int k = 0; k < 2; ++k) \
;         acc[ai][bj][m][n] = __builtin_amdgcn_mfma_f32_16x16x32_bf16(Bt[n][k], At[m][k], acc[ai][bj][m][n], 0, 0, 0); __builtin_amdgcn_s_setprio(0); } while (0)
; #define PG8_WAIT_V(n) asm volatile("s_waitcnt vmcnt(" #n ")" ::: "memory")
; #define PG8_WAIT_L(n) asm volatile("s_waitcnt lgkmcnt(" #n ")" ::: "memory")
; #define PG8_BAR __builtin_amdgcn_s_barrier()
; #define PG8_SCHED __builtin_amdgcn_sched_barrier(0)
; template <class Epi, class Sched>
; __device__ __forceinline__ void gemm_phase(LAS unsigned char* lds, const Gemm g, const Sched& S, const Epi& E) {
;     ...
;             PG8_BAR; PG8_WAIT_L(0); PG8_MMA(1, 0, At, B0); PG8_BAR; PG8_SCHED;
;             PG8_STAGE(PG8_SB(1, 1), b3 + hstepB, voffB);
;             PG8_WAIT_V(6); PG8_BAR; PG8_MMA(1, 1, At, B1); PG8_BAR;
;         }
	s_waitcnt lgkmcnt(0)
	v_mfma_f32_16x16x32_bf16 v[62:65], v[130:133], v[146:149], v[62:65]
	v_mfma_f32_16x16x32_bf16 v[58:61], v[138:141], v[146:149], v[58:61]
	v_mfma_f32_16x16x32_bf16 v[46:49], v[130:133], v[182:185], v[46:49]
	v_mfma_f32_16x16x32_bf16 v[42:45], v[138:141], v[182:185], v[42:45]
	v_mfma_f32_16x16x32_bf16 v[30:33], v[130:133], v[190:193], v[30:33]
	v_mfma_f32_16x16x32_bf16 v[26:29], v[138:141], v[190:193], v[26:29]
	v_mfma_f32_16x16x32_bf16 v[14:17], v[130:133], v[212:215], v[14:17]
	v_mfma_f32_16x16x32_bf16 v[10:13], v[138:141], v[212:215], v[10:13]
	v_mfma_f32_16x16x32_bf16 v[62:65], v[134:137], v[150:153], v[62:65]
	v_mfma_f32_16x16x32_bf16 v[58:61], v[142:145], v[150:153], v[58:61]
	v_mfma_f32_16x16x32_bf16 v[46:49], v[134:137], v[186:189], v[46:49]
	v_mfma_f32_16x16x32_bf16 v[42:45], v[142:145], v[186:189], v[42:45]
	v_mfma_f32_16x16x32_bf16 v[30:33], v[134:137], v[194:197], v[30:33]
	v_mfma_f32_16x16x32_bf16 v[26:29], v[142:145], v[194:197], v[26:29]
	v_mfma_f32_16x16x32_bf16 v[14:17], v[134:137], v[216:219], v[14:17]
	v_mfma_f32_16x16x32_bf16 v[10:13], v[142:145], v[216:219], v[10:13]
	s_barrier
	s_add_u32 s46, s46, 0x200080
	s_addc_u32 s47, s47, 0
	s_add_i32 s23, s48, s27
	s_mov_b32 m0, s23
	v_lshl_add_u64 v[130:131], s[46:47], 0, v[174:175]
	global_load_lds_dwordx4 v[130:131], off
	s_add_i32 m0, s23, 0x2000
	v_lshl_add_u64 v[130:131], s[46:47], 0, v[170:171]
	global_load_lds_dwordx4 v[130:131], off
	s_waitcnt vmcnt(6)
	s_barrier
	v_mfma_f32_16x16x32_bf16 v[54:57], v[220:223], v[146:149], v[54:57]
	v_mfma_f32_16x16x32_bf16 v[50:53], v[228:231], v[146:149], v[50:53]
	v_mfma_f32_16x16x32_bf16 v[38:41], v[220:223], v[182:185], v[38:41]
	v_mfma_f32_16x16x32_bf16 v[34:37], v[228:231], v[182:185], v[34:37]
	v_mfma_f32_16x16x32_bf16 v[22:25], v[220:223], v[190:193], v[22:25]
	v_mfma_f32_16x16x32_bf16 v[18:21], v[228:231], v[190:193], v[18:21]
	v_mfma_f32_16x16x32_bf16 v[6:9], v[220:223], v[212:215], v[6:9]
	v_mfma_f32_16x16x32_bf16 v[2:5], v[228:231], v[212:215], v[2:5]
	v_mfma_f32_16x16x32_bf16 v[54:57], v[224:227], v[150:153], v[54:57]
	v_mfma_f32_16x16x32_bf16 v[50:53], v[232:235], v[150:153], v[50:53]
	v_mfma_f32_16x16x32_bf16 v[38:41], v[224:227], v[186:189], v[38:41]
	v_mfma_f32_16x16x32_bf16 v[34:37], v[232:235], v[186:189], v[34:37]
	v_mfma_f32_16x16x32_bf16 v[22:25], v[224:227], v[194:197], v[22:25]
	v_mfma_f32_16x16x32_bf16 v[18:21], v[232:235], v[194:197], v[18:21]
	v_mfma_f32_16x16x32_bf16 v[6:9], v[224:227], v[216:219], v[6:9]
	v_mfma_f32_16x16x32_bf16 v[2:5], v[232:235], v[216:219], v[2:5]
	s_add_i32 s66, s66, 2
	s_add_u32 s44, s44, 0x100
	s_addc_u32 s45, s45, 0
	s_add_u32 s59, s59, 0x100
	s_addc_u32 s68, s68, 0
	s_cmpk_gt_u32 s66, 0x7d
	s_barrier
	s_cbranch_scc0 .LBB0_899
; #define LAS __attribute__((address_space(3)))
; __device__ __forceinline__ unsigned cvt_pk_bf16(float lo, float hi) { unsigned r; asm volatile("v_cvt_pk_bf16_f32 %0, %1, %2" : "=v"(r) : "v"(lo), "v"(hi)); return r; }
; __device__ __forceinline__ float bf_lo(unsigned w) { return __uint_as_float(w << 16); }
; __device__ __forceinline__ float bf_hi(unsigned w) { return __uint_as_float(w & 0xffff0000u); }
;     __device__ __forceinline__ void operator()(const f32x4 (&acc)[2][2][4][2], const Unit& u, int ui, const LAS float* rtab, int wr, int wc, int fr, int fq) const {
;         const int row0 = u.pm * BM + wr * 64 + fr, col0 = u.pn * BM + wc * 32 + 8 * fq;
; #pragma unroll
;         for (int ai = 0; ai < 2; ++ai) {
;             u32x4 xv[4][2];
; #pragma unroll
;             for (int m = 0; m < 4; ++m)
; #pragma unroll
;                 for (int bj = 0; bj < 2; ++bj) xv[m][bj] = *(const u32x4*)(XB + (size_t)(row0 + ai * HALF + m * 16) * DM + col0 + bj * HALF);
; #pragma unroll
;             for (int m = 0; m < 4; ++m) { const int row = row0 + ai * HALF + m * 16; float ss = 0.f;
; #pragma unroll
;                 for (int bj = 0; bj < 2; ++bj) {
;                     const f32x4 a0 = acc[ai][bj][m][0], a1 = acc[ai][bj][m][1]; const u32x4 xo = xv[m][bj]; u32x4 w;
;                     w.x = cvt_pk_bf16(bf_lo(xo.x) + a0[0], bf_hi(xo.x) + a0[1]); w.y = cvt_pk_bf16(bf_lo(xo.y) + a0[2], bf_hi(xo.y) + a0[3]);
;                     w.z = cvt_pk_bf16(bf_lo(xo.z) + a1[0], bf_hi(xo.z) + a1[1]); w.w = cvt_pk_bf16(bf_lo(xo.w) + a1[2], bf_hi(xo.w) + a1[3]);
;                     *(u32x4*)(XB + (size_t)row * DM + col0 + bj * HALF) = w;
; #pragma unroll
;                     for (int e = 0; e < 4; ++e) { const float lo = bf_lo(w[e]), hi = bf_hi(w[e]); ss += lo * lo + hi * hi; }
;                 }
;                 ss += __shfl_xor(ss, 16); ss += __shfl_xor(ss, 32);
;                 if (fq == 0) ssq_next[(size_t)row * 32 + (u.pn & 7) * 4 + wc] = ss; }
	v_lshl_or_b32 v182, s55, 8, v209
	v_lshl_add_u32 v186, s56, 8, v1
	v_ashrrev_i32_e32 v183, 31, v182
	v_lshlrev_b64 v[130:131], 1, v[182:183]
	v_ashrrev_i32_e32 v187, 31, v186
	v_lshl_add_u64 v[184:185], s[74:75], 0, v[130:131]
	v_lshlrev_b64 v[132:133], 12, v[186:187]
	v_lshl_add_u64 v[134:135], v[184:185], 0, v[132:133]
	global_load_dwordx4 v[212:215], v[134:135], off
	global_load_dwordx4 v[216:219], v[134:135], off offset:256
	v_or_b32_e32 v196, 16, v186
	v_or_b32_e32 v192, 32, v186
	v_or_b32_e32 v188, 48, v186
	v_ashrrev_i32_e32 v197, 31, v196
	v_ashrrev_i32_e32 v193, 31, v192
	v_ashrrev_i32_e32 v189, 31, v188
	v_lshlrev_b64 v[198:199], 12, v[196:197]
	v_lshlrev_b64 v[194:195], 12, v[192:193]
	v_lshlrev_b64 v[190:191], 12, v[188:189]
	v_lshl_add_u64 v[132:133], s[74:75], 0, v[132:133]
	v_lshl_add_u64 v[134:135], v[184:185], 0, v[198:199]
	v_lshl_add_u64 v[136:137], v[184:185], 0, v[194:195]
	v_lshl_add_u64 v[220:221], v[184:185], 0, v[190:191]
	v_lshl_add_u64 v[222:223], v[132:133], 0, v[130:131]
	global_load_dwordx4 v[150:153], v[134:135], off
	global_load_dwordx4 v[146:149], v[134:135], off offset:256
	global_load_dwordx4 v[142:145], v[136:137], off
	global_load_dwordx4 v[138:141], v[136:137], off offset:256
	s_nop 0
	global_load_dwordx4 v[134:137], v[220:221], off
	global_load_dwordx4 v[130:133], v[220:221], off offset:256
	s_lshl_b32 s21, s55, 2
	s_and_b32 s21, s21, 28
	s_waitcnt vmcnt(0)
	v_lshlrev_b32_e32 v211, 16, v212
	v_and_b32_e32 v212, 0xffff0000, v212
	v_lshlrev_b32_e32 v220, 16, v213
	v_and_b32_e32 v213, 0xffff0000, v213
	v_lshlrev_b32_e32 v221, 16, v214
	v_and_b32_e32 v214, 0xffff0000, v214
	v_lshlrev_b32_e32 v227, 16, v218
	v_and_b32_e32 v218, 0xffff0000, v218
	v_lshlrev_b32_e32 v224, 16, v215
	v_and_b32_e32 v215, 0xffff0000, v215
	v_lshlrev_b32_e32 v228, 16, v219
	v_and_b32_e32 v219, 0xffff0000, v219
	v_add_f32_e32 v126, v126, v211
	v_add_f32_e32 v127, v127, v212
	v_add_f32_e32 v128, v128, v220
	v_add_f32_e32 v129, v129, v213
	v_add_f32_e32 v122, v122, v221
	v_add_f32_e32 v123, v123, v214
	v_add_f32_e32 v211, v114, v227
	v_add_f32_e32 v212, v115, v218
	v_cvt_pk_bf16_f32 v114, v126, v127
	v_cvt_pk_bf16_f32 v115, v128, v129
	v_add_f32_e32 v124, v124, v224
	v_add_f32_e32 v125, v125, v215
	v_add_f32_e32 v213, v116, v228
	v_add_f32_e32 v214, v117, v219
	v_cvt_pk_bf16_f32 v116, v122, v123
	v_cvt_pk_bf16_f32 v117, v124, v125
	global_store_dwordx4 v[222:223], v[114:117], off
	v_lshlrev_b32_e32 v122, 16, v114
	v_lshlrev_b32_e32 v123, 16, v115
	v_and_b32_e32 v114, 0xffff0000, v114
	v_and_b32_e32 v115, 0xffff0000, v115
	v_lshlrev_b32_e32 v225, 16, v216
	v_lshlrev_b32_e32 v124, 16, v116
	v_and_b32_e32 v116, 0xffff0000, v116
	v_mul_f32_e32 v114, v114, v114
	v_mul_f32_e32 v115, v115, v115
	v_and_b32_e32 v216, 0xffff0000, v216
	v_add_f32_e32 v118, v118, v225
	v_lshlrev_b32_e32 v125, 16, v117
	v_and_b32_e32 v117, 0xffff0000, v117
	v_mul_f32_e32 v116, v116, v116
	v_fmac_f32_e32 v114, v122, v122
	v_fmac_f32_e32 v115, v123, v123
	v_lshlrev_b32_e32 v226, 16, v217
	v_and_b32_e32 v217, 0xffff0000, v217
	v_add_f32_e32 v119, v119, v216
	v_cvt_pk_bf16_f32 v118, v118, v119
	v_mul_f32_e32 v117, v117, v117
	v_and_b32_e32 v127, 0xffff0000, v118
	v_fmac_f32_e32 v116, v124, v124
	v_add_f32_e32 v114, v114, v115
	v_add_f32_e32 v120, v120, v226
	v_add_f32_e32 v121, v121, v217
	v_cvt_pk_bf16_f32 v119, v120, v121
	v_lshlrev_b32_e32 v126, 16, v118
	v_fmac_f32_e32 v117, v125, v125
	v_mul_f32_e32 v122, v127, v127
	v_add_f32_e32 v114, v114, v116
	v_and_b32_e32 v116, 0xffff0000, v119
	v_fmac_f32_e32 v122, v126, v126
	v_add_f32_e32 v114, v114, v117
	v_lshlrev_b32_e32 v115, 16, v119
	v_mul_f32_e32 v116, v116, v116
	v_add_f32_e32 v114, v114, v122
	v_fmac_f32_e32 v116, v115, v115
	v_cvt_pk_bf16_f32 v120, v211, v212
	v_add_f32_e32 v114, v114, v116
	v_and_b32_e32 v116, 0xffff0000, v120
	v_lshlrev_b32_e32 v115, 16, v120
	v_mul_f32_e32 v116, v116, v116
	v_fmac_f32_e32 v116, v115, v115
	v_cvt_pk_bf16_f32 v121, v213, v214
	v_add_f32_e32 v114, v114, v116
	v_and_b32_e32 v116, 0xffff0000, v121
	v_lshlrev_b32_e32 v115, 16, v121
	v_mul_f32_e32 v116, v116, v116
	v_fmac_f32_e32 v116, v115, v115
	v_add_f32_e32 v115, v114, v116
	v_and_b32_e32 v116, 64, v207
	v_xor_b32_e32 v114, 16, v207
	v_add_u32_e32 v117, 64, v116
	v_cmp_lt_i32_e32 vcc, v114, v117
	global_store_dwordx4 v[222:223], v[118:121], off offset:256
	s_nop 0
	v_cndmask_b32_e32 v114, v207, v114, vcc
	v_lshlrev_b32_e32 v114, 2, v114
	ds_bpermute_b32 v116, v114, v115
	s_waitcnt lgkmcnt(0)
	v_add_f32_e32 v116, v115, v116
	v_xor_b32_e32 v115, 32, v207
	v_cmp_lt_i32_e32 vcc, v115, v117
	s_nop 1
	v_cndmask_b32_e32 v115, v207, v115, vcc
	v_lshlrev_b32_e32 v115, 2, v115
	ds_bpermute_b32 v117, v115, v116
	s_and_saveexec_b64 s[44:45], s[40:41]
	s_cbranch_execz .LBB0_902
	s_waitcnt lgkmcnt(0)
	v_add_f32_e32 v118, v116, v117
	v_lshlrev_b64 v[116:117], 7, v[186:187]
	v_lshl_add_u64 v[116:117], s[0:1], 0, v[116:117]
	s_lshl_b32 s68, s21, 2
	v_lshl_add_u64 v[116:117], v[116:117], 0, s[68:69]
	s_lshl_b32 s68, s53, 2
	v_lshl_add_u64 v[116:117], v[116:117], 0, s[68:69]
	global_store_dword v[116:117], v118, off
